# MFMA order: accumulator chains of two plus every chain boundary shares one operand register with its neighbour (alternating K order)
# speedup vs baseline: 1.0113x; 1.0053x over previous
.LBB0_74:
	s_ashr_i32 s27, s26, 31
	s_lshl_b64 s[28:29], s[26:27], 19
	s_add_u32 s28, s3, s28
	s_addc_u32 s29, s35, s29
	s_and_b64 s[30:31], s[4:5], exec
	s_cselect_b32 s27, s29, s49
	s_cselect_b32 s68, s28, s48
	s_ashr_i32 s23, s22, 31
	s_lshl_b64 s[30:31], s[22:23], 19
	s_add_u32 s30, s50, s30
	s_addc_u32 s31, s51, s31
	s_and_b64 s[70:71], s[4:5], exec
	s_cselect_b32 s69, s31, s47
	s_cselect_b32 s70, s30, s46
	s_lshl_b32 s23, s44, 8
	v_add_u32_e32 v0, s23, v148
	s_add_u32 s71, s46, 0x100
	v_ashrrev_i32_e32 v1, 31, v0
	s_addc_u32 s74, s47, 0
	v_lshl_add_u64 v[144:145], v[0:1], 4, s[12:13]
	s_add_u32 s44, s48, 0x40080
	s_addc_u32 s45, s49, 0
	s_mov_b32 s75, -2
	s_mov_b64 s[46:47], 0
	s_cmp_eq_u32 s59, 1
	s_cbranch_scc1 .Lfa_0
	v_add_u32_e32 v153, s64, v147
	ds_read_b128 v[160:163], v153
	ds_read_b128 v[164:167], v153 offset:1024
	ds_read_b128 v[168:171], v153 offset:2048
	ds_read_b128 v[172:175], v153 offset:3072
	v_add_u32_e32 v153, s65, v147
	ds_read_b128 v[176:179], v153
	ds_read_b128 v[180:183], v153 offset:1024
	ds_read_b128 v[186:189], v153 offset:2048
	ds_read_b128 v[190:193], v153 offset:3072
	s_add_u32 s48, s44, 0xfffc0080
	s_addc_u32 s49, s45, -1
	s_and_b64 s[46:47], s[46:47], exec
	s_cselect_b32 s49, s27, s49
	s_cselect_b32 s48, s68, s48
	s_cselect_b32 s47, s69, s74
	s_cselect_b32 s46, s70, s71
	v_lshl_add_u64 v[154:155], s[44:45], 0, v[138:139]
	s_add_i32 m0, s55, 0xc000
	ds_read_b128 v[194:197], v150
	ds_read_b128 v[198:201], v150 offset:1024
	ds_read_b128 v[202:205], v150 offset:2048
	ds_read_b128 v[206:209], v150 offset:3072
	ds_read_b128 v[210:213], v150 offset:4096
	ds_read_b128 v[214:217], v150 offset:5120
	ds_read_b128 v[218:221], v150 offset:6144
	ds_read_b128 v[222:225], v150 offset:7168
	global_load_lds_dwordx4 v[154:155], off
	v_lshl_add_u64 v[154:155], s[44:45], 0, v[136:137]
	s_add_i32 m0, s55, 0xe000
	s_nop 0
	global_load_lds_dwordx4 v[154:155], off
	s_waitcnt vmcnt(16)
	s_waitcnt lgkmcnt(0)
	s_barrier
	s_setprio 1
	s_waitcnt lgkmcnt(0)
	v_mfma_f32_16x16x32_bf16 v[124:127], v[160:163], v[194:197], 0
	v_mfma_f32_16x16x32_bf16 v[116:119], v[168:171], v[194:197], 0
	v_mfma_f32_16x16x32_bf16 v[108:111], v[160:163], v[202:205], 0
	v_mfma_f32_16x16x32_bf16 v[100:103], v[168:171], v[202:205], 0
	v_mfma_f32_16x16x32_bf16 v[92:95], v[160:163], v[210:213], 0
	v_mfma_f32_16x16x32_bf16 v[84:87], v[168:171], v[210:213], 0
	v_mfma_f32_16x16x32_bf16 v[76:79], v[160:163], v[218:221], 0
	v_mfma_f32_16x16x32_bf16 v[68:71], v[168:171], v[218:221], 0
	v_mfma_f32_16x16x32_bf16 v[124:127], v[164:167], v[198:201], v[124:127]
	v_mfma_f32_16x16x32_bf16 v[116:119], v[172:175], v[198:201], v[116:119]
	v_mfma_f32_16x16x32_bf16 v[108:111], v[164:167], v[206:209], v[108:111]
	v_mfma_f32_16x16x32_bf16 v[100:103], v[172:175], v[206:209], v[100:103]
	v_mfma_f32_16x16x32_bf16 v[92:95], v[164:167], v[214:217], v[92:95]
	v_mfma_f32_16x16x32_bf16 v[84:87], v[172:175], v[214:217], v[84:87]
	v_mfma_f32_16x16x32_bf16 v[76:79], v[164:167], v[222:225], v[76:79]
	v_mfma_f32_16x16x32_bf16 v[68:71], v[172:175], v[222:225], v[68:71]
	s_setprio 0
	s_setprio 1
	v_mfma_f32_16x16x32_bf16 v[120:123], v[176:179], v[194:197], 0
	v_mfma_f32_16x16x32_bf16 v[112:115], v[186:189], v[194:197], 0
	v_mfma_f32_16x16x32_bf16 v[104:107], v[176:179], v[202:205], 0
	v_mfma_f32_16x16x32_bf16 v[96:99], v[186:189], v[202:205], 0
	v_mfma_f32_16x16x32_bf16 v[88:91], v[176:179], v[210:213], 0
	v_mfma_f32_16x16x32_bf16 v[80:83], v[186:189], v[210:213], 0
	v_mfma_f32_16x16x32_bf16 v[72:75], v[176:179], v[218:221], 0
	v_mfma_f32_16x16x32_bf16 v[64:67], v[186:189], v[218:221], 0
	v_mfma_f32_16x16x32_bf16 v[120:123], v[180:183], v[198:201], v[120:123]
	v_mfma_f32_16x16x32_bf16 v[112:115], v[190:193], v[198:201], v[112:115]
	v_mfma_f32_16x16x32_bf16 v[104:107], v[180:183], v[206:209], v[104:107]
	v_mfma_f32_16x16x32_bf16 v[96:99], v[190:193], v[206:209], v[96:99]
	v_mfma_f32_16x16x32_bf16 v[88:91], v[180:183], v[214:217], v[88:91]
	v_mfma_f32_16x16x32_bf16 v[80:83], v[190:193], v[214:217], v[80:83]
	v_mfma_f32_16x16x32_bf16 v[72:75], v[180:183], v[222:225], v[72:75]
	v_mfma_f32_16x16x32_bf16 v[64:67], v[190:193], v[222:225], v[64:67]
	s_setprio 0
	s_barrier
	s_add_i32 s76, s64, s52
	v_lshl_add_u64 v[154:155], s[46:47], 0, v[132:133]
	s_mov_b32 m0, s76
	ds_read_b128 v[194:197], v150 offset:16384
	ds_read_b128 v[198:201], v150 offset:17408
	ds_read_b128 v[202:205], v150 offset:18432
	ds_read_b128 v[206:209], v150 offset:19456
	ds_read_b128 v[210:213], v150 offset:20480
	ds_read_b128 v[214:217], v150 offset:21504
	ds_read_b128 v[218:221], v150 offset:22528
	ds_read_b128 v[222:225], v150 offset:23552
	global_load_lds_dwordx4 v[154:155], off
	s_add_i32 m0, s76, 0x2000
	s_add_u32 s76, s46, 0x40000
	v_lshl_add_u64 v[226:227], s[46:47], 0, v[128:129]
	s_addc_u32 s77, s47, 0
	s_add_i32 s78, s65, s52
	global_load_lds_dwordx4 v[226:227], off
	v_lshl_add_u64 v[228:229], s[76:77], 0, v[132:133]
	s_mov_b32 m0, s78
	v_lshl_add_u64 v[230:231], s[48:49], 0, v[130:131]
	global_load_lds_dwordx4 v[228:229], off
	v_lshl_add_u64 v[228:229], s[76:77], 0, v[128:129]
	s_add_i32 m0, s78, 0x2000
	s_nop 0
	global_load_lds_dwordx4 v[228:229], off
	v_lshl_add_u64 v[228:229], s[48:49], 0, v[134:135]
	s_mov_b32 m0, s55
	s_nop 0
	global_load_lds_dwordx4 v[228:229], off
	s_mov_b32 m0, s56
	s_nop 0
	global_load_lds_dwordx4 v[230:231], off
	s_waitcnt vmcnt(16)
	s_waitcnt lgkmcnt(0)
	s_barrier
	s_setprio 1
	s_waitcnt lgkmcnt(0)
	v_mfma_f32_16x16x32_bf16 v[60:63], v[160:163], v[194:197], 0
	v_mfma_f32_16x16x32_bf16 v[52:55], v[168:171], v[194:197], 0
	v_mfma_f32_16x16x32_bf16 v[44:47], v[160:163], v[202:205], 0
	v_mfma_f32_16x16x32_bf16 v[36:39], v[168:171], v[202:205], 0
	v_mfma_f32_16x16x32_bf16 v[28:31], v[160:163], v[210:213], 0
	v_mfma_f32_16x16x32_bf16 v[20:23], v[168:171], v[210:213], 0
	v_mfma_f32_16x16x32_bf16 v[12:15], v[160:163], v[218:221], 0
	v_mfma_f32_16x16x32_bf16 v[4:7], v[168:171], v[218:221], 0
	v_mfma_f32_16x16x32_bf16 v[60:63], v[164:167], v[198:201], v[60:63]
	v_mfma_f32_16x16x32_bf16 v[52:55], v[172:175], v[198:201], v[52:55]
	v_mfma_f32_16x16x32_bf16 v[44:47], v[164:167], v[206:209], v[44:47]
	v_mfma_f32_16x16x32_bf16 v[36:39], v[172:175], v[206:209], v[36:39]
	v_mfma_f32_16x16x32_bf16 v[28:31], v[164:167], v[214:217], v[28:31]
	v_mfma_f32_16x16x32_bf16 v[20:23], v[172:175], v[214:217], v[20:23]
	v_mfma_f32_16x16x32_bf16 v[12:15], v[164:167], v[222:225], v[12:15]
	v_mfma_f32_16x16x32_bf16 v[4:7], v[172:175], v[222:225], v[4:7]
	s_setprio 0
	s_setprio 1
	v_mfma_f32_16x16x32_bf16 v[56:59], v[176:179], v[194:197], 0
	v_mfma_f32_16x16x32_bf16 v[48:51], v[186:189], v[194:197], 0
	v_mfma_f32_16x16x32_bf16 v[40:43], v[176:179], v[202:205], 0
	v_mfma_f32_16x16x32_bf16 v[32:35], v[186:189], v[202:205], 0
	v_mfma_f32_16x16x32_bf16 v[24:27], v[176:179], v[210:213], 0
	v_mfma_f32_16x16x32_bf16 v[16:19], v[186:189], v[210:213], 0
	v_mfma_f32_16x16x32_bf16 v[8:11], v[176:179], v[218:221], 0
	v_mfma_f32_16x16x32_bf16 v[0:3], v[186:189], v[218:221], 0
	v_mfma_f32_16x16x32_bf16 v[56:59], v[180:183], v[198:201], v[56:59]
	v_mfma_f32_16x16x32_bf16 v[48:51], v[190:193], v[198:201], v[48:51]
	v_mfma_f32_16x16x32_bf16 v[40:43], v[180:183], v[206:209], v[40:43]
	v_mfma_f32_16x16x32_bf16 v[32:35], v[190:193], v[206:209], v[32:35]
	v_mfma_f32_16x16x32_bf16 v[24:27], v[180:183], v[214:217], v[24:27]
	v_mfma_f32_16x16x32_bf16 v[16:19], v[190:193], v[214:217], v[16:19]
	v_mfma_f32_16x16x32_bf16 v[8:11], v[180:183], v[222:225], v[8:11]
	v_mfma_f32_16x16x32_bf16 v[0:3], v[190:193], v[222:225], v[0:3]
	s_setprio 0
	s_barrier
	s_add_i32 s76, 0, 0x18000
	v_add_u32_e32 v153, s76, v147
	s_add_i32 s77, 0, 0x1c000
	ds_read_b128 v[160:163], v153
	ds_read_b128 v[164:167], v153 offset:1024
	ds_read_b128 v[168:171], v153 offset:2048
	ds_read_b128 v[172:175], v153 offset:3072
	v_add_u32_e32 v153, s77, v147
	ds_read_b128 v[176:179], v153
	ds_read_b128 v[180:183], v153 offset:1024
	ds_read_b128 v[186:189], v153 offset:2048
	ds_read_b128 v[190:193], v153 offset:3072
	s_add_u32 s48, s48, 0x40000
	s_addc_u32 s49, s49, 0
	s_mov_b32 m0, s57
	v_lshl_add_u64 v[232:233], s[48:49], 0, v[134:135]
	ds_read_b128 v[194:197], v150 offset:32768
	ds_read_b128 v[198:201], v150 offset:33792
	ds_read_b128 v[202:205], v150 offset:34816
	ds_read_b128 v[206:209], v150 offset:35840
	ds_read_b128 v[210:213], v150 offset:36864
	ds_read_b128 v[214:217], v150 offset:37888
	ds_read_b128 v[218:221], v150 offset:38912
	ds_read_b128 v[222:225], v150 offset:39936
	global_load_lds_dwordx4 v[232:233], off
	v_lshl_add_u64 v[232:233], s[48:49], 0, v[130:131]
	s_mov_b32 m0, s58
	s_nop 0
	global_load_lds_dwordx4 v[232:233], off
	s_waitcnt vmcnt(8)
	s_waitcnt lgkmcnt(0)
	s_barrier
	s_setprio 1
	s_waitcnt lgkmcnt(0)
	v_mfma_f32_16x16x32_bf16 v[124:127], v[160:163], v[194:197], v[124:127]
	v_mfma_f32_16x16x32_bf16 v[124:127], v[164:167], v[198:201], v[124:127]
	v_mfma_f32_16x16x32_bf16 v[116:119], v[172:175], v[198:201], v[116:119]
	v_mfma_f32_16x16x32_bf16 v[116:119], v[168:171], v[194:197], v[116:119]
	v_mfma_f32_16x16x32_bf16 v[100:103], v[168:171], v[202:205], v[100:103]
	v_mfma_f32_16x16x32_bf16 v[100:103], v[172:175], v[206:209], v[100:103]
	v_mfma_f32_16x16x32_bf16 v[108:111], v[164:167], v[206:209], v[108:111]
	v_mfma_f32_16x16x32_bf16 v[108:111], v[160:163], v[202:205], v[108:111]
	v_mfma_f32_16x16x32_bf16 v[92:95], v[160:163], v[210:213], v[92:95]
	v_mfma_f32_16x16x32_bf16 v[92:95], v[164:167], v[214:217], v[92:95]
	v_mfma_f32_16x16x32_bf16 v[84:87], v[172:175], v[214:217], v[84:87]
	v_mfma_f32_16x16x32_bf16 v[84:87], v[168:171], v[210:213], v[84:87]
	v_mfma_f32_16x16x32_bf16 v[68:71], v[168:171], v[218:221], v[68:71]
	v_mfma_f32_16x16x32_bf16 v[68:71], v[172:175], v[222:225], v[68:71]
	v_mfma_f32_16x16x32_bf16 v[76:79], v[164:167], v[222:225], v[76:79]
	v_mfma_f32_16x16x32_bf16 v[76:79], v[160:163], v[218:221], v[76:79]
	s_setprio 0
	s_setprio 1
	v_mfma_f32_16x16x32_bf16 v[120:123], v[176:179], v[194:197], v[120:123]
	v_mfma_f32_16x16x32_bf16 v[120:123], v[180:183], v[198:201], v[120:123]
	v_mfma_f32_16x16x32_bf16 v[112:115], v[190:193], v[198:201], v[112:115]
	v_mfma_f32_16x16x32_bf16 v[112:115], v[186:189], v[194:197], v[112:115]
	v_mfma_f32_16x16x32_bf16 v[96:99], v[186:189], v[202:205], v[96:99]
	v_mfma_f32_16x16x32_bf16 v[96:99], v[190:193], v[206:209], v[96:99]
	v_mfma_f32_16x16x32_bf16 v[104:107], v[180:183], v[206:209], v[104:107]
	v_mfma_f32_16x16x32_bf16 v[104:107], v[176:179], v[202:205], v[104:107]
	v_mfma_f32_16x16x32_bf16 v[88:91], v[176:179], v[210:213], v[88:91]
	v_mfma_f32_16x16x32_bf16 v[88:91], v[180:183], v[214:217], v[88:91]
	v_mfma_f32_16x16x32_bf16 v[80:83], v[190:193], v[214:217], v[80:83]
	v_mfma_f32_16x16x32_bf16 v[80:83], v[186:189], v[210:213], v[80:83]
	v_mfma_f32_16x16x32_bf16 v[64:67], v[186:189], v[218:221], v[64:67]
	v_mfma_f32_16x16x32_bf16 v[64:67], v[190:193], v[222:225], v[64:67]
	v_mfma_f32_16x16x32_bf16 v[72:75], v[180:183], v[222:225], v[72:75]
	v_mfma_f32_16x16x32_bf16 v[72:75], v[176:179], v[218:221], v[72:75]
	s_setprio 0
	s_barrier
	s_add_i32 s48, s76, s52
	v_lshl_add_u64 v[154:155], v[154:155], 0, s[14:15]
	s_mov_b32 m0, s48
	ds_read_b128 v[194:197], v150 offset:49152
	ds_read_b128 v[198:201], v150 offset:50176
	ds_read_b128 v[202:205], v150 offset:51200
	ds_read_b128 v[206:209], v150 offset:52224
	ds_read_b128 v[210:213], v150 offset:53248
	ds_read_b128 v[214:217], v150 offset:54272
	ds_read_b128 v[218:221], v150 offset:55296
	ds_read_b128 v[222:225], v150 offset:56320
	global_load_lds_dwordx4 v[154:155], off
	s_add_i32 m0, s48, 0x2000
	s_add_u32 s46, s46, 0x40080
	v_lshl_add_u64 v[154:155], v[226:227], 0, s[14:15]
	s_addc_u32 s47, s47, 0
	s_add_i32 s48, s77, s52
	global_load_lds_dwordx4 v[154:155], off
	v_lshl_add_u64 v[154:155], s[46:47], 0, v[132:133]
	s_mov_b32 m0, s48
	s_nop 0
	global_load_lds_dwordx4 v[154:155], off
	v_lshl_add_u64 v[154:155], s[46:47], 0, v[128:129]
	s_add_i32 m0, s48, 0x2000
	s_nop 0
	global_load_lds_dwordx4 v[154:155], off
	v_lshl_add_u64 v[154:155], v[228:229], 0, s[14:15]
	s_mov_b32 m0, s60
	s_nop 0
	global_load_lds_dwordx4 v[154:155], off
	v_lshl_add_u64 v[154:155], v[230:231], 0, s[14:15]
	s_mov_b32 m0, s61
	s_nop 0
	global_load_lds_dwordx4 v[154:155], off
	s_waitcnt vmcnt(8)
	s_waitcnt lgkmcnt(0)
	s_barrier
	s_setprio 1
	s_waitcnt lgkmcnt(0)
	v_mfma_f32_16x16x32_bf16 v[60:63], v[160:163], v[194:197], v[60:63]
	v_mfma_f32_16x16x32_bf16 v[60:63], v[164:167], v[198:201], v[60:63]
	v_mfma_f32_16x16x32_bf16 v[52:55], v[172:175], v[198:201], v[52:55]
	v_mfma_f32_16x16x32_bf16 v[52:55], v[168:171], v[194:197], v[52:55]
	v_mfma_f32_16x16x32_bf16 v[36:39], v[168:171], v[202:205], v[36:39]
	v_mfma_f32_16x16x32_bf16 v[36:39], v[172:175], v[206:209], v[36:39]
	v_mfma_f32_16x16x32_bf16 v[44:47], v[164:167], v[206:209], v[44:47]
	v_mfma_f32_16x16x32_bf16 v[44:47], v[160:163], v[202:205], v[44:47]
	v_mfma_f32_16x16x32_bf16 v[28:31], v[160:163], v[210:213], v[28:31]
	v_mfma_f32_16x16x32_bf16 v[28:31], v[164:167], v[214:217], v[28:31]
	v_mfma_f32_16x16x32_bf16 v[20:23], v[172:175], v[214:217], v[20:23]
	v_mfma_f32_16x16x32_bf16 v[20:23], v[168:171], v[210:213], v[20:23]
	v_mfma_f32_16x16x32_bf16 v[4:7], v[168:171], v[218:221], v[4:7]
	v_mfma_f32_16x16x32_bf16 v[4:7], v[172:175], v[222:225], v[4:7]
	v_mfma_f32_16x16x32_bf16 v[12:15], v[164:167], v[222:225], v[12:15]
	v_mfma_f32_16x16x32_bf16 v[12:15], v[160:163], v[218:221], v[12:15]
	s_setprio 0
	s_setprio 1
	v_mfma_f32_16x16x32_bf16 v[56:59], v[176:179], v[194:197], v[56:59]
	v_mfma_f32_16x16x32_bf16 v[56:59], v[180:183], v[198:201], v[56:59]
	v_mfma_f32_16x16x32_bf16 v[48:51], v[190:193], v[198:201], v[48:51]
	v_mfma_f32_16x16x32_bf16 v[48:51], v[186:189], v[194:197], v[48:51]
	v_mfma_f32_16x16x32_bf16 v[32:35], v[186:189], v[202:205], v[32:35]
	v_mfma_f32_16x16x32_bf16 v[32:35], v[190:193], v[206:209], v[32:35]
	v_mfma_f32_16x16x32_bf16 v[40:43], v[180:183], v[206:209], v[40:43]
	v_mfma_f32_16x16x32_bf16 v[40:43], v[176:179], v[202:205], v[40:43]
	v_mfma_f32_16x16x32_bf16 v[24:27], v[176:179], v[210:213], v[24:27]
	v_mfma_f32_16x16x32_bf16 v[24:27], v[180:183], v[214:217], v[24:27]
	v_mfma_f32_16x16x32_bf16 v[16:19], v[190:193], v[214:217], v[16:19]
	v_mfma_f32_16x16x32_bf16 v[16:19], v[186:189], v[210:213], v[16:19]
	v_mfma_f32_16x16x32_bf16 v[0:3], v[186:189], v[218:221], v[0:3]
	v_mfma_f32_16x16x32_bf16 v[0:3], v[190:193], v[222:225], v[0:3]
	v_mfma_f32_16x16x32_bf16 v[8:11], v[180:183], v[222:225], v[8:11]
	v_mfma_f32_16x16x32_bf16 v[8:11], v[176:179], v[218:221], v[8:11]
	s_setprio 0
	s_barrier
	s_add_i32 s75, s75, 2
	s_add_u32 s71, s71, 0x100
	s_addc_u32 s74, s74, 0
	s_add_u32 s44, s44, 0x100
	s_addc_u32 s45, s45, 0
	s_branch .LBB0_76
.Lfa_0:
	v_add_u32_e32 v153, s64, v147
	ds_read_b128 v[160:163], v153
	ds_read_b128 v[164:167], v153 offset:1024
	ds_read_b128 v[168:171], v153 offset:2048
	ds_read_b128 v[172:175], v153 offset:3072
	v_add_u32_e32 v153, s65, v147
	ds_read_b128 v[176:179], v153
	ds_read_b128 v[180:183], v153 offset:1024
	ds_read_b128 v[186:189], v153 offset:2048
	ds_read_b128 v[190:193], v153 offset:3072
	s_add_u32 s48, s44, 0xfffc0080
	s_addc_u32 s49, s45, -1
	s_and_b64 s[46:47], s[46:47], exec
	s_cselect_b32 s49, s27, s49
	s_cselect_b32 s48, s68, s48
	s_cselect_b32 s47, s69, s74
	s_cselect_b32 s46, s70, s71
	v_lshl_add_u64 v[154:155], s[44:45], 0, v[138:139]
	s_add_i32 m0, s55, 0xc000
	ds_read_b128 v[194:197], v150
	ds_read_b128 v[198:201], v150 offset:1024
	ds_read_b128 v[202:205], v150 offset:2048
	ds_read_b128 v[206:209], v150 offset:3072
	ds_read_b128 v[210:213], v150 offset:4096
	ds_read_b128 v[214:217], v150 offset:5120
	ds_read_b128 v[218:221], v150 offset:6144
	ds_read_b128 v[222:225], v150 offset:7168
	global_load_lds_dwordx4 v[154:155], off
	v_lshl_add_u64 v[154:155], s[44:45], 0, v[136:137]
	s_add_i32 m0, s55, 0xe000
	s_nop 0
	global_load_lds_dwordx4 v[154:155], off
	s_waitcnt vmcnt(8)
	s_waitcnt lgkmcnt(0)
	s_barrier
	s_setprio 1
	s_waitcnt lgkmcnt(0)
	v_mfma_f32_16x16x32_bf16 v[124:127], v[160:163], v[194:197], 0
	v_mfma_f32_16x16x32_bf16 v[116:119], v[168:171], v[194:197], 0
	v_mfma_f32_16x16x32_bf16 v[108:111], v[160:163], v[202:205], 0
	v_mfma_f32_16x16x32_bf16 v[100:103], v[168:171], v[202:205], 0
	v_mfma_f32_16x16x32_bf16 v[92:95], v[160:163], v[210:213], 0
	v_mfma_f32_16x16x32_bf16 v[84:87], v[168:171], v[210:213], 0
	v_mfma_f32_16x16x32_bf16 v[76:79], v[160:163], v[218:221], 0
	v_mfma_f32_16x16x32_bf16 v[68:71], v[168:171], v[218:221], 0
	v_mfma_f32_16x16x32_bf16 v[124:127], v[164:167], v[198:201], v[124:127]
	v_mfma_f32_16x16x32_bf16 v[116:119], v[172:175], v[198:201], v[116:119]
	v_mfma_f32_16x16x32_bf16 v[108:111], v[164:167], v[206:209], v[108:111]
	v_mfma_f32_16x16x32_bf16 v[100:103], v[172:175], v[206:209], v[100:103]
	v_mfma_f32_16x16x32_bf16 v[92:95], v[164:167], v[214:217], v[92:95]
	v_mfma_f32_16x16x32_bf16 v[84:87], v[172:175], v[214:217], v[84:87]
	v_mfma_f32_16x16x32_bf16 v[76:79], v[164:167], v[222:225], v[76:79]
	v_mfma_f32_16x16x32_bf16 v[68:71], v[172:175], v[222:225], v[68:71]
	s_setprio 0
	s_setprio 1
	v_mfma_f32_16x16x32_bf16 v[120:123], v[176:179], v[194:197], 0
	v_mfma_f32_16x16x32_bf16 v[112:115], v[186:189], v[194:197], 0
	v_mfma_f32_16x16x32_bf16 v[104:107], v[176:179], v[202:205], 0
	v_mfma_f32_16x16x32_bf16 v[96:99], v[186:189], v[202:205], 0
	v_mfma_f32_16x16x32_bf16 v[88:91], v[176:179], v[210:213], 0
	v_mfma_f32_16x16x32_bf16 v[80:83], v[186:189], v[210:213], 0
	v_mfma_f32_16x16x32_bf16 v[72:75], v[176:179], v[218:221], 0
	v_mfma_f32_16x16x32_bf16 v[64:67], v[186:189], v[218:221], 0
	v_mfma_f32_16x16x32_bf16 v[120:123], v[180:183], v[198:201], v[120:123]
	v_mfma_f32_16x16x32_bf16 v[112:115], v[190:193], v[198:201], v[112:115]
	v_mfma_f32_16x16x32_bf16 v[104:107], v[180:183], v[206:209], v[104:107]
	v_mfma_f32_16x16x32_bf16 v[96:99], v[190:193], v[206:209], v[96:99]
	v_mfma_f32_16x16x32_bf16 v[88:91], v[180:183], v[214:217], v[88:91]
	v_mfma_f32_16x16x32_bf16 v[80:83], v[190:193], v[214:217], v[80:83]
	v_mfma_f32_16x16x32_bf16 v[72:75], v[180:183], v[222:225], v[72:75]
	v_mfma_f32_16x16x32_bf16 v[64:67], v[190:193], v[222:225], v[64:67]
	s_setprio 0
	s_barrier
	s_add_i32 s76, s64, s52
	v_lshl_add_u64 v[154:155], s[46:47], 0, v[132:133]
	s_mov_b32 m0, s76
	ds_read_b128 v[194:197], v150 offset:16384
	ds_read_b128 v[198:201], v150 offset:17408
	ds_read_b128 v[202:205], v150 offset:18432
	ds_read_b128 v[206:209], v150 offset:19456
	ds_read_b128 v[210:213], v150 offset:20480
	ds_read_b128 v[214:217], v150 offset:21504
	ds_read_b128 v[218:221], v150 offset:22528
	ds_read_b128 v[222:225], v150 offset:23552
	global_load_lds_dwordx4 v[154:155], off
	s_add_i32 m0, s76, 0x2000
	s_add_u32 s76, s46, 0x40000
	v_lshl_add_u64 v[226:227], s[46:47], 0, v[128:129]
	s_addc_u32 s77, s47, 0
	s_add_i32 s78, s65, s52
	global_load_lds_dwordx4 v[226:227], off
	v_lshl_add_u64 v[228:229], s[76:77], 0, v[132:133]
	s_mov_b32 m0, s78
	v_lshl_add_u64 v[230:231], s[48:49], 0, v[130:131]
	global_load_lds_dwordx4 v[228:229], off
	v_lshl_add_u64 v[228:229], s[76:77], 0, v[128:129]
	s_add_i32 m0, s78, 0x2000
	s_nop 0
	global_load_lds_dwordx4 v[228:229], off
	v_lshl_add_u64 v[228:229], s[48:49], 0, v[134:135]
	s_mov_b32 m0, s55
	s_nop 0
	global_load_lds_dwordx4 v[228:229], off
	s_mov_b32 m0, s56
	s_nop 0
	global_load_lds_dwordx4 v[230:231], off
	s_waitcnt vmcnt(8)
	s_waitcnt lgkmcnt(0)
	s_barrier
	s_setprio 1
	s_waitcnt lgkmcnt(0)
	v_mfma_f32_16x16x32_bf16 v[60:63], v[160:163], v[194:197], 0
	v_mfma_f32_16x16x32_bf16 v[52:55], v[168:171], v[194:197], 0
	v_mfma_f32_16x16x32_bf16 v[44:47], v[160:163], v[202:205], 0
	v_mfma_f32_16x16x32_bf16 v[36:39], v[168:171], v[202:205], 0
	v_mfma_f32_16x16x32_bf16 v[28:31], v[160:163], v[210:213], 0
	v_mfma_f32_16x16x32_bf16 v[20:23], v[168:171], v[210:213], 0
	v_mfma_f32_16x16x32_bf16 v[12:15], v[160:163], v[218:221], 0
	v_mfma_f32_16x16x32_bf16 v[4:7], v[168:171], v[218:221], 0
	v_mfma_f32_16x16x32_bf16 v[60:63], v[164:167], v[198:201], v[60:63]
	v_mfma_f32_16x16x32_bf16 v[52:55], v[172:175], v[198:201], v[52:55]
	v_mfma_f32_16x16x32_bf16 v[44:47], v[164:167], v[206:209], v[44:47]
	v_mfma_f32_16x16x32_bf16 v[36:39], v[172:175], v[206:209], v[36:39]
	v_mfma_f32_16x16x32_bf16 v[28:31], v[164:167], v[214:217], v[28:31]
	v_mfma_f32_16x16x32_bf16 v[20:23], v[172:175], v[214:217], v[20:23]
	v_mfma_f32_16x16x32_bf16 v[12:15], v[164:167], v[222:225], v[12:15]
	v_mfma_f32_16x16x32_bf16 v[4:7], v[172:175], v[222:225], v[4:7]
	s_setprio 0
	s_setprio 1
	v_mfma_f32_16x16x32_bf16 v[56:59], v[176:179], v[194:197], 0
	v_mfma_f32_16x16x32_bf16 v[48:51], v[186:189], v[194:197], 0
	v_mfma_f32_16x16x32_bf16 v[40:43], v[176:179], v[202:205], 0
	v_mfma_f32_16x16x32_bf16 v[32:35], v[186:189], v[202:205], 0
	v_mfma_f32_16x16x32_bf16 v[24:27], v[176:179], v[210:213], 0
	v_mfma_f32_16x16x32_bf16 v[16:19], v[186:189], v[210:213], 0
	v_mfma_f32_16x16x32_bf16 v[8:11], v[176:179], v[218:221], 0
	v_mfma_f32_16x16x32_bf16 v[0:3], v[186:189], v[218:221], 0
	v_mfma_f32_16x16x32_bf16 v[56:59], v[180:183], v[198:201], v[56:59]
	v_mfma_f32_16x16x32_bf16 v[48:51], v[190:193], v[198:201], v[48:51]
	v_mfma_f32_16x16x32_bf16 v[40:43], v[180:183], v[206:209], v[40:43]
	v_mfma_f32_16x16x32_bf16 v[32:35], v[190:193], v[206:209], v[32:35]
	v_mfma_f32_16x16x32_bf16 v[24:27], v[180:183], v[214:217], v[24:27]
	v_mfma_f32_16x16x32_bf16 v[16:19], v[190:193], v[214:217], v[16:19]
	v_mfma_f32_16x16x32_bf16 v[8:11], v[180:183], v[222:225], v[8:11]
	v_mfma_f32_16x16x32_bf16 v[0:3], v[190:193], v[222:225], v[0:3]
	s_setprio 0
	s_barrier
	s_add_i32 s76, 0, 0x18000
	v_add_u32_e32 v153, s76, v147
	s_add_i32 s77, 0, 0x1c000
	ds_read_b128 v[160:163], v153
	ds_read_b128 v[164:167], v153 offset:1024
	ds_read_b128 v[168:171], v153 offset:2048
	ds_read_b128 v[172:175], v153 offset:3072
	v_add_u32_e32 v153, s77, v147
	ds_read_b128 v[176:179], v153
	ds_read_b128 v[180:183], v153 offset:1024
	ds_read_b128 v[186:189], v153 offset:2048
	ds_read_b128 v[190:193], v153 offset:3072
	s_add_u32 s48, s48, 0x40000
	s_addc_u32 s49, s49, 0
	s_mov_b32 m0, s57
	v_lshl_add_u64 v[232:233], s[48:49], 0, v[134:135]
	ds_read_b128 v[194:197], v150 offset:32768
	ds_read_b128 v[198:201], v150 offset:33792
	ds_read_b128 v[202:205], v150 offset:34816
	ds_read_b128 v[206:209], v150 offset:35840
	ds_read_b128 v[210:213], v150 offset:36864
	ds_read_b128 v[214:217], v150 offset:37888
	ds_read_b128 v[218:221], v150 offset:38912
	ds_read_b128 v[222:225], v150 offset:39936
	global_load_lds_dwordx4 v[232:233], off
	v_lshl_add_u64 v[232:233], s[48:49], 0, v[130:131]
	s_mov_b32 m0, s58
	s_nop 0
	global_load_lds_dwordx4 v[232:233], off
	s_waitcnt vmcnt(8)
	s_waitcnt lgkmcnt(0)
	s_barrier
	s_setprio 1
	s_waitcnt lgkmcnt(0)
	v_mfma_f32_16x16x32_bf16 v[124:127], v[160:163], v[194:197], v[124:127]
	v_mfma_f32_16x16x32_bf16 v[124:127], v[164:167], v[198:201], v[124:127]
	v_mfma_f32_16x16x32_bf16 v[116:119], v[172:175], v[198:201], v[116:119]
	v_mfma_f32_16x16x32_bf16 v[116:119], v[168:171], v[194:197], v[116:119]
	v_mfma_f32_16x16x32_bf16 v[100:103], v[168:171], v[202:205], v[100:103]
	v_mfma_f32_16x16x32_bf16 v[100:103], v[172:175], v[206:209], v[100:103]
	v_mfma_f32_16x16x32_bf16 v[108:111], v[164:167], v[206:209], v[108:111]
	v_mfma_f32_16x16x32_bf16 v[108:111], v[160:163], v[202:205], v[108:111]
	v_mfma_f32_16x16x32_bf16 v[92:95], v[160:163], v[210:213], v[92:95]
	v_mfma_f32_16x16x32_bf16 v[92:95], v[164:167], v[214:217], v[92:95]
	v_mfma_f32_16x16x32_bf16 v[84:87], v[172:175], v[214:217], v[84:87]
	v_mfma_f32_16x16x32_bf16 v[84:87], v[168:171], v[210:213], v[84:87]
	v_mfma_f32_16x16x32_bf16 v[68:71], v[168:171], v[218:221], v[68:71]
	v_mfma_f32_16x16x32_bf16 v[68:71], v[172:175], v[222:225], v[68:71]
	v_mfma_f32_16x16x32_bf16 v[76:79], v[164:167], v[222:225], v[76:79]
	v_mfma_f32_16x16x32_bf16 v[76:79], v[160:163], v[218:221], v[76:79]
	s_setprio 0
	s_setprio 1
	v_mfma_f32_16x16x32_bf16 v[120:123], v[176:179], v[194:197], v[120:123]
	v_mfma_f32_16x16x32_bf16 v[120:123], v[180:183], v[198:201], v[120:123]
	v_mfma_f32_16x16x32_bf16 v[112:115], v[190:193], v[198:201], v[112:115]
	v_mfma_f32_16x16x32_bf16 v[112:115], v[186:189], v[194:197], v[112:115]
	v_mfma_f32_16x16x32_bf16 v[96:99], v[186:189], v[202:205], v[96:99]
	v_mfma_f32_16x16x32_bf16 v[96:99], v[190:193], v[206:209], v[96:99]
	v_mfma_f32_16x16x32_bf16 v[104:107], v[180:183], v[206:209], v[104:107]
	v_mfma_f32_16x16x32_bf16 v[104:107], v[176:179], v[202:205], v[104:107]
	v_mfma_f32_16x16x32_bf16 v[88:91], v[176:179], v[210:213], v[88:91]
	v_mfma_f32_16x16x32_bf16 v[88:91], v[180:183], v[214:217], v[88:91]
	v_mfma_f32_16x16x32_bf16 v[80:83], v[190:193], v[214:217], v[80:83]
	v_mfma_f32_16x16x32_bf16 v[80:83], v[186:189], v[210:213], v[80:83]
	v_mfma_f32_16x16x32_bf16 v[64:67], v[186:189], v[218:221], v[64:67]
	v_mfma_f32_16x16x32_bf16 v[64:67], v[190:193], v[222:225], v[64:67]
	v_mfma_f32_16x16x32_bf16 v[72:75], v[180:183], v[222:225], v[72:75]
	v_mfma_f32_16x16x32_bf16 v[72:75], v[176:179], v[218:221], v[72:75]
	s_setprio 0
	s_barrier
	s_add_i32 s48, s76, s52
	v_lshl_add_u64 v[154:155], v[154:155], 0, s[14:15]
	s_mov_b32 m0, s48
	ds_read_b128 v[194:197], v150 offset:49152
	ds_read_b128 v[198:201], v150 offset:50176
	ds_read_b128 v[202:205], v150 offset:51200
	ds_read_b128 v[206:209], v150 offset:52224
	ds_read_b128 v[210:213], v150 offset:53248
	ds_read_b128 v[214:217], v150 offset:54272
	ds_read_b128 v[218:221], v150 offset:55296
	ds_read_b128 v[222:225], v150 offset:56320
	global_load_lds_dwordx4 v[154:155], off
	s_add_i32 m0, s48, 0x2000
	s_add_u32 s46, s46, 0x40080
	v_lshl_add_u64 v[154:155], v[226:227], 0, s[14:15]
	s_addc_u32 s47, s47, 0
	s_add_i32 s48, s77, s52
	global_load_lds_dwordx4 v[154:155], off
	v_lshl_add_u64 v[154:155], s[46:47], 0, v[132:133]
	s_mov_b32 m0, s48
	s_nop 0
	global_load_lds_dwordx4 v[154:155], off
	v_lshl_add_u64 v[154:155], s[46:47], 0, v[128:129]
	s_add_i32 m0, s48, 0x2000
	s_nop 0
	global_load_lds_dwordx4 v[154:155], off
	v_lshl_add_u64 v[154:155], v[228:229], 0, s[14:15]
	s_mov_b32 m0, s60
	s_nop 0
	global_load_lds_dwordx4 v[154:155], off
	v_lshl_add_u64 v[154:155], v[230:231], 0, s[14:15]
	s_mov_b32 m0, s61
	s_nop 0
	global_load_lds_dwordx4 v[154:155], off
	s_waitcnt vmcnt(8)
	s_waitcnt lgkmcnt(0)
	s_barrier
	s_setprio 1
	s_waitcnt lgkmcnt(0)
	v_mfma_f32_16x16x32_bf16 v[60:63], v[160:163], v[194:197], v[60:63]
	v_mfma_f32_16x16x32_bf16 v[60:63], v[164:167], v[198:201], v[60:63]
	v_mfma_f32_16x16x32_bf16 v[52:55], v[172:175], v[198:201], v[52:55]
	v_mfma_f32_16x16x32_bf16 v[52:55], v[168:171], v[194:197], v[52:55]
	v_mfma_f32_16x16x32_bf16 v[36:39], v[168:171], v[202:205], v[36:39]
	v_mfma_f32_16x16x32_bf16 v[36:39], v[172:175], v[206:209], v[36:39]
	v_mfma_f32_16x16x32_bf16 v[44:47], v[164:167], v[206:209], v[44:47]
	v_mfma_f32_16x16x32_bf16 v[44:47], v[160:163], v[202:205], v[44:47]
	v_mfma_f32_16x16x32_bf16 v[28:31], v[160:163], v[210:213], v[28:31]
	v_mfma_f32_16x16x32_bf16 v[28:31], v[164:167], v[214:217], v[28:31]
	v_mfma_f32_16x16x32_bf16 v[20:23], v[172:175], v[214:217], v[20:23]
	v_mfma_f32_16x16x32_bf16 v[20:23], v[168:171], v[210:213], v[20:23]
	v_mfma_f32_16x16x32_bf16 v[4:7], v[168:171], v[218:221], v[4:7]
	v_mfma_f32_16x16x32_bf16 v[4:7], v[172:175], v[222:225], v[4:7]
	v_mfma_f32_16x16x32_bf16 v[12:15], v[164:167], v[222:225], v[12:15]
	v_mfma_f32_16x16x32_bf16 v[12:15], v[160:163], v[218:221], v[12:15]
	s_setprio 0
	s_setprio 1
	v_mfma_f32_16x16x32_bf16 v[56:59], v[176:179], v[194:197], v[56:59]
	v_mfma_f32_16x16x32_bf16 v[56:59], v[180:183], v[198:201], v[56:59]
	v_mfma_f32_16x16x32_bf16 v[48:51], v[190:193], v[198:201], v[48:51]
	v_mfma_f32_16x16x32_bf16 v[48:51], v[186:189], v[194:197], v[48:51]
	v_mfma_f32_16x16x32_bf16 v[32:35], v[186:189], v[202:205], v[32:35]
	v_mfma_f32_16x16x32_bf16 v[32:35], v[190:193], v[206:209], v[32:35]
	v_mfma_f32_16x16x32_bf16 v[40:43], v[180:183], v[206:209], v[40:43]
	v_mfma_f32_16x16x32_bf16 v[40:43], v[176:179], v[202:205], v[40:43]
	v_mfma_f32_16x16x32_bf16 v[24:27], v[176:179], v[210:213], v[24:27]
	v_mfma_f32_16x16x32_bf16 v[24:27], v[180:183], v[214:217], v[24:27]
	v_mfma_f32_16x16x32_bf16 v[16:19], v[190:193], v[214:217], v[16:19]
	v_mfma_f32_16x16x32_bf16 v[16:19], v[186:189], v[210:213], v[16:19]
	v_mfma_f32_16x16x32_bf16 v[0:3], v[186:189], v[218:221], v[0:3]
	v_mfma_f32_16x16x32_bf16 v[0:3], v[190:193], v[222:225], v[0:3]
	v_mfma_f32_16x16x32_bf16 v[8:11], v[180:183], v[222:225], v[8:11]
	v_mfma_f32_16x16x32_bf16 v[8:11], v[176:179], v[218:221], v[8:11]
	s_setprio 0
	s_barrier
	s_add_i32 s75, s75, 2
	s_add_u32 s71, s71, 0x100
	s_addc_u32 s74, s74, 0
	s_add_u32 s44, s44, 0x100
	s_addc_u32 s45, s45, 0
	s_branch .LBB0_76
.LBB0_75:
	v_add_u32_e32 v153, s64, v147
	ds_read_b128 v[160:163], v153
	ds_read_b128 v[164:167], v153 offset:1024
	ds_read_b128 v[168:171], v153 offset:2048
	ds_read_b128 v[172:175], v153 offset:3072
	v_add_u32_e32 v153, s65, v147
	ds_read_b128 v[176:179], v153
	ds_read_b128 v[180:183], v153 offset:1024
	ds_read_b128 v[186:189], v153 offset:2048
	ds_read_b128 v[190:193], v153 offset:3072
	s_add_u32 s48, s44, 0xfffc0080
	s_addc_u32 s49, s45, -1
	s_and_b64 s[46:47], s[46:47], exec
	s_cselect_b32 s49, s27, s49
	s_cselect_b32 s48, s68, s48
	s_cselect_b32 s47, s69, s74
	s_cselect_b32 s46, s70, s71
	v_lshl_add_u64 v[154:155], s[44:45], 0, v[138:139]
	s_add_i32 m0, s55, 0xc000
	ds_read_b128 v[194:197], v150
	ds_read_b128 v[198:201], v150 offset:1024
	ds_read_b128 v[202:205], v150 offset:2048
	ds_read_b128 v[206:209], v150 offset:3072
	ds_read_b128 v[210:213], v150 offset:4096
	ds_read_b128 v[214:217], v150 offset:5120
	ds_read_b128 v[218:221], v150 offset:6144
	ds_read_b128 v[222:225], v150 offset:7168
	global_load_lds_dwordx4 v[154:155], off
	v_lshl_add_u64 v[154:155], s[44:45], 0, v[136:137]
	s_add_i32 m0, s55, 0xe000
	s_nop 0
	global_load_lds_dwordx4 v[154:155], off
	s_waitcnt vmcnt(8)
	s_waitcnt lgkmcnt(0)
	s_barrier
	s_setprio 1
	s_waitcnt lgkmcnt(0)
	v_mfma_f32_16x16x32_bf16 v[124:127], v[160:163], v[194:197], v[124:127]
	v_mfma_f32_16x16x32_bf16 v[124:127], v[164:167], v[198:201], v[124:127]
	v_mfma_f32_16x16x32_bf16 v[116:119], v[172:175], v[198:201], v[116:119]
	v_mfma_f32_16x16x32_bf16 v[116:119], v[168:171], v[194:197], v[116:119]
	v_mfma_f32_16x16x32_bf16 v[100:103], v[168:171], v[202:205], v[100:103]
	v_mfma_f32_16x16x32_bf16 v[100:103], v[172:175], v[206:209], v[100:103]
	v_mfma_f32_16x16x32_bf16 v[108:111], v[164:167], v[206:209], v[108:111]
	v_mfma_f32_16x16x32_bf16 v[108:111], v[160:163], v[202:205], v[108:111]
	v_mfma_f32_16x16x32_bf16 v[92:95], v[160:163], v[210:213], v[92:95]
	v_mfma_f32_16x16x32_bf16 v[92:95], v[164:167], v[214:217], v[92:95]
	v_mfma_f32_16x16x32_bf16 v[84:87], v[172:175], v[214:217], v[84:87]
	v_mfma_f32_16x16x32_bf16 v[84:87], v[168:171], v[210:213], v[84:87]
	v_mfma_f32_16x16x32_bf16 v[68:71], v[168:171], v[218:221], v[68:71]
	v_mfma_f32_16x16x32_bf16 v[68:71], v[172:175], v[222:225], v[68:71]
	v_mfma_f32_16x16x32_bf16 v[76:79], v[164:167], v[222:225], v[76:79]
	v_mfma_f32_16x16x32_bf16 v[76:79], v[160:163], v[218:221], v[76:79]
	s_setprio 0
	s_setprio 1
	v_mfma_f32_16x16x32_bf16 v[120:123], v[176:179], v[194:197], v[120:123]
	v_mfma_f32_16x16x32_bf16 v[120:123], v[180:183], v[198:201], v[120:123]
	v_mfma_f32_16x16x32_bf16 v[112:115], v[190:193], v[198:201], v[112:115]
	v_mfma_f32_16x16x32_bf16 v[112:115], v[186:189], v[194:197], v[112:115]
	v_mfma_f32_16x16x32_bf16 v[96:99], v[186:189], v[202:205], v[96:99]
	v_mfma_f32_16x16x32_bf16 v[96:99], v[190:193], v[206:209], v[96:99]
	v_mfma_f32_16x16x32_bf16 v[104:107], v[180:183], v[206:209], v[104:107]
	v_mfma_f32_16x16x32_bf16 v[104:107], v[176:179], v[202:205], v[104:107]
	v_mfma_f32_16x16x32_bf16 v[88:91], v[176:179], v[210:213], v[88:91]
	v_mfma_f32_16x16x32_bf16 v[88:91], v[180:183], v[214:217], v[88:91]
	v_mfma_f32_16x16x32_bf16 v[80:83], v[190:193], v[214:217], v[80:83]
	v_mfma_f32_16x16x32_bf16 v[80:83], v[186:189], v[210:213], v[80:83]
	v_mfma_f32_16x16x32_bf16 v[64:67], v[186:189], v[218:221], v[64:67]
	v_mfma_f32_16x16x32_bf16 v[64:67], v[190:193], v[222:225], v[64:67]
	v_mfma_f32_16x16x32_bf16 v[72:75], v[180:183], v[222:225], v[72:75]
	v_mfma_f32_16x16x32_bf16 v[72:75], v[176:179], v[218:221], v[72:75]
	s_setprio 0
	s_barrier
	s_add_i32 s76, s64, s52
	v_lshl_add_u64 v[154:155], s[46:47], 0, v[132:133]
	s_mov_b32 m0, s76
	ds_read_b128 v[194:197], v150 offset:16384
	ds_read_b128 v[198:201], v150 offset:17408
	ds_read_b128 v[202:205], v150 offset:18432
	ds_read_b128 v[206:209], v150 offset:19456
	ds_read_b128 v[210:213], v150 offset:20480
	ds_read_b128 v[214:217], v150 offset:21504
	ds_read_b128 v[218:221], v150 offset:22528
	ds_read_b128 v[222:225], v150 offset:23552
	global_load_lds_dwordx4 v[154:155], off
	s_add_i32 m0, s76, 0x2000
	s_add_u32 s76, s46, 0x40000
	v_lshl_add_u64 v[226:227], s[46:47], 0, v[128:129]
	s_addc_u32 s77, s47, 0
	s_add_i32 s78, s65, s52
	global_load_lds_dwordx4 v[226:227], off
	v_lshl_add_u64 v[228:229], s[76:77], 0, v[132:133]
	s_mov_b32 m0, s78
	v_lshl_add_u64 v[230:231], s[48:49], 0, v[130:131]
	global_load_lds_dwordx4 v[228:229], off
	v_lshl_add_u64 v[228:229], s[76:77], 0, v[128:129]
	s_add_i32 m0, s78, 0x2000
	s_nop 0
	global_load_lds_dwordx4 v[228:229], off
	v_lshl_add_u64 v[228:229], s[48:49], 0, v[134:135]
	s_mov_b32 m0, s55
	s_nop 0
	global_load_lds_dwordx4 v[228:229], off
	s_mov_b32 m0, s56
	s_nop 0
	global_load_lds_dwordx4 v[230:231], off
	s_waitcnt vmcnt(8)
	s_waitcnt lgkmcnt(0)
	s_barrier
	s_setprio 1
	s_waitcnt lgkmcnt(0)
	v_mfma_f32_16x16x32_bf16 v[60:63], v[160:163], v[194:197], v[60:63]
	v_mfma_f32_16x16x32_bf16 v[60:63], v[164:167], v[198:201], v[60:63]
	v_mfma_f32_16x16x32_bf16 v[52:55], v[172:175], v[198:201], v[52:55]
	v_mfma_f32_16x16x32_bf16 v[52:55], v[168:171], v[194:197], v[52:55]
	v_mfma_f32_16x16x32_bf16 v[36:39], v[168:171], v[202:205], v[36:39]
	v_mfma_f32_16x16x32_bf16 v[36:39], v[172:175], v[206:209], v[36:39]
	v_mfma_f32_16x16x32_bf16 v[44:47], v[164:167], v[206:209], v[44:47]
	v_mfma_f32_16x16x32_bf16 v[44:47], v[160:163], v[202:205], v[44:47]
	v_mfma_f32_16x16x32_bf16 v[28:31], v[160:163], v[210:213], v[28:31]
	v_mfma_f32_16x16x32_bf16 v[28:31], v[164:167], v[214:217], v[28:31]
	v_mfma_f32_16x16x32_bf16 v[20:23], v[172:175], v[214:217], v[20:23]
	v_mfma_f32_16x16x32_bf16 v[20:23], v[168:171], v[210:213], v[20:23]
	v_mfma_f32_16x16x32_bf16 v[4:7], v[168:171], v[218:221], v[4:7]
	v_mfma_f32_16x16x32_bf16 v[4:7], v[172:175], v[222:225], v[4:7]
	v_mfma_f32_16x16x32_bf16 v[12:15], v[164:167], v[222:225], v[12:15]
	v_mfma_f32_16x16x32_bf16 v[12:15], v[160:163], v[218:221], v[12:15]
	s_setprio 0
	s_setprio 1
	v_mfma_f32_16x16x32_bf16 v[56:59], v[176:179], v[194:197], v[56:59]
	v_mfma_f32_16x16x32_bf16 v[56:59], v[180:183], v[198:201], v[56:59]
	v_mfma_f32_16x16x32_bf16 v[48:51], v[190:193], v[198:201], v[48:51]
	v_mfma_f32_16x16x32_bf16 v[48:51], v[186:189], v[194:197], v[48:51]
	v_mfma_f32_16x16x32_bf16 v[32:35], v[186:189], v[202:205], v[32:35]
	v_mfma_f32_16x16x32_bf16 v[32:35], v[190:193], v[206:209], v[32:35]
	v_mfma_f32_16x16x32_bf16 v[40:43], v[180:183], v[206:209], v[40:43]
	v_mfma_f32_16x16x32_bf16 v[40:43], v[176:179], v[202:205], v[40:43]
	v_mfma_f32_16x16x32_bf16 v[24:27], v[176:179], v[210:213], v[24:27]
	v_mfma_f32_16x16x32_bf16 v[24:27], v[180:183], v[214:217], v[24:27]
	v_mfma_f32_16x16x32_bf16 v[16:19], v[190:193], v[214:217], v[16:19]
	v_mfma_f32_16x16x32_bf16 v[16:19], v[186:189], v[210:213], v[16:19]
	v_mfma_f32_16x16x32_bf16 v[0:3], v[186:189], v[218:221], v[0:3]
	v_mfma_f32_16x16x32_bf16 v[0:3], v[190:193], v[222:225], v[0:3]
	v_mfma_f32_16x16x32_bf16 v[8:11], v[180:183], v[222:225], v[8:11]
	v_mfma_f32_16x16x32_bf16 v[8:11], v[176:179], v[218:221], v[8:11]
	s_setprio 0
	s_barrier
	s_add_i32 s76, 0, 0x18000
	v_add_u32_e32 v153, s76, v147
	s_add_i32 s77, 0, 0x1c000
	ds_read_b128 v[160:163], v153
	ds_read_b128 v[164:167], v153 offset:1024
	ds_read_b128 v[168:171], v153 offset:2048
	ds_read_b128 v[172:175], v153 offset:3072
	v_add_u32_e32 v153, s77, v147
	ds_read_b128 v[176:179], v153
	ds_read_b128 v[180:183], v153 offset:1024
	ds_read_b128 v[186:189], v153 offset:2048
	ds_read_b128 v[190:193], v153 offset:3072
	s_add_u32 s48, s48, 0x40000
	s_addc_u32 s49, s49, 0
	s_mov_b32 m0, s57
	v_lshl_add_u64 v[232:233], s[48:49], 0, v[134:135]
	ds_read_b128 v[194:197], v150 offset:32768
	ds_read_b128 v[198:201], v150 offset:33792
	ds_read_b128 v[202:205], v150 offset:34816
	ds_read_b128 v[206:209], v150 offset:35840
	ds_read_b128 v[210:213], v150 offset:36864
	ds_read_b128 v[214:217], v150 offset:37888
	ds_read_b128 v[218:221], v150 offset:38912
	ds_read_b128 v[222:225], v150 offset:39936
	global_load_lds_dwordx4 v[232:233], off
	v_lshl_add_u64 v[232:233], s[48:49], 0, v[130:131]
	s_mov_b32 m0, s58
	s_nop 0
	global_load_lds_dwordx4 v[232:233], off
	s_waitcnt vmcnt(8)
	s_waitcnt lgkmcnt(0)
	s_barrier
	s_setprio 1
	s_waitcnt lgkmcnt(0)
	v_mfma_f32_16x16x32_bf16 v[124:127], v[160:163], v[194:197], v[124:127]
	v_mfma_f32_16x16x32_bf16 v[124:127], v[164:167], v[198:201], v[124:127]
	v_mfma_f32_16x16x32_bf16 v[116:119], v[172:175], v[198:201], v[116:119]
	v_mfma_f32_16x16x32_bf16 v[116:119], v[168:171], v[194:197], v[116:119]
	v_mfma_f32_16x16x32_bf16 v[100:103], v[168:171], v[202:205], v[100:103]
	v_mfma_f32_16x16x32_bf16 v[100:103], v[172:175], v[206:209], v[100:103]
	v_mfma_f32_16x16x32_bf16 v[108:111], v[164:167], v[206:209], v[108:111]
	v_mfma_f32_16x16x32_bf16 v[108:111], v[160:163], v[202:205], v[108:111]
	v_mfma_f32_16x16x32_bf16 v[92:95], v[160:163], v[210:213], v[92:95]
	v_mfma_f32_16x16x32_bf16 v[92:95], v[164:167], v[214:217], v[92:95]
	v_mfma_f32_16x16x32_bf16 v[84:87], v[172:175], v[214:217], v[84:87]
	v_mfma_f32_16x16x32_bf16 v[84:87], v[168:171], v[210:213], v[84:87]
	v_mfma_f32_16x16x32_bf16 v[68:71], v[168:171], v[218:221], v[68:71]
	v_mfma_f32_16x16x32_bf16 v[68:71], v[172:175], v[222:225], v[68:71]
	v_mfma_f32_16x16x32_bf16 v[76:79], v[164:167], v[222:225], v[76:79]
	v_mfma_f32_16x16x32_bf16 v[76:79], v[160:163], v[218:221], v[76:79]
	s_setprio 0
	s_setprio 1
	v_mfma_f32_16x16x32_bf16 v[120:123], v[176:179], v[194:197], v[120:123]
	v_mfma_f32_16x16x32_bf16 v[120:123], v[180:183], v[198:201], v[120:123]
	v_mfma_f32_16x16x32_bf16 v[112:115], v[190:193], v[198:201], v[112:115]
	v_mfma_f32_16x16x32_bf16 v[112:115], v[186:189], v[194:197], v[112:115]
	v_mfma_f32_16x16x32_bf16 v[96:99], v[186:189], v[202:205], v[96:99]
	v_mfma_f32_16x16x32_bf16 v[96:99], v[190:193], v[206:209], v[96:99]
	v_mfma_f32_16x16x32_bf16 v[104:107], v[180:183], v[206:209], v[104:107]
	v_mfma_f32_16x16x32_bf16 v[104:107], v[176:179], v[202:205], v[104:107]
	v_mfma_f32_16x16x32_bf16 v[88:91], v[176:179], v[210:213], v[88:91]
	v_mfma_f32_16x16x32_bf16 v[88:91], v[180:183], v[214:217], v[88:91]
	v_mfma_f32_16x16x32_bf16 v[80:83], v[190:193], v[214:217], v[80:83]
	v_mfma_f32_16x16x32_bf16 v[80:83], v[186:189], v[210:213], v[80:83]
	v_mfma_f32_16x16x32_bf16 v[64:67], v[186:189], v[218:221], v[64:67]
	v_mfma_f32_16x16x32_bf16 v[64:67], v[190:193], v[222:225], v[64:67]
	v_mfma_f32_16x16x32_bf16 v[72:75], v[180:183], v[222:225], v[72:75]
	v_mfma_f32_16x16x32_bf16 v[72:75], v[176:179], v[218:221], v[72:75]
	s_setprio 0
	s_barrier
	s_add_i32 s48, s76, s52
	v_lshl_add_u64 v[154:155], v[154:155], 0, s[14:15]
	s_mov_b32 m0, s48
	ds_read_b128 v[194:197], v150 offset:49152
	ds_read_b128 v[198:201], v150 offset:50176
	ds_read_b128 v[202:205], v150 offset:51200
	ds_read_b128 v[206:209], v150 offset:52224
	ds_read_b128 v[210:213], v150 offset:53248
	ds_read_b128 v[214:217], v150 offset:54272
	ds_read_b128 v[218:221], v150 offset:55296
	ds_read_b128 v[222:225], v150 offset:56320
	global_load_lds_dwordx4 v[154:155], off
	s_add_i32 m0, s48, 0x2000
	s_add_u32 s46, s46, 0x40080
	v_lshl_add_u64 v[154:155], v[226:227], 0, s[14:15]
	s_addc_u32 s47, s47, 0
	s_add_i32 s48, s77, s52
	global_load_lds_dwordx4 v[154:155], off
	v_lshl_add_u64 v[154:155], s[46:47], 0, v[132:133]
	s_mov_b32 m0, s48
	s_nop 0
	global_load_lds_dwordx4 v[154:155], off
	v_lshl_add_u64 v[154:155], s[46:47], 0, v[128:129]
	s_add_i32 m0, s48, 0x2000
	s_nop 0
	global_load_lds_dwordx4 v[154:155], off
	v_lshl_add_u64 v[154:155], v[228:229], 0, s[14:15]
	s_mov_b32 m0, s60
	s_nop 0
	global_load_lds_dwordx4 v[154:155], off
	v_lshl_add_u64 v[154:155], v[230:231], 0, s[14:15]
	s_mov_b32 m0, s61
	s_nop 0
	global_load_lds_dwordx4 v[154:155], off
	s_waitcnt vmcnt(8)
	s_waitcnt lgkmcnt(0)
	s_barrier
	s_setprio 1
	s_waitcnt lgkmcnt(0)
	v_mfma_f32_16x16x32_bf16 v[60:63], v[160:163], v[194:197], v[60:63]
	v_mfma_f32_16x16x32_bf16 v[60:63], v[164:167], v[198:201], v[60:63]
	v_mfma_f32_16x16x32_bf16 v[52:55], v[172:175], v[198:201], v[52:55]
	v_mfma_f32_16x16x32_bf16 v[52:55], v[168:171], v[194:197], v[52:55]
	v_mfma_f32_16x16x32_bf16 v[36:39], v[168:171], v[202:205], v[36:39]
	v_mfma_f32_16x16x32_bf16 v[36:39], v[172:175], v[206:209], v[36:39]
	v_mfma_f32_16x16x32_bf16 v[44:47], v[164:167], v[206:209], v[44:47]
	v_mfma_f32_16x16x32_bf16 v[44:47], v[160:163], v[202:205], v[44:47]
	v_mfma_f32_16x16x32_bf16 v[28:31], v[160:163], v[210:213], v[28:31]
	v_mfma_f32_16x16x32_bf16 v[28:31], v[164:167], v[214:217], v[28:31]
	v_mfma_f32_16x16x32_bf16 v[20:23], v[172:175], v[214:217], v[20:23]
	v_mfma_f32_16x16x32_bf16 v[20:23], v[168:171], v[210:213], v[20:23]
	v_mfma_f32_16x16x32_bf16 v[4:7], v[168:171], v[218:221], v[4:7]
	v_mfma_f32_16x16x32_bf16 v[4:7], v[172:175], v[222:225], v[4:7]
	v_mfma_f32_16x16x32_bf16 v[12:15], v[164:167], v[222:225], v[12:15]
	v_mfma_f32_16x16x32_bf16 v[12:15], v[160:163], v[218:221], v[12:15]
	s_setprio 0
	s_setprio 1
	v_mfma_f32_16x16x32_bf16 v[56:59], v[176:179], v[194:197], v[56:59]
	v_mfma_f32_16x16x32_bf16 v[56:59], v[180:183], v[198:201], v[56:59]
	v_mfma_f32_16x16x32_bf16 v[48:51], v[190:193], v[198:201], v[48:51]
	v_mfma_f32_16x16x32_bf16 v[48:51], v[186:189], v[194:197], v[48:51]
	v_mfma_f32_16x16x32_bf16 v[32:35], v[186:189], v[202:205], v[32:35]
	v_mfma_f32_16x16x32_bf16 v[32:35], v[190:193], v[206:209], v[32:35]
	v_mfma_f32_16x16x32_bf16 v[40:43], v[180:183], v[206:209], v[40:43]
	v_mfma_f32_16x16x32_bf16 v[40:43], v[176:179], v[202:205], v[40:43]
	v_mfma_f32_16x16x32_bf16 v[24:27], v[176:179], v[210:213], v[24:27]
	v_mfma_f32_16x16x32_bf16 v[24:27], v[180:183], v[214:217], v[24:27]
	v_mfma_f32_16x16x32_bf16 v[16:19], v[190:193], v[214:217], v[16:19]
	v_mfma_f32_16x16x32_bf16 v[16:19], v[186:189], v[210:213], v[16:19]
	v_mfma_f32_16x16x32_bf16 v[0:3], v[186:189], v[218:221], v[0:3]
	v_mfma_f32_16x16x32_bf16 v[0:3], v[190:193], v[222:225], v[0:3]
	v_mfma_f32_16x16x32_bf16 v[8:11], v[180:183], v[222:225], v[8:11]
	v_mfma_f32_16x16x32_bf16 v[8:11], v[176:179], v[218:221], v[8:11]
	s_setprio 0
	s_barrier
	s_add_i32 s75, s75, 2
	s_add_u32 s71, s71, 0x100
	s_addc_u32 s74, s74, 0
	s_add_u32 s44, s44, 0x100
	s_addc_u32 s45, s45, 0
	s_cmp_gt_u32 s75, 13
	s_cbranch_scc1 .LBB0_78

.Llast_0:
	v_add_u32_e32 v153, s64, v147
	ds_read_b128 v[160:163], v153
	ds_read_b128 v[164:167], v153 offset:1024
	ds_read_b128 v[168:171], v153 offset:2048
	ds_read_b128 v[172:175], v153 offset:3072
	v_add_u32_e32 v153, s65, v147
	ds_read_b128 v[176:179], v153
	ds_read_b128 v[180:183], v153 offset:1024
	ds_read_b128 v[186:189], v153 offset:2048
	ds_read_b128 v[190:193], v153 offset:3072
	s_add_u32 s48, s44, 0xfffc0080
	s_addc_u32 s49, s45, -1
	s_and_b64 s[46:47], s[46:47], exec
	s_cselect_b32 s49, s27, s49
	s_cselect_b32 s48, s68, s48
	s_cselect_b32 s47, s69, s74
	s_cselect_b32 s46, s70, s71
	v_lshl_add_u64 v[154:155], s[44:45], 0, v[138:139]
	s_add_i32 m0, s55, 0xc000
	ds_read_b128 v[194:197], v150
	ds_read_b128 v[198:201], v150 offset:1024
	ds_read_b128 v[202:205], v150 offset:2048
	ds_read_b128 v[206:209], v150 offset:3072
	ds_read_b128 v[210:213], v150 offset:4096
	ds_read_b128 v[214:217], v150 offset:5120
	ds_read_b128 v[218:221], v150 offset:6144
	ds_read_b128 v[222:225], v150 offset:7168
	global_load_lds_dwordx4 v[154:155], off
	v_lshl_add_u64 v[154:155], s[44:45], 0, v[136:137]
	s_add_i32 m0, s55, 0xe000
	s_nop 0
	global_load_lds_dwordx4 v[154:155], off
	s_waitcnt vmcnt(8)
	s_waitcnt lgkmcnt(0)
	s_barrier
	s_setprio 1
	s_waitcnt lgkmcnt(0)
	v_mfma_f32_16x16x32_bf16 v[124:127], v[160:163], v[194:197], v[124:127]
	v_mfma_f32_16x16x32_bf16 v[124:127], v[164:167], v[198:201], v[124:127]
	v_mfma_f32_16x16x32_bf16 v[116:119], v[172:175], v[198:201], v[116:119]
	v_mfma_f32_16x16x32_bf16 v[116:119], v[168:171], v[194:197], v[116:119]
	v_mfma_f32_16x16x32_bf16 v[100:103], v[168:171], v[202:205], v[100:103]
	v_mfma_f32_16x16x32_bf16 v[100:103], v[172:175], v[206:209], v[100:103]
	v_mfma_f32_16x16x32_bf16 v[108:111], v[164:167], v[206:209], v[108:111]
	v_mfma_f32_16x16x32_bf16 v[108:111], v[160:163], v[202:205], v[108:111]
	v_mfma_f32_16x16x32_bf16 v[92:95], v[160:163], v[210:213], v[92:95]
	v_mfma_f32_16x16x32_bf16 v[92:95], v[164:167], v[214:217], v[92:95]
	v_mfma_f32_16x16x32_bf16 v[84:87], v[172:175], v[214:217], v[84:87]
	v_mfma_f32_16x16x32_bf16 v[84:87], v[168:171], v[210:213], v[84:87]
	v_mfma_f32_16x16x32_bf16 v[68:71], v[168:171], v[218:221], v[68:71]
	v_mfma_f32_16x16x32_bf16 v[68:71], v[172:175], v[222:225], v[68:71]
	v_mfma_f32_16x16x32_bf16 v[76:79], v[164:167], v[222:225], v[76:79]
	v_mfma_f32_16x16x32_bf16 v[76:79], v[160:163], v[218:221], v[76:79]
	s_setprio 0
	s_setprio 1
	v_mfma_f32_16x16x32_bf16 v[120:123], v[176:179], v[194:197], v[120:123]
	v_mfma_f32_16x16x32_bf16 v[120:123], v[180:183], v[198:201], v[120:123]
	v_mfma_f32_16x16x32_bf16 v[112:115], v[190:193], v[198:201], v[112:115]
	v_mfma_f32_16x16x32_bf16 v[112:115], v[186:189], v[194:197], v[112:115]
	v_mfma_f32_16x16x32_bf16 v[96:99], v[186:189], v[202:205], v[96:99]
	v_mfma_f32_16x16x32_bf16 v[96:99], v[190:193], v[206:209], v[96:99]
	v_mfma_f32_16x16x32_bf16 v[104:107], v[180:183], v[206:209], v[104:107]
	v_mfma_f32_16x16x32_bf16 v[104:107], v[176:179], v[202:205], v[104:107]
	v_mfma_f32_16x16x32_bf16 v[88:91], v[176:179], v[210:213], v[88:91]
	v_mfma_f32_16x16x32_bf16 v[88:91], v[180:183], v[214:217], v[88:91]
	v_mfma_f32_16x16x32_bf16 v[80:83], v[190:193], v[214:217], v[80:83]
	v_mfma_f32_16x16x32_bf16 v[80:83], v[186:189], v[210:213], v[80:83]
	v_mfma_f32_16x16x32_bf16 v[64:67], v[186:189], v[218:221], v[64:67]
	v_mfma_f32_16x16x32_bf16 v[64:67], v[190:193], v[222:225], v[64:67]
	v_mfma_f32_16x16x32_bf16 v[72:75], v[180:183], v[222:225], v[72:75]
	v_mfma_f32_16x16x32_bf16 v[72:75], v[176:179], v[218:221], v[72:75]
	s_setprio 0
	s_barrier
	s_add_i32 s76, s64, s52
	v_lshl_add_u64 v[154:155], s[46:47], 0, v[132:133]
	s_mov_b32 m0, s76
	ds_read_b128 v[194:197], v150 offset:16384
	ds_read_b128 v[198:201], v150 offset:17408
	ds_read_b128 v[202:205], v150 offset:18432
	ds_read_b128 v[206:209], v150 offset:19456
	ds_read_b128 v[210:213], v150 offset:20480
	ds_read_b128 v[214:217], v150 offset:21504
	ds_read_b128 v[218:221], v150 offset:22528
	ds_read_b128 v[222:225], v150 offset:23552
	global_load_lds_dwordx4 v[154:155], off
	s_add_i32 m0, s76, 0x2000
	s_add_u32 s76, s46, 0x40000
	v_lshl_add_u64 v[226:227], s[46:47], 0, v[128:129]
	s_addc_u32 s77, s47, 0
	s_add_i32 s78, s65, s52
	global_load_lds_dwordx4 v[226:227], off
	v_lshl_add_u64 v[228:229], s[76:77], 0, v[132:133]
	s_mov_b32 m0, s78
	v_lshl_add_u64 v[230:231], s[48:49], 0, v[130:131]
	global_load_lds_dwordx4 v[228:229], off
	v_lshl_add_u64 v[228:229], s[76:77], 0, v[128:129]
	s_add_i32 m0, s78, 0x2000
	s_nop 0
	global_load_lds_dwordx4 v[228:229], off
	v_lshl_add_u64 v[228:229], s[48:49], 0, v[134:135]
	s_mov_b32 m0, s55
	s_nop 0
	global_load_lds_dwordx4 v[228:229], off
	s_mov_b32 m0, s56
	s_nop 0
	global_load_lds_dwordx4 v[230:231], off
	s_waitcnt vmcnt(8)
	s_waitcnt lgkmcnt(0)
	s_barrier
	s_setprio 1
	s_waitcnt lgkmcnt(0)
	v_mfma_f32_16x16x32_bf16 v[60:63], v[160:163], v[194:197], v[60:63]
	v_mfma_f32_16x16x32_bf16 v[60:63], v[164:167], v[198:201], v[60:63]
	v_mfma_f32_16x16x32_bf16 v[52:55], v[172:175], v[198:201], v[52:55]
	v_mfma_f32_16x16x32_bf16 v[52:55], v[168:171], v[194:197], v[52:55]
	v_mfma_f32_16x16x32_bf16 v[36:39], v[168:171], v[202:205], v[36:39]
	v_mfma_f32_16x16x32_bf16 v[36:39], v[172:175], v[206:209], v[36:39]
	v_mfma_f32_16x16x32_bf16 v[44:47], v[164:167], v[206:209], v[44:47]
	v_mfma_f32_16x16x32_bf16 v[44:47], v[160:163], v[202:205], v[44:47]
	v_mfma_f32_16x16x32_bf16 v[28:31], v[160:163], v[210:213], v[28:31]
	v_mfma_f32_16x16x32_bf16 v[28:31], v[164:167], v[214:217], v[28:31]
	v_mfma_f32_16x16x32_bf16 v[20:23], v[172:175], v[214:217], v[20:23]
	v_mfma_f32_16x16x32_bf16 v[20:23], v[168:171], v[210:213], v[20:23]
	v_mfma_f32_16x16x32_bf16 v[4:7], v[168:171], v[218:221], v[4:7]
	v_mfma_f32_16x16x32_bf16 v[4:7], v[172:175], v[222:225], v[4:7]
	v_mfma_f32_16x16x32_bf16 v[12:15], v[164:167], v[222:225], v[12:15]
	v_mfma_f32_16x16x32_bf16 v[12:15], v[160:163], v[218:221], v[12:15]
	s_setprio 0
	s_setprio 1
	v_mfma_f32_16x16x32_bf16 v[56:59], v[176:179], v[194:197], v[56:59]
	v_mfma_f32_16x16x32_bf16 v[56:59], v[180:183], v[198:201], v[56:59]
	v_mfma_f32_16x16x32_bf16 v[48:51], v[190:193], v[198:201], v[48:51]
	v_mfma_f32_16x16x32_bf16 v[48:51], v[186:189], v[194:197], v[48:51]
	v_mfma_f32_16x16x32_bf16 v[32:35], v[186:189], v[202:205], v[32:35]
	v_mfma_f32_16x16x32_bf16 v[32:35], v[190:193], v[206:209], v[32:35]
	v_mfma_f32_16x16x32_bf16 v[40:43], v[180:183], v[206:209], v[40:43]
	v_mfma_f32_16x16x32_bf16 v[40:43], v[176:179], v[202:205], v[40:43]
	v_mfma_f32_16x16x32_bf16 v[24:27], v[176:179], v[210:213], v[24:27]
	v_mfma_f32_16x16x32_bf16 v[24:27], v[180:183], v[214:217], v[24:27]
	v_mfma_f32_16x16x32_bf16 v[16:19], v[190:193], v[214:217], v[16:19]
	v_mfma_f32_16x16x32_bf16 v[16:19], v[186:189], v[210:213], v[16:19]
	v_mfma_f32_16x16x32_bf16 v[0:3], v[186:189], v[218:221], v[0:3]
	v_mfma_f32_16x16x32_bf16 v[0:3], v[190:193], v[222:225], v[0:3]
	v_mfma_f32_16x16x32_bf16 v[8:11], v[180:183], v[222:225], v[8:11]
	v_mfma_f32_16x16x32_bf16 v[8:11], v[176:179], v[218:221], v[8:11]
	s_setprio 0
	s_barrier
	s_add_i32 s76, 0, 0x18000
	v_add_u32_e32 v153, s76, v147
	s_add_i32 s77, 0, 0x1c000
	ds_read_b128 v[160:163], v153
	ds_read_b128 v[164:167], v153 offset:1024
	ds_read_b128 v[168:171], v153 offset:2048
	ds_read_b128 v[172:175], v153 offset:3072
	v_add_u32_e32 v153, s77, v147
	ds_read_b128 v[176:179], v153
	ds_read_b128 v[180:183], v153 offset:1024
	ds_read_b128 v[186:189], v153 offset:2048
	ds_read_b128 v[190:193], v153 offset:3072
	s_add_u32 s48, s48, 0x40000
	s_addc_u32 s49, s49, 0
	s_mov_b32 m0, s57
	v_lshl_add_u64 v[232:233], s[48:49], 0, v[134:135]
	ds_read_b128 v[194:197], v150 offset:32768
	ds_read_b128 v[198:201], v150 offset:33792
	ds_read_b128 v[202:205], v150 offset:34816
	ds_read_b128 v[206:209], v150 offset:35840
	ds_read_b128 v[210:213], v150 offset:36864
	ds_read_b128 v[214:217], v150 offset:37888
	ds_read_b128 v[218:221], v150 offset:38912
	ds_read_b128 v[222:225], v150 offset:39936
	global_load_lds_dwordx4 v[232:233], off
	v_lshl_add_u64 v[232:233], s[48:49], 0, v[130:131]
	s_mov_b32 m0, s58
	s_nop 0
	global_load_lds_dwordx4 v[232:233], off
	s_waitcnt vmcnt(8)
	s_waitcnt lgkmcnt(0)
	s_barrier
	s_setprio 1
	s_waitcnt lgkmcnt(0)
	v_mfma_f32_16x16x32_bf16 v[124:127], v[160:163], v[194:197], v[124:127]
	v_mfma_f32_16x16x32_bf16 v[124:127], v[164:167], v[198:201], v[124:127]
	v_mfma_f32_16x16x32_bf16 v[116:119], v[172:175], v[198:201], v[116:119]
	v_mfma_f32_16x16x32_bf16 v[116:119], v[168:171], v[194:197], v[116:119]
	v_mfma_f32_16x16x32_bf16 v[100:103], v[168:171], v[202:205], v[100:103]
	v_mfma_f32_16x16x32_bf16 v[100:103], v[172:175], v[206:209], v[100:103]
	v_mfma_f32_16x16x32_bf16 v[108:111], v[164:167], v[206:209], v[108:111]
	v_mfma_f32_16x16x32_bf16 v[108:111], v[160:163], v[202:205], v[108:111]
	v_mfma_f32_16x16x32_bf16 v[92:95], v[160:163], v[210:213], v[92:95]
	v_mfma_f32_16x16x32_bf16 v[92:95], v[164:167], v[214:217], v[92:95]
	v_mfma_f32_16x16x32_bf16 v[84:87], v[172:175], v[214:217], v[84:87]
	v_mfma_f32_16x16x32_bf16 v[84:87], v[168:171], v[210:213], v[84:87]
	v_mfma_f32_16x16x32_bf16 v[68:71], v[168:171], v[218:221], v[68:71]
	v_mfma_f32_16x16x32_bf16 v[68:71], v[172:175], v[222:225], v[68:71]
	v_mfma_f32_16x16x32_bf16 v[76:79], v[164:167], v[222:225], v[76:79]
	v_mfma_f32_16x16x32_bf16 v[76:79], v[160:163], v[218:221], v[76:79]
	s_setprio 0
	s_setprio 1
	v_mfma_f32_16x16x32_bf16 v[120:123], v[176:179], v[194:197], v[120:123]
	v_mfma_f32_16x16x32_bf16 v[120:123], v[180:183], v[198:201], v[120:123]
	v_mfma_f32_16x16x32_bf16 v[112:115], v[190:193], v[198:201], v[112:115]
	v_mfma_f32_16x16x32_bf16 v[112:115], v[186:189], v[194:197], v[112:115]
	v_mfma_f32_16x16x32_bf16 v[96:99], v[186:189], v[202:205], v[96:99]
	v_mfma_f32_16x16x32_bf16 v[96:99], v[190:193], v[206:209], v[96:99]
	v_mfma_f32_16x16x32_bf16 v[104:107], v[180:183], v[206:209], v[104:107]
	v_mfma_f32_16x16x32_bf16 v[104:107], v[176:179], v[202:205], v[104:107]
	v_mfma_f32_16x16x32_bf16 v[88:91], v[176:179], v[210:213], v[88:91]
	v_mfma_f32_16x16x32_bf16 v[88:91], v[180:183], v[214:217], v[88:91]
	v_mfma_f32_16x16x32_bf16 v[80:83], v[190:193], v[214:217], v[80:83]
	v_mfma_f32_16x16x32_bf16 v[80:83], v[186:189], v[210:213], v[80:83]
	v_mfma_f32_16x16x32_bf16 v[64:67], v[186:189], v[218:221], v[64:67]
	v_mfma_f32_16x16x32_bf16 v[64:67], v[190:193], v[222:225], v[64:67]
	v_mfma_f32_16x16x32_bf16 v[72:75], v[180:183], v[222:225], v[72:75]
	v_mfma_f32_16x16x32_bf16 v[72:75], v[176:179], v[218:221], v[72:75]
	s_setprio 0
	s_barrier
	v_add_u32_e32 v234, 0x21000, v151
	ds_read_b128 v[236:239], v234
	ds_read_b128 v[240:243], v234 offset:256
	ds_read_b128 v[244:247], v234 offset:512
	ds_read_b128 v[248:251], v234 offset:768
	v_add_u32_e32 v235, s23, v146
	v_mul_u32_u24_e32 v235, 0x1600, v235
	v_lshl_or_b32 v234, s67, 7, v149
	v_lshl_add_u32 v235, v234, 1, v235
	s_add_i32 s48, s76, s52
	v_lshl_add_u64 v[154:155], v[154:155], 0, s[14:15]
	s_mov_b32 m0, s48
	ds_read_b128 v[194:197], v150 offset:49152
	ds_read_b128 v[198:201], v150 offset:50176
	ds_read_b128 v[202:205], v150 offset:51200
	ds_read_b128 v[206:209], v150 offset:52224
	ds_read_b128 v[210:213], v150 offset:53248
	ds_read_b128 v[214:217], v150 offset:54272
	ds_read_b128 v[218:221], v150 offset:55296
	ds_read_b128 v[222:225], v150 offset:56320
	global_load_lds_dwordx4 v[154:155], off
	s_add_i32 m0, s48, 0x2000
	s_add_u32 s46, s46, 0x40080
	v_lshl_add_u64 v[154:155], v[226:227], 0, s[14:15]
	s_addc_u32 s47, s47, 0
	s_add_i32 s48, s77, s52
	global_load_lds_dwordx4 v[154:155], off
	v_lshl_add_u64 v[154:155], s[46:47], 0, v[132:133]
	s_mov_b32 m0, s48
	s_nop 0
	global_load_lds_dwordx4 v[154:155], off
	v_lshl_add_u64 v[154:155], s[46:47], 0, v[128:129]
	s_add_i32 m0, s48, 0x2000
	s_nop 0
	global_load_lds_dwordx4 v[154:155], off
	v_lshl_add_u64 v[154:155], v[228:229], 0, s[14:15]
	s_mov_b32 m0, s60
	s_nop 0
	global_load_lds_dwordx4 v[154:155], off
	v_lshl_add_u64 v[154:155], v[230:231], 0, s[14:15]
	s_mov_b32 m0, s61
	s_nop 0
	global_load_lds_dwordx4 v[154:155], off
	s_waitcnt lgkmcnt(8)
	v_add_f32_e32 v236, v236, v237
	v_add_f32_e32 v238, v238, v239
	v_add_f32_e32 v240, v240, v241
	v_add_f32_e32 v242, v242, v243
	v_add_f32_e32 v244, v244, v245
	v_add_f32_e32 v246, v246, v247
	v_add_f32_e32 v248, v248, v249
	v_add_f32_e32 v250, v250, v251
	v_add_f32_e32 v236, v236, v238
	v_add_f32_e32 v240, v240, v242
	v_add_f32_e32 v244, v244, v246
	v_add_f32_e32 v248, v248, v250
	v_fmamk_f32 v236, v236, 0x3a800000, v152
	v_fmamk_f32 v240, v240, 0x3a800000, v152
	v_fmamk_f32 v244, v244, 0x3a800000, v152
	v_fmamk_f32 v248, v248, 0x3a800000, v152
	v_rsq_f32_e32 v236, v236
	v_rsq_f32_e32 v240, v240
	v_rsq_f32_e32 v244, v244
	v_rsq_f32_e32 v248, v248
	v_mul_f32_e32 v252, 0xbfb8aa3b, v236
	v_mul_f32_e32 v254, v236, v236
	v_pk_mul_f32 v[120:121], v[124:125], v[120:121]
	v_pk_mul_f32 v[122:123], v[126:127], v[122:123]
	v_pk_mul_f32 v[112:113], v[116:117], v[112:113]
	v_pk_mul_f32 v[114:115], v[118:119], v[114:115]
	v_pk_mul_f32 v[124:125], v[124:125], v[252:253] op_sel_hi:[1,0]
	v_pk_mul_f32 v[126:127], v[126:127], v[252:253] op_sel_hi:[1,0]
	v_pk_mul_f32 v[116:117], v[116:117], v[252:253] op_sel_hi:[1,0]
	v_pk_mul_f32 v[118:119], v[118:119], v[252:253] op_sel_hi:[1,0]
	v_exp_f32_e32 v124, v124
	v_exp_f32_e32 v125, v125
	v_exp_f32_e32 v126, v126
	v_exp_f32_e32 v127, v127
	v_exp_f32_e32 v116, v116
	v_exp_f32_e32 v117, v117
	v_exp_f32_e32 v118, v118
	v_exp_f32_e32 v119, v119
	v_pk_add_f32 v[124:125], v[124:125], 1.0 op_sel_hi:[1,0]
	v_pk_add_f32 v[126:127], v[126:127], 1.0 op_sel_hi:[1,0]
	v_pk_add_f32 v[116:117], v[116:117], 1.0 op_sel_hi:[1,0]
	v_pk_add_f32 v[118:119], v[118:119], 1.0 op_sel_hi:[1,0]
	v_rcp_f32_e32 v124, v124
	v_rcp_f32_e32 v125, v125
	v_rcp_f32_e32 v126, v126
	v_rcp_f32_e32 v127, v127
	v_rcp_f32_e32 v116, v116
	v_rcp_f32_e32 v117, v117
	v_rcp_f32_e32 v118, v118
	v_rcp_f32_e32 v119, v119
	v_pk_mul_f32 v[120:121], v[120:121], v[254:255] op_sel_hi:[1,0]
	v_pk_mul_f32 v[122:123], v[122:123], v[254:255] op_sel_hi:[1,0]
	v_pk_mul_f32 v[112:113], v[112:113], v[254:255] op_sel_hi:[1,0]
	v_pk_mul_f32 v[114:115], v[114:115], v[254:255] op_sel_hi:[1,0]
	v_pk_mul_f32 v[120:121], v[120:121], v[124:125]
	v_pk_mul_f32 v[122:123], v[122:123], v[126:127]
	v_pk_mul_f32 v[112:113], v[112:113], v[116:117]
	v_pk_mul_f32 v[114:115], v[114:115], v[118:119]
	v_cvt_pk_bf16_f32 v120, v120, v121
	v_cvt_pk_bf16_f32 v121, v122, v123
	v_cvt_pk_bf16_f32 v122, v112, v113
	v_cvt_pk_bf16_f32 v123, v114, v115
	global_store_dwordx4 v235, v[120:123], s[10:11]
	v_add_u32_e32 v234, 0x16000, v235
	v_mul_f32_e32 v252, 0xbfb8aa3b, v240
	v_mul_f32_e32 v254, v240, v240
	v_pk_mul_f32 v[104:105], v[108:109], v[104:105]
	v_pk_mul_f32 v[106:107], v[110:111], v[106:107]
	v_pk_mul_f32 v[96:97], v[100:101], v[96:97]
	v_pk_mul_f32 v[98:99], v[102:103], v[98:99]
	v_pk_mul_f32 v[108:109], v[108:109], v[252:253] op_sel_hi:[1,0]
	v_pk_mul_f32 v[110:111], v[110:111], v[252:253] op_sel_hi:[1,0]
	v_pk_mul_f32 v[100:101], v[100:101], v[252:253] op_sel_hi:[1,0]
	v_pk_mul_f32 v[102:103], v[102:103], v[252:253] op_sel_hi:[1,0]
	v_exp_f32_e32 v108, v108
	v_exp_f32_e32 v109, v109
	v_exp_f32_e32 v110, v110
	v_exp_f32_e32 v111, v111
	v_exp_f32_e32 v100, v100
	v_exp_f32_e32 v101, v101
	v_exp_f32_e32 v102, v102
	v_exp_f32_e32 v103, v103
	v_pk_add_f32 v[108:109], v[108:109], 1.0 op_sel_hi:[1,0]
	v_pk_add_f32 v[110:111], v[110:111], 1.0 op_sel_hi:[1,0]
	v_pk_add_f32 v[100:101], v[100:101], 1.0 op_sel_hi:[1,0]
	v_pk_add_f32 v[102:103], v[102:103], 1.0 op_sel_hi:[1,0]
	v_rcp_f32_e32 v108, v108
	v_rcp_f32_e32 v109, v109
	v_rcp_f32_e32 v110, v110
	v_rcp_f32_e32 v111, v111
	v_rcp_f32_e32 v100, v100
	v_rcp_f32_e32 v101, v101
	v_rcp_f32_e32 v102, v102
	v_rcp_f32_e32 v103, v103
	v_pk_mul_f32 v[104:105], v[104:105], v[254:255] op_sel_hi:[1,0]
	v_pk_mul_f32 v[106:107], v[106:107], v[254:255] op_sel_hi:[1,0]
	v_pk_mul_f32 v[96:97], v[96:97], v[254:255] op_sel_hi:[1,0]
	v_pk_mul_f32 v[98:99], v[98:99], v[254:255] op_sel_hi:[1,0]
	v_pk_mul_f32 v[104:105], v[104:105], v[108:109]
	v_pk_mul_f32 v[106:107], v[106:107], v[110:111]
	v_pk_mul_f32 v[96:97], v[96:97], v[100:101]
	v_pk_mul_f32 v[98:99], v[98:99], v[102:103]
	v_cvt_pk_bf16_f32 v104, v104, v105
	v_cvt_pk_bf16_f32 v105, v106, v107
	v_cvt_pk_bf16_f32 v106, v96, v97
	v_cvt_pk_bf16_f32 v107, v98, v99
	global_store_dwordx4 v234, v[104:107], s[10:11]
	v_add_u32_e32 v235, 0x16000, v234
	v_mul_f32_e32 v252, 0xbfb8aa3b, v244
	v_mul_f32_e32 v254, v244, v244
	v_pk_mul_f32 v[88:89], v[92:93], v[88:89]
	v_pk_mul_f32 v[90:91], v[94:95], v[90:91]
	v_pk_mul_f32 v[80:81], v[84:85], v[80:81]
	v_pk_mul_f32 v[82:83], v[86:87], v[82:83]
	v_pk_mul_f32 v[92:93], v[92:93], v[252:253] op_sel_hi:[1,0]
	v_pk_mul_f32 v[94:95], v[94:95], v[252:253] op_sel_hi:[1,0]
	v_pk_mul_f32 v[84:85], v[84:85], v[252:253] op_sel_hi:[1,0]
	v_pk_mul_f32 v[86:87], v[86:87], v[252:253] op_sel_hi:[1,0]
	v_exp_f32_e32 v92, v92
	v_exp_f32_e32 v93, v93
	v_exp_f32_e32 v94, v94
	v_exp_f32_e32 v95, v95
	v_exp_f32_e32 v84, v84
	v_exp_f32_e32 v85, v85
	v_exp_f32_e32 v86, v86
	v_exp_f32_e32 v87, v87
	v_pk_add_f32 v[92:93], v[92:93], 1.0 op_sel_hi:[1,0]
	v_pk_add_f32 v[94:95], v[94:95], 1.0 op_sel_hi:[1,0]
	v_pk_add_f32 v[84:85], v[84:85], 1.0 op_sel_hi:[1,0]
	v_pk_add_f32 v[86:87], v[86:87], 1.0 op_sel_hi:[1,0]
	v_rcp_f32_e32 v92, v92
	v_rcp_f32_e32 v93, v93
	v_rcp_f32_e32 v94, v94
	v_rcp_f32_e32 v95, v95
	v_rcp_f32_e32 v84, v84
	v_rcp_f32_e32 v85, v85
	v_rcp_f32_e32 v86, v86
	v_rcp_f32_e32 v87, v87
	v_pk_mul_f32 v[88:89], v[88:89], v[254:255] op_sel_hi:[1,0]
	v_pk_mul_f32 v[90:91], v[90:91], v[254:255] op_sel_hi:[1,0]
	v_pk_mul_f32 v[80:81], v[80:81], v[254:255] op_sel_hi:[1,0]
	v_pk_mul_f32 v[82:83], v[82:83], v[254:255] op_sel_hi:[1,0]
	v_pk_mul_f32 v[88:89], v[88:89], v[92:93]
	v_pk_mul_f32 v[90:91], v[90:91], v[94:95]
	v_pk_mul_f32 v[80:81], v[80:81], v[84:85]
	v_pk_mul_f32 v[82:83], v[82:83], v[86:87]
	v_cvt_pk_bf16_f32 v88, v88, v89
	v_cvt_pk_bf16_f32 v89, v90, v91
	v_cvt_pk_bf16_f32 v90, v80, v81
	v_cvt_pk_bf16_f32 v91, v82, v83
	global_store_dwordx4 v235, v[88:91], s[10:11]
	v_add_u32_e32 v234, 0x16000, v235
	v_mul_f32_e32 v252, 0xbfb8aa3b, v248
	v_mul_f32_e32 v254, v248, v248
	v_pk_mul_f32 v[72:73], v[76:77], v[72:73]
	v_pk_mul_f32 v[74:75], v[78:79], v[74:75]
	v_pk_mul_f32 v[64:65], v[68:69], v[64:65]
	v_pk_mul_f32 v[66:67], v[70:71], v[66:67]
	v_pk_mul_f32 v[76:77], v[76:77], v[252:253] op_sel_hi:[1,0]
	v_pk_mul_f32 v[78:79], v[78:79], v[252:253] op_sel_hi:[1,0]
	v_pk_mul_f32 v[68:69], v[68:69], v[252:253] op_sel_hi:[1,0]
	v_pk_mul_f32 v[70:71], v[70:71], v[252:253] op_sel_hi:[1,0]
	v_exp_f32_e32 v76, v76
	v_exp_f32_e32 v77, v77
	v_exp_f32_e32 v78, v78
	v_exp_f32_e32 v79, v79
	v_exp_f32_e32 v68, v68
	v_exp_f32_e32 v69, v69
	v_exp_f32_e32 v70, v70
	v_exp_f32_e32 v71, v71
	v_pk_add_f32 v[76:77], v[76:77], 1.0 op_sel_hi:[1,0]
	v_pk_add_f32 v[78:79], v[78:79], 1.0 op_sel_hi:[1,0]
	v_pk_add_f32 v[68:69], v[68:69], 1.0 op_sel_hi:[1,0]
	v_pk_add_f32 v[70:71], v[70:71], 1.0 op_sel_hi:[1,0]
	v_rcp_f32_e32 v76, v76
	v_rcp_f32_e32 v77, v77
	v_rcp_f32_e32 v78, v78
	v_rcp_f32_e32 v79, v79
	v_rcp_f32_e32 v68, v68
	v_rcp_f32_e32 v69, v69
	v_rcp_f32_e32 v70, v70
	v_rcp_f32_e32 v71, v71
	v_pk_mul_f32 v[72:73], v[72:73], v[254:255] op_sel_hi:[1,0]
	v_pk_mul_f32 v[74:75], v[74:75], v[254:255] op_sel_hi:[1,0]
	v_pk_mul_f32 v[64:65], v[64:65], v[254:255] op_sel_hi:[1,0]
	v_pk_mul_f32 v[66:67], v[66:67], v[254:255] op_sel_hi:[1,0]
	v_pk_mul_f32 v[72:73], v[72:73], v[76:77]
	v_pk_mul_f32 v[74:75], v[74:75], v[78:79]
	v_pk_mul_f32 v[64:65], v[64:65], v[68:69]
	v_pk_mul_f32 v[66:67], v[66:67], v[70:71]
	v_cvt_pk_bf16_f32 v72, v72, v73
	v_cvt_pk_bf16_f32 v73, v74, v75
	v_cvt_pk_bf16_f32 v74, v64, v65
	v_cvt_pk_bf16_f32 v75, v66, v67
	global_store_dwordx4 v234, v[72:75], s[10:11]
	s_waitcnt vmcnt(12)
	s_waitcnt lgkmcnt(0)
	s_barrier
	s_setprio 1
	s_waitcnt lgkmcnt(0)
	v_mfma_f32_16x16x32_bf16 v[60:63], v[160:163], v[194:197], v[60:63]
	v_mfma_f32_16x16x32_bf16 v[60:63], v[164:167], v[198:201], v[60:63]
	v_mfma_f32_16x16x32_bf16 v[52:55], v[172:175], v[198:201], v[52:55]
	v_mfma_f32_16x16x32_bf16 v[52:55], v[168:171], v[194:197], v[52:55]
	v_mfma_f32_16x16x32_bf16 v[36:39], v[168:171], v[202:205], v[36:39]
	v_mfma_f32_16x16x32_bf16 v[36:39], v[172:175], v[206:209], v[36:39]
	v_mfma_f32_16x16x32_bf16 v[44:47], v[164:167], v[206:209], v[44:47]
	v_mfma_f32_16x16x32_bf16 v[44:47], v[160:163], v[202:205], v[44:47]
	v_mfma_f32_16x16x32_bf16 v[28:31], v[160:163], v[210:213], v[28:31]
	v_mfma_f32_16x16x32_bf16 v[28:31], v[164:167], v[214:217], v[28:31]
	v_mfma_f32_16x16x32_bf16 v[20:23], v[172:175], v[214:217], v[20:23]
	v_mfma_f32_16x16x32_bf16 v[20:23], v[168:171], v[210:213], v[20:23]
	v_mfma_f32_16x16x32_bf16 v[4:7], v[168:171], v[218:221], v[4:7]
	v_mfma_f32_16x16x32_bf16 v[4:7], v[172:175], v[222:225], v[4:7]
	v_mfma_f32_16x16x32_bf16 v[12:15], v[164:167], v[222:225], v[12:15]
	v_mfma_f32_16x16x32_bf16 v[12:15], v[160:163], v[218:221], v[12:15]
	s_setprio 0
	s_setprio 1
	v_mfma_f32_16x16x32_bf16 v[56:59], v[176:179], v[194:197], v[56:59]
	v_mfma_f32_16x16x32_bf16 v[56:59], v[180:183], v[198:201], v[56:59]
	v_mfma_f32_16x16x32_bf16 v[48:51], v[190:193], v[198:201], v[48:51]
	v_mfma_f32_16x16x32_bf16 v[48:51], v[186:189], v[194:197], v[48:51]
	v_mfma_f32_16x16x32_bf16 v[32:35], v[186:189], v[202:205], v[32:35]
	v_mfma_f32_16x16x32_bf16 v[32:35], v[190:193], v[206:209], v[32:35]
	v_mfma_f32_16x16x32_bf16 v[40:43], v[180:183], v[206:209], v[40:43]
	v_mfma_f32_16x16x32_bf16 v[40:43], v[176:179], v[202:205], v[40:43]
	v_mfma_f32_16x16x32_bf16 v[24:27], v[176:179], v[210:213], v[24:27]
	v_mfma_f32_16x16x32_bf16 v[24:27], v[180:183], v[214:217], v[24:27]
	v_mfma_f32_16x16x32_bf16 v[16:19], v[190:193], v[214:217], v[16:19]
	v_mfma_f32_16x16x32_bf16 v[16:19], v[186:189], v[210:213], v[16:19]
	v_mfma_f32_16x16x32_bf16 v[0:3], v[186:189], v[218:221], v[0:3]
	v_mfma_f32_16x16x32_bf16 v[0:3], v[190:193], v[222:225], v[0:3]
	v_mfma_f32_16x16x32_bf16 v[8:11], v[180:183], v[222:225], v[8:11]
	v_mfma_f32_16x16x32_bf16 v[8:11], v[176:179], v[218:221], v[8:11]
	s_setprio 0
	s_barrier
	s_add_i32 s75, s75, 2
	s_add_u32 s71, s71, 0x100
	s_addc_u32 s74, s74, 0
	s_add_u32 s44, s44, 0x100
	s_addc_u32 s45, s45, 0

.LBB0_158:
	s_add_u32 s81, s56, 0x100
	s_addc_u32 s82, s57, 0
	s_mov_b32 s83, -2
	s_waitcnt lgkmcnt(0)
	s_cmp_eq_u32 s70, 1
	s_cbranch_scc1 .Lfa_1
	ds_read_b128 v[128:131], v189
	ds_read_b128 v[132:135], v189 offset:1024
	ds_read_b128 v[136:139], v189 offset:2048
	ds_read_b128 v[140:143], v189 offset:3072
	ds_read_b128 v[144:147], v190
	ds_read_b128 v[148:151], v190 offset:1024
	ds_read_b128 v[172:175], v190 offset:2048
	ds_read_b128 v[176:179], v190 offset:3072
	s_add_u32 s56, s54, 0x100
	s_addc_u32 s57, s55, 0
	s_cmp_eq_u32 s83, 40
	s_cselect_b32 s61, s15, s57
	s_cselect_b32 s60, s14, s56
	s_cselect_b32 s59, s53, s82
	s_cselect_b32 s58, s52, s81
	v_lshl_add_u64 v[222:223], s[54:55], 0, v[166:167]
	s_add_i32 m0, s66, 0xc000
	ds_read_b128 v[180:183], v191
	ds_read_b128 v[194:197], v191 offset:1024
	ds_read_b128 v[198:201], v191 offset:2048
	ds_read_b128 v[202:205], v191 offset:3072
	ds_read_b128 v[206:209], v191 offset:4096
	ds_read_b128 v[210:213], v191 offset:5120
	ds_read_b128 v[214:217], v191 offset:6144
	ds_read_b128 v[218:221], v191 offset:7168
	global_load_lds_dwordx4 v[222:223], off
	v_lshl_add_u64 v[222:223], s[54:55], 0, v[164:165]
	s_add_i32 m0, s66, 0xe000
	s_nop 0
	global_load_lds_dwordx4 v[222:223], off
	s_waitcnt vmcnt(24)
	s_waitcnt lgkmcnt(0)
	s_barrier
	s_setprio 1
	s_waitcnt lgkmcnt(0)
	v_mfma_f32_16x16x32_bf16 v[124:127], v[128:131], v[180:183], 0
	v_mfma_f32_16x16x32_bf16 v[120:123], v[136:139], v[180:183], 0
	v_mfma_f32_16x16x32_bf16 v[108:111], v[128:131], v[198:201], 0
	v_mfma_f32_16x16x32_bf16 v[104:107], v[136:139], v[198:201], 0
	v_mfma_f32_16x16x32_bf16 v[92:95], v[128:131], v[206:209], 0
	v_mfma_f32_16x16x32_bf16 v[88:91], v[136:139], v[206:209], 0
	v_mfma_f32_16x16x32_bf16 v[76:79], v[128:131], v[214:217], 0
	v_mfma_f32_16x16x32_bf16 v[72:75], v[136:139], v[214:217], 0
	v_mfma_f32_16x16x32_bf16 v[124:127], v[132:135], v[194:197], v[124:127]
	v_mfma_f32_16x16x32_bf16 v[120:123], v[140:143], v[194:197], v[120:123]
	v_mfma_f32_16x16x32_bf16 v[108:111], v[132:135], v[202:205], v[108:111]
	v_mfma_f32_16x16x32_bf16 v[104:107], v[140:143], v[202:205], v[104:107]
	v_mfma_f32_16x16x32_bf16 v[92:95], v[132:135], v[210:213], v[92:95]
	v_mfma_f32_16x16x32_bf16 v[88:91], v[140:143], v[210:213], v[88:91]
	v_mfma_f32_16x16x32_bf16 v[76:79], v[132:135], v[218:221], v[76:79]
	v_mfma_f32_16x16x32_bf16 v[72:75], v[140:143], v[218:221], v[72:75]
	s_setprio 0
	s_setprio 1
	v_mfma_f32_16x16x32_bf16 v[116:119], v[144:147], v[180:183], 0
	v_mfma_f32_16x16x32_bf16 v[112:115], v[172:175], v[180:183], 0
	v_mfma_f32_16x16x32_bf16 v[100:103], v[144:147], v[198:201], 0
	v_mfma_f32_16x16x32_bf16 v[96:99], v[172:175], v[198:201], 0
	v_mfma_f32_16x16x32_bf16 v[84:87], v[144:147], v[206:209], 0
	v_mfma_f32_16x16x32_bf16 v[80:83], v[172:175], v[206:209], 0
	v_mfma_f32_16x16x32_bf16 v[68:71], v[144:147], v[214:217], 0
	v_mfma_f32_16x16x32_bf16 v[64:67], v[172:175], v[214:217], 0
	v_mfma_f32_16x16x32_bf16 v[116:119], v[148:151], v[194:197], v[116:119]
	v_mfma_f32_16x16x32_bf16 v[112:115], v[176:179], v[194:197], v[112:115]
	v_mfma_f32_16x16x32_bf16 v[100:103], v[148:151], v[202:205], v[100:103]
	v_mfma_f32_16x16x32_bf16 v[96:99], v[176:179], v[202:205], v[96:99]
	v_mfma_f32_16x16x32_bf16 v[84:87], v[148:151], v[210:213], v[84:87]
	v_mfma_f32_16x16x32_bf16 v[80:83], v[176:179], v[210:213], v[80:83]
	v_mfma_f32_16x16x32_bf16 v[68:71], v[148:151], v[218:221], v[68:71]
	v_mfma_f32_16x16x32_bf16 v[64:67], v[176:179], v[218:221], v[64:67]
	s_setprio 0
	s_barrier
	s_add_i32 s54, s77, s65
	v_lshl_add_u64 v[222:223], s[58:59], 0, v[154:155]
	s_mov_b32 m0, s54
	ds_read_b128 v[180:183], v191 offset:16384
	ds_read_b128 v[194:197], v191 offset:17408
	ds_read_b128 v[198:201], v191 offset:18432
	ds_read_b128 v[202:205], v191 offset:19456
	ds_read_b128 v[206:209], v191 offset:20480
	ds_read_b128 v[210:213], v191 offset:21504
	ds_read_b128 v[214:217], v191 offset:22528
	ds_read_b128 v[218:221], v191 offset:23552
	global_load_lds_dwordx4 v[222:223], off
	s_add_i32 m0, s54, 0x2000
	s_add_u32 s54, s58, 0xb0000
	v_lshl_add_u64 v[224:225], s[58:59], 0, v[162:163]
	s_addc_u32 s55, s59, 0
	s_add_i32 s84, s78, s65
	global_load_lds_dwordx4 v[224:225], off
	v_lshl_add_u64 v[226:227], s[54:55], 0, v[154:155]
	s_mov_b32 m0, s84
	v_lshl_add_u64 v[228:229], s[60:61], 0, v[160:161]
	global_load_lds_dwordx4 v[226:227], off
	v_lshl_add_u64 v[226:227], s[54:55], 0, v[162:163]
	s_add_i32 m0, s84, 0x2000
	s_nop 0
	global_load_lds_dwordx4 v[226:227], off
	v_lshl_add_u64 v[226:227], s[60:61], 0, v[152:153]
	s_mov_b32 m0, s66
	s_nop 0
	global_load_lds_dwordx4 v[226:227], off
	s_mov_b32 m0, s67
	s_nop 0
	global_load_lds_dwordx4 v[228:229], off
	s_waitcnt vmcnt(24)
	s_waitcnt lgkmcnt(0)
	s_barrier
	s_setprio 1
	s_waitcnt lgkmcnt(0)
	v_mfma_f32_16x16x32_bf16 v[60:63], v[128:131], v[180:183], 0
	v_mfma_f32_16x16x32_bf16 v[56:59], v[136:139], v[180:183], 0
	v_mfma_f32_16x16x32_bf16 v[44:47], v[128:131], v[198:201], 0
	v_mfma_f32_16x16x32_bf16 v[40:43], v[136:139], v[198:201], 0
	v_mfma_f32_16x16x32_bf16 v[28:31], v[128:131], v[206:209], 0
	v_mfma_f32_16x16x32_bf16 v[24:27], v[136:139], v[206:209], 0
	v_mfma_f32_16x16x32_bf16 v[12:15], v[128:131], v[214:217], 0
	v_mfma_f32_16x16x32_bf16 v[8:11], v[136:139], v[214:217], 0
	v_mfma_f32_16x16x32_bf16 v[60:63], v[132:135], v[194:197], v[60:63]
	v_mfma_f32_16x16x32_bf16 v[56:59], v[140:143], v[194:197], v[56:59]
	v_mfma_f32_16x16x32_bf16 v[44:47], v[132:135], v[202:205], v[44:47]
	v_mfma_f32_16x16x32_bf16 v[40:43], v[140:143], v[202:205], v[40:43]
	v_mfma_f32_16x16x32_bf16 v[28:31], v[132:135], v[210:213], v[28:31]
	v_mfma_f32_16x16x32_bf16 v[24:27], v[140:143], v[210:213], v[24:27]
	v_mfma_f32_16x16x32_bf16 v[12:15], v[132:135], v[218:221], v[12:15]
	v_mfma_f32_16x16x32_bf16 v[8:11], v[140:143], v[218:221], v[8:11]
	s_setprio 0
	s_setprio 1
	v_mfma_f32_16x16x32_bf16 v[52:55], v[144:147], v[180:183], 0
	v_mfma_f32_16x16x32_bf16 v[48:51], v[172:175], v[180:183], 0
	v_mfma_f32_16x16x32_bf16 v[36:39], v[144:147], v[198:201], 0
	v_mfma_f32_16x16x32_bf16 v[32:35], v[172:175], v[198:201], 0
	v_mfma_f32_16x16x32_bf16 v[20:23], v[144:147], v[206:209], 0
	v_mfma_f32_16x16x32_bf16 v[16:19], v[172:175], v[206:209], 0
	v_mfma_f32_16x16x32_bf16 v[4:7], v[144:147], v[214:217], 0
	v_mfma_f32_16x16x32_bf16 v[0:3], v[172:175], v[214:217], 0
	v_mfma_f32_16x16x32_bf16 v[52:55], v[148:151], v[194:197], v[52:55]
	v_mfma_f32_16x16x32_bf16 v[48:51], v[176:179], v[194:197], v[48:51]
	v_mfma_f32_16x16x32_bf16 v[36:39], v[148:151], v[202:205], v[36:39]
	v_mfma_f32_16x16x32_bf16 v[32:35], v[176:179], v[202:205], v[32:35]
	v_mfma_f32_16x16x32_bf16 v[20:23], v[148:151], v[210:213], v[20:23]
	v_mfma_f32_16x16x32_bf16 v[16:19], v[176:179], v[210:213], v[16:19]
	v_mfma_f32_16x16x32_bf16 v[4:7], v[148:151], v[218:221], v[4:7]
	v_mfma_f32_16x16x32_bf16 v[0:3], v[176:179], v[218:221], v[0:3]
	s_setprio 0
	s_barrier
	s_add_i32 s84, 0, 0x18000
	s_add_i32 s85, 0, 0x1c000
	v_add_u32_e32 v140, s84, v186
	v_add_u32_e32 v176, s85, v186
	ds_read_b128 v[128:131], v140
	ds_read_b128 v[132:135], v140 offset:1024
	ds_read_b128 v[136:139], v140 offset:2048
	ds_read_b128 v[140:143], v140 offset:3072
	ds_read_b128 v[144:147], v176
	ds_read_b128 v[148:151], v176 offset:1024
	ds_read_b128 v[172:175], v176 offset:2048
	ds_read_b128 v[176:179], v176 offset:3072
	s_add_u32 s54, s60, 0xb0000
	s_addc_u32 s55, s61, 0
	s_mov_b32 m0, s68
	v_lshl_add_u64 v[230:231], s[54:55], 0, v[152:153]
	ds_read_b128 v[180:183], v191 offset:32768
	ds_read_b128 v[194:197], v191 offset:33792
	ds_read_b128 v[198:201], v191 offset:34816
	ds_read_b128 v[202:205], v191 offset:35840
	ds_read_b128 v[206:209], v191 offset:36864
	ds_read_b128 v[210:213], v191 offset:37888
	ds_read_b128 v[214:217], v191 offset:38912
	ds_read_b128 v[218:221], v191 offset:39936
	global_load_lds_dwordx4 v[230:231], off
	v_lshl_add_u64 v[230:231], s[54:55], 0, v[160:161]
	s_mov_b32 m0, s69
	s_nop 0
	global_load_lds_dwordx4 v[230:231], off
	s_waitcnt vmcnt(8)
	s_waitcnt lgkmcnt(0)
	s_barrier
	s_setprio 1
	s_waitcnt lgkmcnt(0)
	v_mfma_f32_16x16x32_bf16 v[124:127], v[128:131], v[180:183], v[124:127]
	v_mfma_f32_16x16x32_bf16 v[124:127], v[132:135], v[194:197], v[124:127]
	v_mfma_f32_16x16x32_bf16 v[120:123], v[140:143], v[194:197], v[120:123]
	v_mfma_f32_16x16x32_bf16 v[120:123], v[136:139], v[180:183], v[120:123]
	v_mfma_f32_16x16x32_bf16 v[104:107], v[136:139], v[198:201], v[104:107]
	v_mfma_f32_16x16x32_bf16 v[104:107], v[140:143], v[202:205], v[104:107]
	v_mfma_f32_16x16x32_bf16 v[108:111], v[132:135], v[202:205], v[108:111]
	v_mfma_f32_16x16x32_bf16 v[108:111], v[128:131], v[198:201], v[108:111]
	v_mfma_f32_16x16x32_bf16 v[92:95], v[128:131], v[206:209], v[92:95]
	v_mfma_f32_16x16x32_bf16 v[92:95], v[132:135], v[210:213], v[92:95]
	v_mfma_f32_16x16x32_bf16 v[88:91], v[140:143], v[210:213], v[88:91]
	v_mfma_f32_16x16x32_bf16 v[88:91], v[136:139], v[206:209], v[88:91]
	v_mfma_f32_16x16x32_bf16 v[72:75], v[136:139], v[214:217], v[72:75]
	v_mfma_f32_16x16x32_bf16 v[72:75], v[140:143], v[218:221], v[72:75]
	v_mfma_f32_16x16x32_bf16 v[76:79], v[132:135], v[218:221], v[76:79]
	v_mfma_f32_16x16x32_bf16 v[76:79], v[128:131], v[214:217], v[76:79]
	s_setprio 0
	s_setprio 1
	v_mfma_f32_16x16x32_bf16 v[116:119], v[144:147], v[180:183], v[116:119]
	v_mfma_f32_16x16x32_bf16 v[116:119], v[148:151], v[194:197], v[116:119]
	v_mfma_f32_16x16x32_bf16 v[112:115], v[176:179], v[194:197], v[112:115]
	v_mfma_f32_16x16x32_bf16 v[112:115], v[172:175], v[180:183], v[112:115]
	v_mfma_f32_16x16x32_bf16 v[96:99], v[172:175], v[198:201], v[96:99]
	v_mfma_f32_16x16x32_bf16 v[96:99], v[176:179], v[202:205], v[96:99]
	v_mfma_f32_16x16x32_bf16 v[100:103], v[148:151], v[202:205], v[100:103]
	v_mfma_f32_16x16x32_bf16 v[100:103], v[144:147], v[198:201], v[100:103]
	v_mfma_f32_16x16x32_bf16 v[84:87], v[144:147], v[206:209], v[84:87]
	v_mfma_f32_16x16x32_bf16 v[84:87], v[148:151], v[210:213], v[84:87]
	v_mfma_f32_16x16x32_bf16 v[80:83], v[176:179], v[210:213], v[80:83]
	v_mfma_f32_16x16x32_bf16 v[80:83], v[172:175], v[206:209], v[80:83]
	v_mfma_f32_16x16x32_bf16 v[64:67], v[172:175], v[214:217], v[64:67]
	v_mfma_f32_16x16x32_bf16 v[64:67], v[176:179], v[218:221], v[64:67]
	v_mfma_f32_16x16x32_bf16 v[68:71], v[148:151], v[218:221], v[68:71]
	v_mfma_f32_16x16x32_bf16 v[68:71], v[144:147], v[214:217], v[68:71]
	s_setprio 0
	s_barrier
	s_add_i32 s54, s84, s65
	v_lshl_add_u64 v[222:223], v[222:223], 0, s[28:29]
	s_mov_b32 m0, s54
	ds_read_b128 v[180:183], v191 offset:49152
	ds_read_b128 v[194:197], v191 offset:50176
	ds_read_b128 v[198:201], v191 offset:51200
	ds_read_b128 v[202:205], v191 offset:52224
	ds_read_b128 v[206:209], v191 offset:53248
	ds_read_b128 v[210:213], v191 offset:54272
	ds_read_b128 v[214:217], v191 offset:55296
	ds_read_b128 v[218:221], v191 offset:56320
	global_load_lds_dwordx4 v[222:223], off
	s_add_i32 m0, s54, 0x2000
	s_add_u32 s54, s58, 0xb0080
	v_lshl_add_u64 v[222:223], v[224:225], 0, s[28:29]
	s_addc_u32 s55, s59, 0
	s_add_i32 s58, s85, s65
	global_load_lds_dwordx4 v[222:223], off
	v_lshl_add_u64 v[222:223], s[54:55], 0, v[154:155]
	s_mov_b32 m0, s58
	s_nop 0
	global_load_lds_dwordx4 v[222:223], off
	v_lshl_add_u64 v[222:223], s[54:55], 0, v[162:163]
	s_add_i32 m0, s58, 0x2000
	s_nop 0
	global_load_lds_dwordx4 v[222:223], off
	v_lshl_add_u64 v[222:223], v[226:227], 0, s[28:29]
	s_mov_b32 m0, s3
	s_nop 0
	global_load_lds_dwordx4 v[222:223], off
	v_lshl_add_u64 v[222:223], v[228:229], 0, s[28:29]
	s_mov_b32 m0, s71
	s_nop 0
	global_load_lds_dwordx4 v[222:223], off
	s_waitcnt vmcnt(8)
	s_waitcnt lgkmcnt(0)
	s_barrier
	s_setprio 1
	s_waitcnt lgkmcnt(0)
	v_mfma_f32_16x16x32_bf16 v[60:63], v[128:131], v[180:183], v[60:63]
	v_mfma_f32_16x16x32_bf16 v[60:63], v[132:135], v[194:197], v[60:63]
	v_mfma_f32_16x16x32_bf16 v[56:59], v[140:143], v[194:197], v[56:59]
	v_mfma_f32_16x16x32_bf16 v[56:59], v[136:139], v[180:183], v[56:59]
	v_mfma_f32_16x16x32_bf16 v[40:43], v[136:139], v[198:201], v[40:43]
	v_mfma_f32_16x16x32_bf16 v[40:43], v[140:143], v[202:205], v[40:43]
	v_mfma_f32_16x16x32_bf16 v[44:47], v[132:135], v[202:205], v[44:47]
	v_mfma_f32_16x16x32_bf16 v[44:47], v[128:131], v[198:201], v[44:47]
	v_mfma_f32_16x16x32_bf16 v[28:31], v[128:131], v[206:209], v[28:31]
	v_mfma_f32_16x16x32_bf16 v[28:31], v[132:135], v[210:213], v[28:31]
	v_mfma_f32_16x16x32_bf16 v[24:27], v[140:143], v[210:213], v[24:27]
	v_mfma_f32_16x16x32_bf16 v[24:27], v[136:139], v[206:209], v[24:27]
	v_mfma_f32_16x16x32_bf16 v[8:11], v[136:139], v[214:217], v[8:11]
	v_mfma_f32_16x16x32_bf16 v[8:11], v[140:143], v[218:221], v[8:11]
	v_mfma_f32_16x16x32_bf16 v[12:15], v[132:135], v[218:221], v[12:15]
	v_mfma_f32_16x16x32_bf16 v[12:15], v[128:131], v[214:217], v[12:15]
	s_setprio 0
	s_setprio 1
	v_mfma_f32_16x16x32_bf16 v[52:55], v[144:147], v[180:183], v[52:55]
	v_mfma_f32_16x16x32_bf16 v[52:55], v[148:151], v[194:197], v[52:55]
	v_mfma_f32_16x16x32_bf16 v[48:51], v[176:179], v[194:197], v[48:51]
	v_mfma_f32_16x16x32_bf16 v[48:51], v[172:175], v[180:183], v[48:51]
	v_mfma_f32_16x16x32_bf16 v[32:35], v[172:175], v[198:201], v[32:35]
	v_mfma_f32_16x16x32_bf16 v[32:35], v[176:179], v[202:205], v[32:35]
	v_mfma_f32_16x16x32_bf16 v[36:39], v[148:151], v[202:205], v[36:39]
	v_mfma_f32_16x16x32_bf16 v[36:39], v[144:147], v[198:201], v[36:39]
	v_mfma_f32_16x16x32_bf16 v[20:23], v[144:147], v[206:209], v[20:23]
	v_mfma_f32_16x16x32_bf16 v[20:23], v[148:151], v[210:213], v[20:23]
	v_mfma_f32_16x16x32_bf16 v[16:19], v[176:179], v[210:213], v[16:19]
	v_mfma_f32_16x16x32_bf16 v[16:19], v[172:175], v[206:209], v[16:19]
	v_mfma_f32_16x16x32_bf16 v[0:3], v[172:175], v[214:217], v[0:3]
	v_mfma_f32_16x16x32_bf16 v[0:3], v[176:179], v[218:221], v[0:3]
	v_mfma_f32_16x16x32_bf16 v[4:7], v[148:151], v[218:221], v[4:7]
	v_mfma_f32_16x16x32_bf16 v[4:7], v[144:147], v[214:217], v[4:7]
	s_setprio 0
	s_barrier
	s_add_i32 s83, s83, 2
	s_add_u32 s81, s81, 0x100
	s_addc_u32 s82, s82, 0
	s_cmp_gt_u32 s83, 41
	s_mov_b64 s[54:55], s[56:57]
	s_branch .LBB0_159
.Lfa_1:
	ds_read_b128 v[128:131], v189
	ds_read_b128 v[132:135], v189 offset:1024
	ds_read_b128 v[136:139], v189 offset:2048
	ds_read_b128 v[140:143], v189 offset:3072
	ds_read_b128 v[144:147], v190
	ds_read_b128 v[148:151], v190 offset:1024
	ds_read_b128 v[172:175], v190 offset:2048
	ds_read_b128 v[176:179], v190 offset:3072
	s_add_u32 s56, s54, 0x100
	s_addc_u32 s57, s55, 0
	s_cmp_eq_u32 s83, 40
	s_cselect_b32 s61, s15, s57
	s_cselect_b32 s60, s14, s56
	s_cselect_b32 s59, s53, s82
	s_cselect_b32 s58, s52, s81
	v_lshl_add_u64 v[222:223], s[54:55], 0, v[166:167]
	s_add_i32 m0, s66, 0xc000
	ds_read_b128 v[180:183], v191
	ds_read_b128 v[194:197], v191 offset:1024
	ds_read_b128 v[198:201], v191 offset:2048
	ds_read_b128 v[202:205], v191 offset:3072
	ds_read_b128 v[206:209], v191 offset:4096
	ds_read_b128 v[210:213], v191 offset:5120
	ds_read_b128 v[214:217], v191 offset:6144
	ds_read_b128 v[218:221], v191 offset:7168
	global_load_lds_dwordx4 v[222:223], off
	v_lshl_add_u64 v[222:223], s[54:55], 0, v[164:165]
	s_add_i32 m0, s66, 0xe000
	s_nop 0
	global_load_lds_dwordx4 v[222:223], off
	s_waitcnt vmcnt(8)
	s_waitcnt lgkmcnt(0)
	s_barrier
	s_setprio 1
	s_waitcnt lgkmcnt(0)
	v_mfma_f32_16x16x32_bf16 v[124:127], v[128:131], v[180:183], 0
	v_mfma_f32_16x16x32_bf16 v[120:123], v[136:139], v[180:183], 0
	v_mfma_f32_16x16x32_bf16 v[108:111], v[128:131], v[198:201], 0
	v_mfma_f32_16x16x32_bf16 v[104:107], v[136:139], v[198:201], 0
	v_mfma_f32_16x16x32_bf16 v[92:95], v[128:131], v[206:209], 0
	v_mfma_f32_16x16x32_bf16 v[88:91], v[136:139], v[206:209], 0
	v_mfma_f32_16x16x32_bf16 v[76:79], v[128:131], v[214:217], 0
	v_mfma_f32_16x16x32_bf16 v[72:75], v[136:139], v[214:217], 0
	v_mfma_f32_16x16x32_bf16 v[124:127], v[132:135], v[194:197], v[124:127]
	v_mfma_f32_16x16x32_bf16 v[120:123], v[140:143], v[194:197], v[120:123]
	v_mfma_f32_16x16x32_bf16 v[108:111], v[132:135], v[202:205], v[108:111]
	v_mfma_f32_16x16x32_bf16 v[104:107], v[140:143], v[202:205], v[104:107]
	v_mfma_f32_16x16x32_bf16 v[92:95], v[132:135], v[210:213], v[92:95]
	v_mfma_f32_16x16x32_bf16 v[88:91], v[140:143], v[210:213], v[88:91]
	v_mfma_f32_16x16x32_bf16 v[76:79], v[132:135], v[218:221], v[76:79]
	v_mfma_f32_16x16x32_bf16 v[72:75], v[140:143], v[218:221], v[72:75]
	s_setprio 0
	s_setprio 1
	v_mfma_f32_16x16x32_bf16 v[116:119], v[144:147], v[180:183], 0
	v_mfma_f32_16x16x32_bf16 v[112:115], v[172:175], v[180:183], 0
	v_mfma_f32_16x16x32_bf16 v[100:103], v[144:147], v[198:201], 0
	v_mfma_f32_16x16x32_bf16 v[96:99], v[172:175], v[198:201], 0
	v_mfma_f32_16x16x32_bf16 v[84:87], v[144:147], v[206:209], 0
	v_mfma_f32_16x16x32_bf16 v[80:83], v[172:175], v[206:209], 0
	v_mfma_f32_16x16x32_bf16 v[68:71], v[144:147], v[214:217], 0
	v_mfma_f32_16x16x32_bf16 v[64:67], v[172:175], v[214:217], 0
	v_mfma_f32_16x16x32_bf16 v[116:119], v[148:151], v[194:197], v[116:119]
	v_mfma_f32_16x16x32_bf16 v[112:115], v[176:179], v[194:197], v[112:115]
	v_mfma_f32_16x16x32_bf16 v[100:103], v[148:151], v[202:205], v[100:103]
	v_mfma_f32_16x16x32_bf16 v[96:99], v[176:179], v[202:205], v[96:99]
	v_mfma_f32_16x16x32_bf16 v[84:87], v[148:151], v[210:213], v[84:87]
	v_mfma_f32_16x16x32_bf16 v[80:83], v[176:179], v[210:213], v[80:83]
	v_mfma_f32_16x16x32_bf16 v[68:71], v[148:151], v[218:221], v[68:71]
	v_mfma_f32_16x16x32_bf16 v[64:67], v[176:179], v[218:221], v[64:67]
	s_setprio 0
	s_barrier
	s_add_i32 s54, s77, s65
	v_lshl_add_u64 v[222:223], s[58:59], 0, v[154:155]
	s_mov_b32 m0, s54
	ds_read_b128 v[180:183], v191 offset:16384
	ds_read_b128 v[194:197], v191 offset:17408
	ds_read_b128 v[198:201], v191 offset:18432
	ds_read_b128 v[202:205], v191 offset:19456
	ds_read_b128 v[206:209], v191 offset:20480
	ds_read_b128 v[210:213], v191 offset:21504
	ds_read_b128 v[214:217], v191 offset:22528
	ds_read_b128 v[218:221], v191 offset:23552
	global_load_lds_dwordx4 v[222:223], off
	s_add_i32 m0, s54, 0x2000
	s_add_u32 s54, s58, 0xb0000
	v_lshl_add_u64 v[224:225], s[58:59], 0, v[162:163]
	s_addc_u32 s55, s59, 0
	s_add_i32 s84, s78, s65
	global_load_lds_dwordx4 v[224:225], off
	v_lshl_add_u64 v[226:227], s[54:55], 0, v[154:155]
	s_mov_b32 m0, s84
	v_lshl_add_u64 v[228:229], s[60:61], 0, v[160:161]
	global_load_lds_dwordx4 v[226:227], off
	v_lshl_add_u64 v[226:227], s[54:55], 0, v[162:163]
	s_add_i32 m0, s84, 0x2000
	s_nop 0
	global_load_lds_dwordx4 v[226:227], off
	v_lshl_add_u64 v[226:227], s[60:61], 0, v[152:153]
	s_mov_b32 m0, s66
	s_nop 0
	global_load_lds_dwordx4 v[226:227], off
	s_mov_b32 m0, s67
	s_nop 0
	global_load_lds_dwordx4 v[228:229], off
	s_waitcnt vmcnt(8)
	s_waitcnt lgkmcnt(0)
	s_barrier
	s_setprio 1
	s_waitcnt lgkmcnt(0)
	v_mfma_f32_16x16x32_bf16 v[60:63], v[128:131], v[180:183], 0
	v_mfma_f32_16x16x32_bf16 v[56:59], v[136:139], v[180:183], 0
	v_mfma_f32_16x16x32_bf16 v[44:47], v[128:131], v[198:201], 0
	v_mfma_f32_16x16x32_bf16 v[40:43], v[136:139], v[198:201], 0
	v_mfma_f32_16x16x32_bf16 v[28:31], v[128:131], v[206:209], 0
	v_mfma_f32_16x16x32_bf16 v[24:27], v[136:139], v[206:209], 0
	v_mfma_f32_16x16x32_bf16 v[12:15], v[128:131], v[214:217], 0
	v_mfma_f32_16x16x32_bf16 v[8:11], v[136:139], v[214:217], 0
	v_mfma_f32_16x16x32_bf16 v[60:63], v[132:135], v[194:197], v[60:63]
	v_mfma_f32_16x16x32_bf16 v[56:59], v[140:143], v[194:197], v[56:59]
	v_mfma_f32_16x16x32_bf16 v[44:47], v[132:135], v[202:205], v[44:47]
	v_mfma_f32_16x16x32_bf16 v[40:43], v[140:143], v[202:205], v[40:43]
	v_mfma_f32_16x16x32_bf16 v[28:31], v[132:135], v[210:213], v[28:31]
	v_mfma_f32_16x16x32_bf16 v[24:27], v[140:143], v[210:213], v[24:27]
	v_mfma_f32_16x16x32_bf16 v[12:15], v[132:135], v[218:221], v[12:15]
	v_mfma_f32_16x16x32_bf16 v[8:11], v[140:143], v[218:221], v[8:11]
	s_setprio 0
	s_setprio 1
	v_mfma_f32_16x16x32_bf16 v[52:55], v[144:147], v[180:183], 0
	v_mfma_f32_16x16x32_bf16 v[48:51], v[172:175], v[180:183], 0
	v_mfma_f32_16x16x32_bf16 v[36:39], v[144:147], v[198:201], 0
	v_mfma_f32_16x16x32_bf16 v[32:35], v[172:175], v[198:201], 0
	v_mfma_f32_16x16x32_bf16 v[20:23], v[144:147], v[206:209], 0
	v_mfma_f32_16x16x32_bf16 v[16:19], v[172:175], v[206:209], 0
	v_mfma_f32_16x16x32_bf16 v[4:7], v[144:147], v[214:217], 0
	v_mfma_f32_16x16x32_bf16 v[0:3], v[172:175], v[214:217], 0
	v_mfma_f32_16x16x32_bf16 v[52:55], v[148:151], v[194:197], v[52:55]
	v_mfma_f32_16x16x32_bf16 v[48:51], v[176:179], v[194:197], v[48:51]
	v_mfma_f32_16x16x32_bf16 v[36:39], v[148:151], v[202:205], v[36:39]
	v_mfma_f32_16x16x32_bf16 v[32:35], v[176:179], v[202:205], v[32:35]
	v_mfma_f32_16x16x32_bf16 v[20:23], v[148:151], v[210:213], v[20:23]
	v_mfma_f32_16x16x32_bf16 v[16:19], v[176:179], v[210:213], v[16:19]
	v_mfma_f32_16x16x32_bf16 v[4:7], v[148:151], v[218:221], v[4:7]
	v_mfma_f32_16x16x32_bf16 v[0:3], v[176:179], v[218:221], v[0:3]
	s_setprio 0
	s_barrier
	s_add_i32 s84, 0, 0x18000
	s_add_i32 s85, 0, 0x1c000
	v_add_u32_e32 v140, s84, v186
	v_add_u32_e32 v176, s85, v186
	ds_read_b128 v[128:131], v140
	ds_read_b128 v[132:135], v140 offset:1024
	ds_read_b128 v[136:139], v140 offset:2048
	ds_read_b128 v[140:143], v140 offset:3072
	ds_read_b128 v[144:147], v176
	ds_read_b128 v[148:151], v176 offset:1024
	ds_read_b128 v[172:175], v176 offset:2048
	ds_read_b128 v[176:179], v176 offset:3072
	s_add_u32 s54, s60, 0xb0000
	s_addc_u32 s55, s61, 0
	s_mov_b32 m0, s68
	v_lshl_add_u64 v[230:231], s[54:55], 0, v[152:153]
	ds_read_b128 v[180:183], v191 offset:32768
	ds_read_b128 v[194:197], v191 offset:33792
	ds_read_b128 v[198:201], v191 offset:34816
	ds_read_b128 v[202:205], v191 offset:35840
	ds_read_b128 v[206:209], v191 offset:36864
	ds_read_b128 v[210:213], v191 offset:37888
	ds_read_b128 v[214:217], v191 offset:38912
	ds_read_b128 v[218:221], v191 offset:39936
	global_load_lds_dwordx4 v[230:231], off
	v_lshl_add_u64 v[230:231], s[54:55], 0, v[160:161]
	s_mov_b32 m0, s69
	s_nop 0
	global_load_lds_dwordx4 v[230:231], off
	s_waitcnt vmcnt(8)
	s_waitcnt lgkmcnt(0)
	s_barrier
	s_setprio 1
	s_waitcnt lgkmcnt(0)
	v_mfma_f32_16x16x32_bf16 v[124:127], v[128:131], v[180:183], v[124:127]
	v_mfma_f32_16x16x32_bf16 v[124:127], v[132:135], v[194:197], v[124:127]
	v_mfma_f32_16x16x32_bf16 v[120:123], v[140:143], v[194:197], v[120:123]
	v_mfma_f32_16x16x32_bf16 v[120:123], v[136:139], v[180:183], v[120:123]
	v_mfma_f32_16x16x32_bf16 v[104:107], v[136:139], v[198:201], v[104:107]
	v_mfma_f32_16x16x32_bf16 v[104:107], v[140:143], v[202:205], v[104:107]
	v_mfma_f32_16x16x32_bf16 v[108:111], v[132:135], v[202:205], v[108:111]
	v_mfma_f32_16x16x32_bf16 v[108:111], v[128:131], v[198:201], v[108:111]
	v_mfma_f32_16x16x32_bf16 v[92:95], v[128:131], v[206:209], v[92:95]
	v_mfma_f32_16x16x32_bf16 v[92:95], v[132:135], v[210:213], v[92:95]
	v_mfma_f32_16x16x32_bf16 v[88:91], v[140:143], v[210:213], v[88:91]
	v_mfma_f32_16x16x32_bf16 v[88:91], v[136:139], v[206:209], v[88:91]
	v_mfma_f32_16x16x32_bf16 v[72:75], v[136:139], v[214:217], v[72:75]
	v_mfma_f32_16x16x32_bf16 v[72:75], v[140:143], v[218:221], v[72:75]
	v_mfma_f32_16x16x32_bf16 v[76:79], v[132:135], v[218:221], v[76:79]
	v_mfma_f32_16x16x32_bf16 v[76:79], v[128:131], v[214:217], v[76:79]
	s_setprio 0
	s_setprio 1
	v_mfma_f32_16x16x32_bf16 v[116:119], v[144:147], v[180:183], v[116:119]
	v_mfma_f32_16x16x32_bf16 v[116:119], v[148:151], v[194:197], v[116:119]
	v_mfma_f32_16x16x32_bf16 v[112:115], v[176:179], v[194:197], v[112:115]
	v_mfma_f32_16x16x32_bf16 v[112:115], v[172:175], v[180:183], v[112:115]
	v_mfma_f32_16x16x32_bf16 v[96:99], v[172:175], v[198:201], v[96:99]
	v_mfma_f32_16x16x32_bf16 v[96:99], v[176:179], v[202:205], v[96:99]
	v_mfma_f32_16x16x32_bf16 v[100:103], v[148:151], v[202:205], v[100:103]
	v_mfma_f32_16x16x32_bf16 v[100:103], v[144:147], v[198:201], v[100:103]
	v_mfma_f32_16x16x32_bf16 v[84:87], v[144:147], v[206:209], v[84:87]
	v_mfma_f32_16x16x32_bf16 v[84:87], v[148:151], v[210:213], v[84:87]
	v_mfma_f32_16x16x32_bf16 v[80:83], v[176:179], v[210:213], v[80:83]
	v_mfma_f32_16x16x32_bf16 v[80:83], v[172:175], v[206:209], v[80:83]
	v_mfma_f32_16x16x32_bf16 v[64:67], v[172:175], v[214:217], v[64:67]
	v_mfma_f32_16x16x32_bf16 v[64:67], v[176:179], v[218:221], v[64:67]
	v_mfma_f32_16x16x32_bf16 v[68:71], v[148:151], v[218:221], v[68:71]
	v_mfma_f32_16x16x32_bf16 v[68:71], v[144:147], v[214:217], v[68:71]
	s_setprio 0
	s_barrier
	s_add_i32 s54, s84, s65
	v_lshl_add_u64 v[222:223], v[222:223], 0, s[28:29]
	s_mov_b32 m0, s54
	ds_read_b128 v[180:183], v191 offset:49152
	ds_read_b128 v[194:197], v191 offset:50176
	ds_read_b128 v[198:201], v191 offset:51200
	ds_read_b128 v[202:205], v191 offset:52224
	ds_read_b128 v[206:209], v191 offset:53248
	ds_read_b128 v[210:213], v191 offset:54272
	ds_read_b128 v[214:217], v191 offset:55296
	ds_read_b128 v[218:221], v191 offset:56320
	global_load_lds_dwordx4 v[222:223], off
	s_add_i32 m0, s54, 0x2000
	s_add_u32 s54, s58, 0xb0080
	v_lshl_add_u64 v[222:223], v[224:225], 0, s[28:29]
	s_addc_u32 s55, s59, 0
	s_add_i32 s58, s85, s65
	global_load_lds_dwordx4 v[222:223], off
	v_lshl_add_u64 v[222:223], s[54:55], 0, v[154:155]
	s_mov_b32 m0, s58
	s_nop 0
	global_load_lds_dwordx4 v[222:223], off
	v_lshl_add_u64 v[222:223], s[54:55], 0, v[162:163]
	s_add_i32 m0, s58, 0x2000
	s_nop 0
	global_load_lds_dwordx4 v[222:223], off
	v_lshl_add_u64 v[222:223], v[226:227], 0, s[28:29]
	s_mov_b32 m0, s3
	s_nop 0
	global_load_lds_dwordx4 v[222:223], off
	v_lshl_add_u64 v[222:223], v[228:229], 0, s[28:29]
	s_mov_b32 m0, s71
	s_nop 0
	global_load_lds_dwordx4 v[222:223], off
	s_waitcnt vmcnt(8)
	s_waitcnt lgkmcnt(0)
	s_barrier
	s_setprio 1
	s_waitcnt lgkmcnt(0)
	v_mfma_f32_16x16x32_bf16 v[60:63], v[128:131], v[180:183], v[60:63]
	v_mfma_f32_16x16x32_bf16 v[60:63], v[132:135], v[194:197], v[60:63]
	v_mfma_f32_16x16x32_bf16 v[56:59], v[140:143], v[194:197], v[56:59]
	v_mfma_f32_16x16x32_bf16 v[56:59], v[136:139], v[180:183], v[56:59]
	v_mfma_f32_16x16x32_bf16 v[40:43], v[136:139], v[198:201], v[40:43]
	v_mfma_f32_16x16x32_bf16 v[40:43], v[140:143], v[202:205], v[40:43]
	v_mfma_f32_16x16x32_bf16 v[44:47], v[132:135], v[202:205], v[44:47]
	v_mfma_f32_16x16x32_bf16 v[44:47], v[128:131], v[198:201], v[44:47]
	v_mfma_f32_16x16x32_bf16 v[28:31], v[128:131], v[206:209], v[28:31]
	v_mfma_f32_16x16x32_bf16 v[28:31], v[132:135], v[210:213], v[28:31]
	v_mfma_f32_16x16x32_bf16 v[24:27], v[140:143], v[210:213], v[24:27]
	v_mfma_f32_16x16x32_bf16 v[24:27], v[136:139], v[206:209], v[24:27]
	v_mfma_f32_16x16x32_bf16 v[8:11], v[136:139], v[214:217], v[8:11]
	v_mfma_f32_16x16x32_bf16 v[8:11], v[140:143], v[218:221], v[8:11]
	v_mfma_f32_16x16x32_bf16 v[12:15], v[132:135], v[218:221], v[12:15]
	v_mfma_f32_16x16x32_bf16 v[12:15], v[128:131], v[214:217], v[12:15]
	s_setprio 0
	s_setprio 1
	v_mfma_f32_16x16x32_bf16 v[52:55], v[144:147], v[180:183], v[52:55]
	v_mfma_f32_16x16x32_bf16 v[52:55], v[148:151], v[194:197], v[52:55]
	v_mfma_f32_16x16x32_bf16 v[48:51], v[176:179], v[194:197], v[48:51]
	v_mfma_f32_16x16x32_bf16 v[48:51], v[172:175], v[180:183], v[48:51]
	v_mfma_f32_16x16x32_bf16 v[32:35], v[172:175], v[198:201], v[32:35]
	v_mfma_f32_16x16x32_bf16 v[32:35], v[176:179], v[202:205], v[32:35]
	v_mfma_f32_16x16x32_bf16 v[36:39], v[148:151], v[202:205], v[36:39]
	v_mfma_f32_16x16x32_bf16 v[36:39], v[144:147], v[198:201], v[36:39]
	v_mfma_f32_16x16x32_bf16 v[20:23], v[144:147], v[206:209], v[20:23]
	v_mfma_f32_16x16x32_bf16 v[20:23], v[148:151], v[210:213], v[20:23]
	v_mfma_f32_16x16x32_bf16 v[16:19], v[176:179], v[210:213], v[16:19]
	v_mfma_f32_16x16x32_bf16 v[16:19], v[172:175], v[206:209], v[16:19]
	v_mfma_f32_16x16x32_bf16 v[0:3], v[172:175], v[214:217], v[0:3]
	v_mfma_f32_16x16x32_bf16 v[0:3], v[176:179], v[218:221], v[0:3]
	v_mfma_f32_16x16x32_bf16 v[4:7], v[148:151], v[218:221], v[4:7]
	v_mfma_f32_16x16x32_bf16 v[4:7], v[144:147], v[214:217], v[4:7]
	s_setprio 0
	s_barrier
	s_add_i32 s83, s83, 2
	s_add_u32 s81, s81, 0x100
	s_addc_u32 s82, s82, 0
	s_cmp_gt_u32 s83, 41
	s_mov_b64 s[54:55], s[56:57]
.LBB0_159:
	ds_read_b128 v[128:131], v189
	ds_read_b128 v[132:135], v189 offset:1024
	ds_read_b128 v[136:139], v189 offset:2048
	ds_read_b128 v[140:143], v189 offset:3072
	ds_read_b128 v[144:147], v190
	ds_read_b128 v[148:151], v190 offset:1024
	ds_read_b128 v[172:175], v190 offset:2048
	ds_read_b128 v[176:179], v190 offset:3072
	s_add_u32 s56, s54, 0x100
	s_addc_u32 s57, s55, 0
	s_cmp_eq_u32 s83, 40
	s_cselect_b32 s61, s15, s57
	s_cselect_b32 s60, s14, s56
	s_cselect_b32 s59, s53, s82
	s_cselect_b32 s58, s52, s81
	v_lshl_add_u64 v[222:223], s[54:55], 0, v[166:167]
	s_add_i32 m0, s66, 0xc000
	ds_read_b128 v[180:183], v191
	ds_read_b128 v[194:197], v191 offset:1024
	ds_read_b128 v[198:201], v191 offset:2048
	ds_read_b128 v[202:205], v191 offset:3072
	ds_read_b128 v[206:209], v191 offset:4096
	ds_read_b128 v[210:213], v191 offset:5120
	ds_read_b128 v[214:217], v191 offset:6144
	ds_read_b128 v[218:221], v191 offset:7168
	global_load_lds_dwordx4 v[222:223], off
	v_lshl_add_u64 v[222:223], s[54:55], 0, v[164:165]
	s_add_i32 m0, s66, 0xe000
	s_nop 0
	global_load_lds_dwordx4 v[222:223], off
	s_waitcnt vmcnt(8)
	s_waitcnt lgkmcnt(0)
	s_barrier
	s_setprio 1
	s_waitcnt lgkmcnt(0)
	v_mfma_f32_16x16x32_bf16 v[124:127], v[128:131], v[180:183], v[124:127]
	v_mfma_f32_16x16x32_bf16 v[124:127], v[132:135], v[194:197], v[124:127]
	v_mfma_f32_16x16x32_bf16 v[120:123], v[140:143], v[194:197], v[120:123]
	v_mfma_f32_16x16x32_bf16 v[120:123], v[136:139], v[180:183], v[120:123]
	v_mfma_f32_16x16x32_bf16 v[104:107], v[136:139], v[198:201], v[104:107]
	v_mfma_f32_16x16x32_bf16 v[104:107], v[140:143], v[202:205], v[104:107]
	v_mfma_f32_16x16x32_bf16 v[108:111], v[132:135], v[202:205], v[108:111]
	v_mfma_f32_16x16x32_bf16 v[108:111], v[128:131], v[198:201], v[108:111]
	v_mfma_f32_16x16x32_bf16 v[92:95], v[128:131], v[206:209], v[92:95]
	v_mfma_f32_16x16x32_bf16 v[92:95], v[132:135], v[210:213], v[92:95]
	v_mfma_f32_16x16x32_bf16 v[88:91], v[140:143], v[210:213], v[88:91]
	v_mfma_f32_16x16x32_bf16 v[88:91], v[136:139], v[206:209], v[88:91]
	v_mfma_f32_16x16x32_bf16 v[72:75], v[136:139], v[214:217], v[72:75]
	v_mfma_f32_16x16x32_bf16 v[72:75], v[140:143], v[218:221], v[72:75]
	v_mfma_f32_16x16x32_bf16 v[76:79], v[132:135], v[218:221], v[76:79]
	v_mfma_f32_16x16x32_bf16 v[76:79], v[128:131], v[214:217], v[76:79]
	s_setprio 0
	s_setprio 1
	v_mfma_f32_16x16x32_bf16 v[116:119], v[144:147], v[180:183], v[116:119]
	v_mfma_f32_16x16x32_bf16 v[116:119], v[148:151], v[194:197], v[116:119]
	v_mfma_f32_16x16x32_bf16 v[112:115], v[176:179], v[194:197], v[112:115]
	v_mfma_f32_16x16x32_bf16 v[112:115], v[172:175], v[180:183], v[112:115]
	v_mfma_f32_16x16x32_bf16 v[96:99], v[172:175], v[198:201], v[96:99]
	v_mfma_f32_16x16x32_bf16 v[96:99], v[176:179], v[202:205], v[96:99]
	v_mfma_f32_16x16x32_bf16 v[100:103], v[148:151], v[202:205], v[100:103]
	v_mfma_f32_16x16x32_bf16 v[100:103], v[144:147], v[198:201], v[100:103]
	v_mfma_f32_16x16x32_bf16 v[84:87], v[144:147], v[206:209], v[84:87]
	v_mfma_f32_16x16x32_bf16 v[84:87], v[148:151], v[210:213], v[84:87]
	v_mfma_f32_16x16x32_bf16 v[80:83], v[176:179], v[210:213], v[80:83]
	v_mfma_f32_16x16x32_bf16 v[80:83], v[172:175], v[206:209], v[80:83]
	v_mfma_f32_16x16x32_bf16 v[64:67], v[172:175], v[214:217], v[64:67]
	v_mfma_f32_16x16x32_bf16 v[64:67], v[176:179], v[218:221], v[64:67]
	v_mfma_f32_16x16x32_bf16 v[68:71], v[148:151], v[218:221], v[68:71]
	v_mfma_f32_16x16x32_bf16 v[68:71], v[144:147], v[214:217], v[68:71]
	s_setprio 0
	s_barrier
	s_add_i32 s54, s77, s65
	v_lshl_add_u64 v[222:223], s[58:59], 0, v[154:155]
	s_mov_b32 m0, s54
	ds_read_b128 v[180:183], v191 offset:16384
	ds_read_b128 v[194:197], v191 offset:17408
	ds_read_b128 v[198:201], v191 offset:18432
	ds_read_b128 v[202:205], v191 offset:19456
	ds_read_b128 v[206:209], v191 offset:20480
	ds_read_b128 v[210:213], v191 offset:21504
	ds_read_b128 v[214:217], v191 offset:22528
	ds_read_b128 v[218:221], v191 offset:23552
	global_load_lds_dwordx4 v[222:223], off
	s_add_i32 m0, s54, 0x2000
	s_add_u32 s54, s58, 0xb0000
	v_lshl_add_u64 v[224:225], s[58:59], 0, v[162:163]
	s_addc_u32 s55, s59, 0
	s_add_i32 s84, s78, s65
	global_load_lds_dwordx4 v[224:225], off
	v_lshl_add_u64 v[226:227], s[54:55], 0, v[154:155]
	s_mov_b32 m0, s84
	v_lshl_add_u64 v[228:229], s[60:61], 0, v[160:161]
	global_load_lds_dwordx4 v[226:227], off
	v_lshl_add_u64 v[226:227], s[54:55], 0, v[162:163]
	s_add_i32 m0, s84, 0x2000
	s_nop 0
	global_load_lds_dwordx4 v[226:227], off
	v_lshl_add_u64 v[226:227], s[60:61], 0, v[152:153]
	s_mov_b32 m0, s66
	s_nop 0
	global_load_lds_dwordx4 v[226:227], off
	s_mov_b32 m0, s67
	s_nop 0
	global_load_lds_dwordx4 v[228:229], off
	s_waitcnt vmcnt(8)
	s_waitcnt lgkmcnt(0)
	s_barrier
	s_setprio 1
	s_waitcnt lgkmcnt(0)
	v_mfma_f32_16x16x32_bf16 v[60:63], v[128:131], v[180:183], v[60:63]
	v_mfma_f32_16x16x32_bf16 v[60:63], v[132:135], v[194:197], v[60:63]
	v_mfma_f32_16x16x32_bf16 v[56:59], v[140:143], v[194:197], v[56:59]
	v_mfma_f32_16x16x32_bf16 v[56:59], v[136:139], v[180:183], v[56:59]
	v_mfma_f32_16x16x32_bf16 v[40:43], v[136:139], v[198:201], v[40:43]
	v_mfma_f32_16x16x32_bf16 v[40:43], v[140:143], v[202:205], v[40:43]
	v_mfma_f32_16x16x32_bf16 v[44:47], v[132:135], v[202:205], v[44:47]
	v_mfma_f32_16x16x32_bf16 v[44:47], v[128:131], v[198:201], v[44:47]
	v_mfma_f32_16x16x32_bf16 v[28:31], v[128:131], v[206:209], v[28:31]
	v_mfma_f32_16x16x32_bf16 v[28:31], v[132:135], v[210:213], v[28:31]
	v_mfma_f32_16x16x32_bf16 v[24:27], v[140:143], v[210:213], v[24:27]
	v_mfma_f32_16x16x32_bf16 v[24:27], v[136:139], v[206:209], v[24:27]
	v_mfma_f32_16x16x32_bf16 v[8:11], v[136:139], v[214:217], v[8:11]
	v_mfma_f32_16x16x32_bf16 v[8:11], v[140:143], v[218:221], v[8:11]
	v_mfma_f32_16x16x32_bf16 v[12:15], v[132:135], v[218:221], v[12:15]
	v_mfma_f32_16x16x32_bf16 v[12:15], v[128:131], v[214:217], v[12:15]
	s_setprio 0
	s_setprio 1
	v_mfma_f32_16x16x32_bf16 v[52:55], v[144:147], v[180:183], v[52:55]
	v_mfma_f32_16x16x32_bf16 v[52:55], v[148:151], v[194:197], v[52:55]
	v_mfma_f32_16x16x32_bf16 v[48:51], v[176:179], v[194:197], v[48:51]
	v_mfma_f32_16x16x32_bf16 v[48:51], v[172:175], v[180:183], v[48:51]
	v_mfma_f32_16x16x32_bf16 v[32:35], v[172:175], v[198:201], v[32:35]
	v_mfma_f32_16x16x32_bf16 v[32:35], v[176:179], v[202:205], v[32:35]
	v_mfma_f32_16x16x32_bf16 v[36:39], v[148:151], v[202:205], v[36:39]
	v_mfma_f32_16x16x32_bf16 v[36:39], v[144:147], v[198:201], v[36:39]
	v_mfma_f32_16x16x32_bf16 v[20:23], v[144:147], v[206:209], v[20:23]
	v_mfma_f32_16x16x32_bf16 v[20:23], v[148:151], v[210:213], v[20:23]
	v_mfma_f32_16x16x32_bf16 v[16:19], v[176:179], v[210:213], v[16:19]
	v_mfma_f32_16x16x32_bf16 v[16:19], v[172:175], v[206:209], v[16:19]
	v_mfma_f32_16x16x32_bf16 v[0:3], v[172:175], v[214:217], v[0:3]
	v_mfma_f32_16x16x32_bf16 v[0:3], v[176:179], v[218:221], v[0:3]
	v_mfma_f32_16x16x32_bf16 v[4:7], v[148:151], v[218:221], v[4:7]
	v_mfma_f32_16x16x32_bf16 v[4:7], v[144:147], v[214:217], v[4:7]
	s_setprio 0
	s_barrier
	s_add_i32 s84, 0, 0x18000
	s_add_i32 s85, 0, 0x1c000
	v_add_u32_e32 v140, s84, v186
	v_add_u32_e32 v176, s85, v186
	ds_read_b128 v[128:131], v140
	ds_read_b128 v[132:135], v140 offset:1024
	ds_read_b128 v[136:139], v140 offset:2048
	ds_read_b128 v[140:143], v140 offset:3072
	ds_read_b128 v[144:147], v176
	ds_read_b128 v[148:151], v176 offset:1024
	ds_read_b128 v[172:175], v176 offset:2048
	ds_read_b128 v[176:179], v176 offset:3072
	s_add_u32 s54, s60, 0xb0000
	s_addc_u32 s55, s61, 0
	s_mov_b32 m0, s68
	v_lshl_add_u64 v[230:231], s[54:55], 0, v[152:153]
	ds_read_b128 v[180:183], v191 offset:32768
	ds_read_b128 v[194:197], v191 offset:33792
	ds_read_b128 v[198:201], v191 offset:34816
	ds_read_b128 v[202:205], v191 offset:35840
	ds_read_b128 v[206:209], v191 offset:36864
	ds_read_b128 v[210:213], v191 offset:37888
	ds_read_b128 v[214:217], v191 offset:38912
	ds_read_b128 v[218:221], v191 offset:39936
	global_load_lds_dwordx4 v[230:231], off
	v_lshl_add_u64 v[230:231], s[54:55], 0, v[160:161]
	s_mov_b32 m0, s69
	s_nop 0
	global_load_lds_dwordx4 v[230:231], off
	s_waitcnt vmcnt(8)
	s_waitcnt lgkmcnt(0)
	s_barrier
	s_setprio 1
	s_waitcnt lgkmcnt(0)
	v_mfma_f32_16x16x32_bf16 v[124:127], v[128:131], v[180:183], v[124:127]
	v_mfma_f32_16x16x32_bf16 v[124:127], v[132:135], v[194:197], v[124:127]
	v_mfma_f32_16x16x32_bf16 v[120:123], v[140:143], v[194:197], v[120:123]
	v_mfma_f32_16x16x32_bf16 v[120:123], v[136:139], v[180:183], v[120:123]
	v_mfma_f32_16x16x32_bf16 v[104:107], v[136:139], v[198:201], v[104:107]
	v_mfma_f32_16x16x32_bf16 v[104:107], v[140:143], v[202:205], v[104:107]
	v_mfma_f32_16x16x32_bf16 v[108:111], v[132:135], v[202:205], v[108:111]
	v_mfma_f32_16x16x32_bf16 v[108:111], v[128:131], v[198:201], v[108:111]
	v_mfma_f32_16x16x32_bf16 v[92:95], v[128:131], v[206:209], v[92:95]
	v_mfma_f32_16x16x32_bf16 v[92:95], v[132:135], v[210:213], v[92:95]
	v_mfma_f32_16x16x32_bf16 v[88:91], v[140:143], v[210:213], v[88:91]
	v_mfma_f32_16x16x32_bf16 v[88:91], v[136:139], v[206:209], v[88:91]
	v_mfma_f32_16x16x32_bf16 v[72:75], v[136:139], v[214:217], v[72:75]
	v_mfma_f32_16x16x32_bf16 v[72:75], v[140:143], v[218:221], v[72:75]
	v_mfma_f32_16x16x32_bf16 v[76:79], v[132:135], v[218:221], v[76:79]
	v_mfma_f32_16x16x32_bf16 v[76:79], v[128:131], v[214:217], v[76:79]
	s_setprio 0
	s_setprio 1
	v_mfma_f32_16x16x32_bf16 v[116:119], v[144:147], v[180:183], v[116:119]
	v_mfma_f32_16x16x32_bf16 v[116:119], v[148:151], v[194:197], v[116:119]
	v_mfma_f32_16x16x32_bf16 v[112:115], v[176:179], v[194:197], v[112:115]
	v_mfma_f32_16x16x32_bf16 v[112:115], v[172:175], v[180:183], v[112:115]
	v_mfma_f32_16x16x32_bf16 v[96:99], v[172:175], v[198:201], v[96:99]
	v_mfma_f32_16x16x32_bf16 v[96:99], v[176:179], v[202:205], v[96:99]
	v_mfma_f32_16x16x32_bf16 v[100:103], v[148:151], v[202:205], v[100:103]
	v_mfma_f32_16x16x32_bf16 v[100:103], v[144:147], v[198:201], v[100:103]
	v_mfma_f32_16x16x32_bf16 v[84:87], v[144:147], v[206:209], v[84:87]
	v_mfma_f32_16x16x32_bf16 v[84:87], v[148:151], v[210:213], v[84:87]
	v_mfma_f32_16x16x32_bf16 v[80:83], v[176:179], v[210:213], v[80:83]
	v_mfma_f32_16x16x32_bf16 v[80:83], v[172:175], v[206:209], v[80:83]
	v_mfma_f32_16x16x32_bf16 v[64:67], v[172:175], v[214:217], v[64:67]
	v_mfma_f32_16x16x32_bf16 v[64:67], v[176:179], v[218:221], v[64:67]
	v_mfma_f32_16x16x32_bf16 v[68:71], v[148:151], v[218:221], v[68:71]
	v_mfma_f32_16x16x32_bf16 v[68:71], v[144:147], v[214:217], v[68:71]
	s_setprio 0
	s_barrier
	s_add_i32 s54, s84, s65
	v_lshl_add_u64 v[222:223], v[222:223], 0, s[28:29]
	s_mov_b32 m0, s54
	ds_read_b128 v[180:183], v191 offset:49152
	ds_read_b128 v[194:197], v191 offset:50176
	ds_read_b128 v[198:201], v191 offset:51200
	ds_read_b128 v[202:205], v191 offset:52224
	ds_read_b128 v[206:209], v191 offset:53248
	ds_read_b128 v[210:213], v191 offset:54272
	ds_read_b128 v[214:217], v191 offset:55296
	ds_read_b128 v[218:221], v191 offset:56320
	global_load_lds_dwordx4 v[222:223], off
	s_add_i32 m0, s54, 0x2000
	s_add_u32 s54, s58, 0xb0080
	v_lshl_add_u64 v[222:223], v[224:225], 0, s[28:29]
	s_addc_u32 s55, s59, 0
	s_add_i32 s58, s85, s65
	global_load_lds_dwordx4 v[222:223], off
	v_lshl_add_u64 v[222:223], s[54:55], 0, v[154:155]
	s_mov_b32 m0, s58
	s_nop 0
	global_load_lds_dwordx4 v[222:223], off
	v_lshl_add_u64 v[222:223], s[54:55], 0, v[162:163]
	s_add_i32 m0, s58, 0x2000
	s_nop 0
	global_load_lds_dwordx4 v[222:223], off
	v_lshl_add_u64 v[222:223], v[226:227], 0, s[28:29]
	s_mov_b32 m0, s3
	s_nop 0
	global_load_lds_dwordx4 v[222:223], off
	v_lshl_add_u64 v[222:223], v[228:229], 0, s[28:29]
	s_mov_b32 m0, s71
	s_nop 0
	global_load_lds_dwordx4 v[222:223], off
	s_waitcnt vmcnt(8)
	s_waitcnt lgkmcnt(0)
	s_barrier
	s_setprio 1
	s_waitcnt lgkmcnt(0)
	v_mfma_f32_16x16x32_bf16 v[60:63], v[128:131], v[180:183], v[60:63]
	v_mfma_f32_16x16x32_bf16 v[60:63], v[132:135], v[194:197], v[60:63]
	v_mfma_f32_16x16x32_bf16 v[56:59], v[140:143], v[194:197], v[56:59]
	v_mfma_f32_16x16x32_bf16 v[56:59], v[136:139], v[180:183], v[56:59]
	v_mfma_f32_16x16x32_bf16 v[40:43], v[136:139], v[198:201], v[40:43]
	v_mfma_f32_16x16x32_bf16 v[40:43], v[140:143], v[202:205], v[40:43]
	v_mfma_f32_16x16x32_bf16 v[44:47], v[132:135], v[202:205], v[44:47]
	v_mfma_f32_16x16x32_bf16 v[44:47], v[128:131], v[198:201], v[44:47]
	v_mfma_f32_16x16x32_bf16 v[28:31], v[128:131], v[206:209], v[28:31]
	v_mfma_f32_16x16x32_bf16 v[28:31], v[132:135], v[210:213], v[28:31]
	v_mfma_f32_16x16x32_bf16 v[24:27], v[140:143], v[210:213], v[24:27]
	v_mfma_f32_16x16x32_bf16 v[24:27], v[136:139], v[206:209], v[24:27]
	v_mfma_f32_16x16x32_bf16 v[8:11], v[136:139], v[214:217], v[8:11]
	v_mfma_f32_16x16x32_bf16 v[8:11], v[140:143], v[218:221], v[8:11]
	v_mfma_f32_16x16x32_bf16 v[12:15], v[132:135], v[218:221], v[12:15]
	v_mfma_f32_16x16x32_bf16 v[12:15], v[128:131], v[214:217], v[12:15]
	s_setprio 0
	s_setprio 1
	v_mfma_f32_16x16x32_bf16 v[52:55], v[144:147], v[180:183], v[52:55]
	v_mfma_f32_16x16x32_bf16 v[52:55], v[148:151], v[194:197], v[52:55]
	v_mfma_f32_16x16x32_bf16 v[48:51], v[176:179], v[194:197], v[48:51]
	v_mfma_f32_16x16x32_bf16 v[48:51], v[172:175], v[180:183], v[48:51]
	v_mfma_f32_16x16x32_bf16 v[32:35], v[172:175], v[198:201], v[32:35]
	v_mfma_f32_16x16x32_bf16 v[32:35], v[176:179], v[202:205], v[32:35]
	v_mfma_f32_16x16x32_bf16 v[36:39], v[148:151], v[202:205], v[36:39]
	v_mfma_f32_16x16x32_bf16 v[36:39], v[144:147], v[198:201], v[36:39]
	v_mfma_f32_16x16x32_bf16 v[20:23], v[144:147], v[206:209], v[20:23]
	v_mfma_f32_16x16x32_bf16 v[20:23], v[148:151], v[210:213], v[20:23]
	v_mfma_f32_16x16x32_bf16 v[16:19], v[176:179], v[210:213], v[16:19]
	v_mfma_f32_16x16x32_bf16 v[16:19], v[172:175], v[206:209], v[16:19]
	v_mfma_f32_16x16x32_bf16 v[0:3], v[172:175], v[214:217], v[0:3]
	v_mfma_f32_16x16x32_bf16 v[0:3], v[176:179], v[218:221], v[0:3]
	v_mfma_f32_16x16x32_bf16 v[4:7], v[148:151], v[218:221], v[4:7]
	v_mfma_f32_16x16x32_bf16 v[4:7], v[144:147], v[214:217], v[4:7]
	s_setprio 0
	s_barrier
	s_add_i32 s83, s83, 2
	s_add_u32 s81, s81, 0x100
	s_addc_u32 s82, s82, 0
	s_cmp_gt_u32 s83, 41
	s_mov_b64 s[54:55], s[56:57]
	s_cbranch_scc0 .LBB0_159
	s_and_b64 vcc, exec, s[30:31]
	s_cbranch_vccz .LBB0_162
	s_barrier

.LBB0_254:
	s_ashr_i32 s61, s60, 31
	s_lshl_b64 s[62:63], s[60:61], 19
	s_add_u32 s62, s35, s62
	s_addc_u32 s63, s47, s63
	s_and_b64 s[64:65], s[12:13], exec
	s_cselect_b32 s3, s63, s69
	s_cselect_b32 s61, s62, s68
	s_ashr_i32 s59, s58, 31
	s_lshl_b64 s[64:65], s[58:59], 19
	s_add_u32 s64, s49, s64
	s_addc_u32 s65, s70, s65
	s_and_b64 s[92:93], s[12:13], exec
	s_cselect_b32 s91, s65, s67
	s_cselect_b32 s92, s64, s66
	s_lshl_b32 s59, s14, 8
	v_add_u32_e32 v0, s59, v182
	s_add_u32 s93, s66, 0x100
	s_waitcnt lgkmcnt(0)
	v_ashrrev_i32_e32 v1, 31, v0
	s_addc_u32 s94, s67, 0
	v_lshl_add_u64 v[72:73], v[0:1], 4, s[26:27]
	s_add_u32 s14, s68, 0x40080
	s_addc_u32 s15, s69, 0
	s_mov_b32 s95, -2
	s_mov_b64 s[66:67], 0
	s_cmp_eq_u32 s90, 1
	s_cbranch_scc1 .Lfa_2
	v_add_u32_e32 v74, s83, v181
	ds_read_b128 v[88:91], v74
	ds_read_b128 v[108:111], v74 offset:1024
	ds_read_b128 v[128:131], v74 offset:2048
	ds_read_b128 v[144:147], v74 offset:3072
	v_add_u32_e32 v74, s84, v181
	ds_read_b128 v[148:151], v74
	ds_read_b128 v[152:155], v74 offset:1024
	ds_read_b128 v[176:179], v74 offset:2048
	ds_read_b128 v[190:193], v74 offset:3072
	s_add_u32 s68, s14, 0xfffc0080
	s_addc_u32 s69, s15, -1
	s_and_b64 s[66:67], s[66:67], exec
	s_cselect_b32 s69, s3, s69
	s_cselect_b32 s68, s61, s68
	s_cselect_b32 s67, s91, s94
	s_cselect_b32 s66, s92, s93
	v_lshl_add_u64 v[74:75], s[14:15], 0, v[170:171]
	s_add_i32 m0, s74, 0xc000
	ds_read_b128 v[194:197], v187
	ds_read_b128 v[198:201], v187 offset:1024
	ds_read_b128 v[202:205], v187 offset:2048
	ds_read_b128 v[206:209], v187 offset:3072
	ds_read_b128 v[210:213], v187 offset:4096
	ds_read_b128 v[214:217], v187 offset:5120
	ds_read_b128 v[218:221], v187 offset:6144
	ds_read_b128 v[222:225], v187 offset:7168
	global_load_lds_dwordx4 v[74:75], off
	v_lshl_add_u64 v[74:75], s[14:15], 0, v[168:169]
	s_add_i32 m0, s74, 0xe000
	s_nop 0
	global_load_lds_dwordx4 v[74:75], off
	s_waitcnt vmcnt(24)
	s_waitcnt lgkmcnt(0)
	s_barrier
	s_setprio 1
	s_waitcnt lgkmcnt(0)
	v_mfma_f32_16x16x32_bf16 v[140:143], v[88:91], v[194:197], 0
	v_mfma_f32_16x16x32_bf16 v[136:139], v[128:131], v[194:197], 0
	v_mfma_f32_16x16x32_bf16 v[120:123], v[88:91], v[202:205], 0
	v_mfma_f32_16x16x32_bf16 v[116:119], v[128:131], v[202:205], 0
	v_mfma_f32_16x16x32_bf16 v[100:103], v[88:91], v[210:213], 0
	v_mfma_f32_16x16x32_bf16 v[96:99], v[128:131], v[210:213], 0
	v_mfma_f32_16x16x32_bf16 v[80:83], v[88:91], v[218:221], 0
	v_mfma_f32_16x16x32_bf16 v[74:77], v[128:131], v[218:221], 0
	v_mfma_f32_16x16x32_bf16 v[140:143], v[108:111], v[198:201], v[140:143]
	v_mfma_f32_16x16x32_bf16 v[136:139], v[144:147], v[198:201], v[136:139]
	v_mfma_f32_16x16x32_bf16 v[120:123], v[108:111], v[206:209], v[120:123]
	v_mfma_f32_16x16x32_bf16 v[116:119], v[144:147], v[206:209], v[116:119]
	v_mfma_f32_16x16x32_bf16 v[100:103], v[108:111], v[214:217], v[100:103]
	v_mfma_f32_16x16x32_bf16 v[96:99], v[144:147], v[214:217], v[96:99]
	v_mfma_f32_16x16x32_bf16 v[80:83], v[108:111], v[222:225], v[80:83]
	v_mfma_f32_16x16x32_bf16 v[74:77], v[144:147], v[222:225], v[74:77]
	s_setprio 0
	s_setprio 1
	v_mfma_f32_16x16x32_bf16 v[132:135], v[148:151], v[194:197], 0
	v_mfma_f32_16x16x32_bf16 v[124:127], v[176:179], v[194:197], 0
	v_mfma_f32_16x16x32_bf16 v[112:115], v[148:151], v[202:205], 0
	v_mfma_f32_16x16x32_bf16 v[104:107], v[176:179], v[202:205], 0
	v_mfma_f32_16x16x32_bf16 v[92:95], v[148:151], v[210:213], 0
	v_mfma_f32_16x16x32_bf16 v[84:87], v[176:179], v[210:213], 0
	v_mfma_f32_16x16x32_bf16 v[68:71], v[148:151], v[218:221], 0
	v_mfma_f32_16x16x32_bf16 v[64:67], v[176:179], v[218:221], 0
	v_mfma_f32_16x16x32_bf16 v[132:135], v[152:155], v[198:201], v[132:135]
	v_mfma_f32_16x16x32_bf16 v[124:127], v[190:193], v[198:201], v[124:127]
	v_mfma_f32_16x16x32_bf16 v[112:115], v[152:155], v[206:209], v[112:115]
	v_mfma_f32_16x16x32_bf16 v[104:107], v[190:193], v[206:209], v[104:107]
	v_mfma_f32_16x16x32_bf16 v[92:95], v[152:155], v[214:217], v[92:95]
	v_mfma_f32_16x16x32_bf16 v[84:87], v[190:193], v[214:217], v[84:87]
	v_mfma_f32_16x16x32_bf16 v[68:71], v[152:155], v[222:225], v[68:71]
	v_mfma_f32_16x16x32_bf16 v[64:67], v[190:193], v[222:225], v[64:67]
	s_setprio 0
	s_barrier
	s_add_i32 s96, s83, s71
	v_lshl_add_u64 v[226:227], s[66:67], 0, v[162:163]
	s_mov_b32 m0, s96
	ds_read_b128 v[194:197], v187 offset:16384
	ds_read_b128 v[198:201], v187 offset:17408
	ds_read_b128 v[202:205], v187 offset:18432
	ds_read_b128 v[206:209], v187 offset:19456
	ds_read_b128 v[210:213], v187 offset:20480
	ds_read_b128 v[214:217], v187 offset:21504
	ds_read_b128 v[218:221], v187 offset:22528
	ds_read_b128 v[222:225], v187 offset:23552
	global_load_lds_dwordx4 v[226:227], off
	s_add_i32 m0, s96, 0x2000
	s_add_u32 s96, s66, 0x40000
	v_lshl_add_u64 v[228:229], s[66:67], 0, v[166:167]
	s_addc_u32 s97, s67, 0
	s_add_i32 vcc_lo, s84, s71
	global_load_lds_dwordx4 v[228:229], off
	v_lshl_add_u64 v[78:79], s[96:97], 0, v[162:163]
	s_mov_b32 m0, vcc_lo
	v_lshl_add_u64 v[230:231], s[68:69], 0, v[160:161]
	global_load_lds_dwordx4 v[78:79], off
	v_lshl_add_u64 v[78:79], s[96:97], 0, v[166:167]
	s_add_i32 m0, vcc_lo, 0x2000
	v_lshl_add_u64 v[232:233], s[68:69], 0, v[164:165]
	global_load_lds_dwordx4 v[78:79], off
	s_mov_b32 m0, s74
	s_nop 0
	global_load_lds_dwordx4 v[230:231], off
	s_mov_b32 m0, s75
	s_nop 0
	global_load_lds_dwordx4 v[232:233], off
	s_waitcnt vmcnt(24)
	s_waitcnt lgkmcnt(0)
	s_barrier
	s_setprio 1
	s_waitcnt lgkmcnt(0)
	v_mfma_f32_16x16x32_bf16 v[60:63], v[88:91], v[194:197], 0
	v_mfma_f32_16x16x32_bf16 v[56:59], v[128:131], v[194:197], 0
	v_mfma_f32_16x16x32_bf16 v[44:47], v[88:91], v[202:205], 0
	v_mfma_f32_16x16x32_bf16 v[40:43], v[128:131], v[202:205], 0
	v_mfma_f32_16x16x32_bf16 v[28:31], v[88:91], v[210:213], 0
	v_mfma_f32_16x16x32_bf16 v[24:27], v[128:131], v[210:213], 0
	v_mfma_f32_16x16x32_bf16 v[12:15], v[88:91], v[218:221], 0
	v_mfma_f32_16x16x32_bf16 v[8:11], v[128:131], v[218:221], 0
	v_mfma_f32_16x16x32_bf16 v[60:63], v[108:111], v[198:201], v[60:63]
	v_mfma_f32_16x16x32_bf16 v[56:59], v[144:147], v[198:201], v[56:59]
	v_mfma_f32_16x16x32_bf16 v[44:47], v[108:111], v[206:209], v[44:47]
	v_mfma_f32_16x16x32_bf16 v[40:43], v[144:147], v[206:209], v[40:43]
	v_mfma_f32_16x16x32_bf16 v[28:31], v[108:111], v[214:217], v[28:31]
	v_mfma_f32_16x16x32_bf16 v[24:27], v[144:147], v[214:217], v[24:27]
	v_mfma_f32_16x16x32_bf16 v[12:15], v[108:111], v[222:225], v[12:15]
	v_mfma_f32_16x16x32_bf16 v[8:11], v[144:147], v[222:225], v[8:11]
	s_setprio 0
	s_setprio 1
	v_mfma_f32_16x16x32_bf16 v[52:55], v[148:151], v[194:197], 0
	v_mfma_f32_16x16x32_bf16 v[48:51], v[176:179], v[194:197], 0
	v_mfma_f32_16x16x32_bf16 v[36:39], v[148:151], v[202:205], 0
	v_mfma_f32_16x16x32_bf16 v[32:35], v[176:179], v[202:205], 0
	v_mfma_f32_16x16x32_bf16 v[20:23], v[148:151], v[210:213], 0
	v_mfma_f32_16x16x32_bf16 v[16:19], v[176:179], v[210:213], 0
	v_mfma_f32_16x16x32_bf16 v[4:7], v[148:151], v[218:221], 0
	v_mfma_f32_16x16x32_bf16 v[0:3], v[176:179], v[218:221], 0
	v_mfma_f32_16x16x32_bf16 v[52:55], v[152:155], v[198:201], v[52:55]
	v_mfma_f32_16x16x32_bf16 v[48:51], v[190:193], v[198:201], v[48:51]
	v_mfma_f32_16x16x32_bf16 v[36:39], v[152:155], v[206:209], v[36:39]
	v_mfma_f32_16x16x32_bf16 v[32:35], v[190:193], v[206:209], v[32:35]
	v_mfma_f32_16x16x32_bf16 v[20:23], v[152:155], v[214:217], v[20:23]
	v_mfma_f32_16x16x32_bf16 v[16:19], v[190:193], v[214:217], v[16:19]
	v_mfma_f32_16x16x32_bf16 v[4:7], v[152:155], v[222:225], v[4:7]
	v_mfma_f32_16x16x32_bf16 v[0:3], v[190:193], v[222:225], v[0:3]
	s_setprio 0
	s_barrier
	s_add_i32 s96, 0, 0x18000
	v_add_u32_e32 v78, s96, v181
	s_add_i32 s97, 0, 0x1c000
	ds_read_b128 v[88:91], v78
	ds_read_b128 v[108:111], v78 offset:1024
	ds_read_b128 v[128:131], v78 offset:2048
	ds_read_b128 v[144:147], v78 offset:3072
	v_add_u32_e32 v78, s97, v181
	ds_read_b128 v[148:151], v78
	ds_read_b128 v[152:155], v78 offset:1024
	ds_read_b128 v[176:179], v78 offset:2048
	ds_read_b128 v[190:193], v78 offset:3072
	s_add_u32 s68, s68, 0x40000
	s_addc_u32 s69, s69, 0
	s_mov_b32 m0, s76
	v_lshl_add_u64 v[78:79], s[68:69], 0, v[160:161]
	ds_read_b128 v[194:197], v187 offset:32768
	ds_read_b128 v[198:201], v187 offset:33792
	ds_read_b128 v[202:205], v187 offset:34816
	ds_read_b128 v[206:209], v187 offset:35840
	ds_read_b128 v[210:213], v187 offset:36864
	ds_read_b128 v[214:217], v187 offset:37888
	ds_read_b128 v[218:221], v187 offset:38912
	ds_read_b128 v[222:225], v187 offset:39936
	global_load_lds_dwordx4 v[78:79], off
	v_lshl_add_u64 v[78:79], s[68:69], 0, v[164:165]
	s_mov_b32 m0, s77
	s_nop 0
	global_load_lds_dwordx4 v[78:79], off
	s_waitcnt vmcnt(8)
	s_waitcnt lgkmcnt(0)
	s_barrier
	s_setprio 1
	s_waitcnt lgkmcnt(0)
	v_mfma_f32_16x16x32_bf16 v[140:143], v[88:91], v[194:197], v[140:143]
	v_mfma_f32_16x16x32_bf16 v[136:139], v[128:131], v[194:197], v[136:139]
	v_mfma_f32_16x16x32_bf16 v[120:123], v[88:91], v[202:205], v[120:123]
	v_mfma_f32_16x16x32_bf16 v[116:119], v[128:131], v[202:205], v[116:119]
	v_mfma_f32_16x16x32_bf16 v[100:103], v[88:91], v[210:213], v[100:103]
	v_mfma_f32_16x16x32_bf16 v[96:99], v[128:131], v[210:213], v[96:99]
	v_mfma_f32_16x16x32_bf16 v[78:81], v[88:91], v[218:221], v[80:83]
	v_mfma_f32_16x16x32_bf16 v[74:77], v[128:131], v[218:221], v[74:77]
	v_mfma_f32_16x16x32_bf16 v[140:143], v[108:111], v[198:201], v[140:143]
	v_mfma_f32_16x16x32_bf16 v[136:139], v[144:147], v[198:201], v[136:139]
	v_mfma_f32_16x16x32_bf16 v[120:123], v[108:111], v[206:209], v[120:123]
	v_mfma_f32_16x16x32_bf16 v[116:119], v[144:147], v[206:209], v[116:119]
	v_mfma_f32_16x16x32_bf16 v[100:103], v[108:111], v[214:217], v[100:103]
	v_mfma_f32_16x16x32_bf16 v[96:99], v[144:147], v[214:217], v[96:99]
	v_mfma_f32_16x16x32_bf16 v[80:83], v[108:111], v[222:225], v[78:81]
	v_mfma_f32_16x16x32_bf16 v[76:79], v[144:147], v[222:225], v[74:77]
	s_setprio 0
	s_setprio 1
	v_mfma_f32_16x16x32_bf16 v[132:135], v[148:151], v[194:197], v[132:135]
	v_mfma_f32_16x16x32_bf16 v[132:135], v[152:155], v[198:201], v[132:135]
	v_mfma_f32_16x16x32_bf16 v[124:127], v[190:193], v[198:201], v[124:127]
	v_mfma_f32_16x16x32_bf16 v[124:127], v[176:179], v[194:197], v[124:127]
	v_mfma_f32_16x16x32_bf16 v[104:107], v[176:179], v[202:205], v[104:107]
	v_mfma_f32_16x16x32_bf16 v[104:107], v[190:193], v[206:209], v[104:107]
	v_mfma_f32_16x16x32_bf16 v[112:115], v[152:155], v[206:209], v[112:115]
	v_mfma_f32_16x16x32_bf16 v[112:115], v[148:151], v[202:205], v[112:115]
	v_mfma_f32_16x16x32_bf16 v[92:95], v[148:151], v[210:213], v[92:95]
	v_mfma_f32_16x16x32_bf16 v[92:95], v[152:155], v[214:217], v[92:95]
	v_mfma_f32_16x16x32_bf16 v[84:87], v[190:193], v[214:217], v[84:87]
	v_mfma_f32_16x16x32_bf16 v[84:87], v[176:179], v[210:213], v[84:87]
	v_mfma_f32_16x16x32_bf16 v[64:67], v[176:179], v[218:221], v[64:67]
	v_mfma_f32_16x16x32_bf16 v[64:67], v[190:193], v[222:225], v[64:67]
	v_mfma_f32_16x16x32_bf16 v[68:71], v[152:155], v[222:225], v[68:71]
	v_mfma_f32_16x16x32_bf16 v[68:71], v[148:151], v[218:221], v[68:71]
	s_setprio 0
	s_barrier
	s_add_i32 s68, s96, s71
	v_lshl_add_u64 v[74:75], v[226:227], 0, s[28:29]
	s_mov_b32 m0, s68
	ds_read_b128 v[194:197], v187 offset:49152
	ds_read_b128 v[198:201], v187 offset:50176
	ds_read_b128 v[202:205], v187 offset:51200
	ds_read_b128 v[206:209], v187 offset:52224
	ds_read_b128 v[210:213], v187 offset:53248
	ds_read_b128 v[214:217], v187 offset:54272
	ds_read_b128 v[218:221], v187 offset:55296
	ds_read_b128 v[222:225], v187 offset:56320
	global_load_lds_dwordx4 v[74:75], off
	s_add_i32 m0, s68, 0x2000
	s_add_u32 s66, s66, 0x40080
	v_lshl_add_u64 v[74:75], v[228:229], 0, s[28:29]
	s_addc_u32 s67, s67, 0
	s_add_i32 s68, s97, s71
	global_load_lds_dwordx4 v[74:75], off
	v_lshl_add_u64 v[74:75], s[66:67], 0, v[162:163]
	s_mov_b32 m0, s68
	s_nop 0
	global_load_lds_dwordx4 v[74:75], off
	v_lshl_add_u64 v[74:75], s[66:67], 0, v[166:167]
	s_add_i32 m0, s68, 0x2000
	s_nop 0
	global_load_lds_dwordx4 v[74:75], off
	v_lshl_add_u64 v[74:75], v[230:231], 0, s[28:29]
	s_mov_b32 m0, s78
	s_nop 0
	global_load_lds_dwordx4 v[74:75], off
	v_lshl_add_u64 v[74:75], v[232:233], 0, s[28:29]
	s_mov_b32 m0, s79
	s_nop 0
	global_load_lds_dwordx4 v[74:75], off
	s_waitcnt vmcnt(8)
	s_waitcnt lgkmcnt(0)
	s_barrier
	s_setprio 1
	s_waitcnt lgkmcnt(0)
	v_mfma_f32_16x16x32_bf16 v[60:63], v[88:91], v[194:197], v[60:63]
	v_mfma_f32_16x16x32_bf16 v[60:63], v[108:111], v[198:201], v[60:63]
	v_mfma_f32_16x16x32_bf16 v[56:59], v[144:147], v[198:201], v[56:59]
	v_mfma_f32_16x16x32_bf16 v[56:59], v[128:131], v[194:197], v[56:59]
	v_mfma_f32_16x16x32_bf16 v[40:43], v[128:131], v[202:205], v[40:43]
	v_mfma_f32_16x16x32_bf16 v[40:43], v[144:147], v[206:209], v[40:43]
	v_mfma_f32_16x16x32_bf16 v[44:47], v[108:111], v[206:209], v[44:47]
	v_mfma_f32_16x16x32_bf16 v[44:47], v[88:91], v[202:205], v[44:47]
	v_mfma_f32_16x16x32_bf16 v[28:31], v[88:91], v[210:213], v[28:31]
	v_mfma_f32_16x16x32_bf16 v[28:31], v[108:111], v[214:217], v[28:31]
	v_mfma_f32_16x16x32_bf16 v[24:27], v[144:147], v[214:217], v[24:27]
	v_mfma_f32_16x16x32_bf16 v[24:27], v[128:131], v[210:213], v[24:27]
	v_mfma_f32_16x16x32_bf16 v[8:11], v[128:131], v[218:221], v[8:11]
	v_mfma_f32_16x16x32_bf16 v[8:11], v[144:147], v[222:225], v[8:11]
	v_mfma_f32_16x16x32_bf16 v[12:15], v[108:111], v[222:225], v[12:15]
	v_mfma_f32_16x16x32_bf16 v[12:15], v[88:91], v[218:221], v[12:15]
	s_setprio 0
	s_setprio 1
	v_mfma_f32_16x16x32_bf16 v[52:55], v[148:151], v[194:197], v[52:55]
	v_mfma_f32_16x16x32_bf16 v[52:55], v[152:155], v[198:201], v[52:55]
	v_mfma_f32_16x16x32_bf16 v[48:51], v[190:193], v[198:201], v[48:51]
	v_mfma_f32_16x16x32_bf16 v[48:51], v[176:179], v[194:197], v[48:51]
	v_mfma_f32_16x16x32_bf16 v[32:35], v[176:179], v[202:205], v[32:35]
	v_mfma_f32_16x16x32_bf16 v[32:35], v[190:193], v[206:209], v[32:35]
	v_mfma_f32_16x16x32_bf16 v[36:39], v[152:155], v[206:209], v[36:39]
	v_mfma_f32_16x16x32_bf16 v[36:39], v[148:151], v[202:205], v[36:39]
	v_mfma_f32_16x16x32_bf16 v[20:23], v[148:151], v[210:213], v[20:23]
	v_mfma_f32_16x16x32_bf16 v[20:23], v[152:155], v[214:217], v[20:23]
	v_mfma_f32_16x16x32_bf16 v[16:19], v[190:193], v[214:217], v[16:19]
	v_mfma_f32_16x16x32_bf16 v[16:19], v[176:179], v[210:213], v[16:19]
	v_mfma_f32_16x16x32_bf16 v[0:3], v[176:179], v[218:221], v[0:3]
	v_mfma_f32_16x16x32_bf16 v[0:3], v[190:193], v[222:225], v[0:3]
	v_mfma_f32_16x16x32_bf16 v[4:7], v[152:155], v[222:225], v[4:7]
	v_mfma_f32_16x16x32_bf16 v[4:7], v[148:151], v[218:221], v[4:7]
	s_setprio 0
	s_barrier
	s_add_i32 s95, s95, 2
	s_add_u32 s93, s93, 0x100
	s_addc_u32 s94, s94, 0
	s_add_u32 s14, s14, 0x100
	s_addc_u32 s15, s15, 0
	s_branch .LBB0_256
.Lfa_2:
	v_add_u32_e32 v74, s83, v181
	ds_read_b128 v[88:91], v74
	ds_read_b128 v[108:111], v74 offset:1024
	ds_read_b128 v[128:131], v74 offset:2048
	ds_read_b128 v[144:147], v74 offset:3072
	v_add_u32_e32 v74, s84, v181
	ds_read_b128 v[148:151], v74
	ds_read_b128 v[152:155], v74 offset:1024
	ds_read_b128 v[176:179], v74 offset:2048
	ds_read_b128 v[190:193], v74 offset:3072
	s_add_u32 s68, s14, 0xfffc0080
	s_addc_u32 s69, s15, -1
	s_and_b64 s[66:67], s[66:67], exec
	s_cselect_b32 s69, s3, s69
	s_cselect_b32 s68, s61, s68
	s_cselect_b32 s67, s91, s94
	s_cselect_b32 s66, s92, s93
	v_lshl_add_u64 v[74:75], s[14:15], 0, v[170:171]
	s_add_i32 m0, s74, 0xc000
	ds_read_b128 v[194:197], v187
	ds_read_b128 v[198:201], v187 offset:1024
	ds_read_b128 v[202:205], v187 offset:2048
	ds_read_b128 v[206:209], v187 offset:3072
	ds_read_b128 v[210:213], v187 offset:4096
	ds_read_b128 v[214:217], v187 offset:5120
	ds_read_b128 v[218:221], v187 offset:6144
	ds_read_b128 v[222:225], v187 offset:7168
	global_load_lds_dwordx4 v[74:75], off
	v_lshl_add_u64 v[74:75], s[14:15], 0, v[168:169]
	s_add_i32 m0, s74, 0xe000
	s_nop 0
	global_load_lds_dwordx4 v[74:75], off
	s_waitcnt vmcnt(8)
	s_waitcnt lgkmcnt(0)
	s_barrier
	s_setprio 1
	s_waitcnt lgkmcnt(0)
	v_mfma_f32_16x16x32_bf16 v[140:143], v[88:91], v[194:197], 0
	v_mfma_f32_16x16x32_bf16 v[136:139], v[128:131], v[194:197], 0
	v_mfma_f32_16x16x32_bf16 v[120:123], v[88:91], v[202:205], 0
	v_mfma_f32_16x16x32_bf16 v[116:119], v[128:131], v[202:205], 0
	v_mfma_f32_16x16x32_bf16 v[100:103], v[88:91], v[210:213], 0
	v_mfma_f32_16x16x32_bf16 v[96:99], v[128:131], v[210:213], 0
	v_mfma_f32_16x16x32_bf16 v[80:83], v[88:91], v[218:221], 0
	v_mfma_f32_16x16x32_bf16 v[74:77], v[128:131], v[218:221], 0
	v_mfma_f32_16x16x32_bf16 v[140:143], v[108:111], v[198:201], v[140:143]
	v_mfma_f32_16x16x32_bf16 v[136:139], v[144:147], v[198:201], v[136:139]
	v_mfma_f32_16x16x32_bf16 v[120:123], v[108:111], v[206:209], v[120:123]
	v_mfma_f32_16x16x32_bf16 v[116:119], v[144:147], v[206:209], v[116:119]
	v_mfma_f32_16x16x32_bf16 v[100:103], v[108:111], v[214:217], v[100:103]
	v_mfma_f32_16x16x32_bf16 v[96:99], v[144:147], v[214:217], v[96:99]
	v_mfma_f32_16x16x32_bf16 v[80:83], v[108:111], v[222:225], v[80:83]
	v_mfma_f32_16x16x32_bf16 v[74:77], v[144:147], v[222:225], v[74:77]
	s_setprio 0
	s_setprio 1
	v_mfma_f32_16x16x32_bf16 v[132:135], v[148:151], v[194:197], 0
	v_mfma_f32_16x16x32_bf16 v[124:127], v[176:179], v[194:197], 0
	v_mfma_f32_16x16x32_bf16 v[112:115], v[148:151], v[202:205], 0
	v_mfma_f32_16x16x32_bf16 v[104:107], v[176:179], v[202:205], 0
	v_mfma_f32_16x16x32_bf16 v[92:95], v[148:151], v[210:213], 0
	v_mfma_f32_16x16x32_bf16 v[84:87], v[176:179], v[210:213], 0
	v_mfma_f32_16x16x32_bf16 v[68:71], v[148:151], v[218:221], 0
	v_mfma_f32_16x16x32_bf16 v[64:67], v[176:179], v[218:221], 0
	v_mfma_f32_16x16x32_bf16 v[132:135], v[152:155], v[198:201], v[132:135]
	v_mfma_f32_16x16x32_bf16 v[124:127], v[190:193], v[198:201], v[124:127]
	v_mfma_f32_16x16x32_bf16 v[112:115], v[152:155], v[206:209], v[112:115]
	v_mfma_f32_16x16x32_bf16 v[104:107], v[190:193], v[206:209], v[104:107]
	v_mfma_f32_16x16x32_bf16 v[92:95], v[152:155], v[214:217], v[92:95]
	v_mfma_f32_16x16x32_bf16 v[84:87], v[190:193], v[214:217], v[84:87]
	v_mfma_f32_16x16x32_bf16 v[68:71], v[152:155], v[222:225], v[68:71]
	v_mfma_f32_16x16x32_bf16 v[64:67], v[190:193], v[222:225], v[64:67]
	s_setprio 0
	s_barrier
	s_add_i32 s96, s83, s71
	v_lshl_add_u64 v[226:227], s[66:67], 0, v[162:163]
	s_mov_b32 m0, s96
	ds_read_b128 v[194:197], v187 offset:16384
	ds_read_b128 v[198:201], v187 offset:17408
	ds_read_b128 v[202:205], v187 offset:18432
	ds_read_b128 v[206:209], v187 offset:19456
	ds_read_b128 v[210:213], v187 offset:20480
	ds_read_b128 v[214:217], v187 offset:21504
	ds_read_b128 v[218:221], v187 offset:22528
	ds_read_b128 v[222:225], v187 offset:23552
	global_load_lds_dwordx4 v[226:227], off
	s_add_i32 m0, s96, 0x2000
	s_add_u32 s96, s66, 0x40000
	v_lshl_add_u64 v[228:229], s[66:67], 0, v[166:167]
	s_addc_u32 s97, s67, 0
	s_add_i32 vcc_lo, s84, s71
	global_load_lds_dwordx4 v[228:229], off
	v_lshl_add_u64 v[78:79], s[96:97], 0, v[162:163]
	s_mov_b32 m0, vcc_lo
	v_lshl_add_u64 v[230:231], s[68:69], 0, v[160:161]
	global_load_lds_dwordx4 v[78:79], off
	v_lshl_add_u64 v[78:79], s[96:97], 0, v[166:167]
	s_add_i32 m0, vcc_lo, 0x2000
	v_lshl_add_u64 v[232:233], s[68:69], 0, v[164:165]
	global_load_lds_dwordx4 v[78:79], off
	s_mov_b32 m0, s74
	s_nop 0
	global_load_lds_dwordx4 v[230:231], off
	s_mov_b32 m0, s75
	s_nop 0
	global_load_lds_dwordx4 v[232:233], off
	s_waitcnt vmcnt(8)
	s_waitcnt lgkmcnt(0)
	s_barrier
	s_setprio 1
	s_waitcnt lgkmcnt(0)
	v_mfma_f32_16x16x32_bf16 v[60:63], v[88:91], v[194:197], 0
	v_mfma_f32_16x16x32_bf16 v[56:59], v[128:131], v[194:197], 0
	v_mfma_f32_16x16x32_bf16 v[44:47], v[88:91], v[202:205], 0
	v_mfma_f32_16x16x32_bf16 v[40:43], v[128:131], v[202:205], 0
	v_mfma_f32_16x16x32_bf16 v[28:31], v[88:91], v[210:213], 0
	v_mfma_f32_16x16x32_bf16 v[24:27], v[128:131], v[210:213], 0
	v_mfma_f32_16x16x32_bf16 v[12:15], v[88:91], v[218:221], 0
	v_mfma_f32_16x16x32_bf16 v[8:11], v[128:131], v[218:221], 0
	v_mfma_f32_16x16x32_bf16 v[60:63], v[108:111], v[198:201], v[60:63]
	v_mfma_f32_16x16x32_bf16 v[56:59], v[144:147], v[198:201], v[56:59]
	v_mfma_f32_16x16x32_bf16 v[44:47], v[108:111], v[206:209], v[44:47]
	v_mfma_f32_16x16x32_bf16 v[40:43], v[144:147], v[206:209], v[40:43]
	v_mfma_f32_16x16x32_bf16 v[28:31], v[108:111], v[214:217], v[28:31]
	v_mfma_f32_16x16x32_bf16 v[24:27], v[144:147], v[214:217], v[24:27]
	v_mfma_f32_16x16x32_bf16 v[12:15], v[108:111], v[222:225], v[12:15]
	v_mfma_f32_16x16x32_bf16 v[8:11], v[144:147], v[222:225], v[8:11]
	s_setprio 0
	s_setprio 1
	v_mfma_f32_16x16x32_bf16 v[52:55], v[148:151], v[194:197], 0
	v_mfma_f32_16x16x32_bf16 v[48:51], v[176:179], v[194:197], 0
	v_mfma_f32_16x16x32_bf16 v[36:39], v[148:151], v[202:205], 0
	v_mfma_f32_16x16x32_bf16 v[32:35], v[176:179], v[202:205], 0
	v_mfma_f32_16x16x32_bf16 v[20:23], v[148:151], v[210:213], 0
	v_mfma_f32_16x16x32_bf16 v[16:19], v[176:179], v[210:213], 0
	v_mfma_f32_16x16x32_bf16 v[4:7], v[148:151], v[218:221], 0
	v_mfma_f32_16x16x32_bf16 v[0:3], v[176:179], v[218:221], 0
	v_mfma_f32_16x16x32_bf16 v[52:55], v[152:155], v[198:201], v[52:55]
	v_mfma_f32_16x16x32_bf16 v[48:51], v[190:193], v[198:201], v[48:51]
	v_mfma_f32_16x16x32_bf16 v[36:39], v[152:155], v[206:209], v[36:39]
	v_mfma_f32_16x16x32_bf16 v[32:35], v[190:193], v[206:209], v[32:35]
	v_mfma_f32_16x16x32_bf16 v[20:23], v[152:155], v[214:217], v[20:23]
	v_mfma_f32_16x16x32_bf16 v[16:19], v[190:193], v[214:217], v[16:19]
	v_mfma_f32_16x16x32_bf16 v[4:7], v[152:155], v[222:225], v[4:7]
	v_mfma_f32_16x16x32_bf16 v[0:3], v[190:193], v[222:225], v[0:3]
	s_setprio 0
	s_barrier
	s_add_i32 s96, 0, 0x18000
	v_add_u32_e32 v78, s96, v181
	s_add_i32 s97, 0, 0x1c000
	ds_read_b128 v[88:91], v78
	ds_read_b128 v[108:111], v78 offset:1024
	ds_read_b128 v[128:131], v78 offset:2048
	ds_read_b128 v[144:147], v78 offset:3072
	v_add_u32_e32 v78, s97, v181
	ds_read_b128 v[148:151], v78
	ds_read_b128 v[152:155], v78 offset:1024
	ds_read_b128 v[176:179], v78 offset:2048
	ds_read_b128 v[190:193], v78 offset:3072
	s_add_u32 s68, s68, 0x40000
	s_addc_u32 s69, s69, 0
	s_mov_b32 m0, s76
	v_lshl_add_u64 v[78:79], s[68:69], 0, v[160:161]
	ds_read_b128 v[194:197], v187 offset:32768
	ds_read_b128 v[198:201], v187 offset:33792
	ds_read_b128 v[202:205], v187 offset:34816
	ds_read_b128 v[206:209], v187 offset:35840
	ds_read_b128 v[210:213], v187 offset:36864
	ds_read_b128 v[214:217], v187 offset:37888
	ds_read_b128 v[218:221], v187 offset:38912
	ds_read_b128 v[222:225], v187 offset:39936
	global_load_lds_dwordx4 v[78:79], off
	v_lshl_add_u64 v[78:79], s[68:69], 0, v[164:165]
	s_mov_b32 m0, s77
	s_nop 0
	global_load_lds_dwordx4 v[78:79], off
	s_waitcnt vmcnt(8)
	s_waitcnt lgkmcnt(0)
	s_barrier
	s_setprio 1
	s_waitcnt lgkmcnt(0)
	v_mfma_f32_16x16x32_bf16 v[140:143], v[88:91], v[194:197], v[140:143]
	v_mfma_f32_16x16x32_bf16 v[136:139], v[128:131], v[194:197], v[136:139]
	v_mfma_f32_16x16x32_bf16 v[120:123], v[88:91], v[202:205], v[120:123]
	v_mfma_f32_16x16x32_bf16 v[116:119], v[128:131], v[202:205], v[116:119]
	v_mfma_f32_16x16x32_bf16 v[100:103], v[88:91], v[210:213], v[100:103]
	v_mfma_f32_16x16x32_bf16 v[96:99], v[128:131], v[210:213], v[96:99]
	v_mfma_f32_16x16x32_bf16 v[78:81], v[88:91], v[218:221], v[80:83]
	v_mfma_f32_16x16x32_bf16 v[74:77], v[128:131], v[218:221], v[74:77]
	v_mfma_f32_16x16x32_bf16 v[140:143], v[108:111], v[198:201], v[140:143]
	v_mfma_f32_16x16x32_bf16 v[136:139], v[144:147], v[198:201], v[136:139]
	v_mfma_f32_16x16x32_bf16 v[120:123], v[108:111], v[206:209], v[120:123]
	v_mfma_f32_16x16x32_bf16 v[116:119], v[144:147], v[206:209], v[116:119]
	v_mfma_f32_16x16x32_bf16 v[100:103], v[108:111], v[214:217], v[100:103]
	v_mfma_f32_16x16x32_bf16 v[96:99], v[144:147], v[214:217], v[96:99]
	v_mfma_f32_16x16x32_bf16 v[80:83], v[108:111], v[222:225], v[78:81]
	v_mfma_f32_16x16x32_bf16 v[76:79], v[144:147], v[222:225], v[74:77]
	s_setprio 0
	s_setprio 1
	v_mfma_f32_16x16x32_bf16 v[132:135], v[148:151], v[194:197], v[132:135]
	v_mfma_f32_16x16x32_bf16 v[132:135], v[152:155], v[198:201], v[132:135]
	v_mfma_f32_16x16x32_bf16 v[124:127], v[190:193], v[198:201], v[124:127]
	v_mfma_f32_16x16x32_bf16 v[124:127], v[176:179], v[194:197], v[124:127]
	v_mfma_f32_16x16x32_bf16 v[104:107], v[176:179], v[202:205], v[104:107]
	v_mfma_f32_16x16x32_bf16 v[104:107], v[190:193], v[206:209], v[104:107]
	v_mfma_f32_16x16x32_bf16 v[112:115], v[152:155], v[206:209], v[112:115]
	v_mfma_f32_16x16x32_bf16 v[112:115], v[148:151], v[202:205], v[112:115]
	v_mfma_f32_16x16x32_bf16 v[92:95], v[148:151], v[210:213], v[92:95]
	v_mfma_f32_16x16x32_bf16 v[92:95], v[152:155], v[214:217], v[92:95]
	v_mfma_f32_16x16x32_bf16 v[84:87], v[190:193], v[214:217], v[84:87]
	v_mfma_f32_16x16x32_bf16 v[84:87], v[176:179], v[210:213], v[84:87]
	v_mfma_f32_16x16x32_bf16 v[64:67], v[176:179], v[218:221], v[64:67]
	v_mfma_f32_16x16x32_bf16 v[64:67], v[190:193], v[222:225], v[64:67]
	v_mfma_f32_16x16x32_bf16 v[68:71], v[152:155], v[222:225], v[68:71]
	v_mfma_f32_16x16x32_bf16 v[68:71], v[148:151], v[218:221], v[68:71]
	s_setprio 0
	s_barrier
	s_add_i32 s68, s96, s71
	v_lshl_add_u64 v[74:75], v[226:227], 0, s[28:29]
	s_mov_b32 m0, s68
	ds_read_b128 v[194:197], v187 offset:49152
	ds_read_b128 v[198:201], v187 offset:50176
	ds_read_b128 v[202:205], v187 offset:51200
	ds_read_b128 v[206:209], v187 offset:52224
	ds_read_b128 v[210:213], v187 offset:53248
	ds_read_b128 v[214:217], v187 offset:54272
	ds_read_b128 v[218:221], v187 offset:55296
	ds_read_b128 v[222:225], v187 offset:56320
	global_load_lds_dwordx4 v[74:75], off
	s_add_i32 m0, s68, 0x2000
	s_add_u32 s66, s66, 0x40080
	v_lshl_add_u64 v[74:75], v[228:229], 0, s[28:29]
	s_addc_u32 s67, s67, 0
	s_add_i32 s68, s97, s71
	global_load_lds_dwordx4 v[74:75], off
	v_lshl_add_u64 v[74:75], s[66:67], 0, v[162:163]
	s_mov_b32 m0, s68
	s_nop 0
	global_load_lds_dwordx4 v[74:75], off
	v_lshl_add_u64 v[74:75], s[66:67], 0, v[166:167]
	s_add_i32 m0, s68, 0x2000
	s_nop 0
	global_load_lds_dwordx4 v[74:75], off
	v_lshl_add_u64 v[74:75], v[230:231], 0, s[28:29]
	s_mov_b32 m0, s78
	s_nop 0
	global_load_lds_dwordx4 v[74:75], off
	v_lshl_add_u64 v[74:75], v[232:233], 0, s[28:29]
	s_mov_b32 m0, s79
	s_nop 0
	global_load_lds_dwordx4 v[74:75], off
	s_waitcnt vmcnt(8)
	s_waitcnt lgkmcnt(0)
	s_barrier
	s_setprio 1
	s_waitcnt lgkmcnt(0)
	v_mfma_f32_16x16x32_bf16 v[60:63], v[88:91], v[194:197], v[60:63]
	v_mfma_f32_16x16x32_bf16 v[60:63], v[108:111], v[198:201], v[60:63]
	v_mfma_f32_16x16x32_bf16 v[56:59], v[144:147], v[198:201], v[56:59]
	v_mfma_f32_16x16x32_bf16 v[56:59], v[128:131], v[194:197], v[56:59]
	v_mfma_f32_16x16x32_bf16 v[40:43], v[128:131], v[202:205], v[40:43]
	v_mfma_f32_16x16x32_bf16 v[40:43], v[144:147], v[206:209], v[40:43]
	v_mfma_f32_16x16x32_bf16 v[44:47], v[108:111], v[206:209], v[44:47]
	v_mfma_f32_16x16x32_bf16 v[44:47], v[88:91], v[202:205], v[44:47]
	v_mfma_f32_16x16x32_bf16 v[28:31], v[88:91], v[210:213], v[28:31]
	v_mfma_f32_16x16x32_bf16 v[28:31], v[108:111], v[214:217], v[28:31]
	v_mfma_f32_16x16x32_bf16 v[24:27], v[144:147], v[214:217], v[24:27]
	v_mfma_f32_16x16x32_bf16 v[24:27], v[128:131], v[210:213], v[24:27]
	v_mfma_f32_16x16x32_bf16 v[8:11], v[128:131], v[218:221], v[8:11]
	v_mfma_f32_16x16x32_bf16 v[8:11], v[144:147], v[222:225], v[8:11]
	v_mfma_f32_16x16x32_bf16 v[12:15], v[108:111], v[222:225], v[12:15]
	v_mfma_f32_16x16x32_bf16 v[12:15], v[88:91], v[218:221], v[12:15]
	s_setprio 0
	s_setprio 1
	v_mfma_f32_16x16x32_bf16 v[52:55], v[148:151], v[194:197], v[52:55]
	v_mfma_f32_16x16x32_bf16 v[52:55], v[152:155], v[198:201], v[52:55]
	v_mfma_f32_16x16x32_bf16 v[48:51], v[190:193], v[198:201], v[48:51]
	v_mfma_f32_16x16x32_bf16 v[48:51], v[176:179], v[194:197], v[48:51]
	v_mfma_f32_16x16x32_bf16 v[32:35], v[176:179], v[202:205], v[32:35]
	v_mfma_f32_16x16x32_bf16 v[32:35], v[190:193], v[206:209], v[32:35]
	v_mfma_f32_16x16x32_bf16 v[36:39], v[152:155], v[206:209], v[36:39]
	v_mfma_f32_16x16x32_bf16 v[36:39], v[148:151], v[202:205], v[36:39]
	v_mfma_f32_16x16x32_bf16 v[20:23], v[148:151], v[210:213], v[20:23]
	v_mfma_f32_16x16x32_bf16 v[20:23], v[152:155], v[214:217], v[20:23]
	v_mfma_f32_16x16x32_bf16 v[16:19], v[190:193], v[214:217], v[16:19]
	v_mfma_f32_16x16x32_bf16 v[16:19], v[176:179], v[210:213], v[16:19]
	v_mfma_f32_16x16x32_bf16 v[0:3], v[176:179], v[218:221], v[0:3]
	v_mfma_f32_16x16x32_bf16 v[0:3], v[190:193], v[222:225], v[0:3]
	v_mfma_f32_16x16x32_bf16 v[4:7], v[152:155], v[222:225], v[4:7]
	v_mfma_f32_16x16x32_bf16 v[4:7], v[148:151], v[218:221], v[4:7]
	s_setprio 0
	s_barrier
	s_add_i32 s95, s95, 2
	s_add_u32 s93, s93, 0x100
	s_addc_u32 s94, s94, 0
	s_add_u32 s14, s14, 0x100
	s_addc_u32 s15, s15, 0
	s_branch .LBB0_256
.LBB0_255:
	v_add_u32_e32 v74, s83, v181
	ds_read_b128 v[88:91], v74
	ds_read_b128 v[108:111], v74 offset:1024
	ds_read_b128 v[128:131], v74 offset:2048
	ds_read_b128 v[144:147], v74 offset:3072
	v_add_u32_e32 v74, s84, v181
	ds_read_b128 v[148:151], v74
	ds_read_b128 v[152:155], v74 offset:1024
	ds_read_b128 v[176:179], v74 offset:2048
	ds_read_b128 v[190:193], v74 offset:3072
	s_add_u32 s68, s14, 0xfffc0080
	s_addc_u32 s69, s15, -1
	s_and_b64 s[66:67], s[66:67], exec
	s_cselect_b32 s69, s3, s69
	s_cselect_b32 s68, s61, s68
	s_cselect_b32 s67, s91, s94
	s_cselect_b32 s66, s92, s93
	v_lshl_add_u64 v[74:75], s[14:15], 0, v[170:171]
	s_add_i32 m0, s74, 0xc000
	ds_read_b128 v[194:197], v187
	ds_read_b128 v[198:201], v187 offset:1024
	ds_read_b128 v[202:205], v187 offset:2048
	ds_read_b128 v[206:209], v187 offset:3072
	ds_read_b128 v[210:213], v187 offset:4096
	ds_read_b128 v[214:217], v187 offset:5120
	ds_read_b128 v[218:221], v187 offset:6144
	ds_read_b128 v[222:225], v187 offset:7168
	global_load_lds_dwordx4 v[74:75], off
	v_lshl_add_u64 v[74:75], s[14:15], 0, v[168:169]
	s_add_i32 m0, s74, 0xe000
	s_nop 0
	global_load_lds_dwordx4 v[74:75], off
	s_waitcnt vmcnt(8)
	s_waitcnt lgkmcnt(0)
	s_barrier
	s_setprio 1
	s_waitcnt lgkmcnt(0)
	v_mfma_f32_16x16x32_bf16 v[140:143], v[88:91], v[194:197], v[140:143]
	v_mfma_f32_16x16x32_bf16 v[136:139], v[128:131], v[194:197], v[136:139]
	v_mfma_f32_16x16x32_bf16 v[120:123], v[88:91], v[202:205], v[120:123]
	v_mfma_f32_16x16x32_bf16 v[116:119], v[128:131], v[202:205], v[116:119]
	v_mfma_f32_16x16x32_bf16 v[100:103], v[88:91], v[210:213], v[100:103]
	v_mfma_f32_16x16x32_bf16 v[96:99], v[128:131], v[210:213], v[96:99]
	v_mfma_f32_16x16x32_bf16 v[80:83], v[88:91], v[218:221], v[80:83]
	v_mfma_f32_16x16x32_bf16 v[74:77], v[128:131], v[218:221], v[76:79]
	v_mfma_f32_16x16x32_bf16 v[140:143], v[108:111], v[198:201], v[140:143]
	v_mfma_f32_16x16x32_bf16 v[136:139], v[144:147], v[198:201], v[136:139]
	v_mfma_f32_16x16x32_bf16 v[120:123], v[108:111], v[206:209], v[120:123]
	v_mfma_f32_16x16x32_bf16 v[116:119], v[144:147], v[206:209], v[116:119]
	v_mfma_f32_16x16x32_bf16 v[100:103], v[108:111], v[214:217], v[100:103]
	v_mfma_f32_16x16x32_bf16 v[96:99], v[144:147], v[214:217], v[96:99]
	v_mfma_f32_16x16x32_bf16 v[80:83], v[108:111], v[222:225], v[80:83]
	v_mfma_f32_16x16x32_bf16 v[74:77], v[144:147], v[222:225], v[74:77]
	s_setprio 0
	s_setprio 1
	v_mfma_f32_16x16x32_bf16 v[132:135], v[148:151], v[194:197], v[132:135]
	v_mfma_f32_16x16x32_bf16 v[132:135], v[152:155], v[198:201], v[132:135]
	v_mfma_f32_16x16x32_bf16 v[124:127], v[190:193], v[198:201], v[124:127]
	v_mfma_f32_16x16x32_bf16 v[124:127], v[176:179], v[194:197], v[124:127]
	v_mfma_f32_16x16x32_bf16 v[104:107], v[176:179], v[202:205], v[104:107]
	v_mfma_f32_16x16x32_bf16 v[104:107], v[190:193], v[206:209], v[104:107]
	v_mfma_f32_16x16x32_bf16 v[112:115], v[152:155], v[206:209], v[112:115]
	v_mfma_f32_16x16x32_bf16 v[112:115], v[148:151], v[202:205], v[112:115]
	v_mfma_f32_16x16x32_bf16 v[92:95], v[148:151], v[210:213], v[92:95]
	v_mfma_f32_16x16x32_bf16 v[92:95], v[152:155], v[214:217], v[92:95]
	v_mfma_f32_16x16x32_bf16 v[84:87], v[190:193], v[214:217], v[84:87]
	v_mfma_f32_16x16x32_bf16 v[84:87], v[176:179], v[210:213], v[84:87]
	v_mfma_f32_16x16x32_bf16 v[64:67], v[176:179], v[218:221], v[64:67]
	v_mfma_f32_16x16x32_bf16 v[64:67], v[190:193], v[222:225], v[64:67]
	v_mfma_f32_16x16x32_bf16 v[68:71], v[152:155], v[222:225], v[68:71]
	v_mfma_f32_16x16x32_bf16 v[68:71], v[148:151], v[218:221], v[68:71]
	s_setprio 0
	s_barrier
	s_add_i32 s96, s83, s71
	v_lshl_add_u64 v[226:227], s[66:67], 0, v[162:163]
	s_mov_b32 m0, s96
	ds_read_b128 v[194:197], v187 offset:16384
	ds_read_b128 v[198:201], v187 offset:17408
	ds_read_b128 v[202:205], v187 offset:18432
	ds_read_b128 v[206:209], v187 offset:19456
	ds_read_b128 v[210:213], v187 offset:20480
	ds_read_b128 v[214:217], v187 offset:21504
	ds_read_b128 v[218:221], v187 offset:22528
	ds_read_b128 v[222:225], v187 offset:23552
	global_load_lds_dwordx4 v[226:227], off
	s_add_i32 m0, s96, 0x2000
	s_add_u32 s96, s66, 0x40000
	v_lshl_add_u64 v[228:229], s[66:67], 0, v[166:167]
	s_addc_u32 s97, s67, 0
	s_add_i32 vcc_lo, s84, s71
	global_load_lds_dwordx4 v[228:229], off
	v_lshl_add_u64 v[78:79], s[96:97], 0, v[162:163]
	s_mov_b32 m0, vcc_lo
	v_lshl_add_u64 v[230:231], s[68:69], 0, v[160:161]
	global_load_lds_dwordx4 v[78:79], off
	v_lshl_add_u64 v[78:79], s[96:97], 0, v[166:167]
	s_add_i32 m0, vcc_lo, 0x2000
	v_lshl_add_u64 v[232:233], s[68:69], 0, v[164:165]
	global_load_lds_dwordx4 v[78:79], off
	s_mov_b32 m0, s74
	s_nop 0
	global_load_lds_dwordx4 v[230:231], off
	s_mov_b32 m0, s75
	s_nop 0
	global_load_lds_dwordx4 v[232:233], off
	s_waitcnt vmcnt(8)
	s_waitcnt lgkmcnt(0)
	s_barrier
	s_setprio 1
	s_waitcnt lgkmcnt(0)
	v_mfma_f32_16x16x32_bf16 v[60:63], v[88:91], v[194:197], v[60:63]
	v_mfma_f32_16x16x32_bf16 v[60:63], v[108:111], v[198:201], v[60:63]
	v_mfma_f32_16x16x32_bf16 v[56:59], v[144:147], v[198:201], v[56:59]
	v_mfma_f32_16x16x32_bf16 v[56:59], v[128:131], v[194:197], v[56:59]
	v_mfma_f32_16x16x32_bf16 v[40:43], v[128:131], v[202:205], v[40:43]
	v_mfma_f32_16x16x32_bf16 v[40:43], v[144:147], v[206:209], v[40:43]
	v_mfma_f32_16x16x32_bf16 v[44:47], v[108:111], v[206:209], v[44:47]
	v_mfma_f32_16x16x32_bf16 v[44:47], v[88:91], v[202:205], v[44:47]
	v_mfma_f32_16x16x32_bf16 v[28:31], v[88:91], v[210:213], v[28:31]
	v_mfma_f32_16x16x32_bf16 v[28:31], v[108:111], v[214:217], v[28:31]
	v_mfma_f32_16x16x32_bf16 v[24:27], v[144:147], v[214:217], v[24:27]
	v_mfma_f32_16x16x32_bf16 v[24:27], v[128:131], v[210:213], v[24:27]
	v_mfma_f32_16x16x32_bf16 v[8:11], v[128:131], v[218:221], v[8:11]
	v_mfma_f32_16x16x32_bf16 v[8:11], v[144:147], v[222:225], v[8:11]
	v_mfma_f32_16x16x32_bf16 v[12:15], v[108:111], v[222:225], v[12:15]
	v_mfma_f32_16x16x32_bf16 v[12:15], v[88:91], v[218:221], v[12:15]
	s_setprio 0
	s_setprio 1
	v_mfma_f32_16x16x32_bf16 v[52:55], v[148:151], v[194:197], v[52:55]
	v_mfma_f32_16x16x32_bf16 v[52:55], v[152:155], v[198:201], v[52:55]
	v_mfma_f32_16x16x32_bf16 v[48:51], v[190:193], v[198:201], v[48:51]
	v_mfma_f32_16x16x32_bf16 v[48:51], v[176:179], v[194:197], v[48:51]
	v_mfma_f32_16x16x32_bf16 v[32:35], v[176:179], v[202:205], v[32:35]
	v_mfma_f32_16x16x32_bf16 v[32:35], v[190:193], v[206:209], v[32:35]
	v_mfma_f32_16x16x32_bf16 v[36:39], v[152:155], v[206:209], v[36:39]
	v_mfma_f32_16x16x32_bf16 v[36:39], v[148:151], v[202:205], v[36:39]
	v_mfma_f32_16x16x32_bf16 v[20:23], v[148:151], v[210:213], v[20:23]
	v_mfma_f32_16x16x32_bf16 v[20:23], v[152:155], v[214:217], v[20:23]
	v_mfma_f32_16x16x32_bf16 v[16:19], v[190:193], v[214:217], v[16:19]
	v_mfma_f32_16x16x32_bf16 v[16:19], v[176:179], v[210:213], v[16:19]
	v_mfma_f32_16x16x32_bf16 v[0:3], v[176:179], v[218:221], v[0:3]
	v_mfma_f32_16x16x32_bf16 v[0:3], v[190:193], v[222:225], v[0:3]
	v_mfma_f32_16x16x32_bf16 v[4:7], v[152:155], v[222:225], v[4:7]
	v_mfma_f32_16x16x32_bf16 v[4:7], v[148:151], v[218:221], v[4:7]
	s_setprio 0
	s_barrier
	s_add_i32 s96, 0, 0x18000
	v_add_u32_e32 v78, s96, v181
	s_add_i32 s97, 0, 0x1c000
	ds_read_b128 v[88:91], v78
	ds_read_b128 v[108:111], v78 offset:1024
	ds_read_b128 v[128:131], v78 offset:2048
	ds_read_b128 v[144:147], v78 offset:3072
	v_add_u32_e32 v78, s97, v181
	ds_read_b128 v[148:151], v78
	ds_read_b128 v[152:155], v78 offset:1024
	ds_read_b128 v[176:179], v78 offset:2048
	ds_read_b128 v[190:193], v78 offset:3072
	s_add_u32 s68, s68, 0x40000
	s_addc_u32 s69, s69, 0
	s_mov_b32 m0, s76
	v_lshl_add_u64 v[78:79], s[68:69], 0, v[160:161]
	ds_read_b128 v[194:197], v187 offset:32768
	ds_read_b128 v[198:201], v187 offset:33792
	ds_read_b128 v[202:205], v187 offset:34816
	ds_read_b128 v[206:209], v187 offset:35840
	ds_read_b128 v[210:213], v187 offset:36864
	ds_read_b128 v[214:217], v187 offset:37888
	ds_read_b128 v[218:221], v187 offset:38912
	ds_read_b128 v[222:225], v187 offset:39936
	global_load_lds_dwordx4 v[78:79], off
	v_lshl_add_u64 v[78:79], s[68:69], 0, v[164:165]
	s_mov_b32 m0, s77
	s_nop 0
	global_load_lds_dwordx4 v[78:79], off
	s_waitcnt vmcnt(8)
	s_waitcnt lgkmcnt(0)
	s_barrier
	s_setprio 1
	s_waitcnt lgkmcnt(0)
	v_mfma_f32_16x16x32_bf16 v[140:143], v[88:91], v[194:197], v[140:143]
	v_mfma_f32_16x16x32_bf16 v[136:139], v[128:131], v[194:197], v[136:139]
	v_mfma_f32_16x16x32_bf16 v[120:123], v[88:91], v[202:205], v[120:123]
	v_mfma_f32_16x16x32_bf16 v[116:119], v[128:131], v[202:205], v[116:119]
	v_mfma_f32_16x16x32_bf16 v[100:103], v[88:91], v[210:213], v[100:103]
	v_mfma_f32_16x16x32_bf16 v[96:99], v[128:131], v[210:213], v[96:99]
	v_mfma_f32_16x16x32_bf16 v[78:81], v[88:91], v[218:221], v[80:83]
	v_mfma_f32_16x16x32_bf16 v[74:77], v[128:131], v[218:221], v[74:77]
	v_mfma_f32_16x16x32_bf16 v[140:143], v[108:111], v[198:201], v[140:143]
	v_mfma_f32_16x16x32_bf16 v[136:139], v[144:147], v[198:201], v[136:139]
	v_mfma_f32_16x16x32_bf16 v[120:123], v[108:111], v[206:209], v[120:123]
	v_mfma_f32_16x16x32_bf16 v[116:119], v[144:147], v[206:209], v[116:119]
	v_mfma_f32_16x16x32_bf16 v[100:103], v[108:111], v[214:217], v[100:103]
	v_mfma_f32_16x16x32_bf16 v[96:99], v[144:147], v[214:217], v[96:99]
	v_mfma_f32_16x16x32_bf16 v[80:83], v[108:111], v[222:225], v[78:81]
	v_mfma_f32_16x16x32_bf16 v[76:79], v[144:147], v[222:225], v[74:77]
	s_setprio 0
	s_setprio 1
	v_mfma_f32_16x16x32_bf16 v[132:135], v[148:151], v[194:197], v[132:135]
	v_mfma_f32_16x16x32_bf16 v[132:135], v[152:155], v[198:201], v[132:135]
	v_mfma_f32_16x16x32_bf16 v[124:127], v[190:193], v[198:201], v[124:127]
	v_mfma_f32_16x16x32_bf16 v[124:127], v[176:179], v[194:197], v[124:127]
	v_mfma_f32_16x16x32_bf16 v[104:107], v[176:179], v[202:205], v[104:107]
	v_mfma_f32_16x16x32_bf16 v[104:107], v[190:193], v[206:209], v[104:107]
	v_mfma_f32_16x16x32_bf16 v[112:115], v[152:155], v[206:209], v[112:115]
	v_mfma_f32_16x16x32_bf16 v[112:115], v[148:151], v[202:205], v[112:115]
	v_mfma_f32_16x16x32_bf16 v[92:95], v[148:151], v[210:213], v[92:95]
	v_mfma_f32_16x16x32_bf16 v[92:95], v[152:155], v[214:217], v[92:95]
	v_mfma_f32_16x16x32_bf16 v[84:87], v[190:193], v[214:217], v[84:87]
	v_mfma_f32_16x16x32_bf16 v[84:87], v[176:179], v[210:213], v[84:87]
	v_mfma_f32_16x16x32_bf16 v[64:67], v[176:179], v[218:221], v[64:67]
	v_mfma_f32_16x16x32_bf16 v[64:67], v[190:193], v[222:225], v[64:67]
	v_mfma_f32_16x16x32_bf16 v[68:71], v[152:155], v[222:225], v[68:71]
	v_mfma_f32_16x16x32_bf16 v[68:71], v[148:151], v[218:221], v[68:71]
	s_setprio 0
	s_barrier
	s_add_i32 s68, s96, s71
	v_lshl_add_u64 v[74:75], v[226:227], 0, s[28:29]
	s_mov_b32 m0, s68
	ds_read_b128 v[194:197], v187 offset:49152
	ds_read_b128 v[198:201], v187 offset:50176
	ds_read_b128 v[202:205], v187 offset:51200
	ds_read_b128 v[206:209], v187 offset:52224
	ds_read_b128 v[210:213], v187 offset:53248
	ds_read_b128 v[214:217], v187 offset:54272
	ds_read_b128 v[218:221], v187 offset:55296
	ds_read_b128 v[222:225], v187 offset:56320
	global_load_lds_dwordx4 v[74:75], off
	s_add_i32 m0, s68, 0x2000
	s_add_u32 s66, s66, 0x40080
	v_lshl_add_u64 v[74:75], v[228:229], 0, s[28:29]
	s_addc_u32 s67, s67, 0
	s_add_i32 s68, s97, s71
	global_load_lds_dwordx4 v[74:75], off
	v_lshl_add_u64 v[74:75], s[66:67], 0, v[162:163]
	s_mov_b32 m0, s68
	s_nop 0
	global_load_lds_dwordx4 v[74:75], off
	v_lshl_add_u64 v[74:75], s[66:67], 0, v[166:167]
	s_add_i32 m0, s68, 0x2000
	s_nop 0
	global_load_lds_dwordx4 v[74:75], off
	v_lshl_add_u64 v[74:75], v[230:231], 0, s[28:29]
	s_mov_b32 m0, s78
	s_nop 0
	global_load_lds_dwordx4 v[74:75], off
	v_lshl_add_u64 v[74:75], v[232:233], 0, s[28:29]
	s_mov_b32 m0, s79
	s_nop 0
	global_load_lds_dwordx4 v[74:75], off
	s_waitcnt vmcnt(8)
	s_waitcnt lgkmcnt(0)
	s_barrier
	s_setprio 1
	s_waitcnt lgkmcnt(0)
	v_mfma_f32_16x16x32_bf16 v[60:63], v[88:91], v[194:197], v[60:63]
	v_mfma_f32_16x16x32_bf16 v[60:63], v[108:111], v[198:201], v[60:63]
	v_mfma_f32_16x16x32_bf16 v[56:59], v[144:147], v[198:201], v[56:59]
	v_mfma_f32_16x16x32_bf16 v[56:59], v[128:131], v[194:197], v[56:59]
	v_mfma_f32_16x16x32_bf16 v[40:43], v[128:131], v[202:205], v[40:43]
	v_mfma_f32_16x16x32_bf16 v[40:43], v[144:147], v[206:209], v[40:43]
	v_mfma_f32_16x16x32_bf16 v[44:47], v[108:111], v[206:209], v[44:47]
	v_mfma_f32_16x16x32_bf16 v[44:47], v[88:91], v[202:205], v[44:47]
	v_mfma_f32_16x16x32_bf16 v[28:31], v[88:91], v[210:213], v[28:31]
	v_mfma_f32_16x16x32_bf16 v[28:31], v[108:111], v[214:217], v[28:31]
	v_mfma_f32_16x16x32_bf16 v[24:27], v[144:147], v[214:217], v[24:27]
	v_mfma_f32_16x16x32_bf16 v[24:27], v[128:131], v[210:213], v[24:27]
	v_mfma_f32_16x16x32_bf16 v[8:11], v[128:131], v[218:221], v[8:11]
	v_mfma_f32_16x16x32_bf16 v[8:11], v[144:147], v[222:225], v[8:11]
	v_mfma_f32_16x16x32_bf16 v[12:15], v[108:111], v[222:225], v[12:15]
	v_mfma_f32_16x16x32_bf16 v[12:15], v[88:91], v[218:221], v[12:15]
	s_setprio 0
	s_setprio 1
	v_mfma_f32_16x16x32_bf16 v[52:55], v[148:151], v[194:197], v[52:55]
	v_mfma_f32_16x16x32_bf16 v[52:55], v[152:155], v[198:201], v[52:55]
	v_mfma_f32_16x16x32_bf16 v[48:51], v[190:193], v[198:201], v[48:51]
	v_mfma_f32_16x16x32_bf16 v[48:51], v[176:179], v[194:197], v[48:51]
	v_mfma_f32_16x16x32_bf16 v[32:35], v[176:179], v[202:205], v[32:35]
	v_mfma_f32_16x16x32_bf16 v[32:35], v[190:193], v[206:209], v[32:35]
	v_mfma_f32_16x16x32_bf16 v[36:39], v[152:155], v[206:209], v[36:39]
	v_mfma_f32_16x16x32_bf16 v[36:39], v[148:151], v[202:205], v[36:39]
	v_mfma_f32_16x16x32_bf16 v[20:23], v[148:151], v[210:213], v[20:23]
	v_mfma_f32_16x16x32_bf16 v[20:23], v[152:155], v[214:217], v[20:23]
	v_mfma_f32_16x16x32_bf16 v[16:19], v[190:193], v[214:217], v[16:19]
	v_mfma_f32_16x16x32_bf16 v[16:19], v[176:179], v[210:213], v[16:19]
	v_mfma_f32_16x16x32_bf16 v[0:3], v[176:179], v[218:221], v[0:3]
	v_mfma_f32_16x16x32_bf16 v[0:3], v[190:193], v[222:225], v[0:3]
	v_mfma_f32_16x16x32_bf16 v[4:7], v[152:155], v[222:225], v[4:7]
	v_mfma_f32_16x16x32_bf16 v[4:7], v[148:151], v[218:221], v[4:7]
	s_setprio 0
	s_barrier
	s_add_i32 s95, s95, 2
	s_add_u32 s93, s93, 0x100
	s_addc_u32 s94, s94, 0
	s_add_u32 s14, s14, 0x100
	s_addc_u32 s15, s15, 0
	s_cmp_gt_u32 s95, 13
	s_cbranch_scc1 .LBB0_258

.LBB0_439:
	s_ashr_i32 s53, s52, 31
	s_lshl_b64 s[54:55], s[52:53], 20
	s_add_u32 s54, s35, s54
	s_addc_u32 s55, s66, s55
	s_and_b64 s[56:57], s[12:13], exec
	s_cselect_b32 s15, s55, s63
	s_cselect_b32 s53, s54, s62
	s_ashr_i32 s51, s50, 31
	s_lshl_b64 s[56:57], s[50:51], 20
	s_add_u32 s56, s67, s56
	s_addc_u32 s57, s68, s57
	s_and_b64 s[64:65], s[12:13], exec
	s_cselect_b32 s51, s57, s61
	s_cselect_b32 s59, s56, s60
	s_add_u32 s81, s60, 0x100
	s_addc_u32 s82, s61, 0
	s_add_u32 s60, s62, 0x80080
	s_addc_u32 s61, s63, 0
	s_mov_b32 s83, -2
	s_waitcnt lgkmcnt(0)
	s_cmp_eq_u32 s74, 1
	s_cbranch_scc1 .Lfa_3
	ds_read_b128 v[128:131], v189
	ds_read_b128 v[132:135], v189 offset:1024
	ds_read_b128 v[136:139], v189 offset:2048
	ds_read_b128 v[140:143], v189 offset:3072
	ds_read_b128 v[144:147], v190
	ds_read_b128 v[148:151], v190 offset:1024
	ds_read_b128 v[172:175], v190 offset:2048
	ds_read_b128 v[176:179], v190 offset:3072
	s_add_u32 s62, s60, 0xfff80080
	s_addc_u32 s63, s61, -1
	s_cmp_eq_u32 s83, 28
	s_cselect_b32 s65, s15, s63
	s_cselect_b32 s64, s53, s62
	s_cselect_b32 s63, s51, s82
	s_cselect_b32 s62, s59, s81
	v_lshl_add_u64 v[222:223], s[60:61], 0, v[166:167]
	s_add_i32 m0, s70, 0xc000
	ds_read_b128 v[180:183], v191
	ds_read_b128 v[194:197], v191 offset:1024
	ds_read_b128 v[198:201], v191 offset:2048
	ds_read_b128 v[202:205], v191 offset:3072
	ds_read_b128 v[206:209], v191 offset:4096
	ds_read_b128 v[210:213], v191 offset:5120
	ds_read_b128 v[214:217], v191 offset:6144
	ds_read_b128 v[218:221], v191 offset:7168
	global_load_lds_dwordx4 v[222:223], off
	v_lshl_add_u64 v[222:223], s[60:61], 0, v[164:165]
	s_add_i32 m0, s70, 0xe000
	s_nop 0
	global_load_lds_dwordx4 v[222:223], off
	s_waitcnt vmcnt(24)
	s_waitcnt lgkmcnt(0)
	s_barrier
	s_setprio 1
	s_waitcnt lgkmcnt(0)
	v_mfma_f32_16x16x32_bf16 v[124:127], v[128:131], v[180:183], 0
	v_mfma_f32_16x16x32_bf16 v[120:123], v[136:139], v[180:183], 0
	v_mfma_f32_16x16x32_bf16 v[108:111], v[128:131], v[198:201], 0
	v_mfma_f32_16x16x32_bf16 v[104:107], v[136:139], v[198:201], 0
	v_mfma_f32_16x16x32_bf16 v[92:95], v[128:131], v[206:209], 0
	v_mfma_f32_16x16x32_bf16 v[88:91], v[136:139], v[206:209], 0
	v_mfma_f32_16x16x32_bf16 v[76:79], v[128:131], v[214:217], 0
	v_mfma_f32_16x16x32_bf16 v[72:75], v[136:139], v[214:217], 0
	v_mfma_f32_16x16x32_bf16 v[124:127], v[132:135], v[194:197], v[124:127]
	v_mfma_f32_16x16x32_bf16 v[120:123], v[140:143], v[194:197], v[120:123]
	v_mfma_f32_16x16x32_bf16 v[108:111], v[132:135], v[202:205], v[108:111]
	v_mfma_f32_16x16x32_bf16 v[104:107], v[140:143], v[202:205], v[104:107]
	v_mfma_f32_16x16x32_bf16 v[92:95], v[132:135], v[210:213], v[92:95]
	v_mfma_f32_16x16x32_bf16 v[88:91], v[140:143], v[210:213], v[88:91]
	v_mfma_f32_16x16x32_bf16 v[76:79], v[132:135], v[218:221], v[76:79]
	v_mfma_f32_16x16x32_bf16 v[72:75], v[140:143], v[218:221], v[72:75]
	s_setprio 0
	s_setprio 1
	v_mfma_f32_16x16x32_bf16 v[116:119], v[144:147], v[180:183], 0
	v_mfma_f32_16x16x32_bf16 v[112:115], v[172:175], v[180:183], 0
	v_mfma_f32_16x16x32_bf16 v[100:103], v[144:147], v[198:201], 0
	v_mfma_f32_16x16x32_bf16 v[96:99], v[172:175], v[198:201], 0
	v_mfma_f32_16x16x32_bf16 v[84:87], v[144:147], v[206:209], 0
	v_mfma_f32_16x16x32_bf16 v[80:83], v[172:175], v[206:209], 0
	v_mfma_f32_16x16x32_bf16 v[68:71], v[144:147], v[214:217], 0
	v_mfma_f32_16x16x32_bf16 v[64:67], v[172:175], v[214:217], 0
	v_mfma_f32_16x16x32_bf16 v[116:119], v[148:151], v[194:197], v[116:119]
	v_mfma_f32_16x16x32_bf16 v[112:115], v[176:179], v[194:197], v[112:115]
	v_mfma_f32_16x16x32_bf16 v[100:103], v[148:151], v[202:205], v[100:103]
	v_mfma_f32_16x16x32_bf16 v[96:99], v[176:179], v[202:205], v[96:99]
	v_mfma_f32_16x16x32_bf16 v[84:87], v[148:151], v[210:213], v[84:87]
	v_mfma_f32_16x16x32_bf16 v[80:83], v[176:179], v[210:213], v[80:83]
	v_mfma_f32_16x16x32_bf16 v[68:71], v[148:151], v[218:221], v[68:71]
	v_mfma_f32_16x16x32_bf16 v[64:67], v[176:179], v[218:221], v[64:67]
	s_setprio 0
	s_barrier
	s_add_i32 s84, s79, s69
	v_lshl_add_u64 v[222:223], s[62:63], 0, v[154:155]
	s_mov_b32 m0, s84
	ds_read_b128 v[180:183], v191 offset:16384
	ds_read_b128 v[194:197], v191 offset:17408
	ds_read_b128 v[198:201], v191 offset:18432
	ds_read_b128 v[202:205], v191 offset:19456
	ds_read_b128 v[206:209], v191 offset:20480
	ds_read_b128 v[210:213], v191 offset:21504
	ds_read_b128 v[214:217], v191 offset:22528
	ds_read_b128 v[218:221], v191 offset:23552
	global_load_lds_dwordx4 v[222:223], off
	s_add_i32 m0, s84, 0x2000
	s_add_u32 s84, s62, 0x80000
	v_lshl_add_u64 v[224:225], s[62:63], 0, v[162:163]
	s_addc_u32 s85, s63, 0
	s_add_i32 s86, s80, s69
	global_load_lds_dwordx4 v[224:225], off
	v_lshl_add_u64 v[226:227], s[84:85], 0, v[154:155]
	s_mov_b32 m0, s86
	v_lshl_add_u64 v[228:229], s[64:65], 0, v[160:161]
	global_load_lds_dwordx4 v[226:227], off
	v_lshl_add_u64 v[226:227], s[84:85], 0, v[162:163]
	s_add_i32 m0, s86, 0x2000
	s_nop 0
	global_load_lds_dwordx4 v[226:227], off
	v_lshl_add_u64 v[226:227], s[64:65], 0, v[152:153]
	s_mov_b32 m0, s70
	s_nop 0
	global_load_lds_dwordx4 v[226:227], off
	s_mov_b32 m0, s71
	s_nop 0
	global_load_lds_dwordx4 v[228:229], off
	s_waitcnt vmcnt(24)
	s_waitcnt lgkmcnt(0)
	s_barrier
	s_setprio 1
	s_waitcnt lgkmcnt(0)
	v_mfma_f32_16x16x32_bf16 v[60:63], v[128:131], v[180:183], 0
	v_mfma_f32_16x16x32_bf16 v[56:59], v[136:139], v[180:183], 0
	v_mfma_f32_16x16x32_bf16 v[44:47], v[128:131], v[198:201], 0
	v_mfma_f32_16x16x32_bf16 v[40:43], v[136:139], v[198:201], 0
	v_mfma_f32_16x16x32_bf16 v[28:31], v[128:131], v[206:209], 0
	v_mfma_f32_16x16x32_bf16 v[24:27], v[136:139], v[206:209], 0
	v_mfma_f32_16x16x32_bf16 v[12:15], v[128:131], v[214:217], 0
	v_mfma_f32_16x16x32_bf16 v[8:11], v[136:139], v[214:217], 0
	v_mfma_f32_16x16x32_bf16 v[60:63], v[132:135], v[194:197], v[60:63]
	v_mfma_f32_16x16x32_bf16 v[56:59], v[140:143], v[194:197], v[56:59]
	v_mfma_f32_16x16x32_bf16 v[44:47], v[132:135], v[202:205], v[44:47]
	v_mfma_f32_16x16x32_bf16 v[40:43], v[140:143], v[202:205], v[40:43]
	v_mfma_f32_16x16x32_bf16 v[28:31], v[132:135], v[210:213], v[28:31]
	v_mfma_f32_16x16x32_bf16 v[24:27], v[140:143], v[210:213], v[24:27]
	v_mfma_f32_16x16x32_bf16 v[12:15], v[132:135], v[218:221], v[12:15]
	v_mfma_f32_16x16x32_bf16 v[8:11], v[140:143], v[218:221], v[8:11]
	s_setprio 0
	s_setprio 1
	v_mfma_f32_16x16x32_bf16 v[52:55], v[144:147], v[180:183], 0
	v_mfma_f32_16x16x32_bf16 v[48:51], v[172:175], v[180:183], 0
	v_mfma_f32_16x16x32_bf16 v[36:39], v[144:147], v[198:201], 0
	v_mfma_f32_16x16x32_bf16 v[32:35], v[172:175], v[198:201], 0
	v_mfma_f32_16x16x32_bf16 v[20:23], v[144:147], v[206:209], 0
	v_mfma_f32_16x16x32_bf16 v[16:19], v[172:175], v[206:209], 0
	v_mfma_f32_16x16x32_bf16 v[4:7], v[144:147], v[214:217], 0
	v_mfma_f32_16x16x32_bf16 v[0:3], v[172:175], v[214:217], 0
	v_mfma_f32_16x16x32_bf16 v[52:55], v[148:151], v[194:197], v[52:55]
	v_mfma_f32_16x16x32_bf16 v[48:51], v[176:179], v[194:197], v[48:51]
	v_mfma_f32_16x16x32_bf16 v[36:39], v[148:151], v[202:205], v[36:39]
	v_mfma_f32_16x16x32_bf16 v[32:35], v[176:179], v[202:205], v[32:35]
	v_mfma_f32_16x16x32_bf16 v[20:23], v[148:151], v[210:213], v[20:23]
	v_mfma_f32_16x16x32_bf16 v[16:19], v[176:179], v[210:213], v[16:19]
	v_mfma_f32_16x16x32_bf16 v[4:7], v[148:151], v[218:221], v[4:7]
	v_mfma_f32_16x16x32_bf16 v[0:3], v[176:179], v[218:221], v[0:3]
	s_setprio 0
	s_barrier
	s_add_i32 s84, 0, 0x18000
	s_add_i32 s85, 0, 0x1c000
	v_add_u32_e32 v140, s84, v186
	v_add_u32_e32 v176, s85, v186
	ds_read_b128 v[128:131], v140
	ds_read_b128 v[132:135], v140 offset:1024
	ds_read_b128 v[136:139], v140 offset:2048
	ds_read_b128 v[140:143], v140 offset:3072
	ds_read_b128 v[144:147], v176
	ds_read_b128 v[148:151], v176 offset:1024
	ds_read_b128 v[172:175], v176 offset:2048
	ds_read_b128 v[176:179], v176 offset:3072
	s_add_u32 s64, s64, 0x80000
	s_addc_u32 s65, s65, 0
	s_mov_b32 m0, s72
	v_lshl_add_u64 v[230:231], s[64:65], 0, v[152:153]
	ds_read_b128 v[180:183], v191 offset:32768
	ds_read_b128 v[194:197], v191 offset:33792
	ds_read_b128 v[198:201], v191 offset:34816
	ds_read_b128 v[202:205], v191 offset:35840
	ds_read_b128 v[206:209], v191 offset:36864
	ds_read_b128 v[210:213], v191 offset:37888
	ds_read_b128 v[214:217], v191 offset:38912
	ds_read_b128 v[218:221], v191 offset:39936
	global_load_lds_dwordx4 v[230:231], off
	v_lshl_add_u64 v[230:231], s[64:65], 0, v[160:161]
	s_mov_b32 m0, s73
	s_nop 0
	global_load_lds_dwordx4 v[230:231], off
	s_waitcnt vmcnt(8)
	s_waitcnt lgkmcnt(0)
	s_barrier
	s_setprio 1
	s_waitcnt lgkmcnt(0)
	v_mfma_f32_16x16x32_bf16 v[124:127], v[128:131], v[180:183], v[124:127]
	v_mfma_f32_16x16x32_bf16 v[124:127], v[132:135], v[194:197], v[124:127]
	v_mfma_f32_16x16x32_bf16 v[120:123], v[140:143], v[194:197], v[120:123]
	v_mfma_f32_16x16x32_bf16 v[120:123], v[136:139], v[180:183], v[120:123]
	v_mfma_f32_16x16x32_bf16 v[104:107], v[136:139], v[198:201], v[104:107]
	v_mfma_f32_16x16x32_bf16 v[104:107], v[140:143], v[202:205], v[104:107]
	v_mfma_f32_16x16x32_bf16 v[108:111], v[132:135], v[202:205], v[108:111]
	v_mfma_f32_16x16x32_bf16 v[108:111], v[128:131], v[198:201], v[108:111]
	v_mfma_f32_16x16x32_bf16 v[92:95], v[128:131], v[206:209], v[92:95]
	v_mfma_f32_16x16x32_bf16 v[92:95], v[132:135], v[210:213], v[92:95]
	v_mfma_f32_16x16x32_bf16 v[88:91], v[140:143], v[210:213], v[88:91]
	v_mfma_f32_16x16x32_bf16 v[88:91], v[136:139], v[206:209], v[88:91]
	v_mfma_f32_16x16x32_bf16 v[72:75], v[136:139], v[214:217], v[72:75]
	v_mfma_f32_16x16x32_bf16 v[72:75], v[140:143], v[218:221], v[72:75]
	v_mfma_f32_16x16x32_bf16 v[76:79], v[132:135], v[218:221], v[76:79]
	v_mfma_f32_16x16x32_bf16 v[76:79], v[128:131], v[214:217], v[76:79]
	s_setprio 0
	s_setprio 1
	v_mfma_f32_16x16x32_bf16 v[116:119], v[144:147], v[180:183], v[116:119]
	v_mfma_f32_16x16x32_bf16 v[116:119], v[148:151], v[194:197], v[116:119]
	v_mfma_f32_16x16x32_bf16 v[112:115], v[176:179], v[194:197], v[112:115]
	v_mfma_f32_16x16x32_bf16 v[112:115], v[172:175], v[180:183], v[112:115]
	v_mfma_f32_16x16x32_bf16 v[96:99], v[172:175], v[198:201], v[96:99]
	v_mfma_f32_16x16x32_bf16 v[96:99], v[176:179], v[202:205], v[96:99]
	v_mfma_f32_16x16x32_bf16 v[100:103], v[148:151], v[202:205], v[100:103]
	v_mfma_f32_16x16x32_bf16 v[100:103], v[144:147], v[198:201], v[100:103]
	v_mfma_f32_16x16x32_bf16 v[84:87], v[144:147], v[206:209], v[84:87]
	v_mfma_f32_16x16x32_bf16 v[84:87], v[148:151], v[210:213], v[84:87]
	v_mfma_f32_16x16x32_bf16 v[80:83], v[176:179], v[210:213], v[80:83]
	v_mfma_f32_16x16x32_bf16 v[80:83], v[172:175], v[206:209], v[80:83]
	v_mfma_f32_16x16x32_bf16 v[64:67], v[172:175], v[214:217], v[64:67]
	v_mfma_f32_16x16x32_bf16 v[64:67], v[176:179], v[218:221], v[64:67]
	v_mfma_f32_16x16x32_bf16 v[68:71], v[148:151], v[218:221], v[68:71]
	v_mfma_f32_16x16x32_bf16 v[68:71], v[144:147], v[214:217], v[68:71]
	s_setprio 0
	s_barrier
	s_add_i32 s64, s84, s69
	v_lshl_add_u64 v[222:223], v[222:223], 0, s[26:27]
	s_mov_b32 m0, s64
	ds_read_b128 v[180:183], v191 offset:49152
	ds_read_b128 v[194:197], v191 offset:50176
	ds_read_b128 v[198:201], v191 offset:51200
	ds_read_b128 v[202:205], v191 offset:52224
	ds_read_b128 v[206:209], v191 offset:53248
	ds_read_b128 v[210:213], v191 offset:54272
	ds_read_b128 v[214:217], v191 offset:55296
	ds_read_b128 v[218:221], v191 offset:56320
	global_load_lds_dwordx4 v[222:223], off
	s_add_i32 m0, s64, 0x2000
	s_add_u32 s62, s62, 0x80080
	v_lshl_add_u64 v[222:223], v[224:225], 0, s[26:27]
	s_addc_u32 s63, s63, 0
	s_add_i32 s64, s85, s69
	global_load_lds_dwordx4 v[222:223], off
	v_lshl_add_u64 v[222:223], s[62:63], 0, v[154:155]
	s_mov_b32 m0, s64
	s_nop 0
	global_load_lds_dwordx4 v[222:223], off
	v_lshl_add_u64 v[222:223], s[62:63], 0, v[162:163]
	s_add_i32 m0, s64, 0x2000
	s_nop 0
	global_load_lds_dwordx4 v[222:223], off
	v_lshl_add_u64 v[222:223], v[226:227], 0, s[26:27]
	s_mov_b32 m0, s3
	s_nop 0
	global_load_lds_dwordx4 v[222:223], off
	v_lshl_add_u64 v[222:223], v[228:229], 0, s[26:27]
	s_mov_b32 m0, s75
	s_nop 0
	global_load_lds_dwordx4 v[222:223], off
	s_waitcnt vmcnt(8)
	s_waitcnt lgkmcnt(0)
	s_barrier
	s_setprio 1
	s_waitcnt lgkmcnt(0)
	v_mfma_f32_16x16x32_bf16 v[60:63], v[128:131], v[180:183], v[60:63]
	v_mfma_f32_16x16x32_bf16 v[60:63], v[132:135], v[194:197], v[60:63]
	v_mfma_f32_16x16x32_bf16 v[56:59], v[140:143], v[194:197], v[56:59]
	v_mfma_f32_16x16x32_bf16 v[56:59], v[136:139], v[180:183], v[56:59]
	v_mfma_f32_16x16x32_bf16 v[40:43], v[136:139], v[198:201], v[40:43]
	v_mfma_f32_16x16x32_bf16 v[40:43], v[140:143], v[202:205], v[40:43]
	v_mfma_f32_16x16x32_bf16 v[44:47], v[132:135], v[202:205], v[44:47]
	v_mfma_f32_16x16x32_bf16 v[44:47], v[128:131], v[198:201], v[44:47]
	v_mfma_f32_16x16x32_bf16 v[28:31], v[128:131], v[206:209], v[28:31]
	v_mfma_f32_16x16x32_bf16 v[28:31], v[132:135], v[210:213], v[28:31]
	v_mfma_f32_16x16x32_bf16 v[24:27], v[140:143], v[210:213], v[24:27]
	v_mfma_f32_16x16x32_bf16 v[24:27], v[136:139], v[206:209], v[24:27]
	v_mfma_f32_16x16x32_bf16 v[8:11], v[136:139], v[214:217], v[8:11]
	v_mfma_f32_16x16x32_bf16 v[8:11], v[140:143], v[218:221], v[8:11]
	v_mfma_f32_16x16x32_bf16 v[12:15], v[132:135], v[218:221], v[12:15]
	v_mfma_f32_16x16x32_bf16 v[12:15], v[128:131], v[214:217], v[12:15]
	s_setprio 0
	s_setprio 1
	v_mfma_f32_16x16x32_bf16 v[52:55], v[144:147], v[180:183], v[52:55]
	v_mfma_f32_16x16x32_bf16 v[52:55], v[148:151], v[194:197], v[52:55]
	v_mfma_f32_16x16x32_bf16 v[48:51], v[176:179], v[194:197], v[48:51]
	v_mfma_f32_16x16x32_bf16 v[48:51], v[172:175], v[180:183], v[48:51]
	v_mfma_f32_16x16x32_bf16 v[32:35], v[172:175], v[198:201], v[32:35]
	v_mfma_f32_16x16x32_bf16 v[32:35], v[176:179], v[202:205], v[32:35]
	v_mfma_f32_16x16x32_bf16 v[36:39], v[148:151], v[202:205], v[36:39]
	v_mfma_f32_16x16x32_bf16 v[36:39], v[144:147], v[198:201], v[36:39]
	v_mfma_f32_16x16x32_bf16 v[20:23], v[144:147], v[206:209], v[20:23]
	v_mfma_f32_16x16x32_bf16 v[20:23], v[148:151], v[210:213], v[20:23]
	v_mfma_f32_16x16x32_bf16 v[16:19], v[176:179], v[210:213], v[16:19]
	v_mfma_f32_16x16x32_bf16 v[16:19], v[172:175], v[206:209], v[16:19]
	v_mfma_f32_16x16x32_bf16 v[0:3], v[172:175], v[214:217], v[0:3]
	v_mfma_f32_16x16x32_bf16 v[0:3], v[176:179], v[218:221], v[0:3]
	v_mfma_f32_16x16x32_bf16 v[4:7], v[148:151], v[218:221], v[4:7]
	v_mfma_f32_16x16x32_bf16 v[4:7], v[144:147], v[214:217], v[4:7]
	s_setprio 0
	s_barrier
	s_add_i32 s83, s83, 2
	s_add_u32 s81, s81, 0x100
	s_addc_u32 s82, s82, 0
	s_add_u32 s60, s60, 0x100
	s_addc_u32 s61, s61, 0
	s_cmp_gt_u32 s83, 29
	s_branch .LBB0_440
.Lfa_3:
	ds_read_b128 v[128:131], v189
	ds_read_b128 v[132:135], v189 offset:1024
	ds_read_b128 v[136:139], v189 offset:2048
	ds_read_b128 v[140:143], v189 offset:3072
	ds_read_b128 v[144:147], v190
	ds_read_b128 v[148:151], v190 offset:1024
	ds_read_b128 v[172:175], v190 offset:2048
	ds_read_b128 v[176:179], v190 offset:3072
	s_add_u32 s62, s60, 0xfff80080
	s_addc_u32 s63, s61, -1
	s_cmp_eq_u32 s83, 28
	s_cselect_b32 s65, s15, s63
	s_cselect_b32 s64, s53, s62
	s_cselect_b32 s63, s51, s82
	s_cselect_b32 s62, s59, s81
	v_lshl_add_u64 v[222:223], s[60:61], 0, v[166:167]
	s_add_i32 m0, s70, 0xc000
	ds_read_b128 v[180:183], v191
	ds_read_b128 v[194:197], v191 offset:1024
	ds_read_b128 v[198:201], v191 offset:2048
	ds_read_b128 v[202:205], v191 offset:3072
	ds_read_b128 v[206:209], v191 offset:4096
	ds_read_b128 v[210:213], v191 offset:5120
	ds_read_b128 v[214:217], v191 offset:6144
	ds_read_b128 v[218:221], v191 offset:7168
	global_load_lds_dwordx4 v[222:223], off
	v_lshl_add_u64 v[222:223], s[60:61], 0, v[164:165]
	s_add_i32 m0, s70, 0xe000
	s_nop 0
	global_load_lds_dwordx4 v[222:223], off
	s_waitcnt vmcnt(8)
	s_waitcnt lgkmcnt(0)
	s_barrier
	s_setprio 1
	s_waitcnt lgkmcnt(0)
	v_mfma_f32_16x16x32_bf16 v[124:127], v[128:131], v[180:183], 0
	v_mfma_f32_16x16x32_bf16 v[120:123], v[136:139], v[180:183], 0
	v_mfma_f32_16x16x32_bf16 v[108:111], v[128:131], v[198:201], 0
	v_mfma_f32_16x16x32_bf16 v[104:107], v[136:139], v[198:201], 0
	v_mfma_f32_16x16x32_bf16 v[92:95], v[128:131], v[206:209], 0
	v_mfma_f32_16x16x32_bf16 v[88:91], v[136:139], v[206:209], 0
	v_mfma_f32_16x16x32_bf16 v[76:79], v[128:131], v[214:217], 0
	v_mfma_f32_16x16x32_bf16 v[72:75], v[136:139], v[214:217], 0
	v_mfma_f32_16x16x32_bf16 v[124:127], v[132:135], v[194:197], v[124:127]
	v_mfma_f32_16x16x32_bf16 v[120:123], v[140:143], v[194:197], v[120:123]
	v_mfma_f32_16x16x32_bf16 v[108:111], v[132:135], v[202:205], v[108:111]
	v_mfma_f32_16x16x32_bf16 v[104:107], v[140:143], v[202:205], v[104:107]
	v_mfma_f32_16x16x32_bf16 v[92:95], v[132:135], v[210:213], v[92:95]
	v_mfma_f32_16x16x32_bf16 v[88:91], v[140:143], v[210:213], v[88:91]
	v_mfma_f32_16x16x32_bf16 v[76:79], v[132:135], v[218:221], v[76:79]
	v_mfma_f32_16x16x32_bf16 v[72:75], v[140:143], v[218:221], v[72:75]
	s_setprio 0
	s_setprio 1
	v_mfma_f32_16x16x32_bf16 v[116:119], v[144:147], v[180:183], 0
	v_mfma_f32_16x16x32_bf16 v[112:115], v[172:175], v[180:183], 0
	v_mfma_f32_16x16x32_bf16 v[100:103], v[144:147], v[198:201], 0
	v_mfma_f32_16x16x32_bf16 v[96:99], v[172:175], v[198:201], 0
	v_mfma_f32_16x16x32_bf16 v[84:87], v[144:147], v[206:209], 0
	v_mfma_f32_16x16x32_bf16 v[80:83], v[172:175], v[206:209], 0
	v_mfma_f32_16x16x32_bf16 v[68:71], v[144:147], v[214:217], 0
	v_mfma_f32_16x16x32_bf16 v[64:67], v[172:175], v[214:217], 0
	v_mfma_f32_16x16x32_bf16 v[116:119], v[148:151], v[194:197], v[116:119]
	v_mfma_f32_16x16x32_bf16 v[112:115], v[176:179], v[194:197], v[112:115]
	v_mfma_f32_16x16x32_bf16 v[100:103], v[148:151], v[202:205], v[100:103]
	v_mfma_f32_16x16x32_bf16 v[96:99], v[176:179], v[202:205], v[96:99]
	v_mfma_f32_16x16x32_bf16 v[84:87], v[148:151], v[210:213], v[84:87]
	v_mfma_f32_16x16x32_bf16 v[80:83], v[176:179], v[210:213], v[80:83]
	v_mfma_f32_16x16x32_bf16 v[68:71], v[148:151], v[218:221], v[68:71]
	v_mfma_f32_16x16x32_bf16 v[64:67], v[176:179], v[218:221], v[64:67]
	s_setprio 0
	s_barrier
	s_add_i32 s84, s79, s69
	v_lshl_add_u64 v[222:223], s[62:63], 0, v[154:155]
	s_mov_b32 m0, s84
	ds_read_b128 v[180:183], v191 offset:16384
	ds_read_b128 v[194:197], v191 offset:17408
	ds_read_b128 v[198:201], v191 offset:18432
	ds_read_b128 v[202:205], v191 offset:19456
	ds_read_b128 v[206:209], v191 offset:20480
	ds_read_b128 v[210:213], v191 offset:21504
	ds_read_b128 v[214:217], v191 offset:22528
	ds_read_b128 v[218:221], v191 offset:23552
	global_load_lds_dwordx4 v[222:223], off
	s_add_i32 m0, s84, 0x2000
	s_add_u32 s84, s62, 0x80000
	v_lshl_add_u64 v[224:225], s[62:63], 0, v[162:163]
	s_addc_u32 s85, s63, 0
	s_add_i32 s86, s80, s69
	global_load_lds_dwordx4 v[224:225], off
	v_lshl_add_u64 v[226:227], s[84:85], 0, v[154:155]
	s_mov_b32 m0, s86
	v_lshl_add_u64 v[228:229], s[64:65], 0, v[160:161]
	global_load_lds_dwordx4 v[226:227], off
	v_lshl_add_u64 v[226:227], s[84:85], 0, v[162:163]
	s_add_i32 m0, s86, 0x2000
	s_nop 0
	global_load_lds_dwordx4 v[226:227], off
	v_lshl_add_u64 v[226:227], s[64:65], 0, v[152:153]
	s_mov_b32 m0, s70
	s_nop 0
	global_load_lds_dwordx4 v[226:227], off
	s_mov_b32 m0, s71
	s_nop 0
	global_load_lds_dwordx4 v[228:229], off
	s_waitcnt vmcnt(8)
	s_waitcnt lgkmcnt(0)
	s_barrier
	s_setprio 1
	s_waitcnt lgkmcnt(0)
	v_mfma_f32_16x16x32_bf16 v[60:63], v[128:131], v[180:183], 0
	v_mfma_f32_16x16x32_bf16 v[56:59], v[136:139], v[180:183], 0
	v_mfma_f32_16x16x32_bf16 v[44:47], v[128:131], v[198:201], 0
	v_mfma_f32_16x16x32_bf16 v[40:43], v[136:139], v[198:201], 0
	v_mfma_f32_16x16x32_bf16 v[28:31], v[128:131], v[206:209], 0
	v_mfma_f32_16x16x32_bf16 v[24:27], v[136:139], v[206:209], 0
	v_mfma_f32_16x16x32_bf16 v[12:15], v[128:131], v[214:217], 0
	v_mfma_f32_16x16x32_bf16 v[8:11], v[136:139], v[214:217], 0
	v_mfma_f32_16x16x32_bf16 v[60:63], v[132:135], v[194:197], v[60:63]
	v_mfma_f32_16x16x32_bf16 v[56:59], v[140:143], v[194:197], v[56:59]
	v_mfma_f32_16x16x32_bf16 v[44:47], v[132:135], v[202:205], v[44:47]
	v_mfma_f32_16x16x32_bf16 v[40:43], v[140:143], v[202:205], v[40:43]
	v_mfma_f32_16x16x32_bf16 v[28:31], v[132:135], v[210:213], v[28:31]
	v_mfma_f32_16x16x32_bf16 v[24:27], v[140:143], v[210:213], v[24:27]
	v_mfma_f32_16x16x32_bf16 v[12:15], v[132:135], v[218:221], v[12:15]
	v_mfma_f32_16x16x32_bf16 v[8:11], v[140:143], v[218:221], v[8:11]
	s_setprio 0
	s_setprio 1
	v_mfma_f32_16x16x32_bf16 v[52:55], v[144:147], v[180:183], 0
	v_mfma_f32_16x16x32_bf16 v[48:51], v[172:175], v[180:183], 0
	v_mfma_f32_16x16x32_bf16 v[36:39], v[144:147], v[198:201], 0
	v_mfma_f32_16x16x32_bf16 v[32:35], v[172:175], v[198:201], 0
	v_mfma_f32_16x16x32_bf16 v[20:23], v[144:147], v[206:209], 0
	v_mfma_f32_16x16x32_bf16 v[16:19], v[172:175], v[206:209], 0
	v_mfma_f32_16x16x32_bf16 v[4:7], v[144:147], v[214:217], 0
	v_mfma_f32_16x16x32_bf16 v[0:3], v[172:175], v[214:217], 0
	v_mfma_f32_16x16x32_bf16 v[52:55], v[148:151], v[194:197], v[52:55]
	v_mfma_f32_16x16x32_bf16 v[48:51], v[176:179], v[194:197], v[48:51]
	v_mfma_f32_16x16x32_bf16 v[36:39], v[148:151], v[202:205], v[36:39]
	v_mfma_f32_16x16x32_bf16 v[32:35], v[176:179], v[202:205], v[32:35]
	v_mfma_f32_16x16x32_bf16 v[20:23], v[148:151], v[210:213], v[20:23]
	v_mfma_f32_16x16x32_bf16 v[16:19], v[176:179], v[210:213], v[16:19]
	v_mfma_f32_16x16x32_bf16 v[4:7], v[148:151], v[218:221], v[4:7]
	v_mfma_f32_16x16x32_bf16 v[0:3], v[176:179], v[218:221], v[0:3]
	s_setprio 0
	s_barrier
	s_add_i32 s84, 0, 0x18000
	s_add_i32 s85, 0, 0x1c000
	v_add_u32_e32 v140, s84, v186
	v_add_u32_e32 v176, s85, v186
	ds_read_b128 v[128:131], v140
	ds_read_b128 v[132:135], v140 offset:1024
	ds_read_b128 v[136:139], v140 offset:2048
	ds_read_b128 v[140:143], v140 offset:3072
	ds_read_b128 v[144:147], v176
	ds_read_b128 v[148:151], v176 offset:1024
	ds_read_b128 v[172:175], v176 offset:2048
	ds_read_b128 v[176:179], v176 offset:3072
	s_add_u32 s64, s64, 0x80000
	s_addc_u32 s65, s65, 0
	s_mov_b32 m0, s72
	v_lshl_add_u64 v[230:231], s[64:65], 0, v[152:153]
	ds_read_b128 v[180:183], v191 offset:32768
	ds_read_b128 v[194:197], v191 offset:33792
	ds_read_b128 v[198:201], v191 offset:34816
	ds_read_b128 v[202:205], v191 offset:35840
	ds_read_b128 v[206:209], v191 offset:36864
	ds_read_b128 v[210:213], v191 offset:37888
	ds_read_b128 v[214:217], v191 offset:38912
	ds_read_b128 v[218:221], v191 offset:39936
	global_load_lds_dwordx4 v[230:231], off
	v_lshl_add_u64 v[230:231], s[64:65], 0, v[160:161]
	s_mov_b32 m0, s73
	s_nop 0
	global_load_lds_dwordx4 v[230:231], off
	s_waitcnt vmcnt(8)
	s_waitcnt lgkmcnt(0)
	s_barrier
	s_setprio 1
	s_waitcnt lgkmcnt(0)
	v_mfma_f32_16x16x32_bf16 v[124:127], v[128:131], v[180:183], v[124:127]
	v_mfma_f32_16x16x32_bf16 v[124:127], v[132:135], v[194:197], v[124:127]
	v_mfma_f32_16x16x32_bf16 v[120:123], v[140:143], v[194:197], v[120:123]
	v_mfma_f32_16x16x32_bf16 v[120:123], v[136:139], v[180:183], v[120:123]
	v_mfma_f32_16x16x32_bf16 v[104:107], v[136:139], v[198:201], v[104:107]
	v_mfma_f32_16x16x32_bf16 v[104:107], v[140:143], v[202:205], v[104:107]
	v_mfma_f32_16x16x32_bf16 v[108:111], v[132:135], v[202:205], v[108:111]
	v_mfma_f32_16x16x32_bf16 v[108:111], v[128:131], v[198:201], v[108:111]
	v_mfma_f32_16x16x32_bf16 v[92:95], v[128:131], v[206:209], v[92:95]
	v_mfma_f32_16x16x32_bf16 v[92:95], v[132:135], v[210:213], v[92:95]
	v_mfma_f32_16x16x32_bf16 v[88:91], v[140:143], v[210:213], v[88:91]
	v_mfma_f32_16x16x32_bf16 v[88:91], v[136:139], v[206:209], v[88:91]
	v_mfma_f32_16x16x32_bf16 v[72:75], v[136:139], v[214:217], v[72:75]
	v_mfma_f32_16x16x32_bf16 v[72:75], v[140:143], v[218:221], v[72:75]
	v_mfma_f32_16x16x32_bf16 v[76:79], v[132:135], v[218:221], v[76:79]
	v_mfma_f32_16x16x32_bf16 v[76:79], v[128:131], v[214:217], v[76:79]
	s_setprio 0
	s_setprio 1
	v_mfma_f32_16x16x32_bf16 v[116:119], v[144:147], v[180:183], v[116:119]
	v_mfma_f32_16x16x32_bf16 v[116:119], v[148:151], v[194:197], v[116:119]
	v_mfma_f32_16x16x32_bf16 v[112:115], v[176:179], v[194:197], v[112:115]
	v_mfma_f32_16x16x32_bf16 v[112:115], v[172:175], v[180:183], v[112:115]
	v_mfma_f32_16x16x32_bf16 v[96:99], v[172:175], v[198:201], v[96:99]
	v_mfma_f32_16x16x32_bf16 v[96:99], v[176:179], v[202:205], v[96:99]
	v_mfma_f32_16x16x32_bf16 v[100:103], v[148:151], v[202:205], v[100:103]
	v_mfma_f32_16x16x32_bf16 v[100:103], v[144:147], v[198:201], v[100:103]
	v_mfma_f32_16x16x32_bf16 v[84:87], v[144:147], v[206:209], v[84:87]
	v_mfma_f32_16x16x32_bf16 v[84:87], v[148:151], v[210:213], v[84:87]
	v_mfma_f32_16x16x32_bf16 v[80:83], v[176:179], v[210:213], v[80:83]
	v_mfma_f32_16x16x32_bf16 v[80:83], v[172:175], v[206:209], v[80:83]
	v_mfma_f32_16x16x32_bf16 v[64:67], v[172:175], v[214:217], v[64:67]
	v_mfma_f32_16x16x32_bf16 v[64:67], v[176:179], v[218:221], v[64:67]
	v_mfma_f32_16x16x32_bf16 v[68:71], v[148:151], v[218:221], v[68:71]
	v_mfma_f32_16x16x32_bf16 v[68:71], v[144:147], v[214:217], v[68:71]
	s_setprio 0
	s_barrier
	s_add_i32 s64, s84, s69
	v_lshl_add_u64 v[222:223], v[222:223], 0, s[26:27]
	s_mov_b32 m0, s64
	ds_read_b128 v[180:183], v191 offset:49152
	ds_read_b128 v[194:197], v191 offset:50176
	ds_read_b128 v[198:201], v191 offset:51200
	ds_read_b128 v[202:205], v191 offset:52224
	ds_read_b128 v[206:209], v191 offset:53248
	ds_read_b128 v[210:213], v191 offset:54272
	ds_read_b128 v[214:217], v191 offset:55296
	ds_read_b128 v[218:221], v191 offset:56320
	global_load_lds_dwordx4 v[222:223], off
	s_add_i32 m0, s64, 0x2000
	s_add_u32 s62, s62, 0x80080
	v_lshl_add_u64 v[222:223], v[224:225], 0, s[26:27]
	s_addc_u32 s63, s63, 0
	s_add_i32 s64, s85, s69
	global_load_lds_dwordx4 v[222:223], off
	v_lshl_add_u64 v[222:223], s[62:63], 0, v[154:155]
	s_mov_b32 m0, s64
	s_nop 0
	global_load_lds_dwordx4 v[222:223], off
	v_lshl_add_u64 v[222:223], s[62:63], 0, v[162:163]
	s_add_i32 m0, s64, 0x2000
	s_nop 0
	global_load_lds_dwordx4 v[222:223], off
	v_lshl_add_u64 v[222:223], v[226:227], 0, s[26:27]
	s_mov_b32 m0, s3
	s_nop 0
	global_load_lds_dwordx4 v[222:223], off
	v_lshl_add_u64 v[222:223], v[228:229], 0, s[26:27]
	s_mov_b32 m0, s75
	s_nop 0
	global_load_lds_dwordx4 v[222:223], off
	s_waitcnt vmcnt(8)
	s_waitcnt lgkmcnt(0)
	s_barrier
	s_setprio 1
	s_waitcnt lgkmcnt(0)
	v_mfma_f32_16x16x32_bf16 v[60:63], v[128:131], v[180:183], v[60:63]
	v_mfma_f32_16x16x32_bf16 v[60:63], v[132:135], v[194:197], v[60:63]
	v_mfma_f32_16x16x32_bf16 v[56:59], v[140:143], v[194:197], v[56:59]
	v_mfma_f32_16x16x32_bf16 v[56:59], v[136:139], v[180:183], v[56:59]
	v_mfma_f32_16x16x32_bf16 v[40:43], v[136:139], v[198:201], v[40:43]
	v_mfma_f32_16x16x32_bf16 v[40:43], v[140:143], v[202:205], v[40:43]
	v_mfma_f32_16x16x32_bf16 v[44:47], v[132:135], v[202:205], v[44:47]
	v_mfma_f32_16x16x32_bf16 v[44:47], v[128:131], v[198:201], v[44:47]
	v_mfma_f32_16x16x32_bf16 v[28:31], v[128:131], v[206:209], v[28:31]
	v_mfma_f32_16x16x32_bf16 v[28:31], v[132:135], v[210:213], v[28:31]
	v_mfma_f32_16x16x32_bf16 v[24:27], v[140:143], v[210:213], v[24:27]
	v_mfma_f32_16x16x32_bf16 v[24:27], v[136:139], v[206:209], v[24:27]
	v_mfma_f32_16x16x32_bf16 v[8:11], v[136:139], v[214:217], v[8:11]
	v_mfma_f32_16x16x32_bf16 v[8:11], v[140:143], v[218:221], v[8:11]
	v_mfma_f32_16x16x32_bf16 v[12:15], v[132:135], v[218:221], v[12:15]
	v_mfma_f32_16x16x32_bf16 v[12:15], v[128:131], v[214:217], v[12:15]
	s_setprio 0
	s_setprio 1
	v_mfma_f32_16x16x32_bf16 v[52:55], v[144:147], v[180:183], v[52:55]
	v_mfma_f32_16x16x32_bf16 v[52:55], v[148:151], v[194:197], v[52:55]
	v_mfma_f32_16x16x32_bf16 v[48:51], v[176:179], v[194:197], v[48:51]
	v_mfma_f32_16x16x32_bf16 v[48:51], v[172:175], v[180:183], v[48:51]
	v_mfma_f32_16x16x32_bf16 v[32:35], v[172:175], v[198:201], v[32:35]
	v_mfma_f32_16x16x32_bf16 v[32:35], v[176:179], v[202:205], v[32:35]
	v_mfma_f32_16x16x32_bf16 v[36:39], v[148:151], v[202:205], v[36:39]
	v_mfma_f32_16x16x32_bf16 v[36:39], v[144:147], v[198:201], v[36:39]
	v_mfma_f32_16x16x32_bf16 v[20:23], v[144:147], v[206:209], v[20:23]
	v_mfma_f32_16x16x32_bf16 v[20:23], v[148:151], v[210:213], v[20:23]
	v_mfma_f32_16x16x32_bf16 v[16:19], v[176:179], v[210:213], v[16:19]
	v_mfma_f32_16x16x32_bf16 v[16:19], v[172:175], v[206:209], v[16:19]
	v_mfma_f32_16x16x32_bf16 v[0:3], v[172:175], v[214:217], v[0:3]
	v_mfma_f32_16x16x32_bf16 v[0:3], v[176:179], v[218:221], v[0:3]
	v_mfma_f32_16x16x32_bf16 v[4:7], v[148:151], v[218:221], v[4:7]
	v_mfma_f32_16x16x32_bf16 v[4:7], v[144:147], v[214:217], v[4:7]
	s_setprio 0
	s_barrier
	s_add_i32 s83, s83, 2
	s_add_u32 s81, s81, 0x100
	s_addc_u32 s82, s82, 0
	s_add_u32 s60, s60, 0x100
	s_addc_u32 s61, s61, 0
	s_cmp_gt_u32 s83, 29
.LBB0_440:
	ds_read_b128 v[128:131], v189
	ds_read_b128 v[132:135], v189 offset:1024
	ds_read_b128 v[136:139], v189 offset:2048
	ds_read_b128 v[140:143], v189 offset:3072
	ds_read_b128 v[144:147], v190
	ds_read_b128 v[148:151], v190 offset:1024
	ds_read_b128 v[172:175], v190 offset:2048
	ds_read_b128 v[176:179], v190 offset:3072
	s_add_u32 s62, s60, 0xfff80080
	s_addc_u32 s63, s61, -1
	s_cmp_eq_u32 s83, 28
	s_cselect_b32 s65, s15, s63
	s_cselect_b32 s64, s53, s62
	s_cselect_b32 s63, s51, s82
	s_cselect_b32 s62, s59, s81
	v_lshl_add_u64 v[222:223], s[60:61], 0, v[166:167]
	s_add_i32 m0, s70, 0xc000
	ds_read_b128 v[180:183], v191
	ds_read_b128 v[194:197], v191 offset:1024
	ds_read_b128 v[198:201], v191 offset:2048
	ds_read_b128 v[202:205], v191 offset:3072
	ds_read_b128 v[206:209], v191 offset:4096
	ds_read_b128 v[210:213], v191 offset:5120
	ds_read_b128 v[214:217], v191 offset:6144
	ds_read_b128 v[218:221], v191 offset:7168
	global_load_lds_dwordx4 v[222:223], off
	v_lshl_add_u64 v[222:223], s[60:61], 0, v[164:165]
	s_add_i32 m0, s70, 0xe000
	s_nop 0
	global_load_lds_dwordx4 v[222:223], off
	s_waitcnt vmcnt(8)
	s_waitcnt lgkmcnt(0)
	s_barrier
	s_setprio 1
	s_waitcnt lgkmcnt(0)
	v_mfma_f32_16x16x32_bf16 v[124:127], v[128:131], v[180:183], v[124:127]
	v_mfma_f32_16x16x32_bf16 v[124:127], v[132:135], v[194:197], v[124:127]
	v_mfma_f32_16x16x32_bf16 v[120:123], v[140:143], v[194:197], v[120:123]
	v_mfma_f32_16x16x32_bf16 v[120:123], v[136:139], v[180:183], v[120:123]
	v_mfma_f32_16x16x32_bf16 v[104:107], v[136:139], v[198:201], v[104:107]
	v_mfma_f32_16x16x32_bf16 v[104:107], v[140:143], v[202:205], v[104:107]
	v_mfma_f32_16x16x32_bf16 v[108:111], v[132:135], v[202:205], v[108:111]
	v_mfma_f32_16x16x32_bf16 v[108:111], v[128:131], v[198:201], v[108:111]
	v_mfma_f32_16x16x32_bf16 v[92:95], v[128:131], v[206:209], v[92:95]
	v_mfma_f32_16x16x32_bf16 v[92:95], v[132:135], v[210:213], v[92:95]
	v_mfma_f32_16x16x32_bf16 v[88:91], v[140:143], v[210:213], v[88:91]
	v_mfma_f32_16x16x32_bf16 v[88:91], v[136:139], v[206:209], v[88:91]
	v_mfma_f32_16x16x32_bf16 v[72:75], v[136:139], v[214:217], v[72:75]
	v_mfma_f32_16x16x32_bf16 v[72:75], v[140:143], v[218:221], v[72:75]
	v_mfma_f32_16x16x32_bf16 v[76:79], v[132:135], v[218:221], v[76:79]
	v_mfma_f32_16x16x32_bf16 v[76:79], v[128:131], v[214:217], v[76:79]
	s_setprio 0
	s_setprio 1
	v_mfma_f32_16x16x32_bf16 v[116:119], v[144:147], v[180:183], v[116:119]
	v_mfma_f32_16x16x32_bf16 v[116:119], v[148:151], v[194:197], v[116:119]
	v_mfma_f32_16x16x32_bf16 v[112:115], v[176:179], v[194:197], v[112:115]
	v_mfma_f32_16x16x32_bf16 v[112:115], v[172:175], v[180:183], v[112:115]
	v_mfma_f32_16x16x32_bf16 v[96:99], v[172:175], v[198:201], v[96:99]
	v_mfma_f32_16x16x32_bf16 v[96:99], v[176:179], v[202:205], v[96:99]
	v_mfma_f32_16x16x32_bf16 v[100:103], v[148:151], v[202:205], v[100:103]
	v_mfma_f32_16x16x32_bf16 v[100:103], v[144:147], v[198:201], v[100:103]
	v_mfma_f32_16x16x32_bf16 v[84:87], v[144:147], v[206:209], v[84:87]
	v_mfma_f32_16x16x32_bf16 v[84:87], v[148:151], v[210:213], v[84:87]
	v_mfma_f32_16x16x32_bf16 v[80:83], v[176:179], v[210:213], v[80:83]
	v_mfma_f32_16x16x32_bf16 v[80:83], v[172:175], v[206:209], v[80:83]
	v_mfma_f32_16x16x32_bf16 v[64:67], v[172:175], v[214:217], v[64:67]
	v_mfma_f32_16x16x32_bf16 v[64:67], v[176:179], v[218:221], v[64:67]
	v_mfma_f32_16x16x32_bf16 v[68:71], v[148:151], v[218:221], v[68:71]
	v_mfma_f32_16x16x32_bf16 v[68:71], v[144:147], v[214:217], v[68:71]
	s_setprio 0
	s_barrier
	s_add_i32 s84, s79, s69
	v_lshl_add_u64 v[222:223], s[62:63], 0, v[154:155]
	s_mov_b32 m0, s84
	ds_read_b128 v[180:183], v191 offset:16384
	ds_read_b128 v[194:197], v191 offset:17408
	ds_read_b128 v[198:201], v191 offset:18432
	ds_read_b128 v[202:205], v191 offset:19456
	ds_read_b128 v[206:209], v191 offset:20480
	ds_read_b128 v[210:213], v191 offset:21504
	ds_read_b128 v[214:217], v191 offset:22528
	ds_read_b128 v[218:221], v191 offset:23552
	global_load_lds_dwordx4 v[222:223], off
	s_add_i32 m0, s84, 0x2000
	s_add_u32 s84, s62, 0x80000
	v_lshl_add_u64 v[224:225], s[62:63], 0, v[162:163]
	s_addc_u32 s85, s63, 0
	s_add_i32 s86, s80, s69
	global_load_lds_dwordx4 v[224:225], off
	v_lshl_add_u64 v[226:227], s[84:85], 0, v[154:155]
	s_mov_b32 m0, s86
	v_lshl_add_u64 v[228:229], s[64:65], 0, v[160:161]
	global_load_lds_dwordx4 v[226:227], off
	v_lshl_add_u64 v[226:227], s[84:85], 0, v[162:163]
	s_add_i32 m0, s86, 0x2000
	s_nop 0
	global_load_lds_dwordx4 v[226:227], off
	v_lshl_add_u64 v[226:227], s[64:65], 0, v[152:153]
	s_mov_b32 m0, s70
	s_nop 0
	global_load_lds_dwordx4 v[226:227], off
	s_mov_b32 m0, s71
	s_nop 0
	global_load_lds_dwordx4 v[228:229], off
	s_waitcnt vmcnt(8)
	s_waitcnt lgkmcnt(0)
	s_barrier
	s_setprio 1
	s_waitcnt lgkmcnt(0)
	v_mfma_f32_16x16x32_bf16 v[60:63], v[128:131], v[180:183], v[60:63]
	v_mfma_f32_16x16x32_bf16 v[60:63], v[132:135], v[194:197], v[60:63]
	v_mfma_f32_16x16x32_bf16 v[56:59], v[140:143], v[194:197], v[56:59]
	v_mfma_f32_16x16x32_bf16 v[56:59], v[136:139], v[180:183], v[56:59]
	v_mfma_f32_16x16x32_bf16 v[40:43], v[136:139], v[198:201], v[40:43]
	v_mfma_f32_16x16x32_bf16 v[40:43], v[140:143], v[202:205], v[40:43]
	v_mfma_f32_16x16x32_bf16 v[44:47], v[132:135], v[202:205], v[44:47]
	v_mfma_f32_16x16x32_bf16 v[44:47], v[128:131], v[198:201], v[44:47]
	v_mfma_f32_16x16x32_bf16 v[28:31], v[128:131], v[206:209], v[28:31]
	v_mfma_f32_16x16x32_bf16 v[28:31], v[132:135], v[210:213], v[28:31]
	v_mfma_f32_16x16x32_bf16 v[24:27], v[140:143], v[210:213], v[24:27]
	v_mfma_f32_16x16x32_bf16 v[24:27], v[136:139], v[206:209], v[24:27]
	v_mfma_f32_16x16x32_bf16 v[8:11], v[136:139], v[214:217], v[8:11]
	v_mfma_f32_16x16x32_bf16 v[8:11], v[140:143], v[218:221], v[8:11]
	v_mfma_f32_16x16x32_bf16 v[12:15], v[132:135], v[218:221], v[12:15]
	v_mfma_f32_16x16x32_bf16 v[12:15], v[128:131], v[214:217], v[12:15]
	s_setprio 0
	s_setprio 1
	v_mfma_f32_16x16x32_bf16 v[52:55], v[144:147], v[180:183], v[52:55]
	v_mfma_f32_16x16x32_bf16 v[52:55], v[148:151], v[194:197], v[52:55]
	v_mfma_f32_16x16x32_bf16 v[48:51], v[176:179], v[194:197], v[48:51]
	v_mfma_f32_16x16x32_bf16 v[48:51], v[172:175], v[180:183], v[48:51]
	v_mfma_f32_16x16x32_bf16 v[32:35], v[172:175], v[198:201], v[32:35]
	v_mfma_f32_16x16x32_bf16 v[32:35], v[176:179], v[202:205], v[32:35]
	v_mfma_f32_16x16x32_bf16 v[36:39], v[148:151], v[202:205], v[36:39]
	v_mfma_f32_16x16x32_bf16 v[36:39], v[144:147], v[198:201], v[36:39]
	v_mfma_f32_16x16x32_bf16 v[20:23], v[144:147], v[206:209], v[20:23]
	v_mfma_f32_16x16x32_bf16 v[20:23], v[148:151], v[210:213], v[20:23]
	v_mfma_f32_16x16x32_bf16 v[16:19], v[176:179], v[210:213], v[16:19]
	v_mfma_f32_16x16x32_bf16 v[16:19], v[172:175], v[206:209], v[16:19]
	v_mfma_f32_16x16x32_bf16 v[0:3], v[172:175], v[214:217], v[0:3]
	v_mfma_f32_16x16x32_bf16 v[0:3], v[176:179], v[218:221], v[0:3]
	v_mfma_f32_16x16x32_bf16 v[4:7], v[148:151], v[218:221], v[4:7]
	v_mfma_f32_16x16x32_bf16 v[4:7], v[144:147], v[214:217], v[4:7]
	s_setprio 0
	s_barrier
	s_add_i32 s84, 0, 0x18000
	s_add_i32 s85, 0, 0x1c000
	v_add_u32_e32 v140, s84, v186
	v_add_u32_e32 v176, s85, v186
	ds_read_b128 v[128:131], v140
	ds_read_b128 v[132:135], v140 offset:1024
	ds_read_b128 v[136:139], v140 offset:2048
	ds_read_b128 v[140:143], v140 offset:3072
	ds_read_b128 v[144:147], v176
	ds_read_b128 v[148:151], v176 offset:1024
	ds_read_b128 v[172:175], v176 offset:2048
	ds_read_b128 v[176:179], v176 offset:3072
	s_add_u32 s64, s64, 0x80000
	s_addc_u32 s65, s65, 0
	s_mov_b32 m0, s72
	v_lshl_add_u64 v[230:231], s[64:65], 0, v[152:153]
	ds_read_b128 v[180:183], v191 offset:32768
	ds_read_b128 v[194:197], v191 offset:33792
	ds_read_b128 v[198:201], v191 offset:34816
	ds_read_b128 v[202:205], v191 offset:35840
	ds_read_b128 v[206:209], v191 offset:36864
	ds_read_b128 v[210:213], v191 offset:37888
	ds_read_b128 v[214:217], v191 offset:38912
	ds_read_b128 v[218:221], v191 offset:39936
	global_load_lds_dwordx4 v[230:231], off
	v_lshl_add_u64 v[230:231], s[64:65], 0, v[160:161]
	s_mov_b32 m0, s73
	s_nop 0
	global_load_lds_dwordx4 v[230:231], off
	s_waitcnt vmcnt(8)
	s_waitcnt lgkmcnt(0)
	s_barrier
	s_setprio 1
	s_waitcnt lgkmcnt(0)
	v_mfma_f32_16x16x32_bf16 v[124:127], v[128:131], v[180:183], v[124:127]
	v_mfma_f32_16x16x32_bf16 v[124:127], v[132:135], v[194:197], v[124:127]
	v_mfma_f32_16x16x32_bf16 v[120:123], v[140:143], v[194:197], v[120:123]
	v_mfma_f32_16x16x32_bf16 v[120:123], v[136:139], v[180:183], v[120:123]
	v_mfma_f32_16x16x32_bf16 v[104:107], v[136:139], v[198:201], v[104:107]
	v_mfma_f32_16x16x32_bf16 v[104:107], v[140:143], v[202:205], v[104:107]
	v_mfma_f32_16x16x32_bf16 v[108:111], v[132:135], v[202:205], v[108:111]
	v_mfma_f32_16x16x32_bf16 v[108:111], v[128:131], v[198:201], v[108:111]
	v_mfma_f32_16x16x32_bf16 v[92:95], v[128:131], v[206:209], v[92:95]
	v_mfma_f32_16x16x32_bf16 v[92:95], v[132:135], v[210:213], v[92:95]
	v_mfma_f32_16x16x32_bf16 v[88:91], v[140:143], v[210:213], v[88:91]
	v_mfma_f32_16x16x32_bf16 v[88:91], v[136:139], v[206:209], v[88:91]
	v_mfma_f32_16x16x32_bf16 v[72:75], v[136:139], v[214:217], v[72:75]
	v_mfma_f32_16x16x32_bf16 v[72:75], v[140:143], v[218:221], v[72:75]
	v_mfma_f32_16x16x32_bf16 v[76:79], v[132:135], v[218:221], v[76:79]
	v_mfma_f32_16x16x32_bf16 v[76:79], v[128:131], v[214:217], v[76:79]
	s_setprio 0
	s_setprio 1
	v_mfma_f32_16x16x32_bf16 v[116:119], v[144:147], v[180:183], v[116:119]
	v_mfma_f32_16x16x32_bf16 v[116:119], v[148:151], v[194:197], v[116:119]
	v_mfma_f32_16x16x32_bf16 v[112:115], v[176:179], v[194:197], v[112:115]
	v_mfma_f32_16x16x32_bf16 v[112:115], v[172:175], v[180:183], v[112:115]
	v_mfma_f32_16x16x32_bf16 v[96:99], v[172:175], v[198:201], v[96:99]
	v_mfma_f32_16x16x32_bf16 v[96:99], v[176:179], v[202:205], v[96:99]
	v_mfma_f32_16x16x32_bf16 v[100:103], v[148:151], v[202:205], v[100:103]
	v_mfma_f32_16x16x32_bf16 v[100:103], v[144:147], v[198:201], v[100:103]
	v_mfma_f32_16x16x32_bf16 v[84:87], v[144:147], v[206:209], v[84:87]
	v_mfma_f32_16x16x32_bf16 v[84:87], v[148:151], v[210:213], v[84:87]
	v_mfma_f32_16x16x32_bf16 v[80:83], v[176:179], v[210:213], v[80:83]
	v_mfma_f32_16x16x32_bf16 v[80:83], v[172:175], v[206:209], v[80:83]
	v_mfma_f32_16x16x32_bf16 v[64:67], v[172:175], v[214:217], v[64:67]
	v_mfma_f32_16x16x32_bf16 v[64:67], v[176:179], v[218:221], v[64:67]
	v_mfma_f32_16x16x32_bf16 v[68:71], v[148:151], v[218:221], v[68:71]
	v_mfma_f32_16x16x32_bf16 v[68:71], v[144:147], v[214:217], v[68:71]
	s_setprio 0
	s_barrier
	s_add_i32 s64, s84, s69
	v_lshl_add_u64 v[222:223], v[222:223], 0, s[26:27]
	s_mov_b32 m0, s64
	ds_read_b128 v[180:183], v191 offset:49152
	ds_read_b128 v[194:197], v191 offset:50176
	ds_read_b128 v[198:201], v191 offset:51200
	ds_read_b128 v[202:205], v191 offset:52224
	ds_read_b128 v[206:209], v191 offset:53248
	ds_read_b128 v[210:213], v191 offset:54272
	ds_read_b128 v[214:217], v191 offset:55296
	ds_read_b128 v[218:221], v191 offset:56320
	global_load_lds_dwordx4 v[222:223], off
	s_add_i32 m0, s64, 0x2000
	s_add_u32 s62, s62, 0x80080
	v_lshl_add_u64 v[222:223], v[224:225], 0, s[26:27]
	s_addc_u32 s63, s63, 0
	s_add_i32 s64, s85, s69
	global_load_lds_dwordx4 v[222:223], off
	v_lshl_add_u64 v[222:223], s[62:63], 0, v[154:155]
	s_mov_b32 m0, s64
	s_nop 0
	global_load_lds_dwordx4 v[222:223], off
	v_lshl_add_u64 v[222:223], s[62:63], 0, v[162:163]
	s_add_i32 m0, s64, 0x2000
	s_nop 0
	global_load_lds_dwordx4 v[222:223], off
	v_lshl_add_u64 v[222:223], v[226:227], 0, s[26:27]
	s_mov_b32 m0, s3
	s_nop 0
	global_load_lds_dwordx4 v[222:223], off
	v_lshl_add_u64 v[222:223], v[228:229], 0, s[26:27]
	s_mov_b32 m0, s75
	s_nop 0
	global_load_lds_dwordx4 v[222:223], off
	s_waitcnt vmcnt(8)
	s_waitcnt lgkmcnt(0)
	s_barrier
	s_setprio 1
	s_waitcnt lgkmcnt(0)
	v_mfma_f32_16x16x32_bf16 v[60:63], v[128:131], v[180:183], v[60:63]
	v_mfma_f32_16x16x32_bf16 v[60:63], v[132:135], v[194:197], v[60:63]
	v_mfma_f32_16x16x32_bf16 v[56:59], v[140:143], v[194:197], v[56:59]
	v_mfma_f32_16x16x32_bf16 v[56:59], v[136:139], v[180:183], v[56:59]
	v_mfma_f32_16x16x32_bf16 v[40:43], v[136:139], v[198:201], v[40:43]
	v_mfma_f32_16x16x32_bf16 v[40:43], v[140:143], v[202:205], v[40:43]
	v_mfma_f32_16x16x32_bf16 v[44:47], v[132:135], v[202:205], v[44:47]
	v_mfma_f32_16x16x32_bf16 v[44:47], v[128:131], v[198:201], v[44:47]
	v_mfma_f32_16x16x32_bf16 v[28:31], v[128:131], v[206:209], v[28:31]
	v_mfma_f32_16x16x32_bf16 v[28:31], v[132:135], v[210:213], v[28:31]
	v_mfma_f32_16x16x32_bf16 v[24:27], v[140:143], v[210:213], v[24:27]
	v_mfma_f32_16x16x32_bf16 v[24:27], v[136:139], v[206:209], v[24:27]
	v_mfma_f32_16x16x32_bf16 v[8:11], v[136:139], v[214:217], v[8:11]
	v_mfma_f32_16x16x32_bf16 v[8:11], v[140:143], v[218:221], v[8:11]
	v_mfma_f32_16x16x32_bf16 v[12:15], v[132:135], v[218:221], v[12:15]
	v_mfma_f32_16x16x32_bf16 v[12:15], v[128:131], v[214:217], v[12:15]
	s_setprio 0
	s_setprio 1
	v_mfma_f32_16x16x32_bf16 v[52:55], v[144:147], v[180:183], v[52:55]
	v_mfma_f32_16x16x32_bf16 v[52:55], v[148:151], v[194:197], v[52:55]
	v_mfma_f32_16x16x32_bf16 v[48:51], v[176:179], v[194:197], v[48:51]
	v_mfma_f32_16x16x32_bf16 v[48:51], v[172:175], v[180:183], v[48:51]
	v_mfma_f32_16x16x32_bf16 v[32:35], v[172:175], v[198:201], v[32:35]
	v_mfma_f32_16x16x32_bf16 v[32:35], v[176:179], v[202:205], v[32:35]
	v_mfma_f32_16x16x32_bf16 v[36:39], v[148:151], v[202:205], v[36:39]
	v_mfma_f32_16x16x32_bf16 v[36:39], v[144:147], v[198:201], v[36:39]
	v_mfma_f32_16x16x32_bf16 v[20:23], v[144:147], v[206:209], v[20:23]
	v_mfma_f32_16x16x32_bf16 v[20:23], v[148:151], v[210:213], v[20:23]
	v_mfma_f32_16x16x32_bf16 v[16:19], v[176:179], v[210:213], v[16:19]
	v_mfma_f32_16x16x32_bf16 v[16:19], v[172:175], v[206:209], v[16:19]
	v_mfma_f32_16x16x32_bf16 v[0:3], v[172:175], v[214:217], v[0:3]
	v_mfma_f32_16x16x32_bf16 v[0:3], v[176:179], v[218:221], v[0:3]
	v_mfma_f32_16x16x32_bf16 v[4:7], v[148:151], v[218:221], v[4:7]
	v_mfma_f32_16x16x32_bf16 v[4:7], v[144:147], v[214:217], v[4:7]
	s_setprio 0
	s_barrier
	s_add_i32 s83, s83, 2
	s_add_u32 s81, s81, 0x100
	s_addc_u32 s82, s82, 0
	s_add_u32 s60, s60, 0x100
	s_addc_u32 s61, s61, 0
	s_cmp_gt_u32 s83, 29
	s_cbranch_scc0 .LBB0_440
	s_and_b64 vcc, exec, s[28:29]
	s_cbranch_vccz .LBB0_443
	s_barrier

.LBB0_525:
	s_ashr_i32 s29, s28, 31
	s_lshl_b64 s[30:31], s[28:29], 19
	s_add_u32 s30, s3, s30
	s_addc_u32 s31, s35, s31
	s_and_b64 s[44:45], s[10:11], exec
	s_cselect_b32 s29, s31, s51
	s_cselect_b32 s70, s30, s50
	s_ashr_i32 s27, s26, 31
	s_lshl_b64 s[44:45], s[26:27], 19
	s_add_u32 s44, s52, s44
	s_addc_u32 s45, s53, s45
	s_and_b64 s[72:73], s[10:11], exec
	s_cselect_b32 s71, s45, s49
	s_cselect_b32 s72, s44, s48
	s_lshl_b32 s27, s46, 8
	v_add_u32_e32 v0, s27, v148
	s_add_u32 s73, s48, 0x100
	v_ashrrev_i32_e32 v1, 31, v0
	s_addc_u32 s74, s49, 0
	v_lshl_add_u64 v[144:145], v[0:1], 4, s[16:17]
	s_add_u32 s46, s50, 0x40080
	s_addc_u32 s47, s51, 0
	s_mov_b32 s75, -2
	s_mov_b64 s[48:49], 0
	s_cmp_eq_u32 s61, 1
	s_cbranch_scc1 .Lfa_4
	v_add_u32_e32 v153, s66, v147
	ds_read_b128 v[160:163], v153
	ds_read_b128 v[164:167], v153 offset:1024
	ds_read_b128 v[168:171], v153 offset:2048
	ds_read_b128 v[172:175], v153 offset:3072
	v_add_u32_e32 v153, s67, v147
	ds_read_b128 v[176:179], v153
	ds_read_b128 v[180:183], v153 offset:1024
	ds_read_b128 v[186:189], v153 offset:2048
	ds_read_b128 v[190:193], v153 offset:3072
	s_add_u32 s50, s46, 0xfffc0080
	s_addc_u32 s51, s47, -1
	s_and_b64 s[48:49], s[48:49], exec
	s_cselect_b32 s51, s29, s51
	s_cselect_b32 s50, s70, s50
	s_cselect_b32 s49, s71, s74
	s_cselect_b32 s48, s72, s73
	v_lshl_add_u64 v[154:155], s[46:47], 0, v[138:139]
	s_add_i32 m0, s57, 0xc000
	ds_read_b128 v[194:197], v150
	ds_read_b128 v[198:201], v150 offset:1024
	ds_read_b128 v[202:205], v150 offset:2048
	ds_read_b128 v[206:209], v150 offset:3072
	ds_read_b128 v[210:213], v150 offset:4096
	ds_read_b128 v[214:217], v150 offset:5120
	ds_read_b128 v[218:221], v150 offset:6144
	ds_read_b128 v[222:225], v150 offset:7168
	global_load_lds_dwordx4 v[154:155], off
	v_lshl_add_u64 v[154:155], s[46:47], 0, v[136:137]
	s_add_i32 m0, s57, 0xe000
	s_nop 0
	global_load_lds_dwordx4 v[154:155], off
	s_waitcnt vmcnt(16)
	s_waitcnt lgkmcnt(0)
	s_barrier
	s_setprio 1
	s_waitcnt lgkmcnt(0)
	v_mfma_f32_16x16x32_bf16 v[124:127], v[160:163], v[194:197], 0
	v_mfma_f32_16x16x32_bf16 v[116:119], v[168:171], v[194:197], 0
	v_mfma_f32_16x16x32_bf16 v[108:111], v[160:163], v[202:205], 0
	v_mfma_f32_16x16x32_bf16 v[100:103], v[168:171], v[202:205], 0
	v_mfma_f32_16x16x32_bf16 v[92:95], v[160:163], v[210:213], 0
	v_mfma_f32_16x16x32_bf16 v[84:87], v[168:171], v[210:213], 0
	v_mfma_f32_16x16x32_bf16 v[76:79], v[160:163], v[218:221], 0
	v_mfma_f32_16x16x32_bf16 v[68:71], v[168:171], v[218:221], 0
	v_mfma_f32_16x16x32_bf16 v[124:127], v[164:167], v[198:201], v[124:127]
	v_mfma_f32_16x16x32_bf16 v[116:119], v[172:175], v[198:201], v[116:119]
	v_mfma_f32_16x16x32_bf16 v[108:111], v[164:167], v[206:209], v[108:111]
	v_mfma_f32_16x16x32_bf16 v[100:103], v[172:175], v[206:209], v[100:103]
	v_mfma_f32_16x16x32_bf16 v[92:95], v[164:167], v[214:217], v[92:95]
	v_mfma_f32_16x16x32_bf16 v[84:87], v[172:175], v[214:217], v[84:87]
	v_mfma_f32_16x16x32_bf16 v[76:79], v[164:167], v[222:225], v[76:79]
	v_mfma_f32_16x16x32_bf16 v[68:71], v[172:175], v[222:225], v[68:71]
	s_setprio 0
	s_setprio 1
	v_mfma_f32_16x16x32_bf16 v[120:123], v[176:179], v[194:197], 0
	v_mfma_f32_16x16x32_bf16 v[112:115], v[186:189], v[194:197], 0
	v_mfma_f32_16x16x32_bf16 v[104:107], v[176:179], v[202:205], 0
	v_mfma_f32_16x16x32_bf16 v[96:99], v[186:189], v[202:205], 0
	v_mfma_f32_16x16x32_bf16 v[88:91], v[176:179], v[210:213], 0
	v_mfma_f32_16x16x32_bf16 v[80:83], v[186:189], v[210:213], 0
	v_mfma_f32_16x16x32_bf16 v[72:75], v[176:179], v[218:221], 0
	v_mfma_f32_16x16x32_bf16 v[64:67], v[186:189], v[218:221], 0
	v_mfma_f32_16x16x32_bf16 v[120:123], v[180:183], v[198:201], v[120:123]
	v_mfma_f32_16x16x32_bf16 v[112:115], v[190:193], v[198:201], v[112:115]
	v_mfma_f32_16x16x32_bf16 v[104:107], v[180:183], v[206:209], v[104:107]
	v_mfma_f32_16x16x32_bf16 v[96:99], v[190:193], v[206:209], v[96:99]
	v_mfma_f32_16x16x32_bf16 v[88:91], v[180:183], v[214:217], v[88:91]
	v_mfma_f32_16x16x32_bf16 v[80:83], v[190:193], v[214:217], v[80:83]
	v_mfma_f32_16x16x32_bf16 v[72:75], v[180:183], v[222:225], v[72:75]
	v_mfma_f32_16x16x32_bf16 v[64:67], v[190:193], v[222:225], v[64:67]
	s_setprio 0
	s_barrier
	s_add_i32 s76, s66, s54
	v_lshl_add_u64 v[154:155], s[48:49], 0, v[132:133]
	s_mov_b32 m0, s76
	ds_read_b128 v[194:197], v150 offset:16384
	ds_read_b128 v[198:201], v150 offset:17408
	ds_read_b128 v[202:205], v150 offset:18432
	ds_read_b128 v[206:209], v150 offset:19456
	ds_read_b128 v[210:213], v150 offset:20480
	ds_read_b128 v[214:217], v150 offset:21504
	ds_read_b128 v[218:221], v150 offset:22528
	ds_read_b128 v[222:225], v150 offset:23552
	global_load_lds_dwordx4 v[154:155], off
	s_add_i32 m0, s76, 0x2000
	s_add_u32 s76, s48, 0x40000
	v_lshl_add_u64 v[226:227], s[48:49], 0, v[128:129]
	s_addc_u32 s77, s49, 0
	s_add_i32 s78, s67, s54
	global_load_lds_dwordx4 v[226:227], off
	v_lshl_add_u64 v[228:229], s[76:77], 0, v[132:133]
	s_mov_b32 m0, s78
	v_lshl_add_u64 v[230:231], s[50:51], 0, v[130:131]
	global_load_lds_dwordx4 v[228:229], off
	v_lshl_add_u64 v[228:229], s[76:77], 0, v[128:129]
	s_add_i32 m0, s78, 0x2000
	s_nop 0
	global_load_lds_dwordx4 v[228:229], off
	v_lshl_add_u64 v[228:229], s[50:51], 0, v[134:135]
	s_mov_b32 m0, s57
	s_nop 0
	global_load_lds_dwordx4 v[228:229], off
	s_mov_b32 m0, s58
	s_nop 0
	global_load_lds_dwordx4 v[230:231], off
	s_waitcnt vmcnt(16)
	s_waitcnt lgkmcnt(0)
	s_barrier
	s_setprio 1
	s_waitcnt lgkmcnt(0)
	v_mfma_f32_16x16x32_bf16 v[60:63], v[160:163], v[194:197], 0
	v_mfma_f32_16x16x32_bf16 v[52:55], v[168:171], v[194:197], 0
	v_mfma_f32_16x16x32_bf16 v[44:47], v[160:163], v[202:205], 0
	v_mfma_f32_16x16x32_bf16 v[36:39], v[168:171], v[202:205], 0
	v_mfma_f32_16x16x32_bf16 v[28:31], v[160:163], v[210:213], 0
	v_mfma_f32_16x16x32_bf16 v[20:23], v[168:171], v[210:213], 0
	v_mfma_f32_16x16x32_bf16 v[12:15], v[160:163], v[218:221], 0
	v_mfma_f32_16x16x32_bf16 v[4:7], v[168:171], v[218:221], 0
	v_mfma_f32_16x16x32_bf16 v[60:63], v[164:167], v[198:201], v[60:63]
	v_mfma_f32_16x16x32_bf16 v[52:55], v[172:175], v[198:201], v[52:55]
	v_mfma_f32_16x16x32_bf16 v[44:47], v[164:167], v[206:209], v[44:47]
	v_mfma_f32_16x16x32_bf16 v[36:39], v[172:175], v[206:209], v[36:39]
	v_mfma_f32_16x16x32_bf16 v[28:31], v[164:167], v[214:217], v[28:31]
	v_mfma_f32_16x16x32_bf16 v[20:23], v[172:175], v[214:217], v[20:23]
	v_mfma_f32_16x16x32_bf16 v[12:15], v[164:167], v[222:225], v[12:15]
	v_mfma_f32_16x16x32_bf16 v[4:7], v[172:175], v[222:225], v[4:7]
	s_setprio 0
	s_setprio 1
	v_mfma_f32_16x16x32_bf16 v[56:59], v[176:179], v[194:197], 0
	v_mfma_f32_16x16x32_bf16 v[48:51], v[186:189], v[194:197], 0
	v_mfma_f32_16x16x32_bf16 v[40:43], v[176:179], v[202:205], 0
	v_mfma_f32_16x16x32_bf16 v[32:35], v[186:189], v[202:205], 0
	v_mfma_f32_16x16x32_bf16 v[24:27], v[176:179], v[210:213], 0
	v_mfma_f32_16x16x32_bf16 v[16:19], v[186:189], v[210:213], 0
	v_mfma_f32_16x16x32_bf16 v[8:11], v[176:179], v[218:221], 0
	v_mfma_f32_16x16x32_bf16 v[0:3], v[186:189], v[218:221], 0
	v_mfma_f32_16x16x32_bf16 v[56:59], v[180:183], v[198:201], v[56:59]
	v_mfma_f32_16x16x32_bf16 v[48:51], v[190:193], v[198:201], v[48:51]
	v_mfma_f32_16x16x32_bf16 v[40:43], v[180:183], v[206:209], v[40:43]
	v_mfma_f32_16x16x32_bf16 v[32:35], v[190:193], v[206:209], v[32:35]
	v_mfma_f32_16x16x32_bf16 v[24:27], v[180:183], v[214:217], v[24:27]
	v_mfma_f32_16x16x32_bf16 v[16:19], v[190:193], v[214:217], v[16:19]
	v_mfma_f32_16x16x32_bf16 v[8:11], v[180:183], v[222:225], v[8:11]
	v_mfma_f32_16x16x32_bf16 v[0:3], v[190:193], v[222:225], v[0:3]
	s_setprio 0
	s_barrier
	s_add_i32 s76, 0, 0x18000
	v_add_u32_e32 v153, s76, v147
	s_add_i32 s77, 0, 0x1c000
	ds_read_b128 v[160:163], v153
	ds_read_b128 v[164:167], v153 offset:1024
	ds_read_b128 v[168:171], v153 offset:2048
	ds_read_b128 v[172:175], v153 offset:3072
	v_add_u32_e32 v153, s77, v147
	ds_read_b128 v[176:179], v153
	ds_read_b128 v[180:183], v153 offset:1024
	ds_read_b128 v[186:189], v153 offset:2048
	ds_read_b128 v[190:193], v153 offset:3072
	s_add_u32 s50, s50, 0x40000
	s_addc_u32 s51, s51, 0
	s_mov_b32 m0, s59
	v_lshl_add_u64 v[232:233], s[50:51], 0, v[134:135]
	ds_read_b128 v[194:197], v150 offset:32768
	ds_read_b128 v[198:201], v150 offset:33792
	ds_read_b128 v[202:205], v150 offset:34816
	ds_read_b128 v[206:209], v150 offset:35840
	ds_read_b128 v[210:213], v150 offset:36864
	ds_read_b128 v[214:217], v150 offset:37888
	ds_read_b128 v[218:221], v150 offset:38912
	ds_read_b128 v[222:225], v150 offset:39936
	global_load_lds_dwordx4 v[232:233], off
	v_lshl_add_u64 v[232:233], s[50:51], 0, v[130:131]
	s_mov_b32 m0, s60
	s_nop 0
	global_load_lds_dwordx4 v[232:233], off
	s_waitcnt vmcnt(8)
	s_waitcnt lgkmcnt(0)
	s_barrier
	s_setprio 1
	s_waitcnt lgkmcnt(0)
	v_mfma_f32_16x16x32_bf16 v[124:127], v[160:163], v[194:197], v[124:127]
	v_mfma_f32_16x16x32_bf16 v[124:127], v[164:167], v[198:201], v[124:127]
	v_mfma_f32_16x16x32_bf16 v[116:119], v[172:175], v[198:201], v[116:119]
	v_mfma_f32_16x16x32_bf16 v[116:119], v[168:171], v[194:197], v[116:119]
	v_mfma_f32_16x16x32_bf16 v[100:103], v[168:171], v[202:205], v[100:103]
	v_mfma_f32_16x16x32_bf16 v[100:103], v[172:175], v[206:209], v[100:103]
	v_mfma_f32_16x16x32_bf16 v[108:111], v[164:167], v[206:209], v[108:111]
	v_mfma_f32_16x16x32_bf16 v[108:111], v[160:163], v[202:205], v[108:111]
	v_mfma_f32_16x16x32_bf16 v[92:95], v[160:163], v[210:213], v[92:95]
	v_mfma_f32_16x16x32_bf16 v[92:95], v[164:167], v[214:217], v[92:95]
	v_mfma_f32_16x16x32_bf16 v[84:87], v[172:175], v[214:217], v[84:87]
	v_mfma_f32_16x16x32_bf16 v[84:87], v[168:171], v[210:213], v[84:87]
	v_mfma_f32_16x16x32_bf16 v[68:71], v[168:171], v[218:221], v[68:71]
	v_mfma_f32_16x16x32_bf16 v[68:71], v[172:175], v[222:225], v[68:71]
	v_mfma_f32_16x16x32_bf16 v[76:79], v[164:167], v[222:225], v[76:79]
	v_mfma_f32_16x16x32_bf16 v[76:79], v[160:163], v[218:221], v[76:79]
	s_setprio 0
	s_setprio 1
	v_mfma_f32_16x16x32_bf16 v[120:123], v[176:179], v[194:197], v[120:123]
	v_mfma_f32_16x16x32_bf16 v[120:123], v[180:183], v[198:201], v[120:123]
	v_mfma_f32_16x16x32_bf16 v[112:115], v[190:193], v[198:201], v[112:115]
	v_mfma_f32_16x16x32_bf16 v[112:115], v[186:189], v[194:197], v[112:115]
	v_mfma_f32_16x16x32_bf16 v[96:99], v[186:189], v[202:205], v[96:99]
	v_mfma_f32_16x16x32_bf16 v[96:99], v[190:193], v[206:209], v[96:99]
	v_mfma_f32_16x16x32_bf16 v[104:107], v[180:183], v[206:209], v[104:107]
	v_mfma_f32_16x16x32_bf16 v[104:107], v[176:179], v[202:205], v[104:107]
	v_mfma_f32_16x16x32_bf16 v[88:91], v[176:179], v[210:213], v[88:91]
	v_mfma_f32_16x16x32_bf16 v[88:91], v[180:183], v[214:217], v[88:91]
	v_mfma_f32_16x16x32_bf16 v[80:83], v[190:193], v[214:217], v[80:83]
	v_mfma_f32_16x16x32_bf16 v[80:83], v[186:189], v[210:213], v[80:83]
	v_mfma_f32_16x16x32_bf16 v[64:67], v[186:189], v[218:221], v[64:67]
	v_mfma_f32_16x16x32_bf16 v[64:67], v[190:193], v[222:225], v[64:67]
	v_mfma_f32_16x16x32_bf16 v[72:75], v[180:183], v[222:225], v[72:75]
	v_mfma_f32_16x16x32_bf16 v[72:75], v[176:179], v[218:221], v[72:75]
	s_setprio 0
	s_barrier
	s_add_i32 s50, s76, s54
	v_lshl_add_u64 v[154:155], v[154:155], 0, s[20:21]
	s_mov_b32 m0, s50
	ds_read_b128 v[194:197], v150 offset:49152
	ds_read_b128 v[198:201], v150 offset:50176
	ds_read_b128 v[202:205], v150 offset:51200
	ds_read_b128 v[206:209], v150 offset:52224
	ds_read_b128 v[210:213], v150 offset:53248
	ds_read_b128 v[214:217], v150 offset:54272
	ds_read_b128 v[218:221], v150 offset:55296
	ds_read_b128 v[222:225], v150 offset:56320
	global_load_lds_dwordx4 v[154:155], off
	s_add_i32 m0, s50, 0x2000
	s_add_u32 s48, s48, 0x40080
	v_lshl_add_u64 v[154:155], v[226:227], 0, s[20:21]
	s_addc_u32 s49, s49, 0
	s_add_i32 s50, s77, s54
	global_load_lds_dwordx4 v[154:155], off
	v_lshl_add_u64 v[154:155], s[48:49], 0, v[132:133]
	s_mov_b32 m0, s50
	s_nop 0
	global_load_lds_dwordx4 v[154:155], off
	v_lshl_add_u64 v[154:155], s[48:49], 0, v[128:129]
	s_add_i32 m0, s50, 0x2000
	s_nop 0
	global_load_lds_dwordx4 v[154:155], off
	v_lshl_add_u64 v[154:155], v[228:229], 0, s[20:21]
	s_mov_b32 m0, s62
	s_nop 0
	global_load_lds_dwordx4 v[154:155], off
	v_lshl_add_u64 v[154:155], v[230:231], 0, s[20:21]
	s_mov_b32 m0, s63
	s_nop 0
	global_load_lds_dwordx4 v[154:155], off
	s_waitcnt vmcnt(8)
	s_waitcnt lgkmcnt(0)
	s_barrier
	s_setprio 1
	s_waitcnt lgkmcnt(0)
	v_mfma_f32_16x16x32_bf16 v[60:63], v[160:163], v[194:197], v[60:63]
	v_mfma_f32_16x16x32_bf16 v[60:63], v[164:167], v[198:201], v[60:63]
	v_mfma_f32_16x16x32_bf16 v[52:55], v[172:175], v[198:201], v[52:55]
	v_mfma_f32_16x16x32_bf16 v[52:55], v[168:171], v[194:197], v[52:55]
	v_mfma_f32_16x16x32_bf16 v[36:39], v[168:171], v[202:205], v[36:39]
	v_mfma_f32_16x16x32_bf16 v[36:39], v[172:175], v[206:209], v[36:39]
	v_mfma_f32_16x16x32_bf16 v[44:47], v[164:167], v[206:209], v[44:47]
	v_mfma_f32_16x16x32_bf16 v[44:47], v[160:163], v[202:205], v[44:47]
	v_mfma_f32_16x16x32_bf16 v[28:31], v[160:163], v[210:213], v[28:31]
	v_mfma_f32_16x16x32_bf16 v[28:31], v[164:167], v[214:217], v[28:31]
	v_mfma_f32_16x16x32_bf16 v[20:23], v[172:175], v[214:217], v[20:23]
	v_mfma_f32_16x16x32_bf16 v[20:23], v[168:171], v[210:213], v[20:23]
	v_mfma_f32_16x16x32_bf16 v[4:7], v[168:171], v[218:221], v[4:7]
	v_mfma_f32_16x16x32_bf16 v[4:7], v[172:175], v[222:225], v[4:7]
	v_mfma_f32_16x16x32_bf16 v[12:15], v[164:167], v[222:225], v[12:15]
	v_mfma_f32_16x16x32_bf16 v[12:15], v[160:163], v[218:221], v[12:15]
	s_setprio 0
	s_setprio 1
	v_mfma_f32_16x16x32_bf16 v[56:59], v[176:179], v[194:197], v[56:59]
	v_mfma_f32_16x16x32_bf16 v[56:59], v[180:183], v[198:201], v[56:59]
	v_mfma_f32_16x16x32_bf16 v[48:51], v[190:193], v[198:201], v[48:51]
	v_mfma_f32_16x16x32_bf16 v[48:51], v[186:189], v[194:197], v[48:51]
	v_mfma_f32_16x16x32_bf16 v[32:35], v[186:189], v[202:205], v[32:35]
	v_mfma_f32_16x16x32_bf16 v[32:35], v[190:193], v[206:209], v[32:35]
	v_mfma_f32_16x16x32_bf16 v[40:43], v[180:183], v[206:209], v[40:43]
	v_mfma_f32_16x16x32_bf16 v[40:43], v[176:179], v[202:205], v[40:43]
	v_mfma_f32_16x16x32_bf16 v[24:27], v[176:179], v[210:213], v[24:27]
	v_mfma_f32_16x16x32_bf16 v[24:27], v[180:183], v[214:217], v[24:27]
	v_mfma_f32_16x16x32_bf16 v[16:19], v[190:193], v[214:217], v[16:19]
	v_mfma_f32_16x16x32_bf16 v[16:19], v[186:189], v[210:213], v[16:19]
	v_mfma_f32_16x16x32_bf16 v[0:3], v[186:189], v[218:221], v[0:3]
	v_mfma_f32_16x16x32_bf16 v[0:3], v[190:193], v[222:225], v[0:3]
	v_mfma_f32_16x16x32_bf16 v[8:11], v[180:183], v[222:225], v[8:11]
	v_mfma_f32_16x16x32_bf16 v[8:11], v[176:179], v[218:221], v[8:11]
	s_setprio 0
	s_barrier
	s_add_i32 s75, s75, 2
	s_add_u32 s73, s73, 0x100
	s_addc_u32 s74, s74, 0
	s_add_u32 s46, s46, 0x100
	s_addc_u32 s47, s47, 0
	s_branch .LBB0_527
.Lfa_4:
	v_add_u32_e32 v153, s66, v147
	ds_read_b128 v[160:163], v153
	ds_read_b128 v[164:167], v153 offset:1024
	ds_read_b128 v[168:171], v153 offset:2048
	ds_read_b128 v[172:175], v153 offset:3072
	v_add_u32_e32 v153, s67, v147
	ds_read_b128 v[176:179], v153
	ds_read_b128 v[180:183], v153 offset:1024
	ds_read_b128 v[186:189], v153 offset:2048
	ds_read_b128 v[190:193], v153 offset:3072
	s_add_u32 s50, s46, 0xfffc0080
	s_addc_u32 s51, s47, -1
	s_and_b64 s[48:49], s[48:49], exec
	s_cselect_b32 s51, s29, s51
	s_cselect_b32 s50, s70, s50
	s_cselect_b32 s49, s71, s74
	s_cselect_b32 s48, s72, s73
	v_lshl_add_u64 v[154:155], s[46:47], 0, v[138:139]
	s_add_i32 m0, s57, 0xc000
	ds_read_b128 v[194:197], v150
	ds_read_b128 v[198:201], v150 offset:1024
	ds_read_b128 v[202:205], v150 offset:2048
	ds_read_b128 v[206:209], v150 offset:3072
	ds_read_b128 v[210:213], v150 offset:4096
	ds_read_b128 v[214:217], v150 offset:5120
	ds_read_b128 v[218:221], v150 offset:6144
	ds_read_b128 v[222:225], v150 offset:7168
	global_load_lds_dwordx4 v[154:155], off
	v_lshl_add_u64 v[154:155], s[46:47], 0, v[136:137]
	s_add_i32 m0, s57, 0xe000
	s_nop 0
	global_load_lds_dwordx4 v[154:155], off
	s_waitcnt vmcnt(8)
	s_waitcnt lgkmcnt(0)
	s_barrier
	s_setprio 1
	s_waitcnt lgkmcnt(0)
	v_mfma_f32_16x16x32_bf16 v[124:127], v[160:163], v[194:197], 0
	v_mfma_f32_16x16x32_bf16 v[116:119], v[168:171], v[194:197], 0
	v_mfma_f32_16x16x32_bf16 v[108:111], v[160:163], v[202:205], 0
	v_mfma_f32_16x16x32_bf16 v[100:103], v[168:171], v[202:205], 0
	v_mfma_f32_16x16x32_bf16 v[92:95], v[160:163], v[210:213], 0
	v_mfma_f32_16x16x32_bf16 v[84:87], v[168:171], v[210:213], 0
	v_mfma_f32_16x16x32_bf16 v[76:79], v[160:163], v[218:221], 0
	v_mfma_f32_16x16x32_bf16 v[68:71], v[168:171], v[218:221], 0
	v_mfma_f32_16x16x32_bf16 v[124:127], v[164:167], v[198:201], v[124:127]
	v_mfma_f32_16x16x32_bf16 v[116:119], v[172:175], v[198:201], v[116:119]
	v_mfma_f32_16x16x32_bf16 v[108:111], v[164:167], v[206:209], v[108:111]
	v_mfma_f32_16x16x32_bf16 v[100:103], v[172:175], v[206:209], v[100:103]
	v_mfma_f32_16x16x32_bf16 v[92:95], v[164:167], v[214:217], v[92:95]
	v_mfma_f32_16x16x32_bf16 v[84:87], v[172:175], v[214:217], v[84:87]
	v_mfma_f32_16x16x32_bf16 v[76:79], v[164:167], v[222:225], v[76:79]
	v_mfma_f32_16x16x32_bf16 v[68:71], v[172:175], v[222:225], v[68:71]
	s_setprio 0
	s_setprio 1
	v_mfma_f32_16x16x32_bf16 v[120:123], v[176:179], v[194:197], 0
	v_mfma_f32_16x16x32_bf16 v[112:115], v[186:189], v[194:197], 0
	v_mfma_f32_16x16x32_bf16 v[104:107], v[176:179], v[202:205], 0
	v_mfma_f32_16x16x32_bf16 v[96:99], v[186:189], v[202:205], 0
	v_mfma_f32_16x16x32_bf16 v[88:91], v[176:179], v[210:213], 0
	v_mfma_f32_16x16x32_bf16 v[80:83], v[186:189], v[210:213], 0
	v_mfma_f32_16x16x32_bf16 v[72:75], v[176:179], v[218:221], 0
	v_mfma_f32_16x16x32_bf16 v[64:67], v[186:189], v[218:221], 0
	v_mfma_f32_16x16x32_bf16 v[120:123], v[180:183], v[198:201], v[120:123]
	v_mfma_f32_16x16x32_bf16 v[112:115], v[190:193], v[198:201], v[112:115]
	v_mfma_f32_16x16x32_bf16 v[104:107], v[180:183], v[206:209], v[104:107]
	v_mfma_f32_16x16x32_bf16 v[96:99], v[190:193], v[206:209], v[96:99]
	v_mfma_f32_16x16x32_bf16 v[88:91], v[180:183], v[214:217], v[88:91]
	v_mfma_f32_16x16x32_bf16 v[80:83], v[190:193], v[214:217], v[80:83]
	v_mfma_f32_16x16x32_bf16 v[72:75], v[180:183], v[222:225], v[72:75]
	v_mfma_f32_16x16x32_bf16 v[64:67], v[190:193], v[222:225], v[64:67]
	s_setprio 0
	s_barrier
	s_add_i32 s76, s66, s54
	v_lshl_add_u64 v[154:155], s[48:49], 0, v[132:133]
	s_mov_b32 m0, s76
	ds_read_b128 v[194:197], v150 offset:16384
	ds_read_b128 v[198:201], v150 offset:17408
	ds_read_b128 v[202:205], v150 offset:18432
	ds_read_b128 v[206:209], v150 offset:19456
	ds_read_b128 v[210:213], v150 offset:20480
	ds_read_b128 v[214:217], v150 offset:21504
	ds_read_b128 v[218:221], v150 offset:22528
	ds_read_b128 v[222:225], v150 offset:23552
	global_load_lds_dwordx4 v[154:155], off
	s_add_i32 m0, s76, 0x2000
	s_add_u32 s76, s48, 0x40000
	v_lshl_add_u64 v[226:227], s[48:49], 0, v[128:129]
	s_addc_u32 s77, s49, 0
	s_add_i32 s78, s67, s54
	global_load_lds_dwordx4 v[226:227], off
	v_lshl_add_u64 v[228:229], s[76:77], 0, v[132:133]
	s_mov_b32 m0, s78
	v_lshl_add_u64 v[230:231], s[50:51], 0, v[130:131]
	global_load_lds_dwordx4 v[228:229], off
	v_lshl_add_u64 v[228:229], s[76:77], 0, v[128:129]
	s_add_i32 m0, s78, 0x2000
	s_nop 0
	global_load_lds_dwordx4 v[228:229], off
	v_lshl_add_u64 v[228:229], s[50:51], 0, v[134:135]
	s_mov_b32 m0, s57
	s_nop 0
	global_load_lds_dwordx4 v[228:229], off
	s_mov_b32 m0, s58
	s_nop 0
	global_load_lds_dwordx4 v[230:231], off
	s_waitcnt vmcnt(8)
	s_waitcnt lgkmcnt(0)
	s_barrier
	s_setprio 1
	s_waitcnt lgkmcnt(0)
	v_mfma_f32_16x16x32_bf16 v[60:63], v[160:163], v[194:197], 0
	v_mfma_f32_16x16x32_bf16 v[52:55], v[168:171], v[194:197], 0
	v_mfma_f32_16x16x32_bf16 v[44:47], v[160:163], v[202:205], 0
	v_mfma_f32_16x16x32_bf16 v[36:39], v[168:171], v[202:205], 0
	v_mfma_f32_16x16x32_bf16 v[28:31], v[160:163], v[210:213], 0
	v_mfma_f32_16x16x32_bf16 v[20:23], v[168:171], v[210:213], 0
	v_mfma_f32_16x16x32_bf16 v[12:15], v[160:163], v[218:221], 0
	v_mfma_f32_16x16x32_bf16 v[4:7], v[168:171], v[218:221], 0
	v_mfma_f32_16x16x32_bf16 v[60:63], v[164:167], v[198:201], v[60:63]
	v_mfma_f32_16x16x32_bf16 v[52:55], v[172:175], v[198:201], v[52:55]
	v_mfma_f32_16x16x32_bf16 v[44:47], v[164:167], v[206:209], v[44:47]
	v_mfma_f32_16x16x32_bf16 v[36:39], v[172:175], v[206:209], v[36:39]
	v_mfma_f32_16x16x32_bf16 v[28:31], v[164:167], v[214:217], v[28:31]
	v_mfma_f32_16x16x32_bf16 v[20:23], v[172:175], v[214:217], v[20:23]
	v_mfma_f32_16x16x32_bf16 v[12:15], v[164:167], v[222:225], v[12:15]
	v_mfma_f32_16x16x32_bf16 v[4:7], v[172:175], v[222:225], v[4:7]
	s_setprio 0
	s_setprio 1
	v_mfma_f32_16x16x32_bf16 v[56:59], v[176:179], v[194:197], 0
	v_mfma_f32_16x16x32_bf16 v[48:51], v[186:189], v[194:197], 0
	v_mfma_f32_16x16x32_bf16 v[40:43], v[176:179], v[202:205], 0
	v_mfma_f32_16x16x32_bf16 v[32:35], v[186:189], v[202:205], 0
	v_mfma_f32_16x16x32_bf16 v[24:27], v[176:179], v[210:213], 0
	v_mfma_f32_16x16x32_bf16 v[16:19], v[186:189], v[210:213], 0
	v_mfma_f32_16x16x32_bf16 v[8:11], v[176:179], v[218:221], 0
	v_mfma_f32_16x16x32_bf16 v[0:3], v[186:189], v[218:221], 0
	v_mfma_f32_16x16x32_bf16 v[56:59], v[180:183], v[198:201], v[56:59]
	v_mfma_f32_16x16x32_bf16 v[48:51], v[190:193], v[198:201], v[48:51]
	v_mfma_f32_16x16x32_bf16 v[40:43], v[180:183], v[206:209], v[40:43]
	v_mfma_f32_16x16x32_bf16 v[32:35], v[190:193], v[206:209], v[32:35]
	v_mfma_f32_16x16x32_bf16 v[24:27], v[180:183], v[214:217], v[24:27]
	v_mfma_f32_16x16x32_bf16 v[16:19], v[190:193], v[214:217], v[16:19]
	v_mfma_f32_16x16x32_bf16 v[8:11], v[180:183], v[222:225], v[8:11]
	v_mfma_f32_16x16x32_bf16 v[0:3], v[190:193], v[222:225], v[0:3]
	s_setprio 0
	s_barrier
	s_add_i32 s76, 0, 0x18000
	v_add_u32_e32 v153, s76, v147
	s_add_i32 s77, 0, 0x1c000
	ds_read_b128 v[160:163], v153
	ds_read_b128 v[164:167], v153 offset:1024
	ds_read_b128 v[168:171], v153 offset:2048
	ds_read_b128 v[172:175], v153 offset:3072
	v_add_u32_e32 v153, s77, v147
	ds_read_b128 v[176:179], v153
	ds_read_b128 v[180:183], v153 offset:1024
	ds_read_b128 v[186:189], v153 offset:2048
	ds_read_b128 v[190:193], v153 offset:3072
	s_add_u32 s50, s50, 0x40000
	s_addc_u32 s51, s51, 0
	s_mov_b32 m0, s59
	v_lshl_add_u64 v[232:233], s[50:51], 0, v[134:135]
	ds_read_b128 v[194:197], v150 offset:32768
	ds_read_b128 v[198:201], v150 offset:33792
	ds_read_b128 v[202:205], v150 offset:34816
	ds_read_b128 v[206:209], v150 offset:35840
	ds_read_b128 v[210:213], v150 offset:36864
	ds_read_b128 v[214:217], v150 offset:37888
	ds_read_b128 v[218:221], v150 offset:38912
	ds_read_b128 v[222:225], v150 offset:39936
	global_load_lds_dwordx4 v[232:233], off
	v_lshl_add_u64 v[232:233], s[50:51], 0, v[130:131]
	s_mov_b32 m0, s60
	s_nop 0
	global_load_lds_dwordx4 v[232:233], off
	s_waitcnt vmcnt(8)
	s_waitcnt lgkmcnt(0)
	s_barrier
	s_setprio 1
	s_waitcnt lgkmcnt(0)
	v_mfma_f32_16x16x32_bf16 v[124:127], v[160:163], v[194:197], v[124:127]
	v_mfma_f32_16x16x32_bf16 v[124:127], v[164:167], v[198:201], v[124:127]
	v_mfma_f32_16x16x32_bf16 v[116:119], v[172:175], v[198:201], v[116:119]
	v_mfma_f32_16x16x32_bf16 v[116:119], v[168:171], v[194:197], v[116:119]
	v_mfma_f32_16x16x32_bf16 v[100:103], v[168:171], v[202:205], v[100:103]
	v_mfma_f32_16x16x32_bf16 v[100:103], v[172:175], v[206:209], v[100:103]
	v_mfma_f32_16x16x32_bf16 v[108:111], v[164:167], v[206:209], v[108:111]
	v_mfma_f32_16x16x32_bf16 v[108:111], v[160:163], v[202:205], v[108:111]
	v_mfma_f32_16x16x32_bf16 v[92:95], v[160:163], v[210:213], v[92:95]
	v_mfma_f32_16x16x32_bf16 v[92:95], v[164:167], v[214:217], v[92:95]
	v_mfma_f32_16x16x32_bf16 v[84:87], v[172:175], v[214:217], v[84:87]
	v_mfma_f32_16x16x32_bf16 v[84:87], v[168:171], v[210:213], v[84:87]
	v_mfma_f32_16x16x32_bf16 v[68:71], v[168:171], v[218:221], v[68:71]
	v_mfma_f32_16x16x32_bf16 v[68:71], v[172:175], v[222:225], v[68:71]
	v_mfma_f32_16x16x32_bf16 v[76:79], v[164:167], v[222:225], v[76:79]
	v_mfma_f32_16x16x32_bf16 v[76:79], v[160:163], v[218:221], v[76:79]
	s_setprio 0
	s_setprio 1
	v_mfma_f32_16x16x32_bf16 v[120:123], v[176:179], v[194:197], v[120:123]
	v_mfma_f32_16x16x32_bf16 v[120:123], v[180:183], v[198:201], v[120:123]
	v_mfma_f32_16x16x32_bf16 v[112:115], v[190:193], v[198:201], v[112:115]
	v_mfma_f32_16x16x32_bf16 v[112:115], v[186:189], v[194:197], v[112:115]
	v_mfma_f32_16x16x32_bf16 v[96:99], v[186:189], v[202:205], v[96:99]
	v_mfma_f32_16x16x32_bf16 v[96:99], v[190:193], v[206:209], v[96:99]
	v_mfma_f32_16x16x32_bf16 v[104:107], v[180:183], v[206:209], v[104:107]
	v_mfma_f32_16x16x32_bf16 v[104:107], v[176:179], v[202:205], v[104:107]
	v_mfma_f32_16x16x32_bf16 v[88:91], v[176:179], v[210:213], v[88:91]
	v_mfma_f32_16x16x32_bf16 v[88:91], v[180:183], v[214:217], v[88:91]
	v_mfma_f32_16x16x32_bf16 v[80:83], v[190:193], v[214:217], v[80:83]
	v_mfma_f32_16x16x32_bf16 v[80:83], v[186:189], v[210:213], v[80:83]
	v_mfma_f32_16x16x32_bf16 v[64:67], v[186:189], v[218:221], v[64:67]
	v_mfma_f32_16x16x32_bf16 v[64:67], v[190:193], v[222:225], v[64:67]
	v_mfma_f32_16x16x32_bf16 v[72:75], v[180:183], v[222:225], v[72:75]
	v_mfma_f32_16x16x32_bf16 v[72:75], v[176:179], v[218:221], v[72:75]
	s_setprio 0
	s_barrier
	s_add_i32 s50, s76, s54
	v_lshl_add_u64 v[154:155], v[154:155], 0, s[20:21]
	s_mov_b32 m0, s50
	ds_read_b128 v[194:197], v150 offset:49152
	ds_read_b128 v[198:201], v150 offset:50176
	ds_read_b128 v[202:205], v150 offset:51200
	ds_read_b128 v[206:209], v150 offset:52224
	ds_read_b128 v[210:213], v150 offset:53248
	ds_read_b128 v[214:217], v150 offset:54272
	ds_read_b128 v[218:221], v150 offset:55296
	ds_read_b128 v[222:225], v150 offset:56320
	global_load_lds_dwordx4 v[154:155], off
	s_add_i32 m0, s50, 0x2000
	s_add_u32 s48, s48, 0x40080
	v_lshl_add_u64 v[154:155], v[226:227], 0, s[20:21]
	s_addc_u32 s49, s49, 0
	s_add_i32 s50, s77, s54
	global_load_lds_dwordx4 v[154:155], off
	v_lshl_add_u64 v[154:155], s[48:49], 0, v[132:133]
	s_mov_b32 m0, s50
	s_nop 0
	global_load_lds_dwordx4 v[154:155], off
	v_lshl_add_u64 v[154:155], s[48:49], 0, v[128:129]
	s_add_i32 m0, s50, 0x2000
	s_nop 0
	global_load_lds_dwordx4 v[154:155], off
	v_lshl_add_u64 v[154:155], v[228:229], 0, s[20:21]
	s_mov_b32 m0, s62
	s_nop 0
	global_load_lds_dwordx4 v[154:155], off
	v_lshl_add_u64 v[154:155], v[230:231], 0, s[20:21]
	s_mov_b32 m0, s63
	s_nop 0
	global_load_lds_dwordx4 v[154:155], off
	s_waitcnt vmcnt(8)
	s_waitcnt lgkmcnt(0)
	s_barrier
	s_setprio 1
	s_waitcnt lgkmcnt(0)
	v_mfma_f32_16x16x32_bf16 v[60:63], v[160:163], v[194:197], v[60:63]
	v_mfma_f32_16x16x32_bf16 v[60:63], v[164:167], v[198:201], v[60:63]
	v_mfma_f32_16x16x32_bf16 v[52:55], v[172:175], v[198:201], v[52:55]
	v_mfma_f32_16x16x32_bf16 v[52:55], v[168:171], v[194:197], v[52:55]
	v_mfma_f32_16x16x32_bf16 v[36:39], v[168:171], v[202:205], v[36:39]
	v_mfma_f32_16x16x32_bf16 v[36:39], v[172:175], v[206:209], v[36:39]
	v_mfma_f32_16x16x32_bf16 v[44:47], v[164:167], v[206:209], v[44:47]
	v_mfma_f32_16x16x32_bf16 v[44:47], v[160:163], v[202:205], v[44:47]
	v_mfma_f32_16x16x32_bf16 v[28:31], v[160:163], v[210:213], v[28:31]
	v_mfma_f32_16x16x32_bf16 v[28:31], v[164:167], v[214:217], v[28:31]
	v_mfma_f32_16x16x32_bf16 v[20:23], v[172:175], v[214:217], v[20:23]
	v_mfma_f32_16x16x32_bf16 v[20:23], v[168:171], v[210:213], v[20:23]
	v_mfma_f32_16x16x32_bf16 v[4:7], v[168:171], v[218:221], v[4:7]
	v_mfma_f32_16x16x32_bf16 v[4:7], v[172:175], v[222:225], v[4:7]
	v_mfma_f32_16x16x32_bf16 v[12:15], v[164:167], v[222:225], v[12:15]
	v_mfma_f32_16x16x32_bf16 v[12:15], v[160:163], v[218:221], v[12:15]
	s_setprio 0
	s_setprio 1
	v_mfma_f32_16x16x32_bf16 v[56:59], v[176:179], v[194:197], v[56:59]
	v_mfma_f32_16x16x32_bf16 v[56:59], v[180:183], v[198:201], v[56:59]
	v_mfma_f32_16x16x32_bf16 v[48:51], v[190:193], v[198:201], v[48:51]
	v_mfma_f32_16x16x32_bf16 v[48:51], v[186:189], v[194:197], v[48:51]
	v_mfma_f32_16x16x32_bf16 v[32:35], v[186:189], v[202:205], v[32:35]
	v_mfma_f32_16x16x32_bf16 v[32:35], v[190:193], v[206:209], v[32:35]
	v_mfma_f32_16x16x32_bf16 v[40:43], v[180:183], v[206:209], v[40:43]
	v_mfma_f32_16x16x32_bf16 v[40:43], v[176:179], v[202:205], v[40:43]
	v_mfma_f32_16x16x32_bf16 v[24:27], v[176:179], v[210:213], v[24:27]
	v_mfma_f32_16x16x32_bf16 v[24:27], v[180:183], v[214:217], v[24:27]
	v_mfma_f32_16x16x32_bf16 v[16:19], v[190:193], v[214:217], v[16:19]
	v_mfma_f32_16x16x32_bf16 v[16:19], v[186:189], v[210:213], v[16:19]
	v_mfma_f32_16x16x32_bf16 v[0:3], v[186:189], v[218:221], v[0:3]
	v_mfma_f32_16x16x32_bf16 v[0:3], v[190:193], v[222:225], v[0:3]
	v_mfma_f32_16x16x32_bf16 v[8:11], v[180:183], v[222:225], v[8:11]
	v_mfma_f32_16x16x32_bf16 v[8:11], v[176:179], v[218:221], v[8:11]
	s_setprio 0
	s_barrier
	s_add_i32 s75, s75, 2
	s_add_u32 s73, s73, 0x100
	s_addc_u32 s74, s74, 0
	s_add_u32 s46, s46, 0x100
	s_addc_u32 s47, s47, 0
	s_branch .LBB0_527
.LBB0_526:
	v_add_u32_e32 v153, s66, v147
	ds_read_b128 v[160:163], v153
	ds_read_b128 v[164:167], v153 offset:1024
	ds_read_b128 v[168:171], v153 offset:2048
	ds_read_b128 v[172:175], v153 offset:3072
	v_add_u32_e32 v153, s67, v147
	ds_read_b128 v[176:179], v153
	ds_read_b128 v[180:183], v153 offset:1024
	ds_read_b128 v[186:189], v153 offset:2048
	ds_read_b128 v[190:193], v153 offset:3072
	s_add_u32 s50, s46, 0xfffc0080
	s_addc_u32 s51, s47, -1
	s_and_b64 s[48:49], s[48:49], exec
	s_cselect_b32 s51, s29, s51
	s_cselect_b32 s50, s70, s50
	s_cselect_b32 s49, s71, s74
	s_cselect_b32 s48, s72, s73
	v_lshl_add_u64 v[154:155], s[46:47], 0, v[138:139]
	s_add_i32 m0, s57, 0xc000
	ds_read_b128 v[194:197], v150
	ds_read_b128 v[198:201], v150 offset:1024
	ds_read_b128 v[202:205], v150 offset:2048
	ds_read_b128 v[206:209], v150 offset:3072
	ds_read_b128 v[210:213], v150 offset:4096
	ds_read_b128 v[214:217], v150 offset:5120
	ds_read_b128 v[218:221], v150 offset:6144
	ds_read_b128 v[222:225], v150 offset:7168
	global_load_lds_dwordx4 v[154:155], off
	v_lshl_add_u64 v[154:155], s[46:47], 0, v[136:137]
	s_add_i32 m0, s57, 0xe000
	s_nop 0
	global_load_lds_dwordx4 v[154:155], off
	s_waitcnt vmcnt(8)
	s_waitcnt lgkmcnt(0)
	s_barrier
	s_setprio 1
	s_waitcnt lgkmcnt(0)
	v_mfma_f32_16x16x32_bf16 v[124:127], v[160:163], v[194:197], v[124:127]
	v_mfma_f32_16x16x32_bf16 v[124:127], v[164:167], v[198:201], v[124:127]
	v_mfma_f32_16x16x32_bf16 v[116:119], v[172:175], v[198:201], v[116:119]
	v_mfma_f32_16x16x32_bf16 v[116:119], v[168:171], v[194:197], v[116:119]
	v_mfma_f32_16x16x32_bf16 v[100:103], v[168:171], v[202:205], v[100:103]
	v_mfma_f32_16x16x32_bf16 v[100:103], v[172:175], v[206:209], v[100:103]
	v_mfma_f32_16x16x32_bf16 v[108:111], v[164:167], v[206:209], v[108:111]
	v_mfma_f32_16x16x32_bf16 v[108:111], v[160:163], v[202:205], v[108:111]
	v_mfma_f32_16x16x32_bf16 v[92:95], v[160:163], v[210:213], v[92:95]
	v_mfma_f32_16x16x32_bf16 v[92:95], v[164:167], v[214:217], v[92:95]
	v_mfma_f32_16x16x32_bf16 v[84:87], v[172:175], v[214:217], v[84:87]
	v_mfma_f32_16x16x32_bf16 v[84:87], v[168:171], v[210:213], v[84:87]
	v_mfma_f32_16x16x32_bf16 v[68:71], v[168:171], v[218:221], v[68:71]
	v_mfma_f32_16x16x32_bf16 v[68:71], v[172:175], v[222:225], v[68:71]
	v_mfma_f32_16x16x32_bf16 v[76:79], v[164:167], v[222:225], v[76:79]
	v_mfma_f32_16x16x32_bf16 v[76:79], v[160:163], v[218:221], v[76:79]
	s_setprio 0
	s_setprio 1
	v_mfma_f32_16x16x32_bf16 v[120:123], v[176:179], v[194:197], v[120:123]
	v_mfma_f32_16x16x32_bf16 v[120:123], v[180:183], v[198:201], v[120:123]
	v_mfma_f32_16x16x32_bf16 v[112:115], v[190:193], v[198:201], v[112:115]
	v_mfma_f32_16x16x32_bf16 v[112:115], v[186:189], v[194:197], v[112:115]
	v_mfma_f32_16x16x32_bf16 v[96:99], v[186:189], v[202:205], v[96:99]
	v_mfma_f32_16x16x32_bf16 v[96:99], v[190:193], v[206:209], v[96:99]
	v_mfma_f32_16x16x32_bf16 v[104:107], v[180:183], v[206:209], v[104:107]
	v_mfma_f32_16x16x32_bf16 v[104:107], v[176:179], v[202:205], v[104:107]
	v_mfma_f32_16x16x32_bf16 v[88:91], v[176:179], v[210:213], v[88:91]
	v_mfma_f32_16x16x32_bf16 v[88:91], v[180:183], v[214:217], v[88:91]
	v_mfma_f32_16x16x32_bf16 v[80:83], v[190:193], v[214:217], v[80:83]
	v_mfma_f32_16x16x32_bf16 v[80:83], v[186:189], v[210:213], v[80:83]
	v_mfma_f32_16x16x32_bf16 v[64:67], v[186:189], v[218:221], v[64:67]
	v_mfma_f32_16x16x32_bf16 v[64:67], v[190:193], v[222:225], v[64:67]
	v_mfma_f32_16x16x32_bf16 v[72:75], v[180:183], v[222:225], v[72:75]
	v_mfma_f32_16x16x32_bf16 v[72:75], v[176:179], v[218:221], v[72:75]
	s_setprio 0
	s_barrier
	s_add_i32 s76, s66, s54
	v_lshl_add_u64 v[154:155], s[48:49], 0, v[132:133]
	s_mov_b32 m0, s76
	ds_read_b128 v[194:197], v150 offset:16384
	ds_read_b128 v[198:201], v150 offset:17408
	ds_read_b128 v[202:205], v150 offset:18432
	ds_read_b128 v[206:209], v150 offset:19456
	ds_read_b128 v[210:213], v150 offset:20480
	ds_read_b128 v[214:217], v150 offset:21504
	ds_read_b128 v[218:221], v150 offset:22528
	ds_read_b128 v[222:225], v150 offset:23552
	global_load_lds_dwordx4 v[154:155], off
	s_add_i32 m0, s76, 0x2000
	s_add_u32 s76, s48, 0x40000
	v_lshl_add_u64 v[226:227], s[48:49], 0, v[128:129]
	s_addc_u32 s77, s49, 0
	s_add_i32 s78, s67, s54
	global_load_lds_dwordx4 v[226:227], off
	v_lshl_add_u64 v[228:229], s[76:77], 0, v[132:133]
	s_mov_b32 m0, s78
	v_lshl_add_u64 v[230:231], s[50:51], 0, v[130:131]
	global_load_lds_dwordx4 v[228:229], off
	v_lshl_add_u64 v[228:229], s[76:77], 0, v[128:129]
	s_add_i32 m0, s78, 0x2000
	s_nop 0
	global_load_lds_dwordx4 v[228:229], off
	v_lshl_add_u64 v[228:229], s[50:51], 0, v[134:135]
	s_mov_b32 m0, s57
	s_nop 0
	global_load_lds_dwordx4 v[228:229], off
	s_mov_b32 m0, s58
	s_nop 0
	global_load_lds_dwordx4 v[230:231], off
	s_waitcnt vmcnt(8)
	s_waitcnt lgkmcnt(0)
	s_barrier
	s_setprio 1
	s_waitcnt lgkmcnt(0)
	v_mfma_f32_16x16x32_bf16 v[60:63], v[160:163], v[194:197], v[60:63]
	v_mfma_f32_16x16x32_bf16 v[60:63], v[164:167], v[198:201], v[60:63]
	v_mfma_f32_16x16x32_bf16 v[52:55], v[172:175], v[198:201], v[52:55]
	v_mfma_f32_16x16x32_bf16 v[52:55], v[168:171], v[194:197], v[52:55]
	v_mfma_f32_16x16x32_bf16 v[36:39], v[168:171], v[202:205], v[36:39]
	v_mfma_f32_16x16x32_bf16 v[36:39], v[172:175], v[206:209], v[36:39]
	v_mfma_f32_16x16x32_bf16 v[44:47], v[164:167], v[206:209], v[44:47]
	v_mfma_f32_16x16x32_bf16 v[44:47], v[160:163], v[202:205], v[44:47]
	v_mfma_f32_16x16x32_bf16 v[28:31], v[160:163], v[210:213], v[28:31]
	v_mfma_f32_16x16x32_bf16 v[28:31], v[164:167], v[214:217], v[28:31]
	v_mfma_f32_16x16x32_bf16 v[20:23], v[172:175], v[214:217], v[20:23]
	v_mfma_f32_16x16x32_bf16 v[20:23], v[168:171], v[210:213], v[20:23]
	v_mfma_f32_16x16x32_bf16 v[4:7], v[168:171], v[218:221], v[4:7]
	v_mfma_f32_16x16x32_bf16 v[4:7], v[172:175], v[222:225], v[4:7]
	v_mfma_f32_16x16x32_bf16 v[12:15], v[164:167], v[222:225], v[12:15]
	v_mfma_f32_16x16x32_bf16 v[12:15], v[160:163], v[218:221], v[12:15]
	s_setprio 0
	s_setprio 1
	v_mfma_f32_16x16x32_bf16 v[56:59], v[176:179], v[194:197], v[56:59]
	v_mfma_f32_16x16x32_bf16 v[56:59], v[180:183], v[198:201], v[56:59]
	v_mfma_f32_16x16x32_bf16 v[48:51], v[190:193], v[198:201], v[48:51]
	v_mfma_f32_16x16x32_bf16 v[48:51], v[186:189], v[194:197], v[48:51]
	v_mfma_f32_16x16x32_bf16 v[32:35], v[186:189], v[202:205], v[32:35]
	v_mfma_f32_16x16x32_bf16 v[32:35], v[190:193], v[206:209], v[32:35]
	v_mfma_f32_16x16x32_bf16 v[40:43], v[180:183], v[206:209], v[40:43]
	v_mfma_f32_16x16x32_bf16 v[40:43], v[176:179], v[202:205], v[40:43]
	v_mfma_f32_16x16x32_bf16 v[24:27], v[176:179], v[210:213], v[24:27]
	v_mfma_f32_16x16x32_bf16 v[24:27], v[180:183], v[214:217], v[24:27]
	v_mfma_f32_16x16x32_bf16 v[16:19], v[190:193], v[214:217], v[16:19]
	v_mfma_f32_16x16x32_bf16 v[16:19], v[186:189], v[210:213], v[16:19]
	v_mfma_f32_16x16x32_bf16 v[0:3], v[186:189], v[218:221], v[0:3]
	v_mfma_f32_16x16x32_bf16 v[0:3], v[190:193], v[222:225], v[0:3]
	v_mfma_f32_16x16x32_bf16 v[8:11], v[180:183], v[222:225], v[8:11]
	v_mfma_f32_16x16x32_bf16 v[8:11], v[176:179], v[218:221], v[8:11]
	s_setprio 0
	s_barrier
	s_add_i32 s76, 0, 0x18000
	v_add_u32_e32 v153, s76, v147
	s_add_i32 s77, 0, 0x1c000
	ds_read_b128 v[160:163], v153
	ds_read_b128 v[164:167], v153 offset:1024
	ds_read_b128 v[168:171], v153 offset:2048
	ds_read_b128 v[172:175], v153 offset:3072
	v_add_u32_e32 v153, s77, v147
	ds_read_b128 v[176:179], v153
	ds_read_b128 v[180:183], v153 offset:1024
	ds_read_b128 v[186:189], v153 offset:2048
	ds_read_b128 v[190:193], v153 offset:3072
	s_add_u32 s50, s50, 0x40000
	s_addc_u32 s51, s51, 0
	s_mov_b32 m0, s59
	v_lshl_add_u64 v[232:233], s[50:51], 0, v[134:135]
	ds_read_b128 v[194:197], v150 offset:32768
	ds_read_b128 v[198:201], v150 offset:33792
	ds_read_b128 v[202:205], v150 offset:34816
	ds_read_b128 v[206:209], v150 offset:35840
	ds_read_b128 v[210:213], v150 offset:36864
	ds_read_b128 v[214:217], v150 offset:37888
	ds_read_b128 v[218:221], v150 offset:38912
	ds_read_b128 v[222:225], v150 offset:39936
	global_load_lds_dwordx4 v[232:233], off
	v_lshl_add_u64 v[232:233], s[50:51], 0, v[130:131]
	s_mov_b32 m0, s60
	s_nop 0
	global_load_lds_dwordx4 v[232:233], off
	s_waitcnt vmcnt(8)
	s_waitcnt lgkmcnt(0)
	s_barrier
	s_setprio 1
	s_waitcnt lgkmcnt(0)
	v_mfma_f32_16x16x32_bf16 v[124:127], v[160:163], v[194:197], v[124:127]
	v_mfma_f32_16x16x32_bf16 v[124:127], v[164:167], v[198:201], v[124:127]
	v_mfma_f32_16x16x32_bf16 v[116:119], v[172:175], v[198:201], v[116:119]
	v_mfma_f32_16x16x32_bf16 v[116:119], v[168:171], v[194:197], v[116:119]
	v_mfma_f32_16x16x32_bf16 v[100:103], v[168:171], v[202:205], v[100:103]
	v_mfma_f32_16x16x32_bf16 v[100:103], v[172:175], v[206:209], v[100:103]
	v_mfma_f32_16x16x32_bf16 v[108:111], v[164:167], v[206:209], v[108:111]
	v_mfma_f32_16x16x32_bf16 v[108:111], v[160:163], v[202:205], v[108:111]
	v_mfma_f32_16x16x32_bf16 v[92:95], v[160:163], v[210:213], v[92:95]
	v_mfma_f32_16x16x32_bf16 v[92:95], v[164:167], v[214:217], v[92:95]
	v_mfma_f32_16x16x32_bf16 v[84:87], v[172:175], v[214:217], v[84:87]
	v_mfma_f32_16x16x32_bf16 v[84:87], v[168:171], v[210:213], v[84:87]
	v_mfma_f32_16x16x32_bf16 v[68:71], v[168:171], v[218:221], v[68:71]
	v_mfma_f32_16x16x32_bf16 v[68:71], v[172:175], v[222:225], v[68:71]
	v_mfma_f32_16x16x32_bf16 v[76:79], v[164:167], v[222:225], v[76:79]
	v_mfma_f32_16x16x32_bf16 v[76:79], v[160:163], v[218:221], v[76:79]
	s_setprio 0
	s_setprio 1
	v_mfma_f32_16x16x32_bf16 v[120:123], v[176:179], v[194:197], v[120:123]
	v_mfma_f32_16x16x32_bf16 v[120:123], v[180:183], v[198:201], v[120:123]
	v_mfma_f32_16x16x32_bf16 v[112:115], v[190:193], v[198:201], v[112:115]
	v_mfma_f32_16x16x32_bf16 v[112:115], v[186:189], v[194:197], v[112:115]
	v_mfma_f32_16x16x32_bf16 v[96:99], v[186:189], v[202:205], v[96:99]
	v_mfma_f32_16x16x32_bf16 v[96:99], v[190:193], v[206:209], v[96:99]
	v_mfma_f32_16x16x32_bf16 v[104:107], v[180:183], v[206:209], v[104:107]
	v_mfma_f32_16x16x32_bf16 v[104:107], v[176:179], v[202:205], v[104:107]
	v_mfma_f32_16x16x32_bf16 v[88:91], v[176:179], v[210:213], v[88:91]
	v_mfma_f32_16x16x32_bf16 v[88:91], v[180:183], v[214:217], v[88:91]
	v_mfma_f32_16x16x32_bf16 v[80:83], v[190:193], v[214:217], v[80:83]
	v_mfma_f32_16x16x32_bf16 v[80:83], v[186:189], v[210:213], v[80:83]
	v_mfma_f32_16x16x32_bf16 v[64:67], v[186:189], v[218:221], v[64:67]
	v_mfma_f32_16x16x32_bf16 v[64:67], v[190:193], v[222:225], v[64:67]
	v_mfma_f32_16x16x32_bf16 v[72:75], v[180:183], v[222:225], v[72:75]
	v_mfma_f32_16x16x32_bf16 v[72:75], v[176:179], v[218:221], v[72:75]
	s_setprio 0
	s_barrier
	s_add_i32 s50, s76, s54
	v_lshl_add_u64 v[154:155], v[154:155], 0, s[20:21]
	s_mov_b32 m0, s50
	ds_read_b128 v[194:197], v150 offset:49152
	ds_read_b128 v[198:201], v150 offset:50176
	ds_read_b128 v[202:205], v150 offset:51200
	ds_read_b128 v[206:209], v150 offset:52224
	ds_read_b128 v[210:213], v150 offset:53248
	ds_read_b128 v[214:217], v150 offset:54272
	ds_read_b128 v[218:221], v150 offset:55296
	ds_read_b128 v[222:225], v150 offset:56320
	global_load_lds_dwordx4 v[154:155], off
	s_add_i32 m0, s50, 0x2000
	s_add_u32 s48, s48, 0x40080
	v_lshl_add_u64 v[154:155], v[226:227], 0, s[20:21]
	s_addc_u32 s49, s49, 0
	s_add_i32 s50, s77, s54
	global_load_lds_dwordx4 v[154:155], off
	v_lshl_add_u64 v[154:155], s[48:49], 0, v[132:133]
	s_mov_b32 m0, s50
	s_nop 0
	global_load_lds_dwordx4 v[154:155], off
	v_lshl_add_u64 v[154:155], s[48:49], 0, v[128:129]
	s_add_i32 m0, s50, 0x2000
	s_nop 0
	global_load_lds_dwordx4 v[154:155], off
	v_lshl_add_u64 v[154:155], v[228:229], 0, s[20:21]
	s_mov_b32 m0, s62
	s_nop 0
	global_load_lds_dwordx4 v[154:155], off
	v_lshl_add_u64 v[154:155], v[230:231], 0, s[20:21]
	s_mov_b32 m0, s63
	s_nop 0
	global_load_lds_dwordx4 v[154:155], off
	s_waitcnt vmcnt(8)
	s_waitcnt lgkmcnt(0)
	s_barrier
	s_setprio 1
	s_waitcnt lgkmcnt(0)
	v_mfma_f32_16x16x32_bf16 v[60:63], v[160:163], v[194:197], v[60:63]
	v_mfma_f32_16x16x32_bf16 v[60:63], v[164:167], v[198:201], v[60:63]
	v_mfma_f32_16x16x32_bf16 v[52:55], v[172:175], v[198:201], v[52:55]
	v_mfma_f32_16x16x32_bf16 v[52:55], v[168:171], v[194:197], v[52:55]
	v_mfma_f32_16x16x32_bf16 v[36:39], v[168:171], v[202:205], v[36:39]
	v_mfma_f32_16x16x32_bf16 v[36:39], v[172:175], v[206:209], v[36:39]
	v_mfma_f32_16x16x32_bf16 v[44:47], v[164:167], v[206:209], v[44:47]
	v_mfma_f32_16x16x32_bf16 v[44:47], v[160:163], v[202:205], v[44:47]
	v_mfma_f32_16x16x32_bf16 v[28:31], v[160:163], v[210:213], v[28:31]
	v_mfma_f32_16x16x32_bf16 v[28:31], v[164:167], v[214:217], v[28:31]
	v_mfma_f32_16x16x32_bf16 v[20:23], v[172:175], v[214:217], v[20:23]
	v_mfma_f32_16x16x32_bf16 v[20:23], v[168:171], v[210:213], v[20:23]
	v_mfma_f32_16x16x32_bf16 v[4:7], v[168:171], v[218:221], v[4:7]
	v_mfma_f32_16x16x32_bf16 v[4:7], v[172:175], v[222:225], v[4:7]
	v_mfma_f32_16x16x32_bf16 v[12:15], v[164:167], v[222:225], v[12:15]
	v_mfma_f32_16x16x32_bf16 v[12:15], v[160:163], v[218:221], v[12:15]
	s_setprio 0
	s_setprio 1
	v_mfma_f32_16x16x32_bf16 v[56:59], v[176:179], v[194:197], v[56:59]
	v_mfma_f32_16x16x32_bf16 v[56:59], v[180:183], v[198:201], v[56:59]
	v_mfma_f32_16x16x32_bf16 v[48:51], v[190:193], v[198:201], v[48:51]
	v_mfma_f32_16x16x32_bf16 v[48:51], v[186:189], v[194:197], v[48:51]
	v_mfma_f32_16x16x32_bf16 v[32:35], v[186:189], v[202:205], v[32:35]
	v_mfma_f32_16x16x32_bf16 v[32:35], v[190:193], v[206:209], v[32:35]
	v_mfma_f32_16x16x32_bf16 v[40:43], v[180:183], v[206:209], v[40:43]
	v_mfma_f32_16x16x32_bf16 v[40:43], v[176:179], v[202:205], v[40:43]
	v_mfma_f32_16x16x32_bf16 v[24:27], v[176:179], v[210:213], v[24:27]
	v_mfma_f32_16x16x32_bf16 v[24:27], v[180:183], v[214:217], v[24:27]
	v_mfma_f32_16x16x32_bf16 v[16:19], v[190:193], v[214:217], v[16:19]
	v_mfma_f32_16x16x32_bf16 v[16:19], v[186:189], v[210:213], v[16:19]
	v_mfma_f32_16x16x32_bf16 v[0:3], v[186:189], v[218:221], v[0:3]
	v_mfma_f32_16x16x32_bf16 v[0:3], v[190:193], v[222:225], v[0:3]
	v_mfma_f32_16x16x32_bf16 v[8:11], v[180:183], v[222:225], v[8:11]
	v_mfma_f32_16x16x32_bf16 v[8:11], v[176:179], v[218:221], v[8:11]
	s_setprio 0
	s_barrier
	s_add_i32 s75, s75, 2
	s_add_u32 s73, s73, 0x100
	s_addc_u32 s74, s74, 0
	s_add_u32 s46, s46, 0x100
	s_addc_u32 s47, s47, 0
	s_cmp_gt_u32 s75, 13
	s_cbranch_scc1 .LBB0_529

.Llast_4:
	v_add_u32_e32 v153, s66, v147
	ds_read_b128 v[160:163], v153
	ds_read_b128 v[164:167], v153 offset:1024
	ds_read_b128 v[168:171], v153 offset:2048
	ds_read_b128 v[172:175], v153 offset:3072
	v_add_u32_e32 v153, s67, v147
	ds_read_b128 v[176:179], v153
	ds_read_b128 v[180:183], v153 offset:1024
	ds_read_b128 v[186:189], v153 offset:2048
	ds_read_b128 v[190:193], v153 offset:3072
	s_add_u32 s50, s46, 0xfffc0080
	s_addc_u32 s51, s47, -1
	s_and_b64 s[48:49], s[48:49], exec
	s_cselect_b32 s51, s29, s51
	s_cselect_b32 s50, s70, s50
	s_cselect_b32 s49, s71, s74
	s_cselect_b32 s48, s72, s73
	v_lshl_add_u64 v[154:155], s[46:47], 0, v[138:139]
	s_add_i32 m0, s57, 0xc000
	ds_read_b128 v[194:197], v150
	ds_read_b128 v[198:201], v150 offset:1024
	ds_read_b128 v[202:205], v150 offset:2048
	ds_read_b128 v[206:209], v150 offset:3072
	ds_read_b128 v[210:213], v150 offset:4096
	ds_read_b128 v[214:217], v150 offset:5120
	ds_read_b128 v[218:221], v150 offset:6144
	ds_read_b128 v[222:225], v150 offset:7168
	global_load_lds_dwordx4 v[154:155], off
	v_lshl_add_u64 v[154:155], s[46:47], 0, v[136:137]
	s_add_i32 m0, s57, 0xe000
	s_nop 0
	global_load_lds_dwordx4 v[154:155], off
	s_waitcnt vmcnt(8)
	s_waitcnt lgkmcnt(0)
	s_barrier
	s_setprio 1
	s_waitcnt lgkmcnt(0)
	v_mfma_f32_16x16x32_bf16 v[124:127], v[160:163], v[194:197], v[124:127]
	v_mfma_f32_16x16x32_bf16 v[124:127], v[164:167], v[198:201], v[124:127]
	v_mfma_f32_16x16x32_bf16 v[116:119], v[172:175], v[198:201], v[116:119]
	v_mfma_f32_16x16x32_bf16 v[116:119], v[168:171], v[194:197], v[116:119]
	v_mfma_f32_16x16x32_bf16 v[100:103], v[168:171], v[202:205], v[100:103]
	v_mfma_f32_16x16x32_bf16 v[100:103], v[172:175], v[206:209], v[100:103]
	v_mfma_f32_16x16x32_bf16 v[108:111], v[164:167], v[206:209], v[108:111]
	v_mfma_f32_16x16x32_bf16 v[108:111], v[160:163], v[202:205], v[108:111]
	v_mfma_f32_16x16x32_bf16 v[92:95], v[160:163], v[210:213], v[92:95]
	v_mfma_f32_16x16x32_bf16 v[92:95], v[164:167], v[214:217], v[92:95]
	v_mfma_f32_16x16x32_bf16 v[84:87], v[172:175], v[214:217], v[84:87]
	v_mfma_f32_16x16x32_bf16 v[84:87], v[168:171], v[210:213], v[84:87]
	v_mfma_f32_16x16x32_bf16 v[68:71], v[168:171], v[218:221], v[68:71]
	v_mfma_f32_16x16x32_bf16 v[68:71], v[172:175], v[222:225], v[68:71]
	v_mfma_f32_16x16x32_bf16 v[76:79], v[164:167], v[222:225], v[76:79]
	v_mfma_f32_16x16x32_bf16 v[76:79], v[160:163], v[218:221], v[76:79]
	s_setprio 0
	s_setprio 1
	v_mfma_f32_16x16x32_bf16 v[120:123], v[176:179], v[194:197], v[120:123]
	v_mfma_f32_16x16x32_bf16 v[120:123], v[180:183], v[198:201], v[120:123]
	v_mfma_f32_16x16x32_bf16 v[112:115], v[190:193], v[198:201], v[112:115]
	v_mfma_f32_16x16x32_bf16 v[112:115], v[186:189], v[194:197], v[112:115]
	v_mfma_f32_16x16x32_bf16 v[96:99], v[186:189], v[202:205], v[96:99]
	v_mfma_f32_16x16x32_bf16 v[96:99], v[190:193], v[206:209], v[96:99]
	v_mfma_f32_16x16x32_bf16 v[104:107], v[180:183], v[206:209], v[104:107]
	v_mfma_f32_16x16x32_bf16 v[104:107], v[176:179], v[202:205], v[104:107]
	v_mfma_f32_16x16x32_bf16 v[88:91], v[176:179], v[210:213], v[88:91]
	v_mfma_f32_16x16x32_bf16 v[88:91], v[180:183], v[214:217], v[88:91]
	v_mfma_f32_16x16x32_bf16 v[80:83], v[190:193], v[214:217], v[80:83]
	v_mfma_f32_16x16x32_bf16 v[80:83], v[186:189], v[210:213], v[80:83]
	v_mfma_f32_16x16x32_bf16 v[64:67], v[186:189], v[218:221], v[64:67]
	v_mfma_f32_16x16x32_bf16 v[64:67], v[190:193], v[222:225], v[64:67]
	v_mfma_f32_16x16x32_bf16 v[72:75], v[180:183], v[222:225], v[72:75]
	v_mfma_f32_16x16x32_bf16 v[72:75], v[176:179], v[218:221], v[72:75]
	s_setprio 0
	s_barrier
	s_add_i32 s76, s66, s54
	v_lshl_add_u64 v[154:155], s[48:49], 0, v[132:133]
	s_mov_b32 m0, s76
	ds_read_b128 v[194:197], v150 offset:16384
	ds_read_b128 v[198:201], v150 offset:17408
	ds_read_b128 v[202:205], v150 offset:18432
	ds_read_b128 v[206:209], v150 offset:19456
	ds_read_b128 v[210:213], v150 offset:20480
	ds_read_b128 v[214:217], v150 offset:21504
	ds_read_b128 v[218:221], v150 offset:22528
	ds_read_b128 v[222:225], v150 offset:23552
	global_load_lds_dwordx4 v[154:155], off
	s_add_i32 m0, s76, 0x2000
	s_add_u32 s76, s48, 0x40000
	v_lshl_add_u64 v[226:227], s[48:49], 0, v[128:129]
	s_addc_u32 s77, s49, 0
	s_add_i32 s78, s67, s54
	global_load_lds_dwordx4 v[226:227], off
	v_lshl_add_u64 v[228:229], s[76:77], 0, v[132:133]
	s_mov_b32 m0, s78
	v_lshl_add_u64 v[230:231], s[50:51], 0, v[130:131]
	global_load_lds_dwordx4 v[228:229], off
	v_lshl_add_u64 v[228:229], s[76:77], 0, v[128:129]
	s_add_i32 m0, s78, 0x2000
	s_nop 0
	global_load_lds_dwordx4 v[228:229], off
	v_lshl_add_u64 v[228:229], s[50:51], 0, v[134:135]
	s_mov_b32 m0, s57
	s_nop 0
	global_load_lds_dwordx4 v[228:229], off
	s_mov_b32 m0, s58
	s_nop 0
	global_load_lds_dwordx4 v[230:231], off
	s_waitcnt vmcnt(8)
	s_waitcnt lgkmcnt(0)
	s_barrier
	s_setprio 1
	s_waitcnt lgkmcnt(0)
	v_mfma_f32_16x16x32_bf16 v[60:63], v[160:163], v[194:197], v[60:63]
	v_mfma_f32_16x16x32_bf16 v[60:63], v[164:167], v[198:201], v[60:63]
	v_mfma_f32_16x16x32_bf16 v[52:55], v[172:175], v[198:201], v[52:55]
	v_mfma_f32_16x16x32_bf16 v[52:55], v[168:171], v[194:197], v[52:55]
	v_mfma_f32_16x16x32_bf16 v[36:39], v[168:171], v[202:205], v[36:39]
	v_mfma_f32_16x16x32_bf16 v[36:39], v[172:175], v[206:209], v[36:39]
	v_mfma_f32_16x16x32_bf16 v[44:47], v[164:167], v[206:209], v[44:47]
	v_mfma_f32_16x16x32_bf16 v[44:47], v[160:163], v[202:205], v[44:47]
	v_mfma_f32_16x16x32_bf16 v[28:31], v[160:163], v[210:213], v[28:31]
	v_mfma_f32_16x16x32_bf16 v[28:31], v[164:167], v[214:217], v[28:31]
	v_mfma_f32_16x16x32_bf16 v[20:23], v[172:175], v[214:217], v[20:23]
	v_mfma_f32_16x16x32_bf16 v[20:23], v[168:171], v[210:213], v[20:23]
	v_mfma_f32_16x16x32_bf16 v[4:7], v[168:171], v[218:221], v[4:7]
	v_mfma_f32_16x16x32_bf16 v[4:7], v[172:175], v[222:225], v[4:7]
	v_mfma_f32_16x16x32_bf16 v[12:15], v[164:167], v[222:225], v[12:15]
	v_mfma_f32_16x16x32_bf16 v[12:15], v[160:163], v[218:221], v[12:15]
	s_setprio 0
	s_setprio 1
	v_mfma_f32_16x16x32_bf16 v[56:59], v[176:179], v[194:197], v[56:59]
	v_mfma_f32_16x16x32_bf16 v[56:59], v[180:183], v[198:201], v[56:59]
	v_mfma_f32_16x16x32_bf16 v[48:51], v[190:193], v[198:201], v[48:51]
	v_mfma_f32_16x16x32_bf16 v[48:51], v[186:189], v[194:197], v[48:51]
	v_mfma_f32_16x16x32_bf16 v[32:35], v[186:189], v[202:205], v[32:35]
	v_mfma_f32_16x16x32_bf16 v[32:35], v[190:193], v[206:209], v[32:35]
	v_mfma_f32_16x16x32_bf16 v[40:43], v[180:183], v[206:209], v[40:43]
	v_mfma_f32_16x16x32_bf16 v[40:43], v[176:179], v[202:205], v[40:43]
	v_mfma_f32_16x16x32_bf16 v[24:27], v[176:179], v[210:213], v[24:27]
	v_mfma_f32_16x16x32_bf16 v[24:27], v[180:183], v[214:217], v[24:27]
	v_mfma_f32_16x16x32_bf16 v[16:19], v[190:193], v[214:217], v[16:19]
	v_mfma_f32_16x16x32_bf16 v[16:19], v[186:189], v[210:213], v[16:19]
	v_mfma_f32_16x16x32_bf16 v[0:3], v[186:189], v[218:221], v[0:3]
	v_mfma_f32_16x16x32_bf16 v[0:3], v[190:193], v[222:225], v[0:3]
	v_mfma_f32_16x16x32_bf16 v[8:11], v[180:183], v[222:225], v[8:11]
	v_mfma_f32_16x16x32_bf16 v[8:11], v[176:179], v[218:221], v[8:11]
	s_setprio 0
	s_barrier
	s_add_i32 s76, 0, 0x18000
	v_add_u32_e32 v153, s76, v147
	s_add_i32 s77, 0, 0x1c000
	ds_read_b128 v[160:163], v153
	ds_read_b128 v[164:167], v153 offset:1024
	ds_read_b128 v[168:171], v153 offset:2048
	ds_read_b128 v[172:175], v153 offset:3072
	v_add_u32_e32 v153, s77, v147
	ds_read_b128 v[176:179], v153
	ds_read_b128 v[180:183], v153 offset:1024
	ds_read_b128 v[186:189], v153 offset:2048
	ds_read_b128 v[190:193], v153 offset:3072
	s_add_u32 s50, s50, 0x40000
	s_addc_u32 s51, s51, 0
	s_mov_b32 m0, s59
	v_lshl_add_u64 v[232:233], s[50:51], 0, v[134:135]
	ds_read_b128 v[194:197], v150 offset:32768
	ds_read_b128 v[198:201], v150 offset:33792
	ds_read_b128 v[202:205], v150 offset:34816
	ds_read_b128 v[206:209], v150 offset:35840
	ds_read_b128 v[210:213], v150 offset:36864
	ds_read_b128 v[214:217], v150 offset:37888
	ds_read_b128 v[218:221], v150 offset:38912
	ds_read_b128 v[222:225], v150 offset:39936
	global_load_lds_dwordx4 v[232:233], off
	v_lshl_add_u64 v[232:233], s[50:51], 0, v[130:131]
	s_mov_b32 m0, s60
	s_nop 0
	global_load_lds_dwordx4 v[232:233], off
	s_waitcnt vmcnt(8)
	s_waitcnt lgkmcnt(0)
	s_barrier
	s_setprio 1
	s_waitcnt lgkmcnt(0)
	v_mfma_f32_16x16x32_bf16 v[124:127], v[160:163], v[194:197], v[124:127]
	v_mfma_f32_16x16x32_bf16 v[124:127], v[164:167], v[198:201], v[124:127]
	v_mfma_f32_16x16x32_bf16 v[116:119], v[172:175], v[198:201], v[116:119]
	v_mfma_f32_16x16x32_bf16 v[116:119], v[168:171], v[194:197], v[116:119]
	v_mfma_f32_16x16x32_bf16 v[100:103], v[168:171], v[202:205], v[100:103]
	v_mfma_f32_16x16x32_bf16 v[100:103], v[172:175], v[206:209], v[100:103]
	v_mfma_f32_16x16x32_bf16 v[108:111], v[164:167], v[206:209], v[108:111]
	v_mfma_f32_16x16x32_bf16 v[108:111], v[160:163], v[202:205], v[108:111]
	v_mfma_f32_16x16x32_bf16 v[92:95], v[160:163], v[210:213], v[92:95]
	v_mfma_f32_16x16x32_bf16 v[92:95], v[164:167], v[214:217], v[92:95]
	v_mfma_f32_16x16x32_bf16 v[84:87], v[172:175], v[214:217], v[84:87]
	v_mfma_f32_16x16x32_bf16 v[84:87], v[168:171], v[210:213], v[84:87]
	v_mfma_f32_16x16x32_bf16 v[68:71], v[168:171], v[218:221], v[68:71]
	v_mfma_f32_16x16x32_bf16 v[68:71], v[172:175], v[222:225], v[68:71]
	v_mfma_f32_16x16x32_bf16 v[76:79], v[164:167], v[222:225], v[76:79]
	v_mfma_f32_16x16x32_bf16 v[76:79], v[160:163], v[218:221], v[76:79]
	s_setprio 0
	s_setprio 1
	v_mfma_f32_16x16x32_bf16 v[120:123], v[176:179], v[194:197], v[120:123]
	v_mfma_f32_16x16x32_bf16 v[120:123], v[180:183], v[198:201], v[120:123]
	v_mfma_f32_16x16x32_bf16 v[112:115], v[190:193], v[198:201], v[112:115]
	v_mfma_f32_16x16x32_bf16 v[112:115], v[186:189], v[194:197], v[112:115]
	v_mfma_f32_16x16x32_bf16 v[96:99], v[186:189], v[202:205], v[96:99]
	v_mfma_f32_16x16x32_bf16 v[96:99], v[190:193], v[206:209], v[96:99]
	v_mfma_f32_16x16x32_bf16 v[104:107], v[180:183], v[206:209], v[104:107]
	v_mfma_f32_16x16x32_bf16 v[104:107], v[176:179], v[202:205], v[104:107]
	v_mfma_f32_16x16x32_bf16 v[88:91], v[176:179], v[210:213], v[88:91]
	v_mfma_f32_16x16x32_bf16 v[88:91], v[180:183], v[214:217], v[88:91]
	v_mfma_f32_16x16x32_bf16 v[80:83], v[190:193], v[214:217], v[80:83]
	v_mfma_f32_16x16x32_bf16 v[80:83], v[186:189], v[210:213], v[80:83]
	v_mfma_f32_16x16x32_bf16 v[64:67], v[186:189], v[218:221], v[64:67]
	v_mfma_f32_16x16x32_bf16 v[64:67], v[190:193], v[222:225], v[64:67]
	v_mfma_f32_16x16x32_bf16 v[72:75], v[180:183], v[222:225], v[72:75]
	v_mfma_f32_16x16x32_bf16 v[72:75], v[176:179], v[218:221], v[72:75]
	s_setprio 0
	s_barrier
	v_add_u32_e32 v234, 0x21000, v151
	ds_read_b128 v[236:239], v234
	ds_read_b128 v[240:243], v234 offset:256
	ds_read_b128 v[244:247], v234 offset:512
	ds_read_b128 v[248:251], v234 offset:768
	v_add_u32_e32 v235, s27, v146
	v_mul_u32_u24_e32 v235, 0x1600, v235
	v_lshl_or_b32 v234, s69, 7, v149
	v_lshl_add_u32 v235, v234, 1, v235
	s_add_i32 s50, s76, s54
	v_lshl_add_u64 v[154:155], v[154:155], 0, s[20:21]
	s_mov_b32 m0, s50
	ds_read_b128 v[194:197], v150 offset:49152
	ds_read_b128 v[198:201], v150 offset:50176
	ds_read_b128 v[202:205], v150 offset:51200
	ds_read_b128 v[206:209], v150 offset:52224
	ds_read_b128 v[210:213], v150 offset:53248
	ds_read_b128 v[214:217], v150 offset:54272
	ds_read_b128 v[218:221], v150 offset:55296
	ds_read_b128 v[222:225], v150 offset:56320
	global_load_lds_dwordx4 v[154:155], off
	s_add_i32 m0, s50, 0x2000
	s_add_u32 s48, s48, 0x40080
	v_lshl_add_u64 v[154:155], v[226:227], 0, s[20:21]
	s_addc_u32 s49, s49, 0
	s_add_i32 s50, s77, s54
	global_load_lds_dwordx4 v[154:155], off
	v_lshl_add_u64 v[154:155], s[48:49], 0, v[132:133]
	s_mov_b32 m0, s50
	s_nop 0
	global_load_lds_dwordx4 v[154:155], off
	v_lshl_add_u64 v[154:155], s[48:49], 0, v[128:129]
	s_add_i32 m0, s50, 0x2000
	s_nop 0
	global_load_lds_dwordx4 v[154:155], off
	v_lshl_add_u64 v[154:155], v[228:229], 0, s[20:21]
	s_mov_b32 m0, s62
	s_nop 0
	global_load_lds_dwordx4 v[154:155], off
	v_lshl_add_u64 v[154:155], v[230:231], 0, s[20:21]
	s_mov_b32 m0, s63
	s_nop 0
	global_load_lds_dwordx4 v[154:155], off
	s_waitcnt lgkmcnt(8)
	v_add_f32_e32 v236, v236, v237
	v_add_f32_e32 v238, v238, v239
	v_add_f32_e32 v240, v240, v241
	v_add_f32_e32 v242, v242, v243
	v_add_f32_e32 v244, v244, v245
	v_add_f32_e32 v246, v246, v247
	v_add_f32_e32 v248, v248, v249
	v_add_f32_e32 v250, v250, v251
	v_add_f32_e32 v236, v236, v238
	v_add_f32_e32 v240, v240, v242
	v_add_f32_e32 v244, v244, v246
	v_add_f32_e32 v248, v248, v250
	v_fmamk_f32 v236, v236, 0x3a800000, v152
	v_fmamk_f32 v240, v240, 0x3a800000, v152
	v_fmamk_f32 v244, v244, 0x3a800000, v152
	v_fmamk_f32 v248, v248, 0x3a800000, v152
	v_rsq_f32_e32 v236, v236
	v_rsq_f32_e32 v240, v240
	v_rsq_f32_e32 v244, v244
	v_rsq_f32_e32 v248, v248
	v_mul_f32_e32 v252, 0xbfb8aa3b, v236
	v_mul_f32_e32 v254, v236, v236
	v_pk_mul_f32 v[120:121], v[124:125], v[120:121]
	v_pk_mul_f32 v[122:123], v[126:127], v[122:123]
	v_pk_mul_f32 v[112:113], v[116:117], v[112:113]
	v_pk_mul_f32 v[114:115], v[118:119], v[114:115]
	v_pk_mul_f32 v[124:125], v[124:125], v[252:253] op_sel_hi:[1,0]
	v_pk_mul_f32 v[126:127], v[126:127], v[252:253] op_sel_hi:[1,0]
	v_pk_mul_f32 v[116:117], v[116:117], v[252:253] op_sel_hi:[1,0]
	v_pk_mul_f32 v[118:119], v[118:119], v[252:253] op_sel_hi:[1,0]
	v_exp_f32_e32 v124, v124
	v_exp_f32_e32 v125, v125
	v_exp_f32_e32 v126, v126
	v_exp_f32_e32 v127, v127
	v_exp_f32_e32 v116, v116
	v_exp_f32_e32 v117, v117
	v_exp_f32_e32 v118, v118
	v_exp_f32_e32 v119, v119
	v_pk_add_f32 v[124:125], v[124:125], 1.0 op_sel_hi:[1,0]
	v_pk_add_f32 v[126:127], v[126:127], 1.0 op_sel_hi:[1,0]
	v_pk_add_f32 v[116:117], v[116:117], 1.0 op_sel_hi:[1,0]
	v_pk_add_f32 v[118:119], v[118:119], 1.0 op_sel_hi:[1,0]
	v_rcp_f32_e32 v124, v124
	v_rcp_f32_e32 v125, v125
	v_rcp_f32_e32 v126, v126
	v_rcp_f32_e32 v127, v127
	v_rcp_f32_e32 v116, v116
	v_rcp_f32_e32 v117, v117
	v_rcp_f32_e32 v118, v118
	v_rcp_f32_e32 v119, v119
	v_pk_mul_f32 v[120:121], v[120:121], v[254:255] op_sel_hi:[1,0]
	v_pk_mul_f32 v[122:123], v[122:123], v[254:255] op_sel_hi:[1,0]
	v_pk_mul_f32 v[112:113], v[112:113], v[254:255] op_sel_hi:[1,0]
	v_pk_mul_f32 v[114:115], v[114:115], v[254:255] op_sel_hi:[1,0]
	v_pk_mul_f32 v[120:121], v[120:121], v[124:125]
	v_pk_mul_f32 v[122:123], v[122:123], v[126:127]
	v_pk_mul_f32 v[112:113], v[112:113], v[116:117]
	v_pk_mul_f32 v[114:115], v[114:115], v[118:119]
	v_cvt_pk_bf16_f32 v120, v120, v121
	v_cvt_pk_bf16_f32 v121, v122, v123
	v_cvt_pk_bf16_f32 v122, v112, v113
	v_cvt_pk_bf16_f32 v123, v114, v115
	global_store_dwordx4 v235, v[120:123], s[14:15]
	v_add_u32_e32 v234, 0x16000, v235
	v_mul_f32_e32 v252, 0xbfb8aa3b, v240
	v_mul_f32_e32 v254, v240, v240
	v_pk_mul_f32 v[104:105], v[108:109], v[104:105]
	v_pk_mul_f32 v[106:107], v[110:111], v[106:107]
	v_pk_mul_f32 v[96:97], v[100:101], v[96:97]
	v_pk_mul_f32 v[98:99], v[102:103], v[98:99]
	v_pk_mul_f32 v[108:109], v[108:109], v[252:253] op_sel_hi:[1,0]
	v_pk_mul_f32 v[110:111], v[110:111], v[252:253] op_sel_hi:[1,0]
	v_pk_mul_f32 v[100:101], v[100:101], v[252:253] op_sel_hi:[1,0]
	v_pk_mul_f32 v[102:103], v[102:103], v[252:253] op_sel_hi:[1,0]
	v_exp_f32_e32 v108, v108
	v_exp_f32_e32 v109, v109
	v_exp_f32_e32 v110, v110
	v_exp_f32_e32 v111, v111
	v_exp_f32_e32 v100, v100
	v_exp_f32_e32 v101, v101
	v_exp_f32_e32 v102, v102
	v_exp_f32_e32 v103, v103
	v_pk_add_f32 v[108:109], v[108:109], 1.0 op_sel_hi:[1,0]
	v_pk_add_f32 v[110:111], v[110:111], 1.0 op_sel_hi:[1,0]
	v_pk_add_f32 v[100:101], v[100:101], 1.0 op_sel_hi:[1,0]
	v_pk_add_f32 v[102:103], v[102:103], 1.0 op_sel_hi:[1,0]
	v_rcp_f32_e32 v108, v108
	v_rcp_f32_e32 v109, v109
	v_rcp_f32_e32 v110, v110
	v_rcp_f32_e32 v111, v111
	v_rcp_f32_e32 v100, v100
	v_rcp_f32_e32 v101, v101
	v_rcp_f32_e32 v102, v102
	v_rcp_f32_e32 v103, v103
	v_pk_mul_f32 v[104:105], v[104:105], v[254:255] op_sel_hi:[1,0]
	v_pk_mul_f32 v[106:107], v[106:107], v[254:255] op_sel_hi:[1,0]
	v_pk_mul_f32 v[96:97], v[96:97], v[254:255] op_sel_hi:[1,0]
	v_pk_mul_f32 v[98:99], v[98:99], v[254:255] op_sel_hi:[1,0]
	v_pk_mul_f32 v[104:105], v[104:105], v[108:109]
	v_pk_mul_f32 v[106:107], v[106:107], v[110:111]
	v_pk_mul_f32 v[96:97], v[96:97], v[100:101]
	v_pk_mul_f32 v[98:99], v[98:99], v[102:103]
	v_cvt_pk_bf16_f32 v104, v104, v105
	v_cvt_pk_bf16_f32 v105, v106, v107
	v_cvt_pk_bf16_f32 v106, v96, v97
	v_cvt_pk_bf16_f32 v107, v98, v99
	global_store_dwordx4 v234, v[104:107], s[14:15]
	v_add_u32_e32 v235, 0x16000, v234
	v_mul_f32_e32 v252, 0xbfb8aa3b, v244
	v_mul_f32_e32 v254, v244, v244
	v_pk_mul_f32 v[88:89], v[92:93], v[88:89]
	v_pk_mul_f32 v[90:91], v[94:95], v[90:91]
	v_pk_mul_f32 v[80:81], v[84:85], v[80:81]
	v_pk_mul_f32 v[82:83], v[86:87], v[82:83]
	v_pk_mul_f32 v[92:93], v[92:93], v[252:253] op_sel_hi:[1,0]
	v_pk_mul_f32 v[94:95], v[94:95], v[252:253] op_sel_hi:[1,0]
	v_pk_mul_f32 v[84:85], v[84:85], v[252:253] op_sel_hi:[1,0]
	v_pk_mul_f32 v[86:87], v[86:87], v[252:253] op_sel_hi:[1,0]
	v_exp_f32_e32 v92, v92
	v_exp_f32_e32 v93, v93
	v_exp_f32_e32 v94, v94
	v_exp_f32_e32 v95, v95
	v_exp_f32_e32 v84, v84
	v_exp_f32_e32 v85, v85
	v_exp_f32_e32 v86, v86
	v_exp_f32_e32 v87, v87
	v_pk_add_f32 v[92:93], v[92:93], 1.0 op_sel_hi:[1,0]
	v_pk_add_f32 v[94:95], v[94:95], 1.0 op_sel_hi:[1,0]
	v_pk_add_f32 v[84:85], v[84:85], 1.0 op_sel_hi:[1,0]
	v_pk_add_f32 v[86:87], v[86:87], 1.0 op_sel_hi:[1,0]
	v_rcp_f32_e32 v92, v92
	v_rcp_f32_e32 v93, v93
	v_rcp_f32_e32 v94, v94
	v_rcp_f32_e32 v95, v95
	v_rcp_f32_e32 v84, v84
	v_rcp_f32_e32 v85, v85
	v_rcp_f32_e32 v86, v86
	v_rcp_f32_e32 v87, v87
	v_pk_mul_f32 v[88:89], v[88:89], v[254:255] op_sel_hi:[1,0]
	v_pk_mul_f32 v[90:91], v[90:91], v[254:255] op_sel_hi:[1,0]
	v_pk_mul_f32 v[80:81], v[80:81], v[254:255] op_sel_hi:[1,0]
	v_pk_mul_f32 v[82:83], v[82:83], v[254:255] op_sel_hi:[1,0]
	v_pk_mul_f32 v[88:89], v[88:89], v[92:93]
	v_pk_mul_f32 v[90:91], v[90:91], v[94:95]
	v_pk_mul_f32 v[80:81], v[80:81], v[84:85]
	v_pk_mul_f32 v[82:83], v[82:83], v[86:87]
	v_cvt_pk_bf16_f32 v88, v88, v89
	v_cvt_pk_bf16_f32 v89, v90, v91
	v_cvt_pk_bf16_f32 v90, v80, v81
	v_cvt_pk_bf16_f32 v91, v82, v83
	global_store_dwordx4 v235, v[88:91], s[14:15]
	v_add_u32_e32 v234, 0x16000, v235
	v_mul_f32_e32 v252, 0xbfb8aa3b, v248
	v_mul_f32_e32 v254, v248, v248
	v_pk_mul_f32 v[72:73], v[76:77], v[72:73]
	v_pk_mul_f32 v[74:75], v[78:79], v[74:75]
	v_pk_mul_f32 v[64:65], v[68:69], v[64:65]
	v_pk_mul_f32 v[66:67], v[70:71], v[66:67]
	v_pk_mul_f32 v[76:77], v[76:77], v[252:253] op_sel_hi:[1,0]
	v_pk_mul_f32 v[78:79], v[78:79], v[252:253] op_sel_hi:[1,0]
	v_pk_mul_f32 v[68:69], v[68:69], v[252:253] op_sel_hi:[1,0]
	v_pk_mul_f32 v[70:71], v[70:71], v[252:253] op_sel_hi:[1,0]
	v_exp_f32_e32 v76, v76
	v_exp_f32_e32 v77, v77
	v_exp_f32_e32 v78, v78
	v_exp_f32_e32 v79, v79
	v_exp_f32_e32 v68, v68
	v_exp_f32_e32 v69, v69
	v_exp_f32_e32 v70, v70
	v_exp_f32_e32 v71, v71
	v_pk_add_f32 v[76:77], v[76:77], 1.0 op_sel_hi:[1,0]
	v_pk_add_f32 v[78:79], v[78:79], 1.0 op_sel_hi:[1,0]
	v_pk_add_f32 v[68:69], v[68:69], 1.0 op_sel_hi:[1,0]
	v_pk_add_f32 v[70:71], v[70:71], 1.0 op_sel_hi:[1,0]
	v_rcp_f32_e32 v76, v76
	v_rcp_f32_e32 v77, v77
	v_rcp_f32_e32 v78, v78
	v_rcp_f32_e32 v79, v79
	v_rcp_f32_e32 v68, v68
	v_rcp_f32_e32 v69, v69
	v_rcp_f32_e32 v70, v70
	v_rcp_f32_e32 v71, v71
	v_pk_mul_f32 v[72:73], v[72:73], v[254:255] op_sel_hi:[1,0]
	v_pk_mul_f32 v[74:75], v[74:75], v[254:255] op_sel_hi:[1,0]
	v_pk_mul_f32 v[64:65], v[64:65], v[254:255] op_sel_hi:[1,0]
	v_pk_mul_f32 v[66:67], v[66:67], v[254:255] op_sel_hi:[1,0]
	v_pk_mul_f32 v[72:73], v[72:73], v[76:77]
	v_pk_mul_f32 v[74:75], v[74:75], v[78:79]
	v_pk_mul_f32 v[64:65], v[64:65], v[68:69]
	v_pk_mul_f32 v[66:67], v[66:67], v[70:71]
	v_cvt_pk_bf16_f32 v72, v72, v73
	v_cvt_pk_bf16_f32 v73, v74, v75
	v_cvt_pk_bf16_f32 v74, v64, v65
	v_cvt_pk_bf16_f32 v75, v66, v67
	global_store_dwordx4 v234, v[72:75], s[14:15]
	s_waitcnt vmcnt(12)
	s_waitcnt lgkmcnt(0)
	s_barrier
	s_setprio 1
	s_waitcnt lgkmcnt(0)
	v_mfma_f32_16x16x32_bf16 v[60:63], v[160:163], v[194:197], v[60:63]
	v_mfma_f32_16x16x32_bf16 v[60:63], v[164:167], v[198:201], v[60:63]
	v_mfma_f32_16x16x32_bf16 v[52:55], v[172:175], v[198:201], v[52:55]
	v_mfma_f32_16x16x32_bf16 v[52:55], v[168:171], v[194:197], v[52:55]
	v_mfma_f32_16x16x32_bf16 v[36:39], v[168:171], v[202:205], v[36:39]
	v_mfma_f32_16x16x32_bf16 v[36:39], v[172:175], v[206:209], v[36:39]
	v_mfma_f32_16x16x32_bf16 v[44:47], v[164:167], v[206:209], v[44:47]
	v_mfma_f32_16x16x32_bf16 v[44:47], v[160:163], v[202:205], v[44:47]
	v_mfma_f32_16x16x32_bf16 v[28:31], v[160:163], v[210:213], v[28:31]
	v_mfma_f32_16x16x32_bf16 v[28:31], v[164:167], v[214:217], v[28:31]
	v_mfma_f32_16x16x32_bf16 v[20:23], v[172:175], v[214:217], v[20:23]
	v_mfma_f32_16x16x32_bf16 v[20:23], v[168:171], v[210:213], v[20:23]
	v_mfma_f32_16x16x32_bf16 v[4:7], v[168:171], v[218:221], v[4:7]
	v_mfma_f32_16x16x32_bf16 v[4:7], v[172:175], v[222:225], v[4:7]
	v_mfma_f32_16x16x32_bf16 v[12:15], v[164:167], v[222:225], v[12:15]
	v_mfma_f32_16x16x32_bf16 v[12:15], v[160:163], v[218:221], v[12:15]
	s_setprio 0
	s_setprio 1
	v_mfma_f32_16x16x32_bf16 v[56:59], v[176:179], v[194:197], v[56:59]
	v_mfma_f32_16x16x32_bf16 v[56:59], v[180:183], v[198:201], v[56:59]
	v_mfma_f32_16x16x32_bf16 v[48:51], v[190:193], v[198:201], v[48:51]
	v_mfma_f32_16x16x32_bf16 v[48:51], v[186:189], v[194:197], v[48:51]
	v_mfma_f32_16x16x32_bf16 v[32:35], v[186:189], v[202:205], v[32:35]
	v_mfma_f32_16x16x32_bf16 v[32:35], v[190:193], v[206:209], v[32:35]
	v_mfma_f32_16x16x32_bf16 v[40:43], v[180:183], v[206:209], v[40:43]
	v_mfma_f32_16x16x32_bf16 v[40:43], v[176:179], v[202:205], v[40:43]
	v_mfma_f32_16x16x32_bf16 v[24:27], v[176:179], v[210:213], v[24:27]
	v_mfma_f32_16x16x32_bf16 v[24:27], v[180:183], v[214:217], v[24:27]
	v_mfma_f32_16x16x32_bf16 v[16:19], v[190:193], v[214:217], v[16:19]
	v_mfma_f32_16x16x32_bf16 v[16:19], v[186:189], v[210:213], v[16:19]
	v_mfma_f32_16x16x32_bf16 v[0:3], v[186:189], v[218:221], v[0:3]
	v_mfma_f32_16x16x32_bf16 v[0:3], v[190:193], v[222:225], v[0:3]
	v_mfma_f32_16x16x32_bf16 v[8:11], v[180:183], v[222:225], v[8:11]
	v_mfma_f32_16x16x32_bf16 v[8:11], v[176:179], v[218:221], v[8:11]
	s_setprio 0
	s_barrier
	s_add_i32 s75, s75, 2
	s_add_u32 s73, s73, 0x100
	s_addc_u32 s74, s74, 0
	s_add_u32 s46, s46, 0x100
	s_addc_u32 s47, s47, 0

.LBB0_609:
	s_add_u32 s79, s56, 0x100
	s_addc_u32 s80, s57, 0
	s_mov_b32 s81, -2
	s_waitcnt lgkmcnt(0)
	s_cmp_eq_u32 s70, 1
	s_cbranch_scc1 .Lfa_5
	ds_read_b128 v[128:131], v189
	ds_read_b128 v[132:135], v189 offset:1024
	ds_read_b128 v[136:139], v189 offset:2048
	ds_read_b128 v[140:143], v189 offset:3072
	ds_read_b128 v[144:147], v190
	ds_read_b128 v[148:151], v190 offset:1024
	ds_read_b128 v[172:175], v190 offset:2048
	ds_read_b128 v[176:179], v190 offset:3072
	s_add_u32 s56, s54, 0x100
	s_addc_u32 s57, s55, 0
	s_cmp_eq_u32 s81, 40
	s_cselect_b32 s61, s17, s57
	s_cselect_b32 s60, s16, s56
	s_cselect_b32 s59, s53, s80
	s_cselect_b32 s58, s52, s79
	v_lshl_add_u64 v[222:223], s[54:55], 0, v[166:167]
	s_add_i32 m0, s66, 0xc000
	ds_read_b128 v[180:183], v191
	ds_read_b128 v[194:197], v191 offset:1024
	ds_read_b128 v[198:201], v191 offset:2048
	ds_read_b128 v[202:205], v191 offset:3072
	ds_read_b128 v[206:209], v191 offset:4096
	ds_read_b128 v[210:213], v191 offset:5120
	ds_read_b128 v[214:217], v191 offset:6144
	ds_read_b128 v[218:221], v191 offset:7168
	global_load_lds_dwordx4 v[222:223], off
	v_lshl_add_u64 v[222:223], s[54:55], 0, v[164:165]
	s_add_i32 m0, s66, 0xe000
	s_nop 0
	global_load_lds_dwordx4 v[222:223], off
	s_waitcnt vmcnt(24)
	s_waitcnt lgkmcnt(0)
	s_barrier
	s_setprio 1
	s_waitcnt lgkmcnt(0)
	v_mfma_f32_16x16x32_bf16 v[124:127], v[128:131], v[180:183], 0
	v_mfma_f32_16x16x32_bf16 v[120:123], v[136:139], v[180:183], 0
	v_mfma_f32_16x16x32_bf16 v[108:111], v[128:131], v[198:201], 0
	v_mfma_f32_16x16x32_bf16 v[104:107], v[136:139], v[198:201], 0
	v_mfma_f32_16x16x32_bf16 v[92:95], v[128:131], v[206:209], 0
	v_mfma_f32_16x16x32_bf16 v[88:91], v[136:139], v[206:209], 0
	v_mfma_f32_16x16x32_bf16 v[76:79], v[128:131], v[214:217], 0
	v_mfma_f32_16x16x32_bf16 v[72:75], v[136:139], v[214:217], 0
	v_mfma_f32_16x16x32_bf16 v[124:127], v[132:135], v[194:197], v[124:127]
	v_mfma_f32_16x16x32_bf16 v[120:123], v[140:143], v[194:197], v[120:123]
	v_mfma_f32_16x16x32_bf16 v[108:111], v[132:135], v[202:205], v[108:111]
	v_mfma_f32_16x16x32_bf16 v[104:107], v[140:143], v[202:205], v[104:107]
	v_mfma_f32_16x16x32_bf16 v[92:95], v[132:135], v[210:213], v[92:95]
	v_mfma_f32_16x16x32_bf16 v[88:91], v[140:143], v[210:213], v[88:91]
	v_mfma_f32_16x16x32_bf16 v[76:79], v[132:135], v[218:221], v[76:79]
	v_mfma_f32_16x16x32_bf16 v[72:75], v[140:143], v[218:221], v[72:75]
	s_setprio 0
	s_setprio 1
	v_mfma_f32_16x16x32_bf16 v[116:119], v[144:147], v[180:183], 0
	v_mfma_f32_16x16x32_bf16 v[112:115], v[172:175], v[180:183], 0
	v_mfma_f32_16x16x32_bf16 v[100:103], v[144:147], v[198:201], 0
	v_mfma_f32_16x16x32_bf16 v[96:99], v[172:175], v[198:201], 0
	v_mfma_f32_16x16x32_bf16 v[84:87], v[144:147], v[206:209], 0
	v_mfma_f32_16x16x32_bf16 v[80:83], v[172:175], v[206:209], 0
	v_mfma_f32_16x16x32_bf16 v[68:71], v[144:147], v[214:217], 0
	v_mfma_f32_16x16x32_bf16 v[64:67], v[172:175], v[214:217], 0
	v_mfma_f32_16x16x32_bf16 v[116:119], v[148:151], v[194:197], v[116:119]
	v_mfma_f32_16x16x32_bf16 v[112:115], v[176:179], v[194:197], v[112:115]
	v_mfma_f32_16x16x32_bf16 v[100:103], v[148:151], v[202:205], v[100:103]
	v_mfma_f32_16x16x32_bf16 v[96:99], v[176:179], v[202:205], v[96:99]
	v_mfma_f32_16x16x32_bf16 v[84:87], v[148:151], v[210:213], v[84:87]
	v_mfma_f32_16x16x32_bf16 v[80:83], v[176:179], v[210:213], v[80:83]
	v_mfma_f32_16x16x32_bf16 v[68:71], v[148:151], v[218:221], v[68:71]
	v_mfma_f32_16x16x32_bf16 v[64:67], v[176:179], v[218:221], v[64:67]
	s_setprio 0
	s_barrier
	s_add_i32 s54, s75, s65
	v_lshl_add_u64 v[222:223], s[58:59], 0, v[154:155]
	s_mov_b32 m0, s54
	ds_read_b128 v[180:183], v191 offset:16384
	ds_read_b128 v[194:197], v191 offset:17408
	ds_read_b128 v[198:201], v191 offset:18432
	ds_read_b128 v[202:205], v191 offset:19456
	ds_read_b128 v[206:209], v191 offset:20480
	ds_read_b128 v[210:213], v191 offset:21504
	ds_read_b128 v[214:217], v191 offset:22528
	ds_read_b128 v[218:221], v191 offset:23552
	global_load_lds_dwordx4 v[222:223], off
	s_add_i32 m0, s54, 0x2000
	s_add_u32 s54, s58, 0xb0000
	v_lshl_add_u64 v[224:225], s[58:59], 0, v[162:163]
	s_addc_u32 s55, s59, 0
	s_add_i32 s82, s76, s65
	global_load_lds_dwordx4 v[224:225], off
	v_lshl_add_u64 v[226:227], s[54:55], 0, v[154:155]
	s_mov_b32 m0, s82
	v_lshl_add_u64 v[228:229], s[60:61], 0, v[160:161]
	global_load_lds_dwordx4 v[226:227], off
	v_lshl_add_u64 v[226:227], s[54:55], 0, v[162:163]
	s_add_i32 m0, s82, 0x2000
	s_nop 0
	global_load_lds_dwordx4 v[226:227], off
	v_lshl_add_u64 v[226:227], s[60:61], 0, v[152:153]
	s_mov_b32 m0, s66
	s_nop 0
	global_load_lds_dwordx4 v[226:227], off
	s_mov_b32 m0, s67
	s_nop 0
	global_load_lds_dwordx4 v[228:229], off
	s_waitcnt vmcnt(24)
	s_waitcnt lgkmcnt(0)
	s_barrier
	s_setprio 1
	s_waitcnt lgkmcnt(0)
	v_mfma_f32_16x16x32_bf16 v[60:63], v[128:131], v[180:183], 0
	v_mfma_f32_16x16x32_bf16 v[56:59], v[136:139], v[180:183], 0
	v_mfma_f32_16x16x32_bf16 v[44:47], v[128:131], v[198:201], 0
	v_mfma_f32_16x16x32_bf16 v[40:43], v[136:139], v[198:201], 0
	v_mfma_f32_16x16x32_bf16 v[28:31], v[128:131], v[206:209], 0
	v_mfma_f32_16x16x32_bf16 v[24:27], v[136:139], v[206:209], 0
	v_mfma_f32_16x16x32_bf16 v[12:15], v[128:131], v[214:217], 0
	v_mfma_f32_16x16x32_bf16 v[8:11], v[136:139], v[214:217], 0
	v_mfma_f32_16x16x32_bf16 v[60:63], v[132:135], v[194:197], v[60:63]
	v_mfma_f32_16x16x32_bf16 v[56:59], v[140:143], v[194:197], v[56:59]
	v_mfma_f32_16x16x32_bf16 v[44:47], v[132:135], v[202:205], v[44:47]
	v_mfma_f32_16x16x32_bf16 v[40:43], v[140:143], v[202:205], v[40:43]
	v_mfma_f32_16x16x32_bf16 v[28:31], v[132:135], v[210:213], v[28:31]
	v_mfma_f32_16x16x32_bf16 v[24:27], v[140:143], v[210:213], v[24:27]
	v_mfma_f32_16x16x32_bf16 v[12:15], v[132:135], v[218:221], v[12:15]
	v_mfma_f32_16x16x32_bf16 v[8:11], v[140:143], v[218:221], v[8:11]
	s_setprio 0
	s_setprio 1
	v_mfma_f32_16x16x32_bf16 v[52:55], v[144:147], v[180:183], 0
	v_mfma_f32_16x16x32_bf16 v[48:51], v[172:175], v[180:183], 0
	v_mfma_f32_16x16x32_bf16 v[36:39], v[144:147], v[198:201], 0
	v_mfma_f32_16x16x32_bf16 v[32:35], v[172:175], v[198:201], 0
	v_mfma_f32_16x16x32_bf16 v[20:23], v[144:147], v[206:209], 0
	v_mfma_f32_16x16x32_bf16 v[16:19], v[172:175], v[206:209], 0
	v_mfma_f32_16x16x32_bf16 v[4:7], v[144:147], v[214:217], 0
	v_mfma_f32_16x16x32_bf16 v[0:3], v[172:175], v[214:217], 0
	v_mfma_f32_16x16x32_bf16 v[52:55], v[148:151], v[194:197], v[52:55]
	v_mfma_f32_16x16x32_bf16 v[48:51], v[176:179], v[194:197], v[48:51]
	v_mfma_f32_16x16x32_bf16 v[36:39], v[148:151], v[202:205], v[36:39]
	v_mfma_f32_16x16x32_bf16 v[32:35], v[176:179], v[202:205], v[32:35]
	v_mfma_f32_16x16x32_bf16 v[20:23], v[148:151], v[210:213], v[20:23]
	v_mfma_f32_16x16x32_bf16 v[16:19], v[176:179], v[210:213], v[16:19]
	v_mfma_f32_16x16x32_bf16 v[4:7], v[148:151], v[218:221], v[4:7]
	v_mfma_f32_16x16x32_bf16 v[0:3], v[176:179], v[218:221], v[0:3]
	s_setprio 0
	s_barrier
	s_add_i32 s82, 0, 0x18000
	s_add_i32 s83, 0, 0x1c000
	v_add_u32_e32 v140, s82, v186
	v_add_u32_e32 v176, s83, v186
	ds_read_b128 v[128:131], v140
	ds_read_b128 v[132:135], v140 offset:1024
	ds_read_b128 v[136:139], v140 offset:2048
	ds_read_b128 v[140:143], v140 offset:3072
	ds_read_b128 v[144:147], v176
	ds_read_b128 v[148:151], v176 offset:1024
	ds_read_b128 v[172:175], v176 offset:2048
	ds_read_b128 v[176:179], v176 offset:3072
	s_add_u32 s54, s60, 0xb0000
	s_addc_u32 s55, s61, 0
	s_mov_b32 m0, s68
	v_lshl_add_u64 v[230:231], s[54:55], 0, v[152:153]
	ds_read_b128 v[180:183], v191 offset:32768
	ds_read_b128 v[194:197], v191 offset:33792
	ds_read_b128 v[198:201], v191 offset:34816
	ds_read_b128 v[202:205], v191 offset:35840
	ds_read_b128 v[206:209], v191 offset:36864
	ds_read_b128 v[210:213], v191 offset:37888
	ds_read_b128 v[214:217], v191 offset:38912
	ds_read_b128 v[218:221], v191 offset:39936
	global_load_lds_dwordx4 v[230:231], off
	v_lshl_add_u64 v[230:231], s[54:55], 0, v[160:161]
	s_mov_b32 m0, s69
	s_nop 0
	global_load_lds_dwordx4 v[230:231], off
	s_waitcnt vmcnt(8)
	s_waitcnt lgkmcnt(0)
	s_barrier
	s_setprio 1
	s_waitcnt lgkmcnt(0)
	v_mfma_f32_16x16x32_bf16 v[124:127], v[128:131], v[180:183], v[124:127]
	v_mfma_f32_16x16x32_bf16 v[124:127], v[132:135], v[194:197], v[124:127]
	v_mfma_f32_16x16x32_bf16 v[120:123], v[140:143], v[194:197], v[120:123]
	v_mfma_f32_16x16x32_bf16 v[120:123], v[136:139], v[180:183], v[120:123]
	v_mfma_f32_16x16x32_bf16 v[104:107], v[136:139], v[198:201], v[104:107]
	v_mfma_f32_16x16x32_bf16 v[104:107], v[140:143], v[202:205], v[104:107]
	v_mfma_f32_16x16x32_bf16 v[108:111], v[132:135], v[202:205], v[108:111]
	v_mfma_f32_16x16x32_bf16 v[108:111], v[128:131], v[198:201], v[108:111]
	v_mfma_f32_16x16x32_bf16 v[92:95], v[128:131], v[206:209], v[92:95]
	v_mfma_f32_16x16x32_bf16 v[92:95], v[132:135], v[210:213], v[92:95]
	v_mfma_f32_16x16x32_bf16 v[88:91], v[140:143], v[210:213], v[88:91]
	v_mfma_f32_16x16x32_bf16 v[88:91], v[136:139], v[206:209], v[88:91]
	v_mfma_f32_16x16x32_bf16 v[72:75], v[136:139], v[214:217], v[72:75]
	v_mfma_f32_16x16x32_bf16 v[72:75], v[140:143], v[218:221], v[72:75]
	v_mfma_f32_16x16x32_bf16 v[76:79], v[132:135], v[218:221], v[76:79]
	v_mfma_f32_16x16x32_bf16 v[76:79], v[128:131], v[214:217], v[76:79]
	s_setprio 0
	s_setprio 1
	v_mfma_f32_16x16x32_bf16 v[116:119], v[144:147], v[180:183], v[116:119]
	v_mfma_f32_16x16x32_bf16 v[116:119], v[148:151], v[194:197], v[116:119]
	v_mfma_f32_16x16x32_bf16 v[112:115], v[176:179], v[194:197], v[112:115]
	v_mfma_f32_16x16x32_bf16 v[112:115], v[172:175], v[180:183], v[112:115]
	v_mfma_f32_16x16x32_bf16 v[96:99], v[172:175], v[198:201], v[96:99]
	v_mfma_f32_16x16x32_bf16 v[96:99], v[176:179], v[202:205], v[96:99]
	v_mfma_f32_16x16x32_bf16 v[100:103], v[148:151], v[202:205], v[100:103]
	v_mfma_f32_16x16x32_bf16 v[100:103], v[144:147], v[198:201], v[100:103]
	v_mfma_f32_16x16x32_bf16 v[84:87], v[144:147], v[206:209], v[84:87]
	v_mfma_f32_16x16x32_bf16 v[84:87], v[148:151], v[210:213], v[84:87]
	v_mfma_f32_16x16x32_bf16 v[80:83], v[176:179], v[210:213], v[80:83]
	v_mfma_f32_16x16x32_bf16 v[80:83], v[172:175], v[206:209], v[80:83]
	v_mfma_f32_16x16x32_bf16 v[64:67], v[172:175], v[214:217], v[64:67]
	v_mfma_f32_16x16x32_bf16 v[64:67], v[176:179], v[218:221], v[64:67]
	v_mfma_f32_16x16x32_bf16 v[68:71], v[148:151], v[218:221], v[68:71]
	v_mfma_f32_16x16x32_bf16 v[68:71], v[144:147], v[214:217], v[68:71]
	s_setprio 0
	s_barrier
	s_add_i32 s54, s82, s65
	v_lshl_add_u64 v[222:223], v[222:223], 0, s[28:29]
	s_mov_b32 m0, s54
	ds_read_b128 v[180:183], v191 offset:49152
	ds_read_b128 v[194:197], v191 offset:50176
	ds_read_b128 v[198:201], v191 offset:51200
	ds_read_b128 v[202:205], v191 offset:52224
	ds_read_b128 v[206:209], v191 offset:53248
	ds_read_b128 v[210:213], v191 offset:54272
	ds_read_b128 v[214:217], v191 offset:55296
	ds_read_b128 v[218:221], v191 offset:56320
	global_load_lds_dwordx4 v[222:223], off
	s_add_i32 m0, s54, 0x2000
	s_add_u32 s54, s58, 0xb0080
	v_lshl_add_u64 v[222:223], v[224:225], 0, s[28:29]
	s_addc_u32 s55, s59, 0
	s_add_i32 s58, s83, s65
	global_load_lds_dwordx4 v[222:223], off
	v_lshl_add_u64 v[222:223], s[54:55], 0, v[154:155]
	s_mov_b32 m0, s58
	s_nop 0
	global_load_lds_dwordx4 v[222:223], off
	v_lshl_add_u64 v[222:223], s[54:55], 0, v[162:163]
	s_add_i32 m0, s58, 0x2000
	s_nop 0
	global_load_lds_dwordx4 v[222:223], off
	v_lshl_add_u64 v[222:223], v[226:227], 0, s[28:29]
	s_mov_b32 m0, s3
	s_nop 0
	global_load_lds_dwordx4 v[222:223], off
	v_lshl_add_u64 v[222:223], v[228:229], 0, s[28:29]
	s_mov_b32 m0, s71
	s_nop 0
	global_load_lds_dwordx4 v[222:223], off
	s_waitcnt vmcnt(8)
	s_waitcnt lgkmcnt(0)
	s_barrier
	s_setprio 1
	s_waitcnt lgkmcnt(0)
	v_mfma_f32_16x16x32_bf16 v[60:63], v[128:131], v[180:183], v[60:63]
	v_mfma_f32_16x16x32_bf16 v[60:63], v[132:135], v[194:197], v[60:63]
	v_mfma_f32_16x16x32_bf16 v[56:59], v[140:143], v[194:197], v[56:59]
	v_mfma_f32_16x16x32_bf16 v[56:59], v[136:139], v[180:183], v[56:59]
	v_mfma_f32_16x16x32_bf16 v[40:43], v[136:139], v[198:201], v[40:43]
	v_mfma_f32_16x16x32_bf16 v[40:43], v[140:143], v[202:205], v[40:43]
	v_mfma_f32_16x16x32_bf16 v[44:47], v[132:135], v[202:205], v[44:47]
	v_mfma_f32_16x16x32_bf16 v[44:47], v[128:131], v[198:201], v[44:47]
	v_mfma_f32_16x16x32_bf16 v[28:31], v[128:131], v[206:209], v[28:31]
	v_mfma_f32_16x16x32_bf16 v[28:31], v[132:135], v[210:213], v[28:31]
	v_mfma_f32_16x16x32_bf16 v[24:27], v[140:143], v[210:213], v[24:27]
	v_mfma_f32_16x16x32_bf16 v[24:27], v[136:139], v[206:209], v[24:27]
	v_mfma_f32_16x16x32_bf16 v[8:11], v[136:139], v[214:217], v[8:11]
	v_mfma_f32_16x16x32_bf16 v[8:11], v[140:143], v[218:221], v[8:11]
	v_mfma_f32_16x16x32_bf16 v[12:15], v[132:135], v[218:221], v[12:15]
	v_mfma_f32_16x16x32_bf16 v[12:15], v[128:131], v[214:217], v[12:15]
	s_setprio 0
	s_setprio 1
	v_mfma_f32_16x16x32_bf16 v[52:55], v[144:147], v[180:183], v[52:55]
	v_mfma_f32_16x16x32_bf16 v[52:55], v[148:151], v[194:197], v[52:55]
	v_mfma_f32_16x16x32_bf16 v[48:51], v[176:179], v[194:197], v[48:51]
	v_mfma_f32_16x16x32_bf16 v[48:51], v[172:175], v[180:183], v[48:51]
	v_mfma_f32_16x16x32_bf16 v[32:35], v[172:175], v[198:201], v[32:35]
	v_mfma_f32_16x16x32_bf16 v[32:35], v[176:179], v[202:205], v[32:35]
	v_mfma_f32_16x16x32_bf16 v[36:39], v[148:151], v[202:205], v[36:39]
	v_mfma_f32_16x16x32_bf16 v[36:39], v[144:147], v[198:201], v[36:39]
	v_mfma_f32_16x16x32_bf16 v[20:23], v[144:147], v[206:209], v[20:23]
	v_mfma_f32_16x16x32_bf16 v[20:23], v[148:151], v[210:213], v[20:23]
	v_mfma_f32_16x16x32_bf16 v[16:19], v[176:179], v[210:213], v[16:19]
	v_mfma_f32_16x16x32_bf16 v[16:19], v[172:175], v[206:209], v[16:19]
	v_mfma_f32_16x16x32_bf16 v[0:3], v[172:175], v[214:217], v[0:3]
	v_mfma_f32_16x16x32_bf16 v[0:3], v[176:179], v[218:221], v[0:3]
	v_mfma_f32_16x16x32_bf16 v[4:7], v[148:151], v[218:221], v[4:7]
	v_mfma_f32_16x16x32_bf16 v[4:7], v[144:147], v[214:217], v[4:7]
	s_setprio 0
	s_barrier
	s_add_i32 s81, s81, 2
	s_add_u32 s79, s79, 0x100
	s_addc_u32 s80, s80, 0
	s_cmp_gt_u32 s81, 41
	s_mov_b64 s[54:55], s[56:57]
	s_branch .LBB0_610
.Lfa_5:
	ds_read_b128 v[128:131], v189
	ds_read_b128 v[132:135], v189 offset:1024
	ds_read_b128 v[136:139], v189 offset:2048
	ds_read_b128 v[140:143], v189 offset:3072
	ds_read_b128 v[144:147], v190
	ds_read_b128 v[148:151], v190 offset:1024
	ds_read_b128 v[172:175], v190 offset:2048
	ds_read_b128 v[176:179], v190 offset:3072
	s_add_u32 s56, s54, 0x100
	s_addc_u32 s57, s55, 0
	s_cmp_eq_u32 s81, 40
	s_cselect_b32 s61, s17, s57
	s_cselect_b32 s60, s16, s56
	s_cselect_b32 s59, s53, s80
	s_cselect_b32 s58, s52, s79
	v_lshl_add_u64 v[222:223], s[54:55], 0, v[166:167]
	s_add_i32 m0, s66, 0xc000
	ds_read_b128 v[180:183], v191
	ds_read_b128 v[194:197], v191 offset:1024
	ds_read_b128 v[198:201], v191 offset:2048
	ds_read_b128 v[202:205], v191 offset:3072
	ds_read_b128 v[206:209], v191 offset:4096
	ds_read_b128 v[210:213], v191 offset:5120
	ds_read_b128 v[214:217], v191 offset:6144
	ds_read_b128 v[218:221], v191 offset:7168
	global_load_lds_dwordx4 v[222:223], off
	v_lshl_add_u64 v[222:223], s[54:55], 0, v[164:165]
	s_add_i32 m0, s66, 0xe000
	s_nop 0
	global_load_lds_dwordx4 v[222:223], off
	s_waitcnt vmcnt(8)
	s_waitcnt lgkmcnt(0)
	s_barrier
	s_setprio 1
	s_waitcnt lgkmcnt(0)
	v_mfma_f32_16x16x32_bf16 v[124:127], v[128:131], v[180:183], 0
	v_mfma_f32_16x16x32_bf16 v[120:123], v[136:139], v[180:183], 0
	v_mfma_f32_16x16x32_bf16 v[108:111], v[128:131], v[198:201], 0
	v_mfma_f32_16x16x32_bf16 v[104:107], v[136:139], v[198:201], 0
	v_mfma_f32_16x16x32_bf16 v[92:95], v[128:131], v[206:209], 0
	v_mfma_f32_16x16x32_bf16 v[88:91], v[136:139], v[206:209], 0
	v_mfma_f32_16x16x32_bf16 v[76:79], v[128:131], v[214:217], 0
	v_mfma_f32_16x16x32_bf16 v[72:75], v[136:139], v[214:217], 0
	v_mfma_f32_16x16x32_bf16 v[124:127], v[132:135], v[194:197], v[124:127]
	v_mfma_f32_16x16x32_bf16 v[120:123], v[140:143], v[194:197], v[120:123]
	v_mfma_f32_16x16x32_bf16 v[108:111], v[132:135], v[202:205], v[108:111]
	v_mfma_f32_16x16x32_bf16 v[104:107], v[140:143], v[202:205], v[104:107]
	v_mfma_f32_16x16x32_bf16 v[92:95], v[132:135], v[210:213], v[92:95]
	v_mfma_f32_16x16x32_bf16 v[88:91], v[140:143], v[210:213], v[88:91]
	v_mfma_f32_16x16x32_bf16 v[76:79], v[132:135], v[218:221], v[76:79]
	v_mfma_f32_16x16x32_bf16 v[72:75], v[140:143], v[218:221], v[72:75]
	s_setprio 0
	s_setprio 1
	v_mfma_f32_16x16x32_bf16 v[116:119], v[144:147], v[180:183], 0
	v_mfma_f32_16x16x32_bf16 v[112:115], v[172:175], v[180:183], 0
	v_mfma_f32_16x16x32_bf16 v[100:103], v[144:147], v[198:201], 0
	v_mfma_f32_16x16x32_bf16 v[96:99], v[172:175], v[198:201], 0
	v_mfma_f32_16x16x32_bf16 v[84:87], v[144:147], v[206:209], 0
	v_mfma_f32_16x16x32_bf16 v[80:83], v[172:175], v[206:209], 0
	v_mfma_f32_16x16x32_bf16 v[68:71], v[144:147], v[214:217], 0
	v_mfma_f32_16x16x32_bf16 v[64:67], v[172:175], v[214:217], 0
	v_mfma_f32_16x16x32_bf16 v[116:119], v[148:151], v[194:197], v[116:119]
	v_mfma_f32_16x16x32_bf16 v[112:115], v[176:179], v[194:197], v[112:115]
	v_mfma_f32_16x16x32_bf16 v[100:103], v[148:151], v[202:205], v[100:103]
	v_mfma_f32_16x16x32_bf16 v[96:99], v[176:179], v[202:205], v[96:99]
	v_mfma_f32_16x16x32_bf16 v[84:87], v[148:151], v[210:213], v[84:87]
	v_mfma_f32_16x16x32_bf16 v[80:83], v[176:179], v[210:213], v[80:83]
	v_mfma_f32_16x16x32_bf16 v[68:71], v[148:151], v[218:221], v[68:71]
	v_mfma_f32_16x16x32_bf16 v[64:67], v[176:179], v[218:221], v[64:67]
	s_setprio 0
	s_barrier
	s_add_i32 s54, s75, s65
	v_lshl_add_u64 v[222:223], s[58:59], 0, v[154:155]
	s_mov_b32 m0, s54
	ds_read_b128 v[180:183], v191 offset:16384
	ds_read_b128 v[194:197], v191 offset:17408
	ds_read_b128 v[198:201], v191 offset:18432
	ds_read_b128 v[202:205], v191 offset:19456
	ds_read_b128 v[206:209], v191 offset:20480
	ds_read_b128 v[210:213], v191 offset:21504
	ds_read_b128 v[214:217], v191 offset:22528
	ds_read_b128 v[218:221], v191 offset:23552
	global_load_lds_dwordx4 v[222:223], off
	s_add_i32 m0, s54, 0x2000
	s_add_u32 s54, s58, 0xb0000
	v_lshl_add_u64 v[224:225], s[58:59], 0, v[162:163]
	s_addc_u32 s55, s59, 0
	s_add_i32 s82, s76, s65
	global_load_lds_dwordx4 v[224:225], off
	v_lshl_add_u64 v[226:227], s[54:55], 0, v[154:155]
	s_mov_b32 m0, s82
	v_lshl_add_u64 v[228:229], s[60:61], 0, v[160:161]
	global_load_lds_dwordx4 v[226:227], off
	v_lshl_add_u64 v[226:227], s[54:55], 0, v[162:163]
	s_add_i32 m0, s82, 0x2000
	s_nop 0
	global_load_lds_dwordx4 v[226:227], off
	v_lshl_add_u64 v[226:227], s[60:61], 0, v[152:153]
	s_mov_b32 m0, s66
	s_nop 0
	global_load_lds_dwordx4 v[226:227], off
	s_mov_b32 m0, s67
	s_nop 0
	global_load_lds_dwordx4 v[228:229], off
	s_waitcnt vmcnt(8)
	s_waitcnt lgkmcnt(0)
	s_barrier
	s_setprio 1
	s_waitcnt lgkmcnt(0)
	v_mfma_f32_16x16x32_bf16 v[60:63], v[128:131], v[180:183], 0
	v_mfma_f32_16x16x32_bf16 v[56:59], v[136:139], v[180:183], 0
	v_mfma_f32_16x16x32_bf16 v[44:47], v[128:131], v[198:201], 0
	v_mfma_f32_16x16x32_bf16 v[40:43], v[136:139], v[198:201], 0
	v_mfma_f32_16x16x32_bf16 v[28:31], v[128:131], v[206:209], 0
	v_mfma_f32_16x16x32_bf16 v[24:27], v[136:139], v[206:209], 0
	v_mfma_f32_16x16x32_bf16 v[12:15], v[128:131], v[214:217], 0
	v_mfma_f32_16x16x32_bf16 v[8:11], v[136:139], v[214:217], 0
	v_mfma_f32_16x16x32_bf16 v[60:63], v[132:135], v[194:197], v[60:63]
	v_mfma_f32_16x16x32_bf16 v[56:59], v[140:143], v[194:197], v[56:59]
	v_mfma_f32_16x16x32_bf16 v[44:47], v[132:135], v[202:205], v[44:47]
	v_mfma_f32_16x16x32_bf16 v[40:43], v[140:143], v[202:205], v[40:43]
	v_mfma_f32_16x16x32_bf16 v[28:31], v[132:135], v[210:213], v[28:31]
	v_mfma_f32_16x16x32_bf16 v[24:27], v[140:143], v[210:213], v[24:27]
	v_mfma_f32_16x16x32_bf16 v[12:15], v[132:135], v[218:221], v[12:15]
	v_mfma_f32_16x16x32_bf16 v[8:11], v[140:143], v[218:221], v[8:11]
	s_setprio 0
	s_setprio 1
	v_mfma_f32_16x16x32_bf16 v[52:55], v[144:147], v[180:183], 0
	v_mfma_f32_16x16x32_bf16 v[48:51], v[172:175], v[180:183], 0
	v_mfma_f32_16x16x32_bf16 v[36:39], v[144:147], v[198:201], 0
	v_mfma_f32_16x16x32_bf16 v[32:35], v[172:175], v[198:201], 0
	v_mfma_f32_16x16x32_bf16 v[20:23], v[144:147], v[206:209], 0
	v_mfma_f32_16x16x32_bf16 v[16:19], v[172:175], v[206:209], 0
	v_mfma_f32_16x16x32_bf16 v[4:7], v[144:147], v[214:217], 0
	v_mfma_f32_16x16x32_bf16 v[0:3], v[172:175], v[214:217], 0
	v_mfma_f32_16x16x32_bf16 v[52:55], v[148:151], v[194:197], v[52:55]
	v_mfma_f32_16x16x32_bf16 v[48:51], v[176:179], v[194:197], v[48:51]
	v_mfma_f32_16x16x32_bf16 v[36:39], v[148:151], v[202:205], v[36:39]
	v_mfma_f32_16x16x32_bf16 v[32:35], v[176:179], v[202:205], v[32:35]
	v_mfma_f32_16x16x32_bf16 v[20:23], v[148:151], v[210:213], v[20:23]
	v_mfma_f32_16x16x32_bf16 v[16:19], v[176:179], v[210:213], v[16:19]
	v_mfma_f32_16x16x32_bf16 v[4:7], v[148:151], v[218:221], v[4:7]
	v_mfma_f32_16x16x32_bf16 v[0:3], v[176:179], v[218:221], v[0:3]
	s_setprio 0
	s_barrier
	s_add_i32 s82, 0, 0x18000
	s_add_i32 s83, 0, 0x1c000
	v_add_u32_e32 v140, s82, v186
	v_add_u32_e32 v176, s83, v186
	ds_read_b128 v[128:131], v140
	ds_read_b128 v[132:135], v140 offset:1024
	ds_read_b128 v[136:139], v140 offset:2048
	ds_read_b128 v[140:143], v140 offset:3072
	ds_read_b128 v[144:147], v176
	ds_read_b128 v[148:151], v176 offset:1024
	ds_read_b128 v[172:175], v176 offset:2048
	ds_read_b128 v[176:179], v176 offset:3072
	s_add_u32 s54, s60, 0xb0000
	s_addc_u32 s55, s61, 0
	s_mov_b32 m0, s68
	v_lshl_add_u64 v[230:231], s[54:55], 0, v[152:153]
	ds_read_b128 v[180:183], v191 offset:32768
	ds_read_b128 v[194:197], v191 offset:33792
	ds_read_b128 v[198:201], v191 offset:34816
	ds_read_b128 v[202:205], v191 offset:35840
	ds_read_b128 v[206:209], v191 offset:36864
	ds_read_b128 v[210:213], v191 offset:37888
	ds_read_b128 v[214:217], v191 offset:38912
	ds_read_b128 v[218:221], v191 offset:39936
	global_load_lds_dwordx4 v[230:231], off
	v_lshl_add_u64 v[230:231], s[54:55], 0, v[160:161]
	s_mov_b32 m0, s69
	s_nop 0
	global_load_lds_dwordx4 v[230:231], off
	s_waitcnt vmcnt(8)
	s_waitcnt lgkmcnt(0)
	s_barrier
	s_setprio 1
	s_waitcnt lgkmcnt(0)
	v_mfma_f32_16x16x32_bf16 v[124:127], v[128:131], v[180:183], v[124:127]
	v_mfma_f32_16x16x32_bf16 v[124:127], v[132:135], v[194:197], v[124:127]
	v_mfma_f32_16x16x32_bf16 v[120:123], v[140:143], v[194:197], v[120:123]
	v_mfma_f32_16x16x32_bf16 v[120:123], v[136:139], v[180:183], v[120:123]
	v_mfma_f32_16x16x32_bf16 v[104:107], v[136:139], v[198:201], v[104:107]
	v_mfma_f32_16x16x32_bf16 v[104:107], v[140:143], v[202:205], v[104:107]
	v_mfma_f32_16x16x32_bf16 v[108:111], v[132:135], v[202:205], v[108:111]
	v_mfma_f32_16x16x32_bf16 v[108:111], v[128:131], v[198:201], v[108:111]
	v_mfma_f32_16x16x32_bf16 v[92:95], v[128:131], v[206:209], v[92:95]
	v_mfma_f32_16x16x32_bf16 v[92:95], v[132:135], v[210:213], v[92:95]
	v_mfma_f32_16x16x32_bf16 v[88:91], v[140:143], v[210:213], v[88:91]
	v_mfma_f32_16x16x32_bf16 v[88:91], v[136:139], v[206:209], v[88:91]
	v_mfma_f32_16x16x32_bf16 v[72:75], v[136:139], v[214:217], v[72:75]
	v_mfma_f32_16x16x32_bf16 v[72:75], v[140:143], v[218:221], v[72:75]
	v_mfma_f32_16x16x32_bf16 v[76:79], v[132:135], v[218:221], v[76:79]
	v_mfma_f32_16x16x32_bf16 v[76:79], v[128:131], v[214:217], v[76:79]
	s_setprio 0
	s_setprio 1
	v_mfma_f32_16x16x32_bf16 v[116:119], v[144:147], v[180:183], v[116:119]
	v_mfma_f32_16x16x32_bf16 v[116:119], v[148:151], v[194:197], v[116:119]
	v_mfma_f32_16x16x32_bf16 v[112:115], v[176:179], v[194:197], v[112:115]
	v_mfma_f32_16x16x32_bf16 v[112:115], v[172:175], v[180:183], v[112:115]
	v_mfma_f32_16x16x32_bf16 v[96:99], v[172:175], v[198:201], v[96:99]
	v_mfma_f32_16x16x32_bf16 v[96:99], v[176:179], v[202:205], v[96:99]
	v_mfma_f32_16x16x32_bf16 v[100:103], v[148:151], v[202:205], v[100:103]
	v_mfma_f32_16x16x32_bf16 v[100:103], v[144:147], v[198:201], v[100:103]
	v_mfma_f32_16x16x32_bf16 v[84:87], v[144:147], v[206:209], v[84:87]
	v_mfma_f32_16x16x32_bf16 v[84:87], v[148:151], v[210:213], v[84:87]
	v_mfma_f32_16x16x32_bf16 v[80:83], v[176:179], v[210:213], v[80:83]
	v_mfma_f32_16x16x32_bf16 v[80:83], v[172:175], v[206:209], v[80:83]
	v_mfma_f32_16x16x32_bf16 v[64:67], v[172:175], v[214:217], v[64:67]
	v_mfma_f32_16x16x32_bf16 v[64:67], v[176:179], v[218:221], v[64:67]
	v_mfma_f32_16x16x32_bf16 v[68:71], v[148:151], v[218:221], v[68:71]
	v_mfma_f32_16x16x32_bf16 v[68:71], v[144:147], v[214:217], v[68:71]
	s_setprio 0
	s_barrier
	s_add_i32 s54, s82, s65
	v_lshl_add_u64 v[222:223], v[222:223], 0, s[28:29]
	s_mov_b32 m0, s54
	ds_read_b128 v[180:183], v191 offset:49152
	ds_read_b128 v[194:197], v191 offset:50176
	ds_read_b128 v[198:201], v191 offset:51200
	ds_read_b128 v[202:205], v191 offset:52224
	ds_read_b128 v[206:209], v191 offset:53248
	ds_read_b128 v[210:213], v191 offset:54272
	ds_read_b128 v[214:217], v191 offset:55296
	ds_read_b128 v[218:221], v191 offset:56320
	global_load_lds_dwordx4 v[222:223], off
	s_add_i32 m0, s54, 0x2000
	s_add_u32 s54, s58, 0xb0080
	v_lshl_add_u64 v[222:223], v[224:225], 0, s[28:29]
	s_addc_u32 s55, s59, 0
	s_add_i32 s58, s83, s65
	global_load_lds_dwordx4 v[222:223], off
	v_lshl_add_u64 v[222:223], s[54:55], 0, v[154:155]
	s_mov_b32 m0, s58
	s_nop 0
	global_load_lds_dwordx4 v[222:223], off
	v_lshl_add_u64 v[222:223], s[54:55], 0, v[162:163]
	s_add_i32 m0, s58, 0x2000
	s_nop 0
	global_load_lds_dwordx4 v[222:223], off
	v_lshl_add_u64 v[222:223], v[226:227], 0, s[28:29]
	s_mov_b32 m0, s3
	s_nop 0
	global_load_lds_dwordx4 v[222:223], off
	v_lshl_add_u64 v[222:223], v[228:229], 0, s[28:29]
	s_mov_b32 m0, s71
	s_nop 0
	global_load_lds_dwordx4 v[222:223], off
	s_waitcnt vmcnt(8)
	s_waitcnt lgkmcnt(0)
	s_barrier
	s_setprio 1
	s_waitcnt lgkmcnt(0)
	v_mfma_f32_16x16x32_bf16 v[60:63], v[128:131], v[180:183], v[60:63]
	v_mfma_f32_16x16x32_bf16 v[60:63], v[132:135], v[194:197], v[60:63]
	v_mfma_f32_16x16x32_bf16 v[56:59], v[140:143], v[194:197], v[56:59]
	v_mfma_f32_16x16x32_bf16 v[56:59], v[136:139], v[180:183], v[56:59]
	v_mfma_f32_16x16x32_bf16 v[40:43], v[136:139], v[198:201], v[40:43]
	v_mfma_f32_16x16x32_bf16 v[40:43], v[140:143], v[202:205], v[40:43]
	v_mfma_f32_16x16x32_bf16 v[44:47], v[132:135], v[202:205], v[44:47]
	v_mfma_f32_16x16x32_bf16 v[44:47], v[128:131], v[198:201], v[44:47]
	v_mfma_f32_16x16x32_bf16 v[28:31], v[128:131], v[206:209], v[28:31]
	v_mfma_f32_16x16x32_bf16 v[28:31], v[132:135], v[210:213], v[28:31]
	v_mfma_f32_16x16x32_bf16 v[24:27], v[140:143], v[210:213], v[24:27]
	v_mfma_f32_16x16x32_bf16 v[24:27], v[136:139], v[206:209], v[24:27]
	v_mfma_f32_16x16x32_bf16 v[8:11], v[136:139], v[214:217], v[8:11]
	v_mfma_f32_16x16x32_bf16 v[8:11], v[140:143], v[218:221], v[8:11]
	v_mfma_f32_16x16x32_bf16 v[12:15], v[132:135], v[218:221], v[12:15]
	v_mfma_f32_16x16x32_bf16 v[12:15], v[128:131], v[214:217], v[12:15]
	s_setprio 0
	s_setprio 1
	v_mfma_f32_16x16x32_bf16 v[52:55], v[144:147], v[180:183], v[52:55]
	v_mfma_f32_16x16x32_bf16 v[52:55], v[148:151], v[194:197], v[52:55]
	v_mfma_f32_16x16x32_bf16 v[48:51], v[176:179], v[194:197], v[48:51]
	v_mfma_f32_16x16x32_bf16 v[48:51], v[172:175], v[180:183], v[48:51]
	v_mfma_f32_16x16x32_bf16 v[32:35], v[172:175], v[198:201], v[32:35]
	v_mfma_f32_16x16x32_bf16 v[32:35], v[176:179], v[202:205], v[32:35]
	v_mfma_f32_16x16x32_bf16 v[36:39], v[148:151], v[202:205], v[36:39]
	v_mfma_f32_16x16x32_bf16 v[36:39], v[144:147], v[198:201], v[36:39]
	v_mfma_f32_16x16x32_bf16 v[20:23], v[144:147], v[206:209], v[20:23]
	v_mfma_f32_16x16x32_bf16 v[20:23], v[148:151], v[210:213], v[20:23]
	v_mfma_f32_16x16x32_bf16 v[16:19], v[176:179], v[210:213], v[16:19]
	v_mfma_f32_16x16x32_bf16 v[16:19], v[172:175], v[206:209], v[16:19]
	v_mfma_f32_16x16x32_bf16 v[0:3], v[172:175], v[214:217], v[0:3]
	v_mfma_f32_16x16x32_bf16 v[0:3], v[176:179], v[218:221], v[0:3]
	v_mfma_f32_16x16x32_bf16 v[4:7], v[148:151], v[218:221], v[4:7]
	v_mfma_f32_16x16x32_bf16 v[4:7], v[144:147], v[214:217], v[4:7]
	s_setprio 0
	s_barrier
	s_add_i32 s81, s81, 2
	s_add_u32 s79, s79, 0x100
	s_addc_u32 s80, s80, 0
	s_cmp_gt_u32 s81, 41
	s_mov_b64 s[54:55], s[56:57]
.LBB0_610:
	ds_read_b128 v[128:131], v189
	ds_read_b128 v[132:135], v189 offset:1024
	ds_read_b128 v[136:139], v189 offset:2048
	ds_read_b128 v[140:143], v189 offset:3072
	ds_read_b128 v[144:147], v190
	ds_read_b128 v[148:151], v190 offset:1024
	ds_read_b128 v[172:175], v190 offset:2048
	ds_read_b128 v[176:179], v190 offset:3072
	s_add_u32 s56, s54, 0x100
	s_addc_u32 s57, s55, 0
	s_cmp_eq_u32 s81, 40
	s_cselect_b32 s61, s17, s57
	s_cselect_b32 s60, s16, s56
	s_cselect_b32 s59, s53, s80
	s_cselect_b32 s58, s52, s79
	v_lshl_add_u64 v[222:223], s[54:55], 0, v[166:167]
	s_add_i32 m0, s66, 0xc000
	ds_read_b128 v[180:183], v191
	ds_read_b128 v[194:197], v191 offset:1024
	ds_read_b128 v[198:201], v191 offset:2048
	ds_read_b128 v[202:205], v191 offset:3072
	ds_read_b128 v[206:209], v191 offset:4096
	ds_read_b128 v[210:213], v191 offset:5120
	ds_read_b128 v[214:217], v191 offset:6144
	ds_read_b128 v[218:221], v191 offset:7168
	global_load_lds_dwordx4 v[222:223], off
	v_lshl_add_u64 v[222:223], s[54:55], 0, v[164:165]
	s_add_i32 m0, s66, 0xe000
	s_nop 0
	global_load_lds_dwordx4 v[222:223], off
	s_waitcnt vmcnt(8)
	s_waitcnt lgkmcnt(0)
	s_barrier
	s_setprio 1
	s_waitcnt lgkmcnt(0)
	v_mfma_f32_16x16x32_bf16 v[124:127], v[128:131], v[180:183], v[124:127]
	v_mfma_f32_16x16x32_bf16 v[124:127], v[132:135], v[194:197], v[124:127]
	v_mfma_f32_16x16x32_bf16 v[120:123], v[140:143], v[194:197], v[120:123]
	v_mfma_f32_16x16x32_bf16 v[120:123], v[136:139], v[180:183], v[120:123]
	v_mfma_f32_16x16x32_bf16 v[104:107], v[136:139], v[198:201], v[104:107]
	v_mfma_f32_16x16x32_bf16 v[104:107], v[140:143], v[202:205], v[104:107]
	v_mfma_f32_16x16x32_bf16 v[108:111], v[132:135], v[202:205], v[108:111]
	v_mfma_f32_16x16x32_bf16 v[108:111], v[128:131], v[198:201], v[108:111]
	v_mfma_f32_16x16x32_bf16 v[92:95], v[128:131], v[206:209], v[92:95]
	v_mfma_f32_16x16x32_bf16 v[92:95], v[132:135], v[210:213], v[92:95]
	v_mfma_f32_16x16x32_bf16 v[88:91], v[140:143], v[210:213], v[88:91]
	v_mfma_f32_16x16x32_bf16 v[88:91], v[136:139], v[206:209], v[88:91]
	v_mfma_f32_16x16x32_bf16 v[72:75], v[136:139], v[214:217], v[72:75]
	v_mfma_f32_16x16x32_bf16 v[72:75], v[140:143], v[218:221], v[72:75]
	v_mfma_f32_16x16x32_bf16 v[76:79], v[132:135], v[218:221], v[76:79]
	v_mfma_f32_16x16x32_bf16 v[76:79], v[128:131], v[214:217], v[76:79]
	s_setprio 0
	s_setprio 1
	v_mfma_f32_16x16x32_bf16 v[116:119], v[144:147], v[180:183], v[116:119]
	v_mfma_f32_16x16x32_bf16 v[116:119], v[148:151], v[194:197], v[116:119]
	v_mfma_f32_16x16x32_bf16 v[112:115], v[176:179], v[194:197], v[112:115]
	v_mfma_f32_16x16x32_bf16 v[112:115], v[172:175], v[180:183], v[112:115]
	v_mfma_f32_16x16x32_bf16 v[96:99], v[172:175], v[198:201], v[96:99]
	v_mfma_f32_16x16x32_bf16 v[96:99], v[176:179], v[202:205], v[96:99]
	v_mfma_f32_16x16x32_bf16 v[100:103], v[148:151], v[202:205], v[100:103]
	v_mfma_f32_16x16x32_bf16 v[100:103], v[144:147], v[198:201], v[100:103]
	v_mfma_f32_16x16x32_bf16 v[84:87], v[144:147], v[206:209], v[84:87]
	v_mfma_f32_16x16x32_bf16 v[84:87], v[148:151], v[210:213], v[84:87]
	v_mfma_f32_16x16x32_bf16 v[80:83], v[176:179], v[210:213], v[80:83]
	v_mfma_f32_16x16x32_bf16 v[80:83], v[172:175], v[206:209], v[80:83]
	v_mfma_f32_16x16x32_bf16 v[64:67], v[172:175], v[214:217], v[64:67]
	v_mfma_f32_16x16x32_bf16 v[64:67], v[176:179], v[218:221], v[64:67]
	v_mfma_f32_16x16x32_bf16 v[68:71], v[148:151], v[218:221], v[68:71]
	v_mfma_f32_16x16x32_bf16 v[68:71], v[144:147], v[214:217], v[68:71]
	s_setprio 0
	s_barrier
	s_add_i32 s54, s75, s65
	v_lshl_add_u64 v[222:223], s[58:59], 0, v[154:155]
	s_mov_b32 m0, s54
	ds_read_b128 v[180:183], v191 offset:16384
	ds_read_b128 v[194:197], v191 offset:17408
	ds_read_b128 v[198:201], v191 offset:18432
	ds_read_b128 v[202:205], v191 offset:19456
	ds_read_b128 v[206:209], v191 offset:20480
	ds_read_b128 v[210:213], v191 offset:21504
	ds_read_b128 v[214:217], v191 offset:22528
	ds_read_b128 v[218:221], v191 offset:23552
	global_load_lds_dwordx4 v[222:223], off
	s_add_i32 m0, s54, 0x2000
	s_add_u32 s54, s58, 0xb0000
	v_lshl_add_u64 v[224:225], s[58:59], 0, v[162:163]
	s_addc_u32 s55, s59, 0
	s_add_i32 s82, s76, s65
	global_load_lds_dwordx4 v[224:225], off
	v_lshl_add_u64 v[226:227], s[54:55], 0, v[154:155]
	s_mov_b32 m0, s82
	v_lshl_add_u64 v[228:229], s[60:61], 0, v[160:161]
	global_load_lds_dwordx4 v[226:227], off
	v_lshl_add_u64 v[226:227], s[54:55], 0, v[162:163]
	s_add_i32 m0, s82, 0x2000
	s_nop 0
	global_load_lds_dwordx4 v[226:227], off
	v_lshl_add_u64 v[226:227], s[60:61], 0, v[152:153]
	s_mov_b32 m0, s66
	s_nop 0
	global_load_lds_dwordx4 v[226:227], off
	s_mov_b32 m0, s67
	s_nop 0
	global_load_lds_dwordx4 v[228:229], off
	s_waitcnt vmcnt(8)
	s_waitcnt lgkmcnt(0)
	s_barrier
	s_setprio 1
	s_waitcnt lgkmcnt(0)
	v_mfma_f32_16x16x32_bf16 v[60:63], v[128:131], v[180:183], v[60:63]
	v_mfma_f32_16x16x32_bf16 v[60:63], v[132:135], v[194:197], v[60:63]
	v_mfma_f32_16x16x32_bf16 v[56:59], v[140:143], v[194:197], v[56:59]
	v_mfma_f32_16x16x32_bf16 v[56:59], v[136:139], v[180:183], v[56:59]
	v_mfma_f32_16x16x32_bf16 v[40:43], v[136:139], v[198:201], v[40:43]
	v_mfma_f32_16x16x32_bf16 v[40:43], v[140:143], v[202:205], v[40:43]
	v_mfma_f32_16x16x32_bf16 v[44:47], v[132:135], v[202:205], v[44:47]
	v_mfma_f32_16x16x32_bf16 v[44:47], v[128:131], v[198:201], v[44:47]
	v_mfma_f32_16x16x32_bf16 v[28:31], v[128:131], v[206:209], v[28:31]
	v_mfma_f32_16x16x32_bf16 v[28:31], v[132:135], v[210:213], v[28:31]
	v_mfma_f32_16x16x32_bf16 v[24:27], v[140:143], v[210:213], v[24:27]
	v_mfma_f32_16x16x32_bf16 v[24:27], v[136:139], v[206:209], v[24:27]
	v_mfma_f32_16x16x32_bf16 v[8:11], v[136:139], v[214:217], v[8:11]
	v_mfma_f32_16x16x32_bf16 v[8:11], v[140:143], v[218:221], v[8:11]
	v_mfma_f32_16x16x32_bf16 v[12:15], v[132:135], v[218:221], v[12:15]
	v_mfma_f32_16x16x32_bf16 v[12:15], v[128:131], v[214:217], v[12:15]
	s_setprio 0
	s_setprio 1
	v_mfma_f32_16x16x32_bf16 v[52:55], v[144:147], v[180:183], v[52:55]
	v_mfma_f32_16x16x32_bf16 v[52:55], v[148:151], v[194:197], v[52:55]
	v_mfma_f32_16x16x32_bf16 v[48:51], v[176:179], v[194:197], v[48:51]
	v_mfma_f32_16x16x32_bf16 v[48:51], v[172:175], v[180:183], v[48:51]
	v_mfma_f32_16x16x32_bf16 v[32:35], v[172:175], v[198:201], v[32:35]
	v_mfma_f32_16x16x32_bf16 v[32:35], v[176:179], v[202:205], v[32:35]
	v_mfma_f32_16x16x32_bf16 v[36:39], v[148:151], v[202:205], v[36:39]
	v_mfma_f32_16x16x32_bf16 v[36:39], v[144:147], v[198:201], v[36:39]
	v_mfma_f32_16x16x32_bf16 v[20:23], v[144:147], v[206:209], v[20:23]
	v_mfma_f32_16x16x32_bf16 v[20:23], v[148:151], v[210:213], v[20:23]
	v_mfma_f32_16x16x32_bf16 v[16:19], v[176:179], v[210:213], v[16:19]
	v_mfma_f32_16x16x32_bf16 v[16:19], v[172:175], v[206:209], v[16:19]
	v_mfma_f32_16x16x32_bf16 v[0:3], v[172:175], v[214:217], v[0:3]
	v_mfma_f32_16x16x32_bf16 v[0:3], v[176:179], v[218:221], v[0:3]
	v_mfma_f32_16x16x32_bf16 v[4:7], v[148:151], v[218:221], v[4:7]
	v_mfma_f32_16x16x32_bf16 v[4:7], v[144:147], v[214:217], v[4:7]
	s_setprio 0
	s_barrier
	s_add_i32 s82, 0, 0x18000
	s_add_i32 s83, 0, 0x1c000
	v_add_u32_e32 v140, s82, v186
	v_add_u32_e32 v176, s83, v186
	ds_read_b128 v[128:131], v140
	ds_read_b128 v[132:135], v140 offset:1024
	ds_read_b128 v[136:139], v140 offset:2048
	ds_read_b128 v[140:143], v140 offset:3072
	ds_read_b128 v[144:147], v176
	ds_read_b128 v[148:151], v176 offset:1024
	ds_read_b128 v[172:175], v176 offset:2048
	ds_read_b128 v[176:179], v176 offset:3072
	s_add_u32 s54, s60, 0xb0000
	s_addc_u32 s55, s61, 0
	s_mov_b32 m0, s68
	v_lshl_add_u64 v[230:231], s[54:55], 0, v[152:153]
	ds_read_b128 v[180:183], v191 offset:32768
	ds_read_b128 v[194:197], v191 offset:33792
	ds_read_b128 v[198:201], v191 offset:34816
	ds_read_b128 v[202:205], v191 offset:35840
	ds_read_b128 v[206:209], v191 offset:36864
	ds_read_b128 v[210:213], v191 offset:37888
	ds_read_b128 v[214:217], v191 offset:38912
	ds_read_b128 v[218:221], v191 offset:39936
	global_load_lds_dwordx4 v[230:231], off
	v_lshl_add_u64 v[230:231], s[54:55], 0, v[160:161]
	s_mov_b32 m0, s69
	s_nop 0
	global_load_lds_dwordx4 v[230:231], off
	s_waitcnt vmcnt(8)
	s_waitcnt lgkmcnt(0)
	s_barrier
	s_setprio 1
	s_waitcnt lgkmcnt(0)
	v_mfma_f32_16x16x32_bf16 v[124:127], v[128:131], v[180:183], v[124:127]
	v_mfma_f32_16x16x32_bf16 v[124:127], v[132:135], v[194:197], v[124:127]
	v_mfma_f32_16x16x32_bf16 v[120:123], v[140:143], v[194:197], v[120:123]
	v_mfma_f32_16x16x32_bf16 v[120:123], v[136:139], v[180:183], v[120:123]
	v_mfma_f32_16x16x32_bf16 v[104:107], v[136:139], v[198:201], v[104:107]
	v_mfma_f32_16x16x32_bf16 v[104:107], v[140:143], v[202:205], v[104:107]
	v_mfma_f32_16x16x32_bf16 v[108:111], v[132:135], v[202:205], v[108:111]
	v_mfma_f32_16x16x32_bf16 v[108:111], v[128:131], v[198:201], v[108:111]
	v_mfma_f32_16x16x32_bf16 v[92:95], v[128:131], v[206:209], v[92:95]
	v_mfma_f32_16x16x32_bf16 v[92:95], v[132:135], v[210:213], v[92:95]
	v_mfma_f32_16x16x32_bf16 v[88:91], v[140:143], v[210:213], v[88:91]
	v_mfma_f32_16x16x32_bf16 v[88:91], v[136:139], v[206:209], v[88:91]
	v_mfma_f32_16x16x32_bf16 v[72:75], v[136:139], v[214:217], v[72:75]
	v_mfma_f32_16x16x32_bf16 v[72:75], v[140:143], v[218:221], v[72:75]
	v_mfma_f32_16x16x32_bf16 v[76:79], v[132:135], v[218:221], v[76:79]
	v_mfma_f32_16x16x32_bf16 v[76:79], v[128:131], v[214:217], v[76:79]
	s_setprio 0
	s_setprio 1
	v_mfma_f32_16x16x32_bf16 v[116:119], v[144:147], v[180:183], v[116:119]
	v_mfma_f32_16x16x32_bf16 v[116:119], v[148:151], v[194:197], v[116:119]
	v_mfma_f32_16x16x32_bf16 v[112:115], v[176:179], v[194:197], v[112:115]
	v_mfma_f32_16x16x32_bf16 v[112:115], v[172:175], v[180:183], v[112:115]
	v_mfma_f32_16x16x32_bf16 v[96:99], v[172:175], v[198:201], v[96:99]
	v_mfma_f32_16x16x32_bf16 v[96:99], v[176:179], v[202:205], v[96:99]
	v_mfma_f32_16x16x32_bf16 v[100:103], v[148:151], v[202:205], v[100:103]
	v_mfma_f32_16x16x32_bf16 v[100:103], v[144:147], v[198:201], v[100:103]
	v_mfma_f32_16x16x32_bf16 v[84:87], v[144:147], v[206:209], v[84:87]
	v_mfma_f32_16x16x32_bf16 v[84:87], v[148:151], v[210:213], v[84:87]
	v_mfma_f32_16x16x32_bf16 v[80:83], v[176:179], v[210:213], v[80:83]
	v_mfma_f32_16x16x32_bf16 v[80:83], v[172:175], v[206:209], v[80:83]
	v_mfma_f32_16x16x32_bf16 v[64:67], v[172:175], v[214:217], v[64:67]
	v_mfma_f32_16x16x32_bf16 v[64:67], v[176:179], v[218:221], v[64:67]
	v_mfma_f32_16x16x32_bf16 v[68:71], v[148:151], v[218:221], v[68:71]
	v_mfma_f32_16x16x32_bf16 v[68:71], v[144:147], v[214:217], v[68:71]
	s_setprio 0
	s_barrier
	s_add_i32 s54, s82, s65
	v_lshl_add_u64 v[222:223], v[222:223], 0, s[28:29]
	s_mov_b32 m0, s54
	ds_read_b128 v[180:183], v191 offset:49152
	ds_read_b128 v[194:197], v191 offset:50176
	ds_read_b128 v[198:201], v191 offset:51200
	ds_read_b128 v[202:205], v191 offset:52224
	ds_read_b128 v[206:209], v191 offset:53248
	ds_read_b128 v[210:213], v191 offset:54272
	ds_read_b128 v[214:217], v191 offset:55296
	ds_read_b128 v[218:221], v191 offset:56320
	global_load_lds_dwordx4 v[222:223], off
	s_add_i32 m0, s54, 0x2000
	s_add_u32 s54, s58, 0xb0080
	v_lshl_add_u64 v[222:223], v[224:225], 0, s[28:29]
	s_addc_u32 s55, s59, 0
	s_add_i32 s58, s83, s65
	global_load_lds_dwordx4 v[222:223], off
	v_lshl_add_u64 v[222:223], s[54:55], 0, v[154:155]
	s_mov_b32 m0, s58
	s_nop 0
	global_load_lds_dwordx4 v[222:223], off
	v_lshl_add_u64 v[222:223], s[54:55], 0, v[162:163]
	s_add_i32 m0, s58, 0x2000
	s_nop 0
	global_load_lds_dwordx4 v[222:223], off
	v_lshl_add_u64 v[222:223], v[226:227], 0, s[28:29]
	s_mov_b32 m0, s3
	s_nop 0
	global_load_lds_dwordx4 v[222:223], off
	v_lshl_add_u64 v[222:223], v[228:229], 0, s[28:29]
	s_mov_b32 m0, s71
	s_nop 0
	global_load_lds_dwordx4 v[222:223], off
	s_waitcnt vmcnt(8)
	s_waitcnt lgkmcnt(0)
	s_barrier
	s_setprio 1
	s_waitcnt lgkmcnt(0)
	v_mfma_f32_16x16x32_bf16 v[60:63], v[128:131], v[180:183], v[60:63]
	v_mfma_f32_16x16x32_bf16 v[60:63], v[132:135], v[194:197], v[60:63]
	v_mfma_f32_16x16x32_bf16 v[56:59], v[140:143], v[194:197], v[56:59]
	v_mfma_f32_16x16x32_bf16 v[56:59], v[136:139], v[180:183], v[56:59]
	v_mfma_f32_16x16x32_bf16 v[40:43], v[136:139], v[198:201], v[40:43]
	v_mfma_f32_16x16x32_bf16 v[40:43], v[140:143], v[202:205], v[40:43]
	v_mfma_f32_16x16x32_bf16 v[44:47], v[132:135], v[202:205], v[44:47]
	v_mfma_f32_16x16x32_bf16 v[44:47], v[128:131], v[198:201], v[44:47]
	v_mfma_f32_16x16x32_bf16 v[28:31], v[128:131], v[206:209], v[28:31]
	v_mfma_f32_16x16x32_bf16 v[28:31], v[132:135], v[210:213], v[28:31]
	v_mfma_f32_16x16x32_bf16 v[24:27], v[140:143], v[210:213], v[24:27]
	v_mfma_f32_16x16x32_bf16 v[24:27], v[136:139], v[206:209], v[24:27]
	v_mfma_f32_16x16x32_bf16 v[8:11], v[136:139], v[214:217], v[8:11]
	v_mfma_f32_16x16x32_bf16 v[8:11], v[140:143], v[218:221], v[8:11]
	v_mfma_f32_16x16x32_bf16 v[12:15], v[132:135], v[218:221], v[12:15]
	v_mfma_f32_16x16x32_bf16 v[12:15], v[128:131], v[214:217], v[12:15]
	s_setprio 0
	s_setprio 1
	v_mfma_f32_16x16x32_bf16 v[52:55], v[144:147], v[180:183], v[52:55]
	v_mfma_f32_16x16x32_bf16 v[52:55], v[148:151], v[194:197], v[52:55]
	v_mfma_f32_16x16x32_bf16 v[48:51], v[176:179], v[194:197], v[48:51]
	v_mfma_f32_16x16x32_bf16 v[48:51], v[172:175], v[180:183], v[48:51]
	v_mfma_f32_16x16x32_bf16 v[32:35], v[172:175], v[198:201], v[32:35]
	v_mfma_f32_16x16x32_bf16 v[32:35], v[176:179], v[202:205], v[32:35]
	v_mfma_f32_16x16x32_bf16 v[36:39], v[148:151], v[202:205], v[36:39]
	v_mfma_f32_16x16x32_bf16 v[36:39], v[144:147], v[198:201], v[36:39]
	v_mfma_f32_16x16x32_bf16 v[20:23], v[144:147], v[206:209], v[20:23]
	v_mfma_f32_16x16x32_bf16 v[20:23], v[148:151], v[210:213], v[20:23]
	v_mfma_f32_16x16x32_bf16 v[16:19], v[176:179], v[210:213], v[16:19]
	v_mfma_f32_16x16x32_bf16 v[16:19], v[172:175], v[206:209], v[16:19]
	v_mfma_f32_16x16x32_bf16 v[0:3], v[172:175], v[214:217], v[0:3]
	v_mfma_f32_16x16x32_bf16 v[0:3], v[176:179], v[218:221], v[0:3]
	v_mfma_f32_16x16x32_bf16 v[4:7], v[148:151], v[218:221], v[4:7]
	v_mfma_f32_16x16x32_bf16 v[4:7], v[144:147], v[214:217], v[4:7]
	s_setprio 0
	s_barrier
	s_add_i32 s81, s81, 2
	s_add_u32 s79, s79, 0x100
	s_addc_u32 s80, s80, 0
	s_cmp_gt_u32 s81, 41
	s_mov_b64 s[54:55], s[56:57]
	s_cbranch_scc0 .LBB0_610
	s_and_b64 vcc, exec, s[30:31]
	s_cbranch_vccz .LBB0_613
	s_barrier

.LBB0_873:
	s_ashr_i32 s49, s48, 31
	s_lshl_b64 s[50:51], s[48:49], 19
	s_add_u32 s50, s35, s50
	s_addc_u32 s51, s60, s51
	s_and_b64 s[52:53], s[10:11], exec
	s_cselect_b32 s49, s51, s59
	s_cselect_b32 s80, s50, s58
	s_ashr_i32 s47, s46, 31
	s_lshl_b64 s[52:53], s[46:47], 19
	s_add_u32 s52, s61, s52
	s_addc_u32 s53, s62, s53
	s_and_b64 s[82:83], s[10:11], exec
	s_cselect_b32 s81, s53, s57
	s_cselect_b32 s82, s52, s56
	s_lshl_b32 s47, s54, 8
	v_add_u32_e32 v0, s47, v151
	s_add_u32 s83, s56, 0x100
	v_ashrrev_i32_e32 v1, 31, v0
	s_addc_u32 s84, s57, 0
	v_lshl_add_u64 v[144:145], v[0:1], 4, s[20:21]
	s_add_u32 s54, s58, 0x40080
	s_addc_u32 s55, s59, 0
	s_mov_b32 s85, -2
	s_mov_b64 s[56:57], 0
	s_cmp_eq_u32 s68, 1
	s_cbranch_scc1 .Lfa_8
	v_add_u32_e32 v146, s73, v149
	ds_read_b128 v[162:165], v146
	ds_read_b128 v[166:169], v146 offset:1024
	ds_read_b128 v[170:173], v146 offset:2048
	ds_read_b128 v[174:177], v146 offset:3072
	v_add_u32_e32 v146, s74, v149
	ds_read_b128 v[178:181], v146
	ds_read_b128 v[186:189], v146 offset:1024
	ds_read_b128 v[190:193], v146 offset:2048
	ds_read_b128 v[194:197], v146 offset:3072
	s_add_u32 s58, s54, 0xfffc0080
	s_addc_u32 s59, s55, -1
	s_and_b64 s[56:57], s[56:57], exec
	s_cselect_b32 s59, s49, s59
	s_cselect_b32 s58, s80, s58
	s_cselect_b32 s57, s81, s84
	s_cselect_b32 s56, s82, s83
	v_lshl_add_u64 v[182:183], s[54:55], 0, v[138:139]
	s_add_i32 m0, s64, 0xc000
	ds_read_b128 v[198:201], v154
	ds_read_b128 v[202:205], v154 offset:1024
	ds_read_b128 v[206:209], v154 offset:2048
	ds_read_b128 v[210:213], v154 offset:3072
	ds_read_b128 v[214:217], v154 offset:4096
	ds_read_b128 v[218:221], v154 offset:5120
	ds_read_b128 v[222:225], v154 offset:6144
	ds_read_b128 v[226:229], v154 offset:7168
	global_load_lds_dwordx4 v[182:183], off
	v_lshl_add_u64 v[182:183], s[54:55], 0, v[136:137]
	s_add_i32 m0, s64, 0xe000
	s_nop 0
	global_load_lds_dwordx4 v[182:183], off
	s_waitcnt vmcnt(24)
	s_waitcnt lgkmcnt(0)
	s_barrier
	s_setprio 1
	s_waitcnt lgkmcnt(0)
	v_mfma_f32_16x16x32_bf16 v[124:127], v[162:165], v[198:201], 0
	v_mfma_f32_16x16x32_bf16 v[120:123], v[170:173], v[198:201], 0
	v_mfma_f32_16x16x32_bf16 v[112:115], v[162:165], v[206:209], 0
	v_mfma_f32_16x16x32_bf16 v[104:107], v[170:173], v[206:209], 0
	v_mfma_f32_16x16x32_bf16 v[96:99], v[162:165], v[214:217], 0
	v_mfma_f32_16x16x32_bf16 v[88:91], v[170:173], v[214:217], 0
	v_mfma_f32_16x16x32_bf16 v[80:83], v[162:165], v[222:225], 0
	v_mfma_f32_16x16x32_bf16 v[72:75], v[170:173], v[222:225], 0
	v_mfma_f32_16x16x32_bf16 v[124:127], v[166:169], v[202:205], v[124:127]
	v_mfma_f32_16x16x32_bf16 v[120:123], v[174:177], v[202:205], v[120:123]
	v_mfma_f32_16x16x32_bf16 v[112:115], v[166:169], v[210:213], v[112:115]
	v_mfma_f32_16x16x32_bf16 v[104:107], v[174:177], v[210:213], v[104:107]
	v_mfma_f32_16x16x32_bf16 v[96:99], v[166:169], v[218:221], v[96:99]
	v_mfma_f32_16x16x32_bf16 v[88:91], v[174:177], v[218:221], v[88:91]
	v_mfma_f32_16x16x32_bf16 v[80:83], v[166:169], v[226:229], v[80:83]
	v_mfma_f32_16x16x32_bf16 v[72:75], v[174:177], v[226:229], v[72:75]
	s_setprio 0
	s_setprio 1
	v_mfma_f32_16x16x32_bf16 v[116:119], v[178:181], v[198:201], 0
	v_mfma_f32_16x16x32_bf16 v[108:111], v[190:193], v[198:201], 0
	v_mfma_f32_16x16x32_bf16 v[100:103], v[178:181], v[206:209], 0
	v_mfma_f32_16x16x32_bf16 v[92:95], v[190:193], v[206:209], 0
	v_mfma_f32_16x16x32_bf16 v[84:87], v[178:181], v[214:217], 0
	v_mfma_f32_16x16x32_bf16 v[76:79], v[190:193], v[214:217], 0
	v_mfma_f32_16x16x32_bf16 v[68:71], v[178:181], v[222:225], 0
	v_mfma_f32_16x16x32_bf16 v[64:67], v[190:193], v[222:225], 0
	v_mfma_f32_16x16x32_bf16 v[116:119], v[186:189], v[202:205], v[116:119]
	v_mfma_f32_16x16x32_bf16 v[108:111], v[194:197], v[202:205], v[108:111]
	v_mfma_f32_16x16x32_bf16 v[100:103], v[186:189], v[210:213], v[100:103]
	v_mfma_f32_16x16x32_bf16 v[92:95], v[194:197], v[210:213], v[92:95]
	v_mfma_f32_16x16x32_bf16 v[84:87], v[186:189], v[218:221], v[84:87]
	v_mfma_f32_16x16x32_bf16 v[76:79], v[194:197], v[218:221], v[76:79]
	v_mfma_f32_16x16x32_bf16 v[68:71], v[186:189], v[226:229], v[68:71]
	v_mfma_f32_16x16x32_bf16 v[64:67], v[194:197], v[226:229], v[64:67]
	s_setprio 0
	s_barrier
	s_add_i32 s86, s73, s63
	v_lshl_add_u64 v[182:183], s[56:57], 0, v[130:131]
	s_mov_b32 m0, s86
	ds_read_b128 v[198:201], v154 offset:16384
	ds_read_b128 v[202:205], v154 offset:17408
	ds_read_b128 v[206:209], v154 offset:18432
	ds_read_b128 v[210:213], v154 offset:19456
	ds_read_b128 v[214:217], v154 offset:20480
	ds_read_b128 v[218:221], v154 offset:21504
	ds_read_b128 v[222:225], v154 offset:22528
	ds_read_b128 v[226:229], v154 offset:23552
	global_load_lds_dwordx4 v[182:183], off
	s_add_i32 m0, s86, 0x2000
	s_add_u32 s86, s56, 0x40000
	v_lshl_add_u64 v[230:231], s[56:57], 0, v[134:135]
	s_addc_u32 s87, s57, 0
	s_add_i32 s88, s74, s63
	global_load_lds_dwordx4 v[230:231], off
	v_lshl_add_u64 v[232:233], s[86:87], 0, v[130:131]
	s_mov_b32 m0, s88
	v_lshl_add_u64 v[234:235], s[58:59], 0, v[132:133]
	global_load_lds_dwordx4 v[232:233], off
	v_lshl_add_u64 v[232:233], s[86:87], 0, v[134:135]
	s_add_i32 m0, s88, 0x2000
	s_nop 0
	global_load_lds_dwordx4 v[232:233], off
	v_lshl_add_u64 v[232:233], s[58:59], 0, v[128:129]
	s_mov_b32 m0, s64
	s_nop 0
	global_load_lds_dwordx4 v[232:233], off
	s_mov_b32 m0, s65
	s_nop 0
	global_load_lds_dwordx4 v[234:235], off
	s_waitcnt vmcnt(24)
	s_waitcnt lgkmcnt(0)
	s_barrier
	s_setprio 1
	s_waitcnt lgkmcnt(0)
	v_mfma_f32_16x16x32_bf16 v[60:63], v[162:165], v[198:201], 0
	v_mfma_f32_16x16x32_bf16 v[56:59], v[170:173], v[198:201], 0
	v_mfma_f32_16x16x32_bf16 v[48:51], v[162:165], v[206:209], 0
	v_mfma_f32_16x16x32_bf16 v[40:43], v[170:173], v[206:209], 0
	v_mfma_f32_16x16x32_bf16 v[32:35], v[162:165], v[214:217], 0
	v_mfma_f32_16x16x32_bf16 v[24:27], v[170:173], v[214:217], 0
	v_mfma_f32_16x16x32_bf16 v[16:19], v[162:165], v[222:225], 0
	v_mfma_f32_16x16x32_bf16 v[8:11], v[170:173], v[222:225], 0
	v_mfma_f32_16x16x32_bf16 v[60:63], v[166:169], v[202:205], v[60:63]
	v_mfma_f32_16x16x32_bf16 v[56:59], v[174:177], v[202:205], v[56:59]
	v_mfma_f32_16x16x32_bf16 v[48:51], v[166:169], v[210:213], v[48:51]
	v_mfma_f32_16x16x32_bf16 v[40:43], v[174:177], v[210:213], v[40:43]
	v_mfma_f32_16x16x32_bf16 v[32:35], v[166:169], v[218:221], v[32:35]
	v_mfma_f32_16x16x32_bf16 v[24:27], v[174:177], v[218:221], v[24:27]
	v_mfma_f32_16x16x32_bf16 v[16:19], v[166:169], v[226:229], v[16:19]
	v_mfma_f32_16x16x32_bf16 v[8:11], v[174:177], v[226:229], v[8:11]
	s_setprio 0
	s_setprio 1
	v_mfma_f32_16x16x32_bf16 v[52:55], v[178:181], v[198:201], 0
	v_mfma_f32_16x16x32_bf16 v[44:47], v[190:193], v[198:201], 0
	v_mfma_f32_16x16x32_bf16 v[36:39], v[178:181], v[206:209], 0
	v_mfma_f32_16x16x32_bf16 v[28:31], v[190:193], v[206:209], 0
	v_mfma_f32_16x16x32_bf16 v[20:23], v[178:181], v[214:217], 0
	v_mfma_f32_16x16x32_bf16 v[12:15], v[190:193], v[214:217], 0
	v_mfma_f32_16x16x32_bf16 v[4:7], v[178:181], v[222:225], 0
	v_mfma_f32_16x16x32_bf16 v[0:3], v[190:193], v[222:225], 0
	v_mfma_f32_16x16x32_bf16 v[52:55], v[186:189], v[202:205], v[52:55]
	v_mfma_f32_16x16x32_bf16 v[44:47], v[194:197], v[202:205], v[44:47]
	v_mfma_f32_16x16x32_bf16 v[36:39], v[186:189], v[210:213], v[36:39]
	v_mfma_f32_16x16x32_bf16 v[28:31], v[194:197], v[210:213], v[28:31]
	v_mfma_f32_16x16x32_bf16 v[20:23], v[186:189], v[218:221], v[20:23]
	v_mfma_f32_16x16x32_bf16 v[12:15], v[194:197], v[218:221], v[12:15]
	v_mfma_f32_16x16x32_bf16 v[4:7], v[186:189], v[226:229], v[4:7]
	v_mfma_f32_16x16x32_bf16 v[0:3], v[194:197], v[226:229], v[0:3]
	s_setprio 0
	s_barrier
	s_add_i32 s86, 0, 0x18000
	v_add_u32_e32 v146, s86, v149
	s_add_i32 s87, 0, 0x1c000
	ds_read_b128 v[162:165], v146
	ds_read_b128 v[166:169], v146 offset:1024
	ds_read_b128 v[170:173], v146 offset:2048
	ds_read_b128 v[174:177], v146 offset:3072
	v_add_u32_e32 v146, s87, v149
	ds_read_b128 v[178:181], v146
	ds_read_b128 v[186:189], v146 offset:1024
	ds_read_b128 v[190:193], v146 offset:2048
	ds_read_b128 v[194:197], v146 offset:3072
	s_add_u32 s58, s58, 0x40000
	s_addc_u32 s59, s59, 0
	s_mov_b32 m0, s66
	v_lshl_add_u64 v[236:237], s[58:59], 0, v[128:129]
	ds_read_b128 v[198:201], v154 offset:32768
	ds_read_b128 v[202:205], v154 offset:33792
	ds_read_b128 v[206:209], v154 offset:34816
	ds_read_b128 v[210:213], v154 offset:35840
	ds_read_b128 v[214:217], v154 offset:36864
	ds_read_b128 v[218:221], v154 offset:37888
	ds_read_b128 v[222:225], v154 offset:38912
	ds_read_b128 v[226:229], v154 offset:39936
	global_load_lds_dwordx4 v[236:237], off
	v_lshl_add_u64 v[236:237], s[58:59], 0, v[132:133]
	s_mov_b32 m0, s67
	s_nop 0
	global_load_lds_dwordx4 v[236:237], off
	s_waitcnt vmcnt(8)
	s_waitcnt lgkmcnt(0)
	s_barrier
	s_setprio 1
	s_waitcnt lgkmcnt(0)
	v_mfma_f32_16x16x32_bf16 v[124:127], v[162:165], v[198:201], v[124:127]
	v_mfma_f32_16x16x32_bf16 v[124:127], v[166:169], v[202:205], v[124:127]
	v_mfma_f32_16x16x32_bf16 v[120:123], v[174:177], v[202:205], v[120:123]
	v_mfma_f32_16x16x32_bf16 v[120:123], v[170:173], v[198:201], v[120:123]
	v_mfma_f32_16x16x32_bf16 v[104:107], v[170:173], v[206:209], v[104:107]
	v_mfma_f32_16x16x32_bf16 v[104:107], v[174:177], v[210:213], v[104:107]
	v_mfma_f32_16x16x32_bf16 v[112:115], v[166:169], v[210:213], v[112:115]
	v_mfma_f32_16x16x32_bf16 v[112:115], v[162:165], v[206:209], v[112:115]
	v_mfma_f32_16x16x32_bf16 v[96:99], v[162:165], v[214:217], v[96:99]
	v_mfma_f32_16x16x32_bf16 v[96:99], v[166:169], v[218:221], v[96:99]
	v_mfma_f32_16x16x32_bf16 v[88:91], v[174:177], v[218:221], v[88:91]
	v_mfma_f32_16x16x32_bf16 v[88:91], v[170:173], v[214:217], v[88:91]
	v_mfma_f32_16x16x32_bf16 v[72:75], v[170:173], v[222:225], v[72:75]
	v_mfma_f32_16x16x32_bf16 v[72:75], v[174:177], v[226:229], v[72:75]
	v_mfma_f32_16x16x32_bf16 v[80:83], v[166:169], v[226:229], v[80:83]
	v_mfma_f32_16x16x32_bf16 v[80:83], v[162:165], v[222:225], v[80:83]
	s_setprio 0
	s_setprio 1
	v_mfma_f32_16x16x32_bf16 v[116:119], v[178:181], v[198:201], v[116:119]
	v_mfma_f32_16x16x32_bf16 v[116:119], v[186:189], v[202:205], v[116:119]
	v_mfma_f32_16x16x32_bf16 v[108:111], v[194:197], v[202:205], v[108:111]
	v_mfma_f32_16x16x32_bf16 v[108:111], v[190:193], v[198:201], v[108:111]
	v_mfma_f32_16x16x32_bf16 v[92:95], v[190:193], v[206:209], v[92:95]
	v_mfma_f32_16x16x32_bf16 v[92:95], v[194:197], v[210:213], v[92:95]
	v_mfma_f32_16x16x32_bf16 v[100:103], v[186:189], v[210:213], v[100:103]
	v_mfma_f32_16x16x32_bf16 v[100:103], v[178:181], v[206:209], v[100:103]
	v_mfma_f32_16x16x32_bf16 v[84:87], v[178:181], v[214:217], v[84:87]
	v_mfma_f32_16x16x32_bf16 v[84:87], v[186:189], v[218:221], v[84:87]
	v_mfma_f32_16x16x32_bf16 v[76:79], v[194:197], v[218:221], v[76:79]
	v_mfma_f32_16x16x32_bf16 v[76:79], v[190:193], v[214:217], v[76:79]
	v_mfma_f32_16x16x32_bf16 v[64:67], v[190:193], v[222:225], v[64:67]
	v_mfma_f32_16x16x32_bf16 v[64:67], v[194:197], v[226:229], v[64:67]
	v_mfma_f32_16x16x32_bf16 v[68:71], v[186:189], v[226:229], v[68:71]
	v_mfma_f32_16x16x32_bf16 v[68:71], v[178:181], v[222:225], v[68:71]
	s_setprio 0
	s_barrier
	s_add_i32 s58, s86, s63
	v_lshl_add_u64 v[182:183], v[182:183], 0, s[22:23]
	s_mov_b32 m0, s58
	ds_read_b128 v[198:201], v154 offset:49152
	ds_read_b128 v[202:205], v154 offset:50176
	ds_read_b128 v[206:209], v154 offset:51200
	ds_read_b128 v[210:213], v154 offset:52224
	ds_read_b128 v[214:217], v154 offset:53248
	ds_read_b128 v[218:221], v154 offset:54272
	ds_read_b128 v[222:225], v154 offset:55296
	ds_read_b128 v[226:229], v154 offset:56320
	global_load_lds_dwordx4 v[182:183], off
	s_add_i32 m0, s58, 0x2000
	s_add_u32 s56, s56, 0x40080
	v_lshl_add_u64 v[182:183], v[230:231], 0, s[22:23]
	s_addc_u32 s57, s57, 0
	s_add_i32 s58, s87, s63
	global_load_lds_dwordx4 v[182:183], off
	v_lshl_add_u64 v[182:183], s[56:57], 0, v[130:131]
	s_mov_b32 m0, s58
	s_nop 0
	global_load_lds_dwordx4 v[182:183], off
	v_lshl_add_u64 v[182:183], s[56:57], 0, v[134:135]
	s_add_i32 m0, s58, 0x2000
	s_nop 0
	global_load_lds_dwordx4 v[182:183], off
	v_lshl_add_u64 v[182:183], v[232:233], 0, s[22:23]
	s_mov_b32 m0, s69
	s_nop 0
	global_load_lds_dwordx4 v[182:183], off
	v_lshl_add_u64 v[182:183], v[234:235], 0, s[22:23]
	s_mov_b32 m0, s70
	s_nop 0
	global_load_lds_dwordx4 v[182:183], off
	s_waitcnt vmcnt(8)
	s_waitcnt lgkmcnt(0)
	s_barrier
	s_setprio 1
	s_waitcnt lgkmcnt(0)
	v_mfma_f32_16x16x32_bf16 v[60:63], v[162:165], v[198:201], v[60:63]
	v_mfma_f32_16x16x32_bf16 v[60:63], v[166:169], v[202:205], v[60:63]
	v_mfma_f32_16x16x32_bf16 v[56:59], v[174:177], v[202:205], v[56:59]
	v_mfma_f32_16x16x32_bf16 v[56:59], v[170:173], v[198:201], v[56:59]
	v_mfma_f32_16x16x32_bf16 v[40:43], v[170:173], v[206:209], v[40:43]
	v_mfma_f32_16x16x32_bf16 v[40:43], v[174:177], v[210:213], v[40:43]
	v_mfma_f32_16x16x32_bf16 v[48:51], v[166:169], v[210:213], v[48:51]
	v_mfma_f32_16x16x32_bf16 v[48:51], v[162:165], v[206:209], v[48:51]
	v_mfma_f32_16x16x32_bf16 v[32:35], v[162:165], v[214:217], v[32:35]
	v_mfma_f32_16x16x32_bf16 v[32:35], v[166:169], v[218:221], v[32:35]
	v_mfma_f32_16x16x32_bf16 v[24:27], v[174:177], v[218:221], v[24:27]
	v_mfma_f32_16x16x32_bf16 v[24:27], v[170:173], v[214:217], v[24:27]
	v_mfma_f32_16x16x32_bf16 v[8:11], v[170:173], v[222:225], v[8:11]
	v_mfma_f32_16x16x32_bf16 v[8:11], v[174:177], v[226:229], v[8:11]
	v_mfma_f32_16x16x32_bf16 v[16:19], v[166:169], v[226:229], v[16:19]
	v_mfma_f32_16x16x32_bf16 v[16:19], v[162:165], v[222:225], v[16:19]
	s_setprio 0
	s_setprio 1
	v_mfma_f32_16x16x32_bf16 v[52:55], v[178:181], v[198:201], v[52:55]
	v_mfma_f32_16x16x32_bf16 v[52:55], v[186:189], v[202:205], v[52:55]
	v_mfma_f32_16x16x32_bf16 v[44:47], v[194:197], v[202:205], v[44:47]
	v_mfma_f32_16x16x32_bf16 v[44:47], v[190:193], v[198:201], v[44:47]
	v_mfma_f32_16x16x32_bf16 v[28:31], v[190:193], v[206:209], v[28:31]
	v_mfma_f32_16x16x32_bf16 v[28:31], v[194:197], v[210:213], v[28:31]
	v_mfma_f32_16x16x32_bf16 v[36:39], v[186:189], v[210:213], v[36:39]
	v_mfma_f32_16x16x32_bf16 v[36:39], v[178:181], v[206:209], v[36:39]
	v_mfma_f32_16x16x32_bf16 v[20:23], v[178:181], v[214:217], v[20:23]
	v_mfma_f32_16x16x32_bf16 v[20:23], v[186:189], v[218:221], v[20:23]
	v_mfma_f32_16x16x32_bf16 v[12:15], v[194:197], v[218:221], v[12:15]
	v_mfma_f32_16x16x32_bf16 v[12:15], v[190:193], v[214:217], v[12:15]
	v_mfma_f32_16x16x32_bf16 v[0:3], v[190:193], v[222:225], v[0:3]
	v_mfma_f32_16x16x32_bf16 v[0:3], v[194:197], v[226:229], v[0:3]
	v_mfma_f32_16x16x32_bf16 v[4:7], v[186:189], v[226:229], v[4:7]
	v_mfma_f32_16x16x32_bf16 v[4:7], v[178:181], v[222:225], v[4:7]
	s_setprio 0
	s_barrier
	s_add_i32 s85, s85, 2
	s_add_u32 s83, s83, 0x100
	s_addc_u32 s84, s84, 0
	s_add_u32 s54, s54, 0x100
	s_addc_u32 s55, s55, 0
	s_branch .LBB0_875
.Lfa_8:
	v_add_u32_e32 v146, s73, v149
	ds_read_b128 v[162:165], v146
	ds_read_b128 v[166:169], v146 offset:1024
	ds_read_b128 v[170:173], v146 offset:2048
	ds_read_b128 v[174:177], v146 offset:3072
	v_add_u32_e32 v146, s74, v149
	ds_read_b128 v[178:181], v146
	ds_read_b128 v[186:189], v146 offset:1024
	ds_read_b128 v[190:193], v146 offset:2048
	ds_read_b128 v[194:197], v146 offset:3072
	s_add_u32 s58, s54, 0xfffc0080
	s_addc_u32 s59, s55, -1
	s_and_b64 s[56:57], s[56:57], exec
	s_cselect_b32 s59, s49, s59
	s_cselect_b32 s58, s80, s58
	s_cselect_b32 s57, s81, s84
	s_cselect_b32 s56, s82, s83
	v_lshl_add_u64 v[182:183], s[54:55], 0, v[138:139]
	s_add_i32 m0, s64, 0xc000
	ds_read_b128 v[198:201], v154
	ds_read_b128 v[202:205], v154 offset:1024
	ds_read_b128 v[206:209], v154 offset:2048
	ds_read_b128 v[210:213], v154 offset:3072
	ds_read_b128 v[214:217], v154 offset:4096
	ds_read_b128 v[218:221], v154 offset:5120
	ds_read_b128 v[222:225], v154 offset:6144
	ds_read_b128 v[226:229], v154 offset:7168
	global_load_lds_dwordx4 v[182:183], off
	v_lshl_add_u64 v[182:183], s[54:55], 0, v[136:137]
	s_add_i32 m0, s64, 0xe000
	s_nop 0
	global_load_lds_dwordx4 v[182:183], off
	s_waitcnt vmcnt(8)
	s_waitcnt lgkmcnt(0)
	s_barrier
	s_setprio 1
	s_waitcnt lgkmcnt(0)
	v_mfma_f32_16x16x32_bf16 v[124:127], v[162:165], v[198:201], 0
	v_mfma_f32_16x16x32_bf16 v[120:123], v[170:173], v[198:201], 0
	v_mfma_f32_16x16x32_bf16 v[112:115], v[162:165], v[206:209], 0
	v_mfma_f32_16x16x32_bf16 v[104:107], v[170:173], v[206:209], 0
	v_mfma_f32_16x16x32_bf16 v[96:99], v[162:165], v[214:217], 0
	v_mfma_f32_16x16x32_bf16 v[88:91], v[170:173], v[214:217], 0
	v_mfma_f32_16x16x32_bf16 v[80:83], v[162:165], v[222:225], 0
	v_mfma_f32_16x16x32_bf16 v[72:75], v[170:173], v[222:225], 0
	v_mfma_f32_16x16x32_bf16 v[124:127], v[166:169], v[202:205], v[124:127]
	v_mfma_f32_16x16x32_bf16 v[120:123], v[174:177], v[202:205], v[120:123]
	v_mfma_f32_16x16x32_bf16 v[112:115], v[166:169], v[210:213], v[112:115]
	v_mfma_f32_16x16x32_bf16 v[104:107], v[174:177], v[210:213], v[104:107]
	v_mfma_f32_16x16x32_bf16 v[96:99], v[166:169], v[218:221], v[96:99]
	v_mfma_f32_16x16x32_bf16 v[88:91], v[174:177], v[218:221], v[88:91]
	v_mfma_f32_16x16x32_bf16 v[80:83], v[166:169], v[226:229], v[80:83]
	v_mfma_f32_16x16x32_bf16 v[72:75], v[174:177], v[226:229], v[72:75]
	s_setprio 0
	s_setprio 1
	v_mfma_f32_16x16x32_bf16 v[116:119], v[178:181], v[198:201], 0
	v_mfma_f32_16x16x32_bf16 v[108:111], v[190:193], v[198:201], 0
	v_mfma_f32_16x16x32_bf16 v[100:103], v[178:181], v[206:209], 0
	v_mfma_f32_16x16x32_bf16 v[92:95], v[190:193], v[206:209], 0
	v_mfma_f32_16x16x32_bf16 v[84:87], v[178:181], v[214:217], 0
	v_mfma_f32_16x16x32_bf16 v[76:79], v[190:193], v[214:217], 0
	v_mfma_f32_16x16x32_bf16 v[68:71], v[178:181], v[222:225], 0
	v_mfma_f32_16x16x32_bf16 v[64:67], v[190:193], v[222:225], 0
	v_mfma_f32_16x16x32_bf16 v[116:119], v[186:189], v[202:205], v[116:119]
	v_mfma_f32_16x16x32_bf16 v[108:111], v[194:197], v[202:205], v[108:111]
	v_mfma_f32_16x16x32_bf16 v[100:103], v[186:189], v[210:213], v[100:103]
	v_mfma_f32_16x16x32_bf16 v[92:95], v[194:197], v[210:213], v[92:95]
	v_mfma_f32_16x16x32_bf16 v[84:87], v[186:189], v[218:221], v[84:87]
	v_mfma_f32_16x16x32_bf16 v[76:79], v[194:197], v[218:221], v[76:79]
	v_mfma_f32_16x16x32_bf16 v[68:71], v[186:189], v[226:229], v[68:71]
	v_mfma_f32_16x16x32_bf16 v[64:67], v[194:197], v[226:229], v[64:67]
	s_setprio 0
	s_barrier
	s_add_i32 s86, s73, s63
	v_lshl_add_u64 v[182:183], s[56:57], 0, v[130:131]
	s_mov_b32 m0, s86
	ds_read_b128 v[198:201], v154 offset:16384
	ds_read_b128 v[202:205], v154 offset:17408
	ds_read_b128 v[206:209], v154 offset:18432
	ds_read_b128 v[210:213], v154 offset:19456
	ds_read_b128 v[214:217], v154 offset:20480
	ds_read_b128 v[218:221], v154 offset:21504
	ds_read_b128 v[222:225], v154 offset:22528
	ds_read_b128 v[226:229], v154 offset:23552
	global_load_lds_dwordx4 v[182:183], off
	s_add_i32 m0, s86, 0x2000
	s_add_u32 s86, s56, 0x40000
	v_lshl_add_u64 v[230:231], s[56:57], 0, v[134:135]
	s_addc_u32 s87, s57, 0
	s_add_i32 s88, s74, s63
	global_load_lds_dwordx4 v[230:231], off
	v_lshl_add_u64 v[232:233], s[86:87], 0, v[130:131]
	s_mov_b32 m0, s88
	v_lshl_add_u64 v[234:235], s[58:59], 0, v[132:133]
	global_load_lds_dwordx4 v[232:233], off
	v_lshl_add_u64 v[232:233], s[86:87], 0, v[134:135]
	s_add_i32 m0, s88, 0x2000
	s_nop 0
	global_load_lds_dwordx4 v[232:233], off
	v_lshl_add_u64 v[232:233], s[58:59], 0, v[128:129]
	s_mov_b32 m0, s64
	s_nop 0
	global_load_lds_dwordx4 v[232:233], off
	s_mov_b32 m0, s65
	s_nop 0
	global_load_lds_dwordx4 v[234:235], off
	s_waitcnt vmcnt(8)
	s_waitcnt lgkmcnt(0)
	s_barrier
	s_setprio 1
	s_waitcnt lgkmcnt(0)
	v_mfma_f32_16x16x32_bf16 v[60:63], v[162:165], v[198:201], 0
	v_mfma_f32_16x16x32_bf16 v[56:59], v[170:173], v[198:201], 0
	v_mfma_f32_16x16x32_bf16 v[48:51], v[162:165], v[206:209], 0
	v_mfma_f32_16x16x32_bf16 v[40:43], v[170:173], v[206:209], 0
	v_mfma_f32_16x16x32_bf16 v[32:35], v[162:165], v[214:217], 0
	v_mfma_f32_16x16x32_bf16 v[24:27], v[170:173], v[214:217], 0
	v_mfma_f32_16x16x32_bf16 v[16:19], v[162:165], v[222:225], 0
	v_mfma_f32_16x16x32_bf16 v[8:11], v[170:173], v[222:225], 0
	v_mfma_f32_16x16x32_bf16 v[60:63], v[166:169], v[202:205], v[60:63]
	v_mfma_f32_16x16x32_bf16 v[56:59], v[174:177], v[202:205], v[56:59]
	v_mfma_f32_16x16x32_bf16 v[48:51], v[166:169], v[210:213], v[48:51]
	v_mfma_f32_16x16x32_bf16 v[40:43], v[174:177], v[210:213], v[40:43]
	v_mfma_f32_16x16x32_bf16 v[32:35], v[166:169], v[218:221], v[32:35]
	v_mfma_f32_16x16x32_bf16 v[24:27], v[174:177], v[218:221], v[24:27]
	v_mfma_f32_16x16x32_bf16 v[16:19], v[166:169], v[226:229], v[16:19]
	v_mfma_f32_16x16x32_bf16 v[8:11], v[174:177], v[226:229], v[8:11]
	s_setprio 0
	s_setprio 1
	v_mfma_f32_16x16x32_bf16 v[52:55], v[178:181], v[198:201], 0
	v_mfma_f32_16x16x32_bf16 v[44:47], v[190:193], v[198:201], 0
	v_mfma_f32_16x16x32_bf16 v[36:39], v[178:181], v[206:209], 0
	v_mfma_f32_16x16x32_bf16 v[28:31], v[190:193], v[206:209], 0
	v_mfma_f32_16x16x32_bf16 v[20:23], v[178:181], v[214:217], 0
	v_mfma_f32_16x16x32_bf16 v[12:15], v[190:193], v[214:217], 0
	v_mfma_f32_16x16x32_bf16 v[4:7], v[178:181], v[222:225], 0
	v_mfma_f32_16x16x32_bf16 v[0:3], v[190:193], v[222:225], 0
	v_mfma_f32_16x16x32_bf16 v[52:55], v[186:189], v[202:205], v[52:55]
	v_mfma_f32_16x16x32_bf16 v[44:47], v[194:197], v[202:205], v[44:47]
	v_mfma_f32_16x16x32_bf16 v[36:39], v[186:189], v[210:213], v[36:39]
	v_mfma_f32_16x16x32_bf16 v[28:31], v[194:197], v[210:213], v[28:31]
	v_mfma_f32_16x16x32_bf16 v[20:23], v[186:189], v[218:221], v[20:23]
	v_mfma_f32_16x16x32_bf16 v[12:15], v[194:197], v[218:221], v[12:15]
	v_mfma_f32_16x16x32_bf16 v[4:7], v[186:189], v[226:229], v[4:7]
	v_mfma_f32_16x16x32_bf16 v[0:3], v[194:197], v[226:229], v[0:3]
	s_setprio 0
	s_barrier
	s_add_i32 s86, 0, 0x18000
	v_add_u32_e32 v146, s86, v149
	s_add_i32 s87, 0, 0x1c000
	ds_read_b128 v[162:165], v146
	ds_read_b128 v[166:169], v146 offset:1024
	ds_read_b128 v[170:173], v146 offset:2048
	ds_read_b128 v[174:177], v146 offset:3072
	v_add_u32_e32 v146, s87, v149
	ds_read_b128 v[178:181], v146
	ds_read_b128 v[186:189], v146 offset:1024
	ds_read_b128 v[190:193], v146 offset:2048
	ds_read_b128 v[194:197], v146 offset:3072
	s_add_u32 s58, s58, 0x40000
	s_addc_u32 s59, s59, 0
	s_mov_b32 m0, s66
	v_lshl_add_u64 v[236:237], s[58:59], 0, v[128:129]
	ds_read_b128 v[198:201], v154 offset:32768
	ds_read_b128 v[202:205], v154 offset:33792
	ds_read_b128 v[206:209], v154 offset:34816
	ds_read_b128 v[210:213], v154 offset:35840
	ds_read_b128 v[214:217], v154 offset:36864
	ds_read_b128 v[218:221], v154 offset:37888
	ds_read_b128 v[222:225], v154 offset:38912
	ds_read_b128 v[226:229], v154 offset:39936
	global_load_lds_dwordx4 v[236:237], off
	v_lshl_add_u64 v[236:237], s[58:59], 0, v[132:133]
	s_mov_b32 m0, s67
	s_nop 0
	global_load_lds_dwordx4 v[236:237], off
	s_waitcnt vmcnt(8)
	s_waitcnt lgkmcnt(0)
	s_barrier
	s_setprio 1
	s_waitcnt lgkmcnt(0)
	v_mfma_f32_16x16x32_bf16 v[124:127], v[162:165], v[198:201], v[124:127]
	v_mfma_f32_16x16x32_bf16 v[124:127], v[166:169], v[202:205], v[124:127]
	v_mfma_f32_16x16x32_bf16 v[120:123], v[174:177], v[202:205], v[120:123]
	v_mfma_f32_16x16x32_bf16 v[120:123], v[170:173], v[198:201], v[120:123]
	v_mfma_f32_16x16x32_bf16 v[104:107], v[170:173], v[206:209], v[104:107]
	v_mfma_f32_16x16x32_bf16 v[104:107], v[174:177], v[210:213], v[104:107]
	v_mfma_f32_16x16x32_bf16 v[112:115], v[166:169], v[210:213], v[112:115]
	v_mfma_f32_16x16x32_bf16 v[112:115], v[162:165], v[206:209], v[112:115]
	v_mfma_f32_16x16x32_bf16 v[96:99], v[162:165], v[214:217], v[96:99]
	v_mfma_f32_16x16x32_bf16 v[96:99], v[166:169], v[218:221], v[96:99]
	v_mfma_f32_16x16x32_bf16 v[88:91], v[174:177], v[218:221], v[88:91]
	v_mfma_f32_16x16x32_bf16 v[88:91], v[170:173], v[214:217], v[88:91]
	v_mfma_f32_16x16x32_bf16 v[72:75], v[170:173], v[222:225], v[72:75]
	v_mfma_f32_16x16x32_bf16 v[72:75], v[174:177], v[226:229], v[72:75]
	v_mfma_f32_16x16x32_bf16 v[80:83], v[166:169], v[226:229], v[80:83]
	v_mfma_f32_16x16x32_bf16 v[80:83], v[162:165], v[222:225], v[80:83]
	s_setprio 0
	s_setprio 1
	v_mfma_f32_16x16x32_bf16 v[116:119], v[178:181], v[198:201], v[116:119]
	v_mfma_f32_16x16x32_bf16 v[116:119], v[186:189], v[202:205], v[116:119]
	v_mfma_f32_16x16x32_bf16 v[108:111], v[194:197], v[202:205], v[108:111]
	v_mfma_f32_16x16x32_bf16 v[108:111], v[190:193], v[198:201], v[108:111]
	v_mfma_f32_16x16x32_bf16 v[92:95], v[190:193], v[206:209], v[92:95]
	v_mfma_f32_16x16x32_bf16 v[92:95], v[194:197], v[210:213], v[92:95]
	v_mfma_f32_16x16x32_bf16 v[100:103], v[186:189], v[210:213], v[100:103]
	v_mfma_f32_16x16x32_bf16 v[100:103], v[178:181], v[206:209], v[100:103]
	v_mfma_f32_16x16x32_bf16 v[84:87], v[178:181], v[214:217], v[84:87]
	v_mfma_f32_16x16x32_bf16 v[84:87], v[186:189], v[218:221], v[84:87]
	v_mfma_f32_16x16x32_bf16 v[76:79], v[194:197], v[218:221], v[76:79]
	v_mfma_f32_16x16x32_bf16 v[76:79], v[190:193], v[214:217], v[76:79]
	v_mfma_f32_16x16x32_bf16 v[64:67], v[190:193], v[222:225], v[64:67]
	v_mfma_f32_16x16x32_bf16 v[64:67], v[194:197], v[226:229], v[64:67]
	v_mfma_f32_16x16x32_bf16 v[68:71], v[186:189], v[226:229], v[68:71]
	v_mfma_f32_16x16x32_bf16 v[68:71], v[178:181], v[222:225], v[68:71]
	s_setprio 0
	s_barrier
	s_add_i32 s58, s86, s63
	v_lshl_add_u64 v[182:183], v[182:183], 0, s[22:23]
	s_mov_b32 m0, s58
	ds_read_b128 v[198:201], v154 offset:49152
	ds_read_b128 v[202:205], v154 offset:50176
	ds_read_b128 v[206:209], v154 offset:51200
	ds_read_b128 v[210:213], v154 offset:52224
	ds_read_b128 v[214:217], v154 offset:53248
	ds_read_b128 v[218:221], v154 offset:54272
	ds_read_b128 v[222:225], v154 offset:55296
	ds_read_b128 v[226:229], v154 offset:56320
	global_load_lds_dwordx4 v[182:183], off
	s_add_i32 m0, s58, 0x2000
	s_add_u32 s56, s56, 0x40080
	v_lshl_add_u64 v[182:183], v[230:231], 0, s[22:23]
	s_addc_u32 s57, s57, 0
	s_add_i32 s58, s87, s63
	global_load_lds_dwordx4 v[182:183], off
	v_lshl_add_u64 v[182:183], s[56:57], 0, v[130:131]
	s_mov_b32 m0, s58
	s_nop 0
	global_load_lds_dwordx4 v[182:183], off
	v_lshl_add_u64 v[182:183], s[56:57], 0, v[134:135]
	s_add_i32 m0, s58, 0x2000
	s_nop 0
	global_load_lds_dwordx4 v[182:183], off
	v_lshl_add_u64 v[182:183], v[232:233], 0, s[22:23]
	s_mov_b32 m0, s69
	s_nop 0
	global_load_lds_dwordx4 v[182:183], off
	v_lshl_add_u64 v[182:183], v[234:235], 0, s[22:23]
	s_mov_b32 m0, s70
	s_nop 0
	global_load_lds_dwordx4 v[182:183], off
	s_waitcnt vmcnt(8)
	s_waitcnt lgkmcnt(0)
	s_barrier
	s_setprio 1
	s_waitcnt lgkmcnt(0)
	v_mfma_f32_16x16x32_bf16 v[60:63], v[162:165], v[198:201], v[60:63]
	v_mfma_f32_16x16x32_bf16 v[60:63], v[166:169], v[202:205], v[60:63]
	v_mfma_f32_16x16x32_bf16 v[56:59], v[174:177], v[202:205], v[56:59]
	v_mfma_f32_16x16x32_bf16 v[56:59], v[170:173], v[198:201], v[56:59]
	v_mfma_f32_16x16x32_bf16 v[40:43], v[170:173], v[206:209], v[40:43]
	v_mfma_f32_16x16x32_bf16 v[40:43], v[174:177], v[210:213], v[40:43]
	v_mfma_f32_16x16x32_bf16 v[48:51], v[166:169], v[210:213], v[48:51]
	v_mfma_f32_16x16x32_bf16 v[48:51], v[162:165], v[206:209], v[48:51]
	v_mfma_f32_16x16x32_bf16 v[32:35], v[162:165], v[214:217], v[32:35]
	v_mfma_f32_16x16x32_bf16 v[32:35], v[166:169], v[218:221], v[32:35]
	v_mfma_f32_16x16x32_bf16 v[24:27], v[174:177], v[218:221], v[24:27]
	v_mfma_f32_16x16x32_bf16 v[24:27], v[170:173], v[214:217], v[24:27]
	v_mfma_f32_16x16x32_bf16 v[8:11], v[170:173], v[222:225], v[8:11]
	v_mfma_f32_16x16x32_bf16 v[8:11], v[174:177], v[226:229], v[8:11]
	v_mfma_f32_16x16x32_bf16 v[16:19], v[166:169], v[226:229], v[16:19]
	v_mfma_f32_16x16x32_bf16 v[16:19], v[162:165], v[222:225], v[16:19]
	s_setprio 0
	s_setprio 1
	v_mfma_f32_16x16x32_bf16 v[52:55], v[178:181], v[198:201], v[52:55]
	v_mfma_f32_16x16x32_bf16 v[52:55], v[186:189], v[202:205], v[52:55]
	v_mfma_f32_16x16x32_bf16 v[44:47], v[194:197], v[202:205], v[44:47]
	v_mfma_f32_16x16x32_bf16 v[44:47], v[190:193], v[198:201], v[44:47]
	v_mfma_f32_16x16x32_bf16 v[28:31], v[190:193], v[206:209], v[28:31]
	v_mfma_f32_16x16x32_bf16 v[28:31], v[194:197], v[210:213], v[28:31]
	v_mfma_f32_16x16x32_bf16 v[36:39], v[186:189], v[210:213], v[36:39]
	v_mfma_f32_16x16x32_bf16 v[36:39], v[178:181], v[206:209], v[36:39]
	v_mfma_f32_16x16x32_bf16 v[20:23], v[178:181], v[214:217], v[20:23]
	v_mfma_f32_16x16x32_bf16 v[20:23], v[186:189], v[218:221], v[20:23]
	v_mfma_f32_16x16x32_bf16 v[12:15], v[194:197], v[218:221], v[12:15]
	v_mfma_f32_16x16x32_bf16 v[12:15], v[190:193], v[214:217], v[12:15]
	v_mfma_f32_16x16x32_bf16 v[0:3], v[190:193], v[222:225], v[0:3]
	v_mfma_f32_16x16x32_bf16 v[0:3], v[194:197], v[226:229], v[0:3]
	v_mfma_f32_16x16x32_bf16 v[4:7], v[186:189], v[226:229], v[4:7]
	v_mfma_f32_16x16x32_bf16 v[4:7], v[178:181], v[222:225], v[4:7]
	s_setprio 0
	s_barrier
	s_add_i32 s85, s85, 2
	s_add_u32 s83, s83, 0x100
	s_addc_u32 s84, s84, 0
	s_add_u32 s54, s54, 0x100
	s_addc_u32 s55, s55, 0
	s_branch .LBB0_875
.LBB0_874:
	v_add_u32_e32 v146, s73, v149
	ds_read_b128 v[162:165], v146
	ds_read_b128 v[166:169], v146 offset:1024
	ds_read_b128 v[170:173], v146 offset:2048
	ds_read_b128 v[174:177], v146 offset:3072
	v_add_u32_e32 v146, s74, v149
	ds_read_b128 v[178:181], v146
	ds_read_b128 v[186:189], v146 offset:1024
	ds_read_b128 v[190:193], v146 offset:2048
	ds_read_b128 v[194:197], v146 offset:3072
	s_add_u32 s58, s54, 0xfffc0080
	s_addc_u32 s59, s55, -1
	s_and_b64 s[56:57], s[56:57], exec
	s_cselect_b32 s59, s49, s59
	s_cselect_b32 s58, s80, s58
	s_cselect_b32 s57, s81, s84
	s_cselect_b32 s56, s82, s83
	v_lshl_add_u64 v[182:183], s[54:55], 0, v[138:139]
	s_add_i32 m0, s64, 0xc000
	ds_read_b128 v[198:201], v154
	ds_read_b128 v[202:205], v154 offset:1024
	ds_read_b128 v[206:209], v154 offset:2048
	ds_read_b128 v[210:213], v154 offset:3072
	ds_read_b128 v[214:217], v154 offset:4096
	ds_read_b128 v[218:221], v154 offset:5120
	ds_read_b128 v[222:225], v154 offset:6144
	ds_read_b128 v[226:229], v154 offset:7168
	global_load_lds_dwordx4 v[182:183], off
	v_lshl_add_u64 v[182:183], s[54:55], 0, v[136:137]
	s_add_i32 m0, s64, 0xe000
	s_nop 0
	global_load_lds_dwordx4 v[182:183], off
	s_waitcnt vmcnt(8)
	s_waitcnt lgkmcnt(0)
	s_barrier
	s_setprio 1
	s_waitcnt lgkmcnt(0)
	v_mfma_f32_16x16x32_bf16 v[124:127], v[162:165], v[198:201], v[124:127]
	v_mfma_f32_16x16x32_bf16 v[124:127], v[166:169], v[202:205], v[124:127]
	v_mfma_f32_16x16x32_bf16 v[120:123], v[174:177], v[202:205], v[120:123]
	v_mfma_f32_16x16x32_bf16 v[120:123], v[170:173], v[198:201], v[120:123]
	v_mfma_f32_16x16x32_bf16 v[104:107], v[170:173], v[206:209], v[104:107]
	v_mfma_f32_16x16x32_bf16 v[104:107], v[174:177], v[210:213], v[104:107]
	v_mfma_f32_16x16x32_bf16 v[112:115], v[166:169], v[210:213], v[112:115]
	v_mfma_f32_16x16x32_bf16 v[112:115], v[162:165], v[206:209], v[112:115]
	v_mfma_f32_16x16x32_bf16 v[96:99], v[162:165], v[214:217], v[96:99]
	v_mfma_f32_16x16x32_bf16 v[96:99], v[166:169], v[218:221], v[96:99]
	v_mfma_f32_16x16x32_bf16 v[88:91], v[174:177], v[218:221], v[88:91]
	v_mfma_f32_16x16x32_bf16 v[88:91], v[170:173], v[214:217], v[88:91]
	v_mfma_f32_16x16x32_bf16 v[72:75], v[170:173], v[222:225], v[72:75]
	v_mfma_f32_16x16x32_bf16 v[72:75], v[174:177], v[226:229], v[72:75]
	v_mfma_f32_16x16x32_bf16 v[80:83], v[166:169], v[226:229], v[80:83]
	v_mfma_f32_16x16x32_bf16 v[80:83], v[162:165], v[222:225], v[80:83]
	s_setprio 0
	s_setprio 1
	v_mfma_f32_16x16x32_bf16 v[116:119], v[178:181], v[198:201], v[116:119]
	v_mfma_f32_16x16x32_bf16 v[116:119], v[186:189], v[202:205], v[116:119]
	v_mfma_f32_16x16x32_bf16 v[108:111], v[194:197], v[202:205], v[108:111]
	v_mfma_f32_16x16x32_bf16 v[108:111], v[190:193], v[198:201], v[108:111]
	v_mfma_f32_16x16x32_bf16 v[92:95], v[190:193], v[206:209], v[92:95]
	v_mfma_f32_16x16x32_bf16 v[92:95], v[194:197], v[210:213], v[92:95]
	v_mfma_f32_16x16x32_bf16 v[100:103], v[186:189], v[210:213], v[100:103]
	v_mfma_f32_16x16x32_bf16 v[100:103], v[178:181], v[206:209], v[100:103]
	v_mfma_f32_16x16x32_bf16 v[84:87], v[178:181], v[214:217], v[84:87]
	v_mfma_f32_16x16x32_bf16 v[84:87], v[186:189], v[218:221], v[84:87]
	v_mfma_f32_16x16x32_bf16 v[76:79], v[194:197], v[218:221], v[76:79]
	v_mfma_f32_16x16x32_bf16 v[76:79], v[190:193], v[214:217], v[76:79]
	v_mfma_f32_16x16x32_bf16 v[64:67], v[190:193], v[222:225], v[64:67]
	v_mfma_f32_16x16x32_bf16 v[64:67], v[194:197], v[226:229], v[64:67]
	v_mfma_f32_16x16x32_bf16 v[68:71], v[186:189], v[226:229], v[68:71]
	v_mfma_f32_16x16x32_bf16 v[68:71], v[178:181], v[222:225], v[68:71]
	s_setprio 0
	s_barrier
	s_add_i32 s86, s73, s63
	v_lshl_add_u64 v[182:183], s[56:57], 0, v[130:131]
	s_mov_b32 m0, s86
	ds_read_b128 v[198:201], v154 offset:16384
	ds_read_b128 v[202:205], v154 offset:17408
	ds_read_b128 v[206:209], v154 offset:18432
	ds_read_b128 v[210:213], v154 offset:19456
	ds_read_b128 v[214:217], v154 offset:20480
	ds_read_b128 v[218:221], v154 offset:21504
	ds_read_b128 v[222:225], v154 offset:22528
	ds_read_b128 v[226:229], v154 offset:23552
	global_load_lds_dwordx4 v[182:183], off
	s_add_i32 m0, s86, 0x2000
	s_add_u32 s86, s56, 0x40000
	v_lshl_add_u64 v[230:231], s[56:57], 0, v[134:135]
	s_addc_u32 s87, s57, 0
	s_add_i32 s88, s74, s63
	global_load_lds_dwordx4 v[230:231], off
	v_lshl_add_u64 v[232:233], s[86:87], 0, v[130:131]
	s_mov_b32 m0, s88
	v_lshl_add_u64 v[234:235], s[58:59], 0, v[132:133]
	global_load_lds_dwordx4 v[232:233], off
	v_lshl_add_u64 v[232:233], s[86:87], 0, v[134:135]
	s_add_i32 m0, s88, 0x2000
	s_nop 0
	global_load_lds_dwordx4 v[232:233], off
	v_lshl_add_u64 v[232:233], s[58:59], 0, v[128:129]
	s_mov_b32 m0, s64
	s_nop 0
	global_load_lds_dwordx4 v[232:233], off
	s_mov_b32 m0, s65
	s_nop 0
	global_load_lds_dwordx4 v[234:235], off
	s_waitcnt vmcnt(8)
	s_waitcnt lgkmcnt(0)
	s_barrier
	s_setprio 1
	s_waitcnt lgkmcnt(0)
	v_mfma_f32_16x16x32_bf16 v[60:63], v[162:165], v[198:201], v[60:63]
	v_mfma_f32_16x16x32_bf16 v[60:63], v[166:169], v[202:205], v[60:63]
	v_mfma_f32_16x16x32_bf16 v[56:59], v[174:177], v[202:205], v[56:59]
	v_mfma_f32_16x16x32_bf16 v[56:59], v[170:173], v[198:201], v[56:59]
	v_mfma_f32_16x16x32_bf16 v[40:43], v[170:173], v[206:209], v[40:43]
	v_mfma_f32_16x16x32_bf16 v[40:43], v[174:177], v[210:213], v[40:43]
	v_mfma_f32_16x16x32_bf16 v[48:51], v[166:169], v[210:213], v[48:51]
	v_mfma_f32_16x16x32_bf16 v[48:51], v[162:165], v[206:209], v[48:51]
	v_mfma_f32_16x16x32_bf16 v[32:35], v[162:165], v[214:217], v[32:35]
	v_mfma_f32_16x16x32_bf16 v[32:35], v[166:169], v[218:221], v[32:35]
	v_mfma_f32_16x16x32_bf16 v[24:27], v[174:177], v[218:221], v[24:27]
	v_mfma_f32_16x16x32_bf16 v[24:27], v[170:173], v[214:217], v[24:27]
	v_mfma_f32_16x16x32_bf16 v[8:11], v[170:173], v[222:225], v[8:11]
	v_mfma_f32_16x16x32_bf16 v[8:11], v[174:177], v[226:229], v[8:11]
	v_mfma_f32_16x16x32_bf16 v[16:19], v[166:169], v[226:229], v[16:19]
	v_mfma_f32_16x16x32_bf16 v[16:19], v[162:165], v[222:225], v[16:19]
	s_setprio 0
	s_setprio 1
	v_mfma_f32_16x16x32_bf16 v[52:55], v[178:181], v[198:201], v[52:55]
	v_mfma_f32_16x16x32_bf16 v[52:55], v[186:189], v[202:205], v[52:55]
	v_mfma_f32_16x16x32_bf16 v[44:47], v[194:197], v[202:205], v[44:47]
	v_mfma_f32_16x16x32_bf16 v[44:47], v[190:193], v[198:201], v[44:47]
	v_mfma_f32_16x16x32_bf16 v[28:31], v[190:193], v[206:209], v[28:31]
	v_mfma_f32_16x16x32_bf16 v[28:31], v[194:197], v[210:213], v[28:31]
	v_mfma_f32_16x16x32_bf16 v[36:39], v[186:189], v[210:213], v[36:39]
	v_mfma_f32_16x16x32_bf16 v[36:39], v[178:181], v[206:209], v[36:39]
	v_mfma_f32_16x16x32_bf16 v[20:23], v[178:181], v[214:217], v[20:23]
	v_mfma_f32_16x16x32_bf16 v[20:23], v[186:189], v[218:221], v[20:23]
	v_mfma_f32_16x16x32_bf16 v[12:15], v[194:197], v[218:221], v[12:15]
	v_mfma_f32_16x16x32_bf16 v[12:15], v[190:193], v[214:217], v[12:15]
	v_mfma_f32_16x16x32_bf16 v[0:3], v[190:193], v[222:225], v[0:3]
	v_mfma_f32_16x16x32_bf16 v[0:3], v[194:197], v[226:229], v[0:3]
	v_mfma_f32_16x16x32_bf16 v[4:7], v[186:189], v[226:229], v[4:7]
	v_mfma_f32_16x16x32_bf16 v[4:7], v[178:181], v[222:225], v[4:7]
	s_setprio 0
	s_barrier
	s_add_i32 s86, 0, 0x18000
	v_add_u32_e32 v146, s86, v149
	s_add_i32 s87, 0, 0x1c000
	ds_read_b128 v[162:165], v146
	ds_read_b128 v[166:169], v146 offset:1024
	ds_read_b128 v[170:173], v146 offset:2048
	ds_read_b128 v[174:177], v146 offset:3072
	v_add_u32_e32 v146, s87, v149
	ds_read_b128 v[178:181], v146
	ds_read_b128 v[186:189], v146 offset:1024
	ds_read_b128 v[190:193], v146 offset:2048
	ds_read_b128 v[194:197], v146 offset:3072
	s_add_u32 s58, s58, 0x40000
	s_addc_u32 s59, s59, 0
	s_mov_b32 m0, s66
	v_lshl_add_u64 v[236:237], s[58:59], 0, v[128:129]
	ds_read_b128 v[198:201], v154 offset:32768
	ds_read_b128 v[202:205], v154 offset:33792
	ds_read_b128 v[206:209], v154 offset:34816
	ds_read_b128 v[210:213], v154 offset:35840
	ds_read_b128 v[214:217], v154 offset:36864
	ds_read_b128 v[218:221], v154 offset:37888
	ds_read_b128 v[222:225], v154 offset:38912
	ds_read_b128 v[226:229], v154 offset:39936
	global_load_lds_dwordx4 v[236:237], off
	v_lshl_add_u64 v[236:237], s[58:59], 0, v[132:133]
	s_mov_b32 m0, s67
	s_nop 0
	global_load_lds_dwordx4 v[236:237], off
	s_waitcnt vmcnt(8)
	s_waitcnt lgkmcnt(0)
	s_barrier
	s_setprio 1
	s_waitcnt lgkmcnt(0)
	v_mfma_f32_16x16x32_bf16 v[124:127], v[162:165], v[198:201], v[124:127]
	v_mfma_f32_16x16x32_bf16 v[124:127], v[166:169], v[202:205], v[124:127]
	v_mfma_f32_16x16x32_bf16 v[120:123], v[174:177], v[202:205], v[120:123]
	v_mfma_f32_16x16x32_bf16 v[120:123], v[170:173], v[198:201], v[120:123]
	v_mfma_f32_16x16x32_bf16 v[104:107], v[170:173], v[206:209], v[104:107]
	v_mfma_f32_16x16x32_bf16 v[104:107], v[174:177], v[210:213], v[104:107]
	v_mfma_f32_16x16x32_bf16 v[112:115], v[166:169], v[210:213], v[112:115]
	v_mfma_f32_16x16x32_bf16 v[112:115], v[162:165], v[206:209], v[112:115]
	v_mfma_f32_16x16x32_bf16 v[96:99], v[162:165], v[214:217], v[96:99]
	v_mfma_f32_16x16x32_bf16 v[96:99], v[166:169], v[218:221], v[96:99]
	v_mfma_f32_16x16x32_bf16 v[88:91], v[174:177], v[218:221], v[88:91]
	v_mfma_f32_16x16x32_bf16 v[88:91], v[170:173], v[214:217], v[88:91]
	v_mfma_f32_16x16x32_bf16 v[72:75], v[170:173], v[222:225], v[72:75]
	v_mfma_f32_16x16x32_bf16 v[72:75], v[174:177], v[226:229], v[72:75]
	v_mfma_f32_16x16x32_bf16 v[80:83], v[166:169], v[226:229], v[80:83]
	v_mfma_f32_16x16x32_bf16 v[80:83], v[162:165], v[222:225], v[80:83]
	s_setprio 0
	s_setprio 1
	v_mfma_f32_16x16x32_bf16 v[116:119], v[178:181], v[198:201], v[116:119]
	v_mfma_f32_16x16x32_bf16 v[116:119], v[186:189], v[202:205], v[116:119]
	v_mfma_f32_16x16x32_bf16 v[108:111], v[194:197], v[202:205], v[108:111]
	v_mfma_f32_16x16x32_bf16 v[108:111], v[190:193], v[198:201], v[108:111]
	v_mfma_f32_16x16x32_bf16 v[92:95], v[190:193], v[206:209], v[92:95]
	v_mfma_f32_16x16x32_bf16 v[92:95], v[194:197], v[210:213], v[92:95]
	v_mfma_f32_16x16x32_bf16 v[100:103], v[186:189], v[210:213], v[100:103]
	v_mfma_f32_16x16x32_bf16 v[100:103], v[178:181], v[206:209], v[100:103]
	v_mfma_f32_16x16x32_bf16 v[84:87], v[178:181], v[214:217], v[84:87]
	v_mfma_f32_16x16x32_bf16 v[84:87], v[186:189], v[218:221], v[84:87]
	v_mfma_f32_16x16x32_bf16 v[76:79], v[194:197], v[218:221], v[76:79]
	v_mfma_f32_16x16x32_bf16 v[76:79], v[190:193], v[214:217], v[76:79]
	v_mfma_f32_16x16x32_bf16 v[64:67], v[190:193], v[222:225], v[64:67]
	v_mfma_f32_16x16x32_bf16 v[64:67], v[194:197], v[226:229], v[64:67]
	v_mfma_f32_16x16x32_bf16 v[68:71], v[186:189], v[226:229], v[68:71]
	v_mfma_f32_16x16x32_bf16 v[68:71], v[178:181], v[222:225], v[68:71]
	s_setprio 0
	s_barrier
	s_add_i32 s58, s86, s63
	v_lshl_add_u64 v[182:183], v[182:183], 0, s[22:23]
	s_mov_b32 m0, s58
	ds_read_b128 v[198:201], v154 offset:49152
	ds_read_b128 v[202:205], v154 offset:50176
	ds_read_b128 v[206:209], v154 offset:51200
	ds_read_b128 v[210:213], v154 offset:52224
	ds_read_b128 v[214:217], v154 offset:53248
	ds_read_b128 v[218:221], v154 offset:54272
	ds_read_b128 v[222:225], v154 offset:55296
	ds_read_b128 v[226:229], v154 offset:56320
	global_load_lds_dwordx4 v[182:183], off
	s_add_i32 m0, s58, 0x2000
	s_add_u32 s56, s56, 0x40080
	v_lshl_add_u64 v[182:183], v[230:231], 0, s[22:23]
	s_addc_u32 s57, s57, 0
	s_add_i32 s58, s87, s63
	global_load_lds_dwordx4 v[182:183], off
	v_lshl_add_u64 v[182:183], s[56:57], 0, v[130:131]
	s_mov_b32 m0, s58
	s_nop 0
	global_load_lds_dwordx4 v[182:183], off
	v_lshl_add_u64 v[182:183], s[56:57], 0, v[134:135]
	s_add_i32 m0, s58, 0x2000
	s_nop 0
	global_load_lds_dwordx4 v[182:183], off
	v_lshl_add_u64 v[182:183], v[232:233], 0, s[22:23]
	s_mov_b32 m0, s69
	s_nop 0
	global_load_lds_dwordx4 v[182:183], off
	v_lshl_add_u64 v[182:183], v[234:235], 0, s[22:23]
	s_mov_b32 m0, s70
	s_nop 0
	global_load_lds_dwordx4 v[182:183], off
	s_waitcnt vmcnt(8)
	s_waitcnt lgkmcnt(0)
	s_barrier
	s_setprio 1
	s_waitcnt lgkmcnt(0)
	v_mfma_f32_16x16x32_bf16 v[60:63], v[162:165], v[198:201], v[60:63]
	v_mfma_f32_16x16x32_bf16 v[60:63], v[166:169], v[202:205], v[60:63]
	v_mfma_f32_16x16x32_bf16 v[56:59], v[174:177], v[202:205], v[56:59]
	v_mfma_f32_16x16x32_bf16 v[56:59], v[170:173], v[198:201], v[56:59]
	v_mfma_f32_16x16x32_bf16 v[40:43], v[170:173], v[206:209], v[40:43]
	v_mfma_f32_16x16x32_bf16 v[40:43], v[174:177], v[210:213], v[40:43]
	v_mfma_f32_16x16x32_bf16 v[48:51], v[166:169], v[210:213], v[48:51]
	v_mfma_f32_16x16x32_bf16 v[48:51], v[162:165], v[206:209], v[48:51]
	v_mfma_f32_16x16x32_bf16 v[32:35], v[162:165], v[214:217], v[32:35]
	v_mfma_f32_16x16x32_bf16 v[32:35], v[166:169], v[218:221], v[32:35]
	v_mfma_f32_16x16x32_bf16 v[24:27], v[174:177], v[218:221], v[24:27]
	v_mfma_f32_16x16x32_bf16 v[24:27], v[170:173], v[214:217], v[24:27]
	v_mfma_f32_16x16x32_bf16 v[8:11], v[170:173], v[222:225], v[8:11]
	v_mfma_f32_16x16x32_bf16 v[8:11], v[174:177], v[226:229], v[8:11]
	v_mfma_f32_16x16x32_bf16 v[16:19], v[166:169], v[226:229], v[16:19]
	v_mfma_f32_16x16x32_bf16 v[16:19], v[162:165], v[222:225], v[16:19]
	s_setprio 0
	s_setprio 1
	v_mfma_f32_16x16x32_bf16 v[52:55], v[178:181], v[198:201], v[52:55]
	v_mfma_f32_16x16x32_bf16 v[52:55], v[186:189], v[202:205], v[52:55]
	v_mfma_f32_16x16x32_bf16 v[44:47], v[194:197], v[202:205], v[44:47]
	v_mfma_f32_16x16x32_bf16 v[44:47], v[190:193], v[198:201], v[44:47]
	v_mfma_f32_16x16x32_bf16 v[28:31], v[190:193], v[206:209], v[28:31]
	v_mfma_f32_16x16x32_bf16 v[28:31], v[194:197], v[210:213], v[28:31]
	v_mfma_f32_16x16x32_bf16 v[36:39], v[186:189], v[210:213], v[36:39]
	v_mfma_f32_16x16x32_bf16 v[36:39], v[178:181], v[206:209], v[36:39]
	v_mfma_f32_16x16x32_bf16 v[20:23], v[178:181], v[214:217], v[20:23]
	v_mfma_f32_16x16x32_bf16 v[20:23], v[186:189], v[218:221], v[20:23]
	v_mfma_f32_16x16x32_bf16 v[12:15], v[194:197], v[218:221], v[12:15]
	v_mfma_f32_16x16x32_bf16 v[12:15], v[190:193], v[214:217], v[12:15]
	v_mfma_f32_16x16x32_bf16 v[0:3], v[190:193], v[222:225], v[0:3]
	v_mfma_f32_16x16x32_bf16 v[0:3], v[194:197], v[226:229], v[0:3]
	v_mfma_f32_16x16x32_bf16 v[4:7], v[186:189], v[226:229], v[4:7]
	v_mfma_f32_16x16x32_bf16 v[4:7], v[178:181], v[222:225], v[4:7]
	s_setprio 0
	s_barrier
	s_add_i32 s85, s85, 2
	s_add_u32 s83, s83, 0x100
	s_addc_u32 s84, s84, 0
	s_add_u32 s54, s54, 0x100
	s_addc_u32 s55, s55, 0
	s_cmp_gt_u32 s85, 13
	s_cbranch_scc1 .LBB0_877

.LBB0_1010:
	s_ashr_i32 s51, s50, 31
	s_lshl_b64 s[52:53], s[50:51], 19
	s_add_u32 s52, s33, s52
	s_addc_u32 s53, s35, s53
	s_and_b64 s[54:55], s[12:13], exec
	s_cselect_b32 s15, s53, s61
	s_cselect_b32 s51, s52, s60
	s_ashr_i32 s49, s48, 31
	s_lshl_b64 s[54:55], s[48:49], 19
	s_add_u32 s54, s64, s54
	s_addc_u32 s55, s65, s55
	s_and_b64 s[62:63], s[12:13], exec
	s_cselect_b32 s49, s55, s59
	s_cselect_b32 s57, s54, s58
	s_add_u32 s78, s58, 0x100
	s_addc_u32 s79, s59, 0
	s_add_u32 s58, s60, 0x40080
	s_addc_u32 s59, s61, 0
	s_mov_b32 s80, -2
	s_waitcnt lgkmcnt(0)
	s_cmp_eq_u32 s71, 1
	s_cbranch_scc1 .Lfa_9
	ds_read_b128 v[128:131], v188
	ds_read_b128 v[132:135], v188 offset:1024
	ds_read_b128 v[136:139], v188 offset:2048
	ds_read_b128 v[140:143], v188 offset:3072
	ds_read_b128 v[144:147], v189
	ds_read_b128 v[148:151], v189 offset:1024
	ds_read_b128 v[172:175], v189 offset:2048
	ds_read_b128 v[176:179], v189 offset:3072
	s_add_u32 s60, s58, 0xfffc0080
	s_addc_u32 s61, s59, -1
	s_cmp_eq_u32 s80, 12
	s_cselect_b32 s63, s15, s61
	s_cselect_b32 s62, s51, s60
	s_cselect_b32 s61, s49, s79
	s_cselect_b32 s60, s57, s78
	v_lshl_add_u64 v[220:221], s[58:59], 0, v[166:167]
	s_add_i32 m0, s67, 0xc000
	ds_read_b128 v[180:183], v190
	ds_read_b128 v[192:195], v190 offset:1024
	ds_read_b128 v[196:199], v190 offset:2048
	ds_read_b128 v[200:203], v190 offset:3072
	ds_read_b128 v[204:207], v190 offset:4096
	ds_read_b128 v[208:211], v190 offset:5120
	ds_read_b128 v[212:215], v190 offset:6144
	ds_read_b128 v[216:219], v190 offset:7168
	global_load_lds_dwordx4 v[220:221], off
	v_lshl_add_u64 v[220:221], s[58:59], 0, v[164:165]
	s_add_i32 m0, s67, 0xe000
	s_nop 0
	global_load_lds_dwordx4 v[220:221], off
	s_waitcnt vmcnt(24)
	s_waitcnt lgkmcnt(0)
	s_barrier
	s_setprio 1
	s_waitcnt lgkmcnt(0)
	v_mfma_f32_16x16x32_bf16 v[124:127], v[128:131], v[180:183], 0
	v_mfma_f32_16x16x32_bf16 v[120:123], v[136:139], v[180:183], 0
	v_mfma_f32_16x16x32_bf16 v[108:111], v[128:131], v[196:199], 0
	v_mfma_f32_16x16x32_bf16 v[104:107], v[136:139], v[196:199], 0
	v_mfma_f32_16x16x32_bf16 v[92:95], v[128:131], v[204:207], 0
	v_mfma_f32_16x16x32_bf16 v[88:91], v[136:139], v[204:207], 0
	v_mfma_f32_16x16x32_bf16 v[76:79], v[128:131], v[212:215], 0
	v_mfma_f32_16x16x32_bf16 v[72:75], v[136:139], v[212:215], 0
	v_mfma_f32_16x16x32_bf16 v[124:127], v[132:135], v[192:195], v[124:127]
	v_mfma_f32_16x16x32_bf16 v[120:123], v[140:143], v[192:195], v[120:123]
	v_mfma_f32_16x16x32_bf16 v[108:111], v[132:135], v[200:203], v[108:111]
	v_mfma_f32_16x16x32_bf16 v[104:107], v[140:143], v[200:203], v[104:107]
	v_mfma_f32_16x16x32_bf16 v[92:95], v[132:135], v[208:211], v[92:95]
	v_mfma_f32_16x16x32_bf16 v[88:91], v[140:143], v[208:211], v[88:91]
	v_mfma_f32_16x16x32_bf16 v[76:79], v[132:135], v[216:219], v[76:79]
	v_mfma_f32_16x16x32_bf16 v[72:75], v[140:143], v[216:219], v[72:75]
	s_setprio 0
	s_setprio 1
	v_mfma_f32_16x16x32_bf16 v[116:119], v[144:147], v[180:183], 0
	v_mfma_f32_16x16x32_bf16 v[112:115], v[172:175], v[180:183], 0
	v_mfma_f32_16x16x32_bf16 v[100:103], v[144:147], v[196:199], 0
	v_mfma_f32_16x16x32_bf16 v[96:99], v[172:175], v[196:199], 0
	v_mfma_f32_16x16x32_bf16 v[84:87], v[144:147], v[204:207], 0
	v_mfma_f32_16x16x32_bf16 v[80:83], v[172:175], v[204:207], 0
	v_mfma_f32_16x16x32_bf16 v[68:71], v[144:147], v[212:215], 0
	v_mfma_f32_16x16x32_bf16 v[64:67], v[172:175], v[212:215], 0
	v_mfma_f32_16x16x32_bf16 v[116:119], v[148:151], v[192:195], v[116:119]
	v_mfma_f32_16x16x32_bf16 v[112:115], v[176:179], v[192:195], v[112:115]
	v_mfma_f32_16x16x32_bf16 v[100:103], v[148:151], v[200:203], v[100:103]
	v_mfma_f32_16x16x32_bf16 v[96:99], v[176:179], v[200:203], v[96:99]
	v_mfma_f32_16x16x32_bf16 v[84:87], v[148:151], v[208:211], v[84:87]
	v_mfma_f32_16x16x32_bf16 v[80:83], v[176:179], v[208:211], v[80:83]
	v_mfma_f32_16x16x32_bf16 v[68:71], v[148:151], v[216:219], v[68:71]
	v_mfma_f32_16x16x32_bf16 v[64:67], v[176:179], v[216:219], v[64:67]
	s_setprio 0
	s_barrier
	s_add_i32 s81, s76, s66
	v_lshl_add_u64 v[220:221], s[60:61], 0, v[154:155]
	s_mov_b32 m0, s81
	ds_read_b128 v[180:183], v190 offset:16384
	ds_read_b128 v[192:195], v190 offset:17408
	ds_read_b128 v[196:199], v190 offset:18432
	ds_read_b128 v[200:203], v190 offset:19456
	ds_read_b128 v[204:207], v190 offset:20480
	ds_read_b128 v[208:211], v190 offset:21504
	ds_read_b128 v[212:215], v190 offset:22528
	ds_read_b128 v[216:219], v190 offset:23552
	global_load_lds_dwordx4 v[220:221], off
	s_add_i32 m0, s81, 0x2000
	s_add_u32 s82, s60, 0x40000
	v_lshl_add_u64 v[222:223], s[60:61], 0, v[162:163]
	s_addc_u32 s83, s61, 0
	s_add_i32 s81, s77, s66
	global_load_lds_dwordx4 v[222:223], off
	v_lshl_add_u64 v[224:225], s[82:83], 0, v[154:155]
	s_mov_b32 m0, s81
	v_lshl_add_u64 v[226:227], s[62:63], 0, v[160:161]
	global_load_lds_dwordx4 v[224:225], off
	v_lshl_add_u64 v[224:225], s[82:83], 0, v[162:163]
	s_add_i32 m0, s81, 0x2000
	s_nop 0
	global_load_lds_dwordx4 v[224:225], off
	v_lshl_add_u64 v[224:225], s[62:63], 0, v[152:153]
	s_mov_b32 m0, s67
	s_nop 0
	global_load_lds_dwordx4 v[224:225], off
	s_mov_b32 m0, s68
	s_nop 0
	global_load_lds_dwordx4 v[226:227], off
	s_waitcnt vmcnt(24)
	s_waitcnt lgkmcnt(0)
	s_barrier
	s_setprio 1
	s_waitcnt lgkmcnt(0)
	v_mfma_f32_16x16x32_bf16 v[60:63], v[128:131], v[180:183], 0
	v_mfma_f32_16x16x32_bf16 v[56:59], v[136:139], v[180:183], 0
	v_mfma_f32_16x16x32_bf16 v[44:47], v[128:131], v[196:199], 0
	v_mfma_f32_16x16x32_bf16 v[40:43], v[136:139], v[196:199], 0
	v_mfma_f32_16x16x32_bf16 v[28:31], v[128:131], v[204:207], 0
	v_mfma_f32_16x16x32_bf16 v[24:27], v[136:139], v[204:207], 0
	v_mfma_f32_16x16x32_bf16 v[12:15], v[128:131], v[212:215], 0
	v_mfma_f32_16x16x32_bf16 v[8:11], v[136:139], v[212:215], 0
	v_mfma_f32_16x16x32_bf16 v[60:63], v[132:135], v[192:195], v[60:63]
	v_mfma_f32_16x16x32_bf16 v[56:59], v[140:143], v[192:195], v[56:59]
	v_mfma_f32_16x16x32_bf16 v[44:47], v[132:135], v[200:203], v[44:47]
	v_mfma_f32_16x16x32_bf16 v[40:43], v[140:143], v[200:203], v[40:43]
	v_mfma_f32_16x16x32_bf16 v[28:31], v[132:135], v[208:211], v[28:31]
	v_mfma_f32_16x16x32_bf16 v[24:27], v[140:143], v[208:211], v[24:27]
	v_mfma_f32_16x16x32_bf16 v[12:15], v[132:135], v[216:219], v[12:15]
	v_mfma_f32_16x16x32_bf16 v[8:11], v[140:143], v[216:219], v[8:11]
	s_setprio 0
	s_setprio 1
	v_mfma_f32_16x16x32_bf16 v[52:55], v[144:147], v[180:183], 0
	v_mfma_f32_16x16x32_bf16 v[48:51], v[172:175], v[180:183], 0
	v_mfma_f32_16x16x32_bf16 v[36:39], v[144:147], v[196:199], 0
	v_mfma_f32_16x16x32_bf16 v[32:35], v[172:175], v[196:199], 0
	v_mfma_f32_16x16x32_bf16 v[20:23], v[144:147], v[204:207], 0
	v_mfma_f32_16x16x32_bf16 v[16:19], v[172:175], v[204:207], 0
	v_mfma_f32_16x16x32_bf16 v[4:7], v[144:147], v[212:215], 0
	v_mfma_f32_16x16x32_bf16 v[0:3], v[172:175], v[212:215], 0
	v_mfma_f32_16x16x32_bf16 v[52:55], v[148:151], v[192:195], v[52:55]
	v_mfma_f32_16x16x32_bf16 v[48:51], v[176:179], v[192:195], v[48:51]
	v_mfma_f32_16x16x32_bf16 v[36:39], v[148:151], v[200:203], v[36:39]
	v_mfma_f32_16x16x32_bf16 v[32:35], v[176:179], v[200:203], v[32:35]
	v_mfma_f32_16x16x32_bf16 v[20:23], v[148:151], v[208:211], v[20:23]
	v_mfma_f32_16x16x32_bf16 v[16:19], v[176:179], v[208:211], v[16:19]
	v_mfma_f32_16x16x32_bf16 v[4:7], v[148:151], v[216:219], v[4:7]
	v_mfma_f32_16x16x32_bf16 v[0:3], v[176:179], v[216:219], v[0:3]
	s_setprio 0
	s_barrier
	s_add_i32 s81, 0, 0x18000
	s_add_i32 s82, 0, 0x1c000
	v_add_u32_e32 v140, s81, v185
	v_add_u32_e32 v176, s82, v185
	ds_read_b128 v[128:131], v140
	ds_read_b128 v[132:135], v140 offset:1024
	ds_read_b128 v[136:139], v140 offset:2048
	ds_read_b128 v[140:143], v140 offset:3072
	ds_read_b128 v[144:147], v176
	ds_read_b128 v[148:151], v176 offset:1024
	ds_read_b128 v[172:175], v176 offset:2048
	ds_read_b128 v[176:179], v176 offset:3072
	s_add_u32 s62, s62, 0x40000
	s_addc_u32 s63, s63, 0
	s_mov_b32 m0, s69
	v_lshl_add_u64 v[228:229], s[62:63], 0, v[152:153]
	ds_read_b128 v[180:183], v190 offset:32768
	ds_read_b128 v[192:195], v190 offset:33792
	ds_read_b128 v[196:199], v190 offset:34816
	ds_read_b128 v[200:203], v190 offset:35840
	ds_read_b128 v[204:207], v190 offset:36864
	ds_read_b128 v[208:211], v190 offset:37888
	ds_read_b128 v[212:215], v190 offset:38912
	ds_read_b128 v[216:219], v190 offset:39936
	global_load_lds_dwordx4 v[228:229], off
	v_lshl_add_u64 v[228:229], s[62:63], 0, v[160:161]
	s_mov_b32 m0, s70
	s_nop 0
	global_load_lds_dwordx4 v[228:229], off
	s_waitcnt vmcnt(8)
	s_waitcnt lgkmcnt(0)
	s_barrier
	s_setprio 1
	s_waitcnt lgkmcnt(0)
	v_mfma_f32_16x16x32_bf16 v[124:127], v[128:131], v[180:183], v[124:127]
	v_mfma_f32_16x16x32_bf16 v[124:127], v[132:135], v[192:195], v[124:127]
	v_mfma_f32_16x16x32_bf16 v[120:123], v[140:143], v[192:195], v[120:123]
	v_mfma_f32_16x16x32_bf16 v[120:123], v[136:139], v[180:183], v[120:123]
	v_mfma_f32_16x16x32_bf16 v[104:107], v[136:139], v[196:199], v[104:107]
	v_mfma_f32_16x16x32_bf16 v[104:107], v[140:143], v[200:203], v[104:107]
	v_mfma_f32_16x16x32_bf16 v[108:111], v[132:135], v[200:203], v[108:111]
	v_mfma_f32_16x16x32_bf16 v[108:111], v[128:131], v[196:199], v[108:111]
	v_mfma_f32_16x16x32_bf16 v[92:95], v[128:131], v[204:207], v[92:95]
	v_mfma_f32_16x16x32_bf16 v[92:95], v[132:135], v[208:211], v[92:95]
	v_mfma_f32_16x16x32_bf16 v[88:91], v[140:143], v[208:211], v[88:91]
	v_mfma_f32_16x16x32_bf16 v[88:91], v[136:139], v[204:207], v[88:91]
	v_mfma_f32_16x16x32_bf16 v[72:75], v[136:139], v[212:215], v[72:75]
	v_mfma_f32_16x16x32_bf16 v[72:75], v[140:143], v[216:219], v[72:75]
	v_mfma_f32_16x16x32_bf16 v[76:79], v[132:135], v[216:219], v[76:79]
	v_mfma_f32_16x16x32_bf16 v[76:79], v[128:131], v[212:215], v[76:79]
	s_setprio 0
	s_setprio 1
	v_mfma_f32_16x16x32_bf16 v[116:119], v[144:147], v[180:183], v[116:119]
	v_mfma_f32_16x16x32_bf16 v[116:119], v[148:151], v[192:195], v[116:119]
	v_mfma_f32_16x16x32_bf16 v[112:115], v[176:179], v[192:195], v[112:115]
	v_mfma_f32_16x16x32_bf16 v[112:115], v[172:175], v[180:183], v[112:115]
	v_mfma_f32_16x16x32_bf16 v[96:99], v[172:175], v[196:199], v[96:99]
	v_mfma_f32_16x16x32_bf16 v[96:99], v[176:179], v[200:203], v[96:99]
	v_mfma_f32_16x16x32_bf16 v[100:103], v[148:151], v[200:203], v[100:103]
	v_mfma_f32_16x16x32_bf16 v[100:103], v[144:147], v[196:199], v[100:103]
	v_mfma_f32_16x16x32_bf16 v[84:87], v[144:147], v[204:207], v[84:87]
	v_mfma_f32_16x16x32_bf16 v[84:87], v[148:151], v[208:211], v[84:87]
	v_mfma_f32_16x16x32_bf16 v[80:83], v[176:179], v[208:211], v[80:83]
	v_mfma_f32_16x16x32_bf16 v[80:83], v[172:175], v[204:207], v[80:83]
	v_mfma_f32_16x16x32_bf16 v[64:67], v[172:175], v[212:215], v[64:67]
	v_mfma_f32_16x16x32_bf16 v[64:67], v[176:179], v[216:219], v[64:67]
	v_mfma_f32_16x16x32_bf16 v[68:71], v[148:151], v[216:219], v[68:71]
	v_mfma_f32_16x16x32_bf16 v[68:71], v[144:147], v[212:215], v[68:71]
	s_setprio 0
	s_barrier
	s_add_i32 s62, s81, s66
	v_lshl_add_u64 v[220:221], v[220:221], 0, s[26:27]
	s_mov_b32 m0, s62
	ds_read_b128 v[180:183], v190 offset:49152
	ds_read_b128 v[192:195], v190 offset:50176
	ds_read_b128 v[196:199], v190 offset:51200
	ds_read_b128 v[200:203], v190 offset:52224
	ds_read_b128 v[204:207], v190 offset:53248
	ds_read_b128 v[208:211], v190 offset:54272
	ds_read_b128 v[212:215], v190 offset:55296
	ds_read_b128 v[216:219], v190 offset:56320
	global_load_lds_dwordx4 v[220:221], off
	s_add_i32 m0, s62, 0x2000
	s_add_u32 s60, s60, 0x40080
	v_lshl_add_u64 v[220:221], v[222:223], 0, s[26:27]
	s_addc_u32 s61, s61, 0
	s_add_i32 s62, s82, s66
	global_load_lds_dwordx4 v[220:221], off
	v_lshl_add_u64 v[220:221], s[60:61], 0, v[154:155]
	s_mov_b32 m0, s62
	s_nop 0
	global_load_lds_dwordx4 v[220:221], off
	v_lshl_add_u64 v[220:221], s[60:61], 0, v[162:163]
	s_add_i32 m0, s62, 0x2000
	s_nop 0
	global_load_lds_dwordx4 v[220:221], off
	v_lshl_add_u64 v[220:221], v[224:225], 0, s[26:27]
	s_mov_b32 m0, s3
	s_nop 0
	global_load_lds_dwordx4 v[220:221], off
	v_lshl_add_u64 v[220:221], v[226:227], 0, s[26:27]
	s_mov_b32 m0, s72
	s_nop 0
	global_load_lds_dwordx4 v[220:221], off
	s_waitcnt vmcnt(8)
	s_waitcnt lgkmcnt(0)
	s_barrier
	s_setprio 1
	s_waitcnt lgkmcnt(0)
	v_mfma_f32_16x16x32_bf16 v[60:63], v[128:131], v[180:183], v[60:63]
	v_mfma_f32_16x16x32_bf16 v[60:63], v[132:135], v[192:195], v[60:63]
	v_mfma_f32_16x16x32_bf16 v[56:59], v[140:143], v[192:195], v[56:59]
	v_mfma_f32_16x16x32_bf16 v[56:59], v[136:139], v[180:183], v[56:59]
	v_mfma_f32_16x16x32_bf16 v[40:43], v[136:139], v[196:199], v[40:43]
	v_mfma_f32_16x16x32_bf16 v[40:43], v[140:143], v[200:203], v[40:43]
	v_mfma_f32_16x16x32_bf16 v[44:47], v[132:135], v[200:203], v[44:47]
	v_mfma_f32_16x16x32_bf16 v[44:47], v[128:131], v[196:199], v[44:47]
	v_mfma_f32_16x16x32_bf16 v[28:31], v[128:131], v[204:207], v[28:31]
	v_mfma_f32_16x16x32_bf16 v[28:31], v[132:135], v[208:211], v[28:31]
	v_mfma_f32_16x16x32_bf16 v[24:27], v[140:143], v[208:211], v[24:27]
	v_mfma_f32_16x16x32_bf16 v[24:27], v[136:139], v[204:207], v[24:27]
	v_mfma_f32_16x16x32_bf16 v[8:11], v[136:139], v[212:215], v[8:11]
	v_mfma_f32_16x16x32_bf16 v[8:11], v[140:143], v[216:219], v[8:11]
	v_mfma_f32_16x16x32_bf16 v[12:15], v[132:135], v[216:219], v[12:15]
	v_mfma_f32_16x16x32_bf16 v[12:15], v[128:131], v[212:215], v[12:15]
	s_setprio 0
	s_setprio 1
	v_mfma_f32_16x16x32_bf16 v[52:55], v[144:147], v[180:183], v[52:55]
	v_mfma_f32_16x16x32_bf16 v[52:55], v[148:151], v[192:195], v[52:55]
	v_mfma_f32_16x16x32_bf16 v[48:51], v[176:179], v[192:195], v[48:51]
	v_mfma_f32_16x16x32_bf16 v[48:51], v[172:175], v[180:183], v[48:51]
	v_mfma_f32_16x16x32_bf16 v[32:35], v[172:175], v[196:199], v[32:35]
	v_mfma_f32_16x16x32_bf16 v[32:35], v[176:179], v[200:203], v[32:35]
	v_mfma_f32_16x16x32_bf16 v[36:39], v[148:151], v[200:203], v[36:39]
	v_mfma_f32_16x16x32_bf16 v[36:39], v[144:147], v[196:199], v[36:39]
	v_mfma_f32_16x16x32_bf16 v[20:23], v[144:147], v[204:207], v[20:23]
	v_mfma_f32_16x16x32_bf16 v[20:23], v[148:151], v[208:211], v[20:23]
	v_mfma_f32_16x16x32_bf16 v[16:19], v[176:179], v[208:211], v[16:19]
	v_mfma_f32_16x16x32_bf16 v[16:19], v[172:175], v[204:207], v[16:19]
	v_mfma_f32_16x16x32_bf16 v[0:3], v[172:175], v[212:215], v[0:3]
	v_mfma_f32_16x16x32_bf16 v[0:3], v[176:179], v[216:219], v[0:3]
	v_mfma_f32_16x16x32_bf16 v[4:7], v[148:151], v[216:219], v[4:7]
	v_mfma_f32_16x16x32_bf16 v[4:7], v[144:147], v[212:215], v[4:7]
	s_setprio 0
	s_barrier
	s_add_i32 s80, s80, 2
	s_add_u32 s78, s78, 0x100
	s_addc_u32 s79, s79, 0
	s_add_u32 s58, s58, 0x100
	s_addc_u32 s59, s59, 0
	s_cmp_gt_u32 s80, 13
	s_branch .LBB0_1011
.Lfa_9:
	ds_read_b128 v[128:131], v188
	ds_read_b128 v[132:135], v188 offset:1024
	ds_read_b128 v[136:139], v188 offset:2048
	ds_read_b128 v[140:143], v188 offset:3072
	ds_read_b128 v[144:147], v189
	ds_read_b128 v[148:151], v189 offset:1024
	ds_read_b128 v[172:175], v189 offset:2048
	ds_read_b128 v[176:179], v189 offset:3072
	s_add_u32 s60, s58, 0xfffc0080
	s_addc_u32 s61, s59, -1
	s_cmp_eq_u32 s80, 12
	s_cselect_b32 s63, s15, s61
	s_cselect_b32 s62, s51, s60
	s_cselect_b32 s61, s49, s79
	s_cselect_b32 s60, s57, s78
	v_lshl_add_u64 v[220:221], s[58:59], 0, v[166:167]
	s_add_i32 m0, s67, 0xc000
	ds_read_b128 v[180:183], v190
	ds_read_b128 v[192:195], v190 offset:1024
	ds_read_b128 v[196:199], v190 offset:2048
	ds_read_b128 v[200:203], v190 offset:3072
	ds_read_b128 v[204:207], v190 offset:4096
	ds_read_b128 v[208:211], v190 offset:5120
	ds_read_b128 v[212:215], v190 offset:6144
	ds_read_b128 v[216:219], v190 offset:7168
	global_load_lds_dwordx4 v[220:221], off
	v_lshl_add_u64 v[220:221], s[58:59], 0, v[164:165]
	s_add_i32 m0, s67, 0xe000
	s_nop 0
	global_load_lds_dwordx4 v[220:221], off
	s_waitcnt vmcnt(8)
	s_waitcnt lgkmcnt(0)
	s_barrier
	s_setprio 1
	s_waitcnt lgkmcnt(0)
	v_mfma_f32_16x16x32_bf16 v[124:127], v[128:131], v[180:183], 0
	v_mfma_f32_16x16x32_bf16 v[120:123], v[136:139], v[180:183], 0
	v_mfma_f32_16x16x32_bf16 v[108:111], v[128:131], v[196:199], 0
	v_mfma_f32_16x16x32_bf16 v[104:107], v[136:139], v[196:199], 0
	v_mfma_f32_16x16x32_bf16 v[92:95], v[128:131], v[204:207], 0
	v_mfma_f32_16x16x32_bf16 v[88:91], v[136:139], v[204:207], 0
	v_mfma_f32_16x16x32_bf16 v[76:79], v[128:131], v[212:215], 0
	v_mfma_f32_16x16x32_bf16 v[72:75], v[136:139], v[212:215], 0
	v_mfma_f32_16x16x32_bf16 v[124:127], v[132:135], v[192:195], v[124:127]
	v_mfma_f32_16x16x32_bf16 v[120:123], v[140:143], v[192:195], v[120:123]
	v_mfma_f32_16x16x32_bf16 v[108:111], v[132:135], v[200:203], v[108:111]
	v_mfma_f32_16x16x32_bf16 v[104:107], v[140:143], v[200:203], v[104:107]
	v_mfma_f32_16x16x32_bf16 v[92:95], v[132:135], v[208:211], v[92:95]
	v_mfma_f32_16x16x32_bf16 v[88:91], v[140:143], v[208:211], v[88:91]
	v_mfma_f32_16x16x32_bf16 v[76:79], v[132:135], v[216:219], v[76:79]
	v_mfma_f32_16x16x32_bf16 v[72:75], v[140:143], v[216:219], v[72:75]
	s_setprio 0
	s_setprio 1
	v_mfma_f32_16x16x32_bf16 v[116:119], v[144:147], v[180:183], 0
	v_mfma_f32_16x16x32_bf16 v[112:115], v[172:175], v[180:183], 0
	v_mfma_f32_16x16x32_bf16 v[100:103], v[144:147], v[196:199], 0
	v_mfma_f32_16x16x32_bf16 v[96:99], v[172:175], v[196:199], 0
	v_mfma_f32_16x16x32_bf16 v[84:87], v[144:147], v[204:207], 0
	v_mfma_f32_16x16x32_bf16 v[80:83], v[172:175], v[204:207], 0
	v_mfma_f32_16x16x32_bf16 v[68:71], v[144:147], v[212:215], 0
	v_mfma_f32_16x16x32_bf16 v[64:67], v[172:175], v[212:215], 0
	v_mfma_f32_16x16x32_bf16 v[116:119], v[148:151], v[192:195], v[116:119]
	v_mfma_f32_16x16x32_bf16 v[112:115], v[176:179], v[192:195], v[112:115]
	v_mfma_f32_16x16x32_bf16 v[100:103], v[148:151], v[200:203], v[100:103]
	v_mfma_f32_16x16x32_bf16 v[96:99], v[176:179], v[200:203], v[96:99]
	v_mfma_f32_16x16x32_bf16 v[84:87], v[148:151], v[208:211], v[84:87]
	v_mfma_f32_16x16x32_bf16 v[80:83], v[176:179], v[208:211], v[80:83]
	v_mfma_f32_16x16x32_bf16 v[68:71], v[148:151], v[216:219], v[68:71]
	v_mfma_f32_16x16x32_bf16 v[64:67], v[176:179], v[216:219], v[64:67]
	s_setprio 0
	s_barrier
	s_add_i32 s81, s76, s66
	v_lshl_add_u64 v[220:221], s[60:61], 0, v[154:155]
	s_mov_b32 m0, s81
	ds_read_b128 v[180:183], v190 offset:16384
	ds_read_b128 v[192:195], v190 offset:17408
	ds_read_b128 v[196:199], v190 offset:18432
	ds_read_b128 v[200:203], v190 offset:19456
	ds_read_b128 v[204:207], v190 offset:20480
	ds_read_b128 v[208:211], v190 offset:21504
	ds_read_b128 v[212:215], v190 offset:22528
	ds_read_b128 v[216:219], v190 offset:23552
	global_load_lds_dwordx4 v[220:221], off
	s_add_i32 m0, s81, 0x2000
	s_add_u32 s82, s60, 0x40000
	v_lshl_add_u64 v[222:223], s[60:61], 0, v[162:163]
	s_addc_u32 s83, s61, 0
	s_add_i32 s81, s77, s66
	global_load_lds_dwordx4 v[222:223], off
	v_lshl_add_u64 v[224:225], s[82:83], 0, v[154:155]
	s_mov_b32 m0, s81
	v_lshl_add_u64 v[226:227], s[62:63], 0, v[160:161]
	global_load_lds_dwordx4 v[224:225], off
	v_lshl_add_u64 v[224:225], s[82:83], 0, v[162:163]
	s_add_i32 m0, s81, 0x2000
	s_nop 0
	global_load_lds_dwordx4 v[224:225], off
	v_lshl_add_u64 v[224:225], s[62:63], 0, v[152:153]
	s_mov_b32 m0, s67
	s_nop 0
	global_load_lds_dwordx4 v[224:225], off
	s_mov_b32 m0, s68
	s_nop 0
	global_load_lds_dwordx4 v[226:227], off
	s_waitcnt vmcnt(8)
	s_waitcnt lgkmcnt(0)
	s_barrier
	s_setprio 1
	s_waitcnt lgkmcnt(0)
	v_mfma_f32_16x16x32_bf16 v[60:63], v[128:131], v[180:183], 0
	v_mfma_f32_16x16x32_bf16 v[56:59], v[136:139], v[180:183], 0
	v_mfma_f32_16x16x32_bf16 v[44:47], v[128:131], v[196:199], 0
	v_mfma_f32_16x16x32_bf16 v[40:43], v[136:139], v[196:199], 0
	v_mfma_f32_16x16x32_bf16 v[28:31], v[128:131], v[204:207], 0
	v_mfma_f32_16x16x32_bf16 v[24:27], v[136:139], v[204:207], 0
	v_mfma_f32_16x16x32_bf16 v[12:15], v[128:131], v[212:215], 0
	v_mfma_f32_16x16x32_bf16 v[8:11], v[136:139], v[212:215], 0
	v_mfma_f32_16x16x32_bf16 v[60:63], v[132:135], v[192:195], v[60:63]
	v_mfma_f32_16x16x32_bf16 v[56:59], v[140:143], v[192:195], v[56:59]
	v_mfma_f32_16x16x32_bf16 v[44:47], v[132:135], v[200:203], v[44:47]
	v_mfma_f32_16x16x32_bf16 v[40:43], v[140:143], v[200:203], v[40:43]
	v_mfma_f32_16x16x32_bf16 v[28:31], v[132:135], v[208:211], v[28:31]
	v_mfma_f32_16x16x32_bf16 v[24:27], v[140:143], v[208:211], v[24:27]
	v_mfma_f32_16x16x32_bf16 v[12:15], v[132:135], v[216:219], v[12:15]
	v_mfma_f32_16x16x32_bf16 v[8:11], v[140:143], v[216:219], v[8:11]
	s_setprio 0
	s_setprio 1
	v_mfma_f32_16x16x32_bf16 v[52:55], v[144:147], v[180:183], 0
	v_mfma_f32_16x16x32_bf16 v[48:51], v[172:175], v[180:183], 0
	v_mfma_f32_16x16x32_bf16 v[36:39], v[144:147], v[196:199], 0
	v_mfma_f32_16x16x32_bf16 v[32:35], v[172:175], v[196:199], 0
	v_mfma_f32_16x16x32_bf16 v[20:23], v[144:147], v[204:207], 0
	v_mfma_f32_16x16x32_bf16 v[16:19], v[172:175], v[204:207], 0
	v_mfma_f32_16x16x32_bf16 v[4:7], v[144:147], v[212:215], 0
	v_mfma_f32_16x16x32_bf16 v[0:3], v[172:175], v[212:215], 0
	v_mfma_f32_16x16x32_bf16 v[52:55], v[148:151], v[192:195], v[52:55]
	v_mfma_f32_16x16x32_bf16 v[48:51], v[176:179], v[192:195], v[48:51]
	v_mfma_f32_16x16x32_bf16 v[36:39], v[148:151], v[200:203], v[36:39]
	v_mfma_f32_16x16x32_bf16 v[32:35], v[176:179], v[200:203], v[32:35]
	v_mfma_f32_16x16x32_bf16 v[20:23], v[148:151], v[208:211], v[20:23]
	v_mfma_f32_16x16x32_bf16 v[16:19], v[176:179], v[208:211], v[16:19]
	v_mfma_f32_16x16x32_bf16 v[4:7], v[148:151], v[216:219], v[4:7]
	v_mfma_f32_16x16x32_bf16 v[0:3], v[176:179], v[216:219], v[0:3]
	s_setprio 0
	s_barrier
	s_add_i32 s81, 0, 0x18000
	s_add_i32 s82, 0, 0x1c000
	v_add_u32_e32 v140, s81, v185
	v_add_u32_e32 v176, s82, v185
	ds_read_b128 v[128:131], v140
	ds_read_b128 v[132:135], v140 offset:1024
	ds_read_b128 v[136:139], v140 offset:2048
	ds_read_b128 v[140:143], v140 offset:3072
	ds_read_b128 v[144:147], v176
	ds_read_b128 v[148:151], v176 offset:1024
	ds_read_b128 v[172:175], v176 offset:2048
	ds_read_b128 v[176:179], v176 offset:3072
	s_add_u32 s62, s62, 0x40000
	s_addc_u32 s63, s63, 0
	s_mov_b32 m0, s69
	v_lshl_add_u64 v[228:229], s[62:63], 0, v[152:153]
	ds_read_b128 v[180:183], v190 offset:32768
	ds_read_b128 v[192:195], v190 offset:33792
	ds_read_b128 v[196:199], v190 offset:34816
	ds_read_b128 v[200:203], v190 offset:35840
	ds_read_b128 v[204:207], v190 offset:36864
	ds_read_b128 v[208:211], v190 offset:37888
	ds_read_b128 v[212:215], v190 offset:38912
	ds_read_b128 v[216:219], v190 offset:39936
	global_load_lds_dwordx4 v[228:229], off
	v_lshl_add_u64 v[228:229], s[62:63], 0, v[160:161]
	s_mov_b32 m0, s70
	s_nop 0
	global_load_lds_dwordx4 v[228:229], off
	s_waitcnt vmcnt(8)
	s_waitcnt lgkmcnt(0)
	s_barrier
	s_setprio 1
	s_waitcnt lgkmcnt(0)
	v_mfma_f32_16x16x32_bf16 v[124:127], v[128:131], v[180:183], v[124:127]
	v_mfma_f32_16x16x32_bf16 v[124:127], v[132:135], v[192:195], v[124:127]
	v_mfma_f32_16x16x32_bf16 v[120:123], v[140:143], v[192:195], v[120:123]
	v_mfma_f32_16x16x32_bf16 v[120:123], v[136:139], v[180:183], v[120:123]
	v_mfma_f32_16x16x32_bf16 v[104:107], v[136:139], v[196:199], v[104:107]
	v_mfma_f32_16x16x32_bf16 v[104:107], v[140:143], v[200:203], v[104:107]
	v_mfma_f32_16x16x32_bf16 v[108:111], v[132:135], v[200:203], v[108:111]
	v_mfma_f32_16x16x32_bf16 v[108:111], v[128:131], v[196:199], v[108:111]
	v_mfma_f32_16x16x32_bf16 v[92:95], v[128:131], v[204:207], v[92:95]
	v_mfma_f32_16x16x32_bf16 v[92:95], v[132:135], v[208:211], v[92:95]
	v_mfma_f32_16x16x32_bf16 v[88:91], v[140:143], v[208:211], v[88:91]
	v_mfma_f32_16x16x32_bf16 v[88:91], v[136:139], v[204:207], v[88:91]
	v_mfma_f32_16x16x32_bf16 v[72:75], v[136:139], v[212:215], v[72:75]
	v_mfma_f32_16x16x32_bf16 v[72:75], v[140:143], v[216:219], v[72:75]
	v_mfma_f32_16x16x32_bf16 v[76:79], v[132:135], v[216:219], v[76:79]
	v_mfma_f32_16x16x32_bf16 v[76:79], v[128:131], v[212:215], v[76:79]
	s_setprio 0
	s_setprio 1
	v_mfma_f32_16x16x32_bf16 v[116:119], v[144:147], v[180:183], v[116:119]
	v_mfma_f32_16x16x32_bf16 v[116:119], v[148:151], v[192:195], v[116:119]
	v_mfma_f32_16x16x32_bf16 v[112:115], v[176:179], v[192:195], v[112:115]
	v_mfma_f32_16x16x32_bf16 v[112:115], v[172:175], v[180:183], v[112:115]
	v_mfma_f32_16x16x32_bf16 v[96:99], v[172:175], v[196:199], v[96:99]
	v_mfma_f32_16x16x32_bf16 v[96:99], v[176:179], v[200:203], v[96:99]
	v_mfma_f32_16x16x32_bf16 v[100:103], v[148:151], v[200:203], v[100:103]
	v_mfma_f32_16x16x32_bf16 v[100:103], v[144:147], v[196:199], v[100:103]
	v_mfma_f32_16x16x32_bf16 v[84:87], v[144:147], v[204:207], v[84:87]
	v_mfma_f32_16x16x32_bf16 v[84:87], v[148:151], v[208:211], v[84:87]
	v_mfma_f32_16x16x32_bf16 v[80:83], v[176:179], v[208:211], v[80:83]
	v_mfma_f32_16x16x32_bf16 v[80:83], v[172:175], v[204:207], v[80:83]
	v_mfma_f32_16x16x32_bf16 v[64:67], v[172:175], v[212:215], v[64:67]
	v_mfma_f32_16x16x32_bf16 v[64:67], v[176:179], v[216:219], v[64:67]
	v_mfma_f32_16x16x32_bf16 v[68:71], v[148:151], v[216:219], v[68:71]
	v_mfma_f32_16x16x32_bf16 v[68:71], v[144:147], v[212:215], v[68:71]
	s_setprio 0
	s_barrier
	s_add_i32 s62, s81, s66
	v_lshl_add_u64 v[220:221], v[220:221], 0, s[26:27]
	s_mov_b32 m0, s62
	ds_read_b128 v[180:183], v190 offset:49152
	ds_read_b128 v[192:195], v190 offset:50176
	ds_read_b128 v[196:199], v190 offset:51200
	ds_read_b128 v[200:203], v190 offset:52224
	ds_read_b128 v[204:207], v190 offset:53248
	ds_read_b128 v[208:211], v190 offset:54272
	ds_read_b128 v[212:215], v190 offset:55296
	ds_read_b128 v[216:219], v190 offset:56320
	global_load_lds_dwordx4 v[220:221], off
	s_add_i32 m0, s62, 0x2000
	s_add_u32 s60, s60, 0x40080
	v_lshl_add_u64 v[220:221], v[222:223], 0, s[26:27]
	s_addc_u32 s61, s61, 0
	s_add_i32 s62, s82, s66
	global_load_lds_dwordx4 v[220:221], off
	v_lshl_add_u64 v[220:221], s[60:61], 0, v[154:155]
	s_mov_b32 m0, s62
	s_nop 0
	global_load_lds_dwordx4 v[220:221], off
	v_lshl_add_u64 v[220:221], s[60:61], 0, v[162:163]
	s_add_i32 m0, s62, 0x2000
	s_nop 0
	global_load_lds_dwordx4 v[220:221], off
	v_lshl_add_u64 v[220:221], v[224:225], 0, s[26:27]
	s_mov_b32 m0, s3
	s_nop 0
	global_load_lds_dwordx4 v[220:221], off
	v_lshl_add_u64 v[220:221], v[226:227], 0, s[26:27]
	s_mov_b32 m0, s72
	s_nop 0
	global_load_lds_dwordx4 v[220:221], off
	s_waitcnt vmcnt(8)
	s_waitcnt lgkmcnt(0)
	s_barrier
	s_setprio 1
	s_waitcnt lgkmcnt(0)
	v_mfma_f32_16x16x32_bf16 v[60:63], v[128:131], v[180:183], v[60:63]
	v_mfma_f32_16x16x32_bf16 v[60:63], v[132:135], v[192:195], v[60:63]
	v_mfma_f32_16x16x32_bf16 v[56:59], v[140:143], v[192:195], v[56:59]
	v_mfma_f32_16x16x32_bf16 v[56:59], v[136:139], v[180:183], v[56:59]
	v_mfma_f32_16x16x32_bf16 v[40:43], v[136:139], v[196:199], v[40:43]
	v_mfma_f32_16x16x32_bf16 v[40:43], v[140:143], v[200:203], v[40:43]
	v_mfma_f32_16x16x32_bf16 v[44:47], v[132:135], v[200:203], v[44:47]
	v_mfma_f32_16x16x32_bf16 v[44:47], v[128:131], v[196:199], v[44:47]
	v_mfma_f32_16x16x32_bf16 v[28:31], v[128:131], v[204:207], v[28:31]
	v_mfma_f32_16x16x32_bf16 v[28:31], v[132:135], v[208:211], v[28:31]
	v_mfma_f32_16x16x32_bf16 v[24:27], v[140:143], v[208:211], v[24:27]
	v_mfma_f32_16x16x32_bf16 v[24:27], v[136:139], v[204:207], v[24:27]
	v_mfma_f32_16x16x32_bf16 v[8:11], v[136:139], v[212:215], v[8:11]
	v_mfma_f32_16x16x32_bf16 v[8:11], v[140:143], v[216:219], v[8:11]
	v_mfma_f32_16x16x32_bf16 v[12:15], v[132:135], v[216:219], v[12:15]
	v_mfma_f32_16x16x32_bf16 v[12:15], v[128:131], v[212:215], v[12:15]
	s_setprio 0
	s_setprio 1
	v_mfma_f32_16x16x32_bf16 v[52:55], v[144:147], v[180:183], v[52:55]
	v_mfma_f32_16x16x32_bf16 v[52:55], v[148:151], v[192:195], v[52:55]
	v_mfma_f32_16x16x32_bf16 v[48:51], v[176:179], v[192:195], v[48:51]
	v_mfma_f32_16x16x32_bf16 v[48:51], v[172:175], v[180:183], v[48:51]
	v_mfma_f32_16x16x32_bf16 v[32:35], v[172:175], v[196:199], v[32:35]
	v_mfma_f32_16x16x32_bf16 v[32:35], v[176:179], v[200:203], v[32:35]
	v_mfma_f32_16x16x32_bf16 v[36:39], v[148:151], v[200:203], v[36:39]
	v_mfma_f32_16x16x32_bf16 v[36:39], v[144:147], v[196:199], v[36:39]
	v_mfma_f32_16x16x32_bf16 v[20:23], v[144:147], v[204:207], v[20:23]
	v_mfma_f32_16x16x32_bf16 v[20:23], v[148:151], v[208:211], v[20:23]
	v_mfma_f32_16x16x32_bf16 v[16:19], v[176:179], v[208:211], v[16:19]
	v_mfma_f32_16x16x32_bf16 v[16:19], v[172:175], v[204:207], v[16:19]
	v_mfma_f32_16x16x32_bf16 v[0:3], v[172:175], v[212:215], v[0:3]
	v_mfma_f32_16x16x32_bf16 v[0:3], v[176:179], v[216:219], v[0:3]
	v_mfma_f32_16x16x32_bf16 v[4:7], v[148:151], v[216:219], v[4:7]
	v_mfma_f32_16x16x32_bf16 v[4:7], v[144:147], v[212:215], v[4:7]
	s_setprio 0
	s_barrier
	s_add_i32 s80, s80, 2
	s_add_u32 s78, s78, 0x100
	s_addc_u32 s79, s79, 0
	s_add_u32 s58, s58, 0x100
	s_addc_u32 s59, s59, 0
	s_cmp_gt_u32 s80, 13
.LBB0_1011:
	ds_read_b128 v[128:131], v188
	ds_read_b128 v[132:135], v188 offset:1024
	ds_read_b128 v[136:139], v188 offset:2048
	ds_read_b128 v[140:143], v188 offset:3072
	ds_read_b128 v[144:147], v189
	ds_read_b128 v[148:151], v189 offset:1024
	ds_read_b128 v[172:175], v189 offset:2048
	ds_read_b128 v[176:179], v189 offset:3072
	s_add_u32 s60, s58, 0xfffc0080
	s_addc_u32 s61, s59, -1
	s_cmp_eq_u32 s80, 12
	s_cselect_b32 s63, s15, s61
	s_cselect_b32 s62, s51, s60
	s_cselect_b32 s61, s49, s79
	s_cselect_b32 s60, s57, s78
	v_lshl_add_u64 v[220:221], s[58:59], 0, v[166:167]
	s_add_i32 m0, s67, 0xc000
	ds_read_b128 v[180:183], v190
	ds_read_b128 v[192:195], v190 offset:1024
	ds_read_b128 v[196:199], v190 offset:2048
	ds_read_b128 v[200:203], v190 offset:3072
	ds_read_b128 v[204:207], v190 offset:4096
	ds_read_b128 v[208:211], v190 offset:5120
	ds_read_b128 v[212:215], v190 offset:6144
	ds_read_b128 v[216:219], v190 offset:7168
	global_load_lds_dwordx4 v[220:221], off
	v_lshl_add_u64 v[220:221], s[58:59], 0, v[164:165]
	s_add_i32 m0, s67, 0xe000
	s_nop 0
	global_load_lds_dwordx4 v[220:221], off
	s_waitcnt vmcnt(8)
	s_waitcnt lgkmcnt(0)
	s_barrier
	s_setprio 1
	s_waitcnt lgkmcnt(0)
	v_mfma_f32_16x16x32_bf16 v[124:127], v[128:131], v[180:183], v[124:127]
	v_mfma_f32_16x16x32_bf16 v[124:127], v[132:135], v[192:195], v[124:127]
	v_mfma_f32_16x16x32_bf16 v[120:123], v[140:143], v[192:195], v[120:123]
	v_mfma_f32_16x16x32_bf16 v[120:123], v[136:139], v[180:183], v[120:123]
	v_mfma_f32_16x16x32_bf16 v[104:107], v[136:139], v[196:199], v[104:107]
	v_mfma_f32_16x16x32_bf16 v[104:107], v[140:143], v[200:203], v[104:107]
	v_mfma_f32_16x16x32_bf16 v[108:111], v[132:135], v[200:203], v[108:111]
	v_mfma_f32_16x16x32_bf16 v[108:111], v[128:131], v[196:199], v[108:111]
	v_mfma_f32_16x16x32_bf16 v[92:95], v[128:131], v[204:207], v[92:95]
	v_mfma_f32_16x16x32_bf16 v[92:95], v[132:135], v[208:211], v[92:95]
	v_mfma_f32_16x16x32_bf16 v[88:91], v[140:143], v[208:211], v[88:91]
	v_mfma_f32_16x16x32_bf16 v[88:91], v[136:139], v[204:207], v[88:91]
	v_mfma_f32_16x16x32_bf16 v[72:75], v[136:139], v[212:215], v[72:75]
	v_mfma_f32_16x16x32_bf16 v[72:75], v[140:143], v[216:219], v[72:75]
	v_mfma_f32_16x16x32_bf16 v[76:79], v[132:135], v[216:219], v[76:79]
	v_mfma_f32_16x16x32_bf16 v[76:79], v[128:131], v[212:215], v[76:79]
	s_setprio 0
	s_setprio 1
	v_mfma_f32_16x16x32_bf16 v[116:119], v[144:147], v[180:183], v[116:119]
	v_mfma_f32_16x16x32_bf16 v[116:119], v[148:151], v[192:195], v[116:119]
	v_mfma_f32_16x16x32_bf16 v[112:115], v[176:179], v[192:195], v[112:115]
	v_mfma_f32_16x16x32_bf16 v[112:115], v[172:175], v[180:183], v[112:115]
	v_mfma_f32_16x16x32_bf16 v[96:99], v[172:175], v[196:199], v[96:99]
	v_mfma_f32_16x16x32_bf16 v[96:99], v[176:179], v[200:203], v[96:99]
	v_mfma_f32_16x16x32_bf16 v[100:103], v[148:151], v[200:203], v[100:103]
	v_mfma_f32_16x16x32_bf16 v[100:103], v[144:147], v[196:199], v[100:103]
	v_mfma_f32_16x16x32_bf16 v[84:87], v[144:147], v[204:207], v[84:87]
	v_mfma_f32_16x16x32_bf16 v[84:87], v[148:151], v[208:211], v[84:87]
	v_mfma_f32_16x16x32_bf16 v[80:83], v[176:179], v[208:211], v[80:83]
	v_mfma_f32_16x16x32_bf16 v[80:83], v[172:175], v[204:207], v[80:83]
	v_mfma_f32_16x16x32_bf16 v[64:67], v[172:175], v[212:215], v[64:67]
	v_mfma_f32_16x16x32_bf16 v[64:67], v[176:179], v[216:219], v[64:67]
	v_mfma_f32_16x16x32_bf16 v[68:71], v[148:151], v[216:219], v[68:71]
	v_mfma_f32_16x16x32_bf16 v[68:71], v[144:147], v[212:215], v[68:71]
	s_setprio 0
	s_barrier
	s_add_i32 s81, s76, s66
	v_lshl_add_u64 v[220:221], s[60:61], 0, v[154:155]
	s_mov_b32 m0, s81
	ds_read_b128 v[180:183], v190 offset:16384
	ds_read_b128 v[192:195], v190 offset:17408
	ds_read_b128 v[196:199], v190 offset:18432
	ds_read_b128 v[200:203], v190 offset:19456
	ds_read_b128 v[204:207], v190 offset:20480
	ds_read_b128 v[208:211], v190 offset:21504
	ds_read_b128 v[212:215], v190 offset:22528
	ds_read_b128 v[216:219], v190 offset:23552
	global_load_lds_dwordx4 v[220:221], off
	s_add_i32 m0, s81, 0x2000
	s_add_u32 s82, s60, 0x40000
	v_lshl_add_u64 v[222:223], s[60:61], 0, v[162:163]
	s_addc_u32 s83, s61, 0
	s_add_i32 s81, s77, s66
	global_load_lds_dwordx4 v[222:223], off
	v_lshl_add_u64 v[224:225], s[82:83], 0, v[154:155]
	s_mov_b32 m0, s81
	v_lshl_add_u64 v[226:227], s[62:63], 0, v[160:161]
	global_load_lds_dwordx4 v[224:225], off
	v_lshl_add_u64 v[224:225], s[82:83], 0, v[162:163]
	s_add_i32 m0, s81, 0x2000
	s_nop 0
	global_load_lds_dwordx4 v[224:225], off
	v_lshl_add_u64 v[224:225], s[62:63], 0, v[152:153]
	s_mov_b32 m0, s67
	s_nop 0
	global_load_lds_dwordx4 v[224:225], off
	s_mov_b32 m0, s68
	s_nop 0
	global_load_lds_dwordx4 v[226:227], off
	s_waitcnt vmcnt(8)
	s_waitcnt lgkmcnt(0)
	s_barrier
	s_setprio 1
	s_waitcnt lgkmcnt(0)
	v_mfma_f32_16x16x32_bf16 v[60:63], v[128:131], v[180:183], v[60:63]
	v_mfma_f32_16x16x32_bf16 v[60:63], v[132:135], v[192:195], v[60:63]
	v_mfma_f32_16x16x32_bf16 v[56:59], v[140:143], v[192:195], v[56:59]
	v_mfma_f32_16x16x32_bf16 v[56:59], v[136:139], v[180:183], v[56:59]
	v_mfma_f32_16x16x32_bf16 v[40:43], v[136:139], v[196:199], v[40:43]
	v_mfma_f32_16x16x32_bf16 v[40:43], v[140:143], v[200:203], v[40:43]
	v_mfma_f32_16x16x32_bf16 v[44:47], v[132:135], v[200:203], v[44:47]
	v_mfma_f32_16x16x32_bf16 v[44:47], v[128:131], v[196:199], v[44:47]
	v_mfma_f32_16x16x32_bf16 v[28:31], v[128:131], v[204:207], v[28:31]
	v_mfma_f32_16x16x32_bf16 v[28:31], v[132:135], v[208:211], v[28:31]
	v_mfma_f32_16x16x32_bf16 v[24:27], v[140:143], v[208:211], v[24:27]
	v_mfma_f32_16x16x32_bf16 v[24:27], v[136:139], v[204:207], v[24:27]
	v_mfma_f32_16x16x32_bf16 v[8:11], v[136:139], v[212:215], v[8:11]
	v_mfma_f32_16x16x32_bf16 v[8:11], v[140:143], v[216:219], v[8:11]
	v_mfma_f32_16x16x32_bf16 v[12:15], v[132:135], v[216:219], v[12:15]
	v_mfma_f32_16x16x32_bf16 v[12:15], v[128:131], v[212:215], v[12:15]
	s_setprio 0
	s_setprio 1
	v_mfma_f32_16x16x32_bf16 v[52:55], v[144:147], v[180:183], v[52:55]
	v_mfma_f32_16x16x32_bf16 v[52:55], v[148:151], v[192:195], v[52:55]
	v_mfma_f32_16x16x32_bf16 v[48:51], v[176:179], v[192:195], v[48:51]
	v_mfma_f32_16x16x32_bf16 v[48:51], v[172:175], v[180:183], v[48:51]
	v_mfma_f32_16x16x32_bf16 v[32:35], v[172:175], v[196:199], v[32:35]
	v_mfma_f32_16x16x32_bf16 v[32:35], v[176:179], v[200:203], v[32:35]
	v_mfma_f32_16x16x32_bf16 v[36:39], v[148:151], v[200:203], v[36:39]
	v_mfma_f32_16x16x32_bf16 v[36:39], v[144:147], v[196:199], v[36:39]
	v_mfma_f32_16x16x32_bf16 v[20:23], v[144:147], v[204:207], v[20:23]
	v_mfma_f32_16x16x32_bf16 v[20:23], v[148:151], v[208:211], v[20:23]
	v_mfma_f32_16x16x32_bf16 v[16:19], v[176:179], v[208:211], v[16:19]
	v_mfma_f32_16x16x32_bf16 v[16:19], v[172:175], v[204:207], v[16:19]
	v_mfma_f32_16x16x32_bf16 v[0:3], v[172:175], v[212:215], v[0:3]
	v_mfma_f32_16x16x32_bf16 v[0:3], v[176:179], v[216:219], v[0:3]
	v_mfma_f32_16x16x32_bf16 v[4:7], v[148:151], v[216:219], v[4:7]
	v_mfma_f32_16x16x32_bf16 v[4:7], v[144:147], v[212:215], v[4:7]
	s_setprio 0
	s_barrier
	s_add_i32 s81, 0, 0x18000
	s_add_i32 s82, 0, 0x1c000
	v_add_u32_e32 v140, s81, v185
	v_add_u32_e32 v176, s82, v185
	ds_read_b128 v[128:131], v140
	ds_read_b128 v[132:135], v140 offset:1024
	ds_read_b128 v[136:139], v140 offset:2048
	ds_read_b128 v[140:143], v140 offset:3072
	ds_read_b128 v[144:147], v176
	ds_read_b128 v[148:151], v176 offset:1024
	ds_read_b128 v[172:175], v176 offset:2048
	ds_read_b128 v[176:179], v176 offset:3072
	s_add_u32 s62, s62, 0x40000
	s_addc_u32 s63, s63, 0
	s_mov_b32 m0, s69
	v_lshl_add_u64 v[228:229], s[62:63], 0, v[152:153]
	ds_read_b128 v[180:183], v190 offset:32768
	ds_read_b128 v[192:195], v190 offset:33792
	ds_read_b128 v[196:199], v190 offset:34816
	ds_read_b128 v[200:203], v190 offset:35840
	ds_read_b128 v[204:207], v190 offset:36864
	ds_read_b128 v[208:211], v190 offset:37888
	ds_read_b128 v[212:215], v190 offset:38912
	ds_read_b128 v[216:219], v190 offset:39936
	global_load_lds_dwordx4 v[228:229], off
	v_lshl_add_u64 v[228:229], s[62:63], 0, v[160:161]
	s_mov_b32 m0, s70
	s_nop 0
	global_load_lds_dwordx4 v[228:229], off
	s_waitcnt vmcnt(8)
	s_waitcnt lgkmcnt(0)
	s_barrier
	s_setprio 1
	s_waitcnt lgkmcnt(0)
	v_mfma_f32_16x16x32_bf16 v[124:127], v[128:131], v[180:183], v[124:127]
	v_mfma_f32_16x16x32_bf16 v[124:127], v[132:135], v[192:195], v[124:127]
	v_mfma_f32_16x16x32_bf16 v[120:123], v[140:143], v[192:195], v[120:123]
	v_mfma_f32_16x16x32_bf16 v[120:123], v[136:139], v[180:183], v[120:123]
	v_mfma_f32_16x16x32_bf16 v[104:107], v[136:139], v[196:199], v[104:107]
	v_mfma_f32_16x16x32_bf16 v[104:107], v[140:143], v[200:203], v[104:107]
	v_mfma_f32_16x16x32_bf16 v[108:111], v[132:135], v[200:203], v[108:111]
	v_mfma_f32_16x16x32_bf16 v[108:111], v[128:131], v[196:199], v[108:111]
	v_mfma_f32_16x16x32_bf16 v[92:95], v[128:131], v[204:207], v[92:95]
	v_mfma_f32_16x16x32_bf16 v[92:95], v[132:135], v[208:211], v[92:95]
	v_mfma_f32_16x16x32_bf16 v[88:91], v[140:143], v[208:211], v[88:91]
	v_mfma_f32_16x16x32_bf16 v[88:91], v[136:139], v[204:207], v[88:91]
	v_mfma_f32_16x16x32_bf16 v[72:75], v[136:139], v[212:215], v[72:75]
	v_mfma_f32_16x16x32_bf16 v[72:75], v[140:143], v[216:219], v[72:75]
	v_mfma_f32_16x16x32_bf16 v[76:79], v[132:135], v[216:219], v[76:79]
	v_mfma_f32_16x16x32_bf16 v[76:79], v[128:131], v[212:215], v[76:79]
	s_setprio 0
	s_setprio 1
	v_mfma_f32_16x16x32_bf16 v[116:119], v[144:147], v[180:183], v[116:119]
	v_mfma_f32_16x16x32_bf16 v[116:119], v[148:151], v[192:195], v[116:119]
	v_mfma_f32_16x16x32_bf16 v[112:115], v[176:179], v[192:195], v[112:115]
	v_mfma_f32_16x16x32_bf16 v[112:115], v[172:175], v[180:183], v[112:115]
	v_mfma_f32_16x16x32_bf16 v[96:99], v[172:175], v[196:199], v[96:99]
	v_mfma_f32_16x16x32_bf16 v[96:99], v[176:179], v[200:203], v[96:99]
	v_mfma_f32_16x16x32_bf16 v[100:103], v[148:151], v[200:203], v[100:103]
	v_mfma_f32_16x16x32_bf16 v[100:103], v[144:147], v[196:199], v[100:103]
	v_mfma_f32_16x16x32_bf16 v[84:87], v[144:147], v[204:207], v[84:87]
	v_mfma_f32_16x16x32_bf16 v[84:87], v[148:151], v[208:211], v[84:87]
	v_mfma_f32_16x16x32_bf16 v[80:83], v[176:179], v[208:211], v[80:83]
	v_mfma_f32_16x16x32_bf16 v[80:83], v[172:175], v[204:207], v[80:83]
	v_mfma_f32_16x16x32_bf16 v[64:67], v[172:175], v[212:215], v[64:67]
	v_mfma_f32_16x16x32_bf16 v[64:67], v[176:179], v[216:219], v[64:67]
	v_mfma_f32_16x16x32_bf16 v[68:71], v[148:151], v[216:219], v[68:71]
	v_mfma_f32_16x16x32_bf16 v[68:71], v[144:147], v[212:215], v[68:71]
	s_setprio 0
	s_barrier
	s_add_i32 s62, s81, s66
	v_lshl_add_u64 v[220:221], v[220:221], 0, s[26:27]
	s_mov_b32 m0, s62
	ds_read_b128 v[180:183], v190 offset:49152
	ds_read_b128 v[192:195], v190 offset:50176
	ds_read_b128 v[196:199], v190 offset:51200
	ds_read_b128 v[200:203], v190 offset:52224
	ds_read_b128 v[204:207], v190 offset:53248
	ds_read_b128 v[208:211], v190 offset:54272
	ds_read_b128 v[212:215], v190 offset:55296
	ds_read_b128 v[216:219], v190 offset:56320
	global_load_lds_dwordx4 v[220:221], off
	s_add_i32 m0, s62, 0x2000
	s_add_u32 s60, s60, 0x40080
	v_lshl_add_u64 v[220:221], v[222:223], 0, s[26:27]
	s_addc_u32 s61, s61, 0
	s_add_i32 s62, s82, s66
	global_load_lds_dwordx4 v[220:221], off
	v_lshl_add_u64 v[220:221], s[60:61], 0, v[154:155]
	s_mov_b32 m0, s62
	s_nop 0
	global_load_lds_dwordx4 v[220:221], off
	v_lshl_add_u64 v[220:221], s[60:61], 0, v[162:163]
	s_add_i32 m0, s62, 0x2000
	s_nop 0
	global_load_lds_dwordx4 v[220:221], off
	v_lshl_add_u64 v[220:221], v[224:225], 0, s[26:27]
	s_mov_b32 m0, s3
	s_nop 0
	global_load_lds_dwordx4 v[220:221], off
	v_lshl_add_u64 v[220:221], v[226:227], 0, s[26:27]
	s_mov_b32 m0, s72
	s_nop 0
	global_load_lds_dwordx4 v[220:221], off
	s_waitcnt vmcnt(8)
	s_waitcnt lgkmcnt(0)
	s_barrier
	s_setprio 1
	s_waitcnt lgkmcnt(0)
	v_mfma_f32_16x16x32_bf16 v[60:63], v[128:131], v[180:183], v[60:63]
	v_mfma_f32_16x16x32_bf16 v[60:63], v[132:135], v[192:195], v[60:63]
	v_mfma_f32_16x16x32_bf16 v[56:59], v[140:143], v[192:195], v[56:59]
	v_mfma_f32_16x16x32_bf16 v[56:59], v[136:139], v[180:183], v[56:59]
	v_mfma_f32_16x16x32_bf16 v[40:43], v[136:139], v[196:199], v[40:43]
	v_mfma_f32_16x16x32_bf16 v[40:43], v[140:143], v[200:203], v[40:43]
	v_mfma_f32_16x16x32_bf16 v[44:47], v[132:135], v[200:203], v[44:47]
	v_mfma_f32_16x16x32_bf16 v[44:47], v[128:131], v[196:199], v[44:47]
	v_mfma_f32_16x16x32_bf16 v[28:31], v[128:131], v[204:207], v[28:31]
	v_mfma_f32_16x16x32_bf16 v[28:31], v[132:135], v[208:211], v[28:31]
	v_mfma_f32_16x16x32_bf16 v[24:27], v[140:143], v[208:211], v[24:27]
	v_mfma_f32_16x16x32_bf16 v[24:27], v[136:139], v[204:207], v[24:27]
	v_mfma_f32_16x16x32_bf16 v[8:11], v[136:139], v[212:215], v[8:11]
	v_mfma_f32_16x16x32_bf16 v[8:11], v[140:143], v[216:219], v[8:11]
	v_mfma_f32_16x16x32_bf16 v[12:15], v[132:135], v[216:219], v[12:15]
	v_mfma_f32_16x16x32_bf16 v[12:15], v[128:131], v[212:215], v[12:15]
	s_setprio 0
	s_setprio 1
	v_mfma_f32_16x16x32_bf16 v[52:55], v[144:147], v[180:183], v[52:55]
	v_mfma_f32_16x16x32_bf16 v[52:55], v[148:151], v[192:195], v[52:55]
	v_mfma_f32_16x16x32_bf16 v[48:51], v[176:179], v[192:195], v[48:51]
	v_mfma_f32_16x16x32_bf16 v[48:51], v[172:175], v[180:183], v[48:51]
	v_mfma_f32_16x16x32_bf16 v[32:35], v[172:175], v[196:199], v[32:35]
	v_mfma_f32_16x16x32_bf16 v[32:35], v[176:179], v[200:203], v[32:35]
	v_mfma_f32_16x16x32_bf16 v[36:39], v[148:151], v[200:203], v[36:39]
	v_mfma_f32_16x16x32_bf16 v[36:39], v[144:147], v[196:199], v[36:39]
	v_mfma_f32_16x16x32_bf16 v[20:23], v[144:147], v[204:207], v[20:23]
	v_mfma_f32_16x16x32_bf16 v[20:23], v[148:151], v[208:211], v[20:23]
	v_mfma_f32_16x16x32_bf16 v[16:19], v[176:179], v[208:211], v[16:19]
	v_mfma_f32_16x16x32_bf16 v[16:19], v[172:175], v[204:207], v[16:19]
	v_mfma_f32_16x16x32_bf16 v[0:3], v[172:175], v[212:215], v[0:3]
	v_mfma_f32_16x16x32_bf16 v[0:3], v[176:179], v[216:219], v[0:3]
	v_mfma_f32_16x16x32_bf16 v[4:7], v[148:151], v[216:219], v[4:7]
	v_mfma_f32_16x16x32_bf16 v[4:7], v[144:147], v[212:215], v[4:7]
	s_setprio 0
	s_barrier
	s_add_i32 s80, s80, 2
	s_add_u32 s78, s78, 0x100
	s_addc_u32 s79, s79, 0
	s_add_u32 s58, s58, 0x100
	s_addc_u32 s59, s59, 0
	s_cmp_gt_u32 s80, 13
	s_cbranch_scc0 .LBB0_1011
	s_and_b64 vcc, exec, s[28:29]
	s_cbranch_vccz .LBB0_1014
	s_barrier

.LBB0_1096:
	s_ashr_i32 s25, s24, 31
	s_lshl_b64 s[26:27], s[24:25], 19
	s_add_u32 s26, s3, s26
	s_addc_u32 s27, s33, s27
	s_and_b64 s[28:29], s[6:7], exec
	s_cselect_b32 s25, s27, s47
	s_cselect_b32 s65, s26, s46
	s_ashr_i32 s23, s22, 31
	s_lshl_b64 s[28:29], s[22:23], 19
	s_add_u32 s28, s35, s28
	s_addc_u32 s29, s48, s29
	s_and_b64 s[66:67], s[6:7], exec
	s_cselect_b32 s66, s29, s45
	s_cselect_b32 s67, s28, s44
	s_lshl_b32 s23, s30, 8
	v_add_u32_e32 v0, s23, v148
	s_add_u32 s68, s44, 0x100
	v_ashrrev_i32_e32 v1, 31, v0
	s_addc_u32 s69, s45, 0
	v_lshl_add_u64 v[144:145], v[0:1], 4, s[12:13]
	s_add_u32 s30, s46, 0x40080
	s_addc_u32 s31, s47, 0
	s_mov_b32 s70, -2
	s_mov_b64 s[44:45], 0
	s_cmp_eq_u32 s56, 1
	s_cbranch_scc1 .Lfa_10
	v_add_u32_e32 v153, s61, v147
	ds_read_b128 v[160:163], v153
	ds_read_b128 v[164:167], v153 offset:1024
	ds_read_b128 v[168:171], v153 offset:2048
	ds_read_b128 v[172:175], v153 offset:3072
	v_add_u32_e32 v153, s62, v147
	ds_read_b128 v[176:179], v153
	ds_read_b128 v[180:183], v153 offset:1024
	ds_read_b128 v[184:187], v153 offset:2048
	ds_read_b128 v[188:191], v153 offset:3072
	s_add_u32 s46, s30, 0xfffc0080
	s_addc_u32 s47, s31, -1
	s_and_b64 s[44:45], s[44:45], exec
	s_cselect_b32 s47, s25, s47
	s_cselect_b32 s46, s65, s46
	s_cselect_b32 s45, s66, s69
	s_cselect_b32 s44, s67, s68
	v_lshl_add_u64 v[154:155], s[30:31], 0, v[138:139]
	s_add_i32 m0, s52, 0xc000
	ds_read_b128 v[192:195], v150
	ds_read_b128 v[196:199], v150 offset:1024
	ds_read_b128 v[200:203], v150 offset:2048
	ds_read_b128 v[204:207], v150 offset:3072
	ds_read_b128 v[208:211], v150 offset:4096
	ds_read_b128 v[212:215], v150 offset:5120
	ds_read_b128 v[216:219], v150 offset:6144
	ds_read_b128 v[220:223], v150 offset:7168
	global_load_lds_dwordx4 v[154:155], off
	v_lshl_add_u64 v[154:155], s[30:31], 0, v[136:137]
	s_add_i32 m0, s52, 0xe000
	s_nop 0
	global_load_lds_dwordx4 v[154:155], off
	s_waitcnt vmcnt(16)
	s_waitcnt lgkmcnt(0)
	s_barrier
	s_setprio 1
	s_waitcnt lgkmcnt(0)
	v_mfma_f32_16x16x32_bf16 v[124:127], v[160:163], v[192:195], 0
	v_mfma_f32_16x16x32_bf16 v[116:119], v[168:171], v[192:195], 0
	v_mfma_f32_16x16x32_bf16 v[108:111], v[160:163], v[200:203], 0
	v_mfma_f32_16x16x32_bf16 v[100:103], v[168:171], v[200:203], 0
	v_mfma_f32_16x16x32_bf16 v[92:95], v[160:163], v[208:211], 0
	v_mfma_f32_16x16x32_bf16 v[84:87], v[168:171], v[208:211], 0
	v_mfma_f32_16x16x32_bf16 v[76:79], v[160:163], v[216:219], 0
	v_mfma_f32_16x16x32_bf16 v[68:71], v[168:171], v[216:219], 0
	v_mfma_f32_16x16x32_bf16 v[124:127], v[164:167], v[196:199], v[124:127]
	v_mfma_f32_16x16x32_bf16 v[116:119], v[172:175], v[196:199], v[116:119]
	v_mfma_f32_16x16x32_bf16 v[108:111], v[164:167], v[204:207], v[108:111]
	v_mfma_f32_16x16x32_bf16 v[100:103], v[172:175], v[204:207], v[100:103]
	v_mfma_f32_16x16x32_bf16 v[92:95], v[164:167], v[212:215], v[92:95]
	v_mfma_f32_16x16x32_bf16 v[84:87], v[172:175], v[212:215], v[84:87]
	v_mfma_f32_16x16x32_bf16 v[76:79], v[164:167], v[220:223], v[76:79]
	v_mfma_f32_16x16x32_bf16 v[68:71], v[172:175], v[220:223], v[68:71]
	s_setprio 0
	s_setprio 1
	v_mfma_f32_16x16x32_bf16 v[120:123], v[176:179], v[192:195], 0
	v_mfma_f32_16x16x32_bf16 v[112:115], v[184:187], v[192:195], 0
	v_mfma_f32_16x16x32_bf16 v[104:107], v[176:179], v[200:203], 0
	v_mfma_f32_16x16x32_bf16 v[96:99], v[184:187], v[200:203], 0
	v_mfma_f32_16x16x32_bf16 v[88:91], v[176:179], v[208:211], 0
	v_mfma_f32_16x16x32_bf16 v[80:83], v[184:187], v[208:211], 0
	v_mfma_f32_16x16x32_bf16 v[72:75], v[176:179], v[216:219], 0
	v_mfma_f32_16x16x32_bf16 v[64:67], v[184:187], v[216:219], 0
	v_mfma_f32_16x16x32_bf16 v[120:123], v[180:183], v[196:199], v[120:123]
	v_mfma_f32_16x16x32_bf16 v[112:115], v[188:191], v[196:199], v[112:115]
	v_mfma_f32_16x16x32_bf16 v[104:107], v[180:183], v[204:207], v[104:107]
	v_mfma_f32_16x16x32_bf16 v[96:99], v[188:191], v[204:207], v[96:99]
	v_mfma_f32_16x16x32_bf16 v[88:91], v[180:183], v[212:215], v[88:91]
	v_mfma_f32_16x16x32_bf16 v[80:83], v[188:191], v[212:215], v[80:83]
	v_mfma_f32_16x16x32_bf16 v[72:75], v[180:183], v[220:223], v[72:75]
	v_mfma_f32_16x16x32_bf16 v[64:67], v[188:191], v[220:223], v[64:67]
	s_setprio 0
	s_barrier
	s_add_i32 s71, s61, s49
	v_lshl_add_u64 v[154:155], s[44:45], 0, v[132:133]
	s_mov_b32 m0, s71
	ds_read_b128 v[192:195], v150 offset:16384
	ds_read_b128 v[196:199], v150 offset:17408
	ds_read_b128 v[200:203], v150 offset:18432
	ds_read_b128 v[204:207], v150 offset:19456
	ds_read_b128 v[208:211], v150 offset:20480
	ds_read_b128 v[212:215], v150 offset:21504
	ds_read_b128 v[216:219], v150 offset:22528
	ds_read_b128 v[220:223], v150 offset:23552
	global_load_lds_dwordx4 v[154:155], off
	s_add_i32 m0, s71, 0x2000
	s_add_u32 s72, s44, 0x40000
	v_lshl_add_u64 v[224:225], s[44:45], 0, v[128:129]
	s_addc_u32 s73, s45, 0
	s_add_i32 s71, s62, s49
	global_load_lds_dwordx4 v[224:225], off
	v_lshl_add_u64 v[226:227], s[72:73], 0, v[132:133]
	s_mov_b32 m0, s71
	v_lshl_add_u64 v[228:229], s[46:47], 0, v[130:131]
	global_load_lds_dwordx4 v[226:227], off
	v_lshl_add_u64 v[226:227], s[72:73], 0, v[128:129]
	s_add_i32 m0, s71, 0x2000
	s_nop 0
	global_load_lds_dwordx4 v[226:227], off
	v_lshl_add_u64 v[226:227], s[46:47], 0, v[134:135]
	s_mov_b32 m0, s52
	s_nop 0
	global_load_lds_dwordx4 v[226:227], off
	s_mov_b32 m0, s53
	s_nop 0
	global_load_lds_dwordx4 v[228:229], off
	s_waitcnt vmcnt(16)
	s_waitcnt lgkmcnt(0)
	s_barrier
	s_setprio 1
	s_waitcnt lgkmcnt(0)
	v_mfma_f32_16x16x32_bf16 v[60:63], v[160:163], v[192:195], 0
	v_mfma_f32_16x16x32_bf16 v[52:55], v[168:171], v[192:195], 0
	v_mfma_f32_16x16x32_bf16 v[44:47], v[160:163], v[200:203], 0
	v_mfma_f32_16x16x32_bf16 v[36:39], v[168:171], v[200:203], 0
	v_mfma_f32_16x16x32_bf16 v[28:31], v[160:163], v[208:211], 0
	v_mfma_f32_16x16x32_bf16 v[20:23], v[168:171], v[208:211], 0
	v_mfma_f32_16x16x32_bf16 v[12:15], v[160:163], v[216:219], 0
	v_mfma_f32_16x16x32_bf16 v[4:7], v[168:171], v[216:219], 0
	v_mfma_f32_16x16x32_bf16 v[60:63], v[164:167], v[196:199], v[60:63]
	v_mfma_f32_16x16x32_bf16 v[52:55], v[172:175], v[196:199], v[52:55]
	v_mfma_f32_16x16x32_bf16 v[44:47], v[164:167], v[204:207], v[44:47]
	v_mfma_f32_16x16x32_bf16 v[36:39], v[172:175], v[204:207], v[36:39]
	v_mfma_f32_16x16x32_bf16 v[28:31], v[164:167], v[212:215], v[28:31]
	v_mfma_f32_16x16x32_bf16 v[20:23], v[172:175], v[212:215], v[20:23]
	v_mfma_f32_16x16x32_bf16 v[12:15], v[164:167], v[220:223], v[12:15]
	v_mfma_f32_16x16x32_bf16 v[4:7], v[172:175], v[220:223], v[4:7]
	s_setprio 0
	s_setprio 1
	v_mfma_f32_16x16x32_bf16 v[56:59], v[176:179], v[192:195], 0
	v_mfma_f32_16x16x32_bf16 v[48:51], v[184:187], v[192:195], 0
	v_mfma_f32_16x16x32_bf16 v[40:43], v[176:179], v[200:203], 0
	v_mfma_f32_16x16x32_bf16 v[32:35], v[184:187], v[200:203], 0
	v_mfma_f32_16x16x32_bf16 v[24:27], v[176:179], v[208:211], 0
	v_mfma_f32_16x16x32_bf16 v[16:19], v[184:187], v[208:211], 0
	v_mfma_f32_16x16x32_bf16 v[8:11], v[176:179], v[216:219], 0
	v_mfma_f32_16x16x32_bf16 v[0:3], v[184:187], v[216:219], 0
	v_mfma_f32_16x16x32_bf16 v[56:59], v[180:183], v[196:199], v[56:59]
	v_mfma_f32_16x16x32_bf16 v[48:51], v[188:191], v[196:199], v[48:51]
	v_mfma_f32_16x16x32_bf16 v[40:43], v[180:183], v[204:207], v[40:43]
	v_mfma_f32_16x16x32_bf16 v[32:35], v[188:191], v[204:207], v[32:35]
	v_mfma_f32_16x16x32_bf16 v[24:27], v[180:183], v[212:215], v[24:27]
	v_mfma_f32_16x16x32_bf16 v[16:19], v[188:191], v[212:215], v[16:19]
	v_mfma_f32_16x16x32_bf16 v[8:11], v[180:183], v[220:223], v[8:11]
	v_mfma_f32_16x16x32_bf16 v[0:3], v[188:191], v[220:223], v[0:3]
	s_setprio 0
	s_barrier
	s_add_i32 s71, 0, 0x18000
	v_add_u32_e32 v153, s71, v147
	s_add_i32 s72, 0, 0x1c000
	ds_read_b128 v[160:163], v153
	ds_read_b128 v[164:167], v153 offset:1024
	ds_read_b128 v[168:171], v153 offset:2048
	ds_read_b128 v[172:175], v153 offset:3072
	v_add_u32_e32 v153, s72, v147
	ds_read_b128 v[176:179], v153
	ds_read_b128 v[180:183], v153 offset:1024
	ds_read_b128 v[184:187], v153 offset:2048
	ds_read_b128 v[188:191], v153 offset:3072
	s_add_u32 s46, s46, 0x40000
	s_addc_u32 s47, s47, 0
	s_mov_b32 m0, s54
	v_lshl_add_u64 v[230:231], s[46:47], 0, v[134:135]
	ds_read_b128 v[192:195], v150 offset:32768
	ds_read_b128 v[196:199], v150 offset:33792
	ds_read_b128 v[200:203], v150 offset:34816
	ds_read_b128 v[204:207], v150 offset:35840
	ds_read_b128 v[208:211], v150 offset:36864
	ds_read_b128 v[212:215], v150 offset:37888
	ds_read_b128 v[216:219], v150 offset:38912
	ds_read_b128 v[220:223], v150 offset:39936
	global_load_lds_dwordx4 v[230:231], off
	v_lshl_add_u64 v[230:231], s[46:47], 0, v[130:131]
	s_mov_b32 m0, s55
	s_nop 0
	global_load_lds_dwordx4 v[230:231], off
	s_waitcnt vmcnt(8)
	s_waitcnt lgkmcnt(0)
	s_barrier
	s_setprio 1
	s_waitcnt lgkmcnt(0)
	v_mfma_f32_16x16x32_bf16 v[124:127], v[160:163], v[192:195], v[124:127]
	v_mfma_f32_16x16x32_bf16 v[124:127], v[164:167], v[196:199], v[124:127]
	v_mfma_f32_16x16x32_bf16 v[116:119], v[172:175], v[196:199], v[116:119]
	v_mfma_f32_16x16x32_bf16 v[116:119], v[168:171], v[192:195], v[116:119]
	v_mfma_f32_16x16x32_bf16 v[100:103], v[168:171], v[200:203], v[100:103]
	v_mfma_f32_16x16x32_bf16 v[100:103], v[172:175], v[204:207], v[100:103]
	v_mfma_f32_16x16x32_bf16 v[108:111], v[164:167], v[204:207], v[108:111]
	v_mfma_f32_16x16x32_bf16 v[108:111], v[160:163], v[200:203], v[108:111]
	v_mfma_f32_16x16x32_bf16 v[92:95], v[160:163], v[208:211], v[92:95]
	v_mfma_f32_16x16x32_bf16 v[92:95], v[164:167], v[212:215], v[92:95]
	v_mfma_f32_16x16x32_bf16 v[84:87], v[172:175], v[212:215], v[84:87]
	v_mfma_f32_16x16x32_bf16 v[84:87], v[168:171], v[208:211], v[84:87]
	v_mfma_f32_16x16x32_bf16 v[68:71], v[168:171], v[216:219], v[68:71]
	v_mfma_f32_16x16x32_bf16 v[68:71], v[172:175], v[220:223], v[68:71]
	v_mfma_f32_16x16x32_bf16 v[76:79], v[164:167], v[220:223], v[76:79]
	v_mfma_f32_16x16x32_bf16 v[76:79], v[160:163], v[216:219], v[76:79]
	s_setprio 0
	s_setprio 1
	v_mfma_f32_16x16x32_bf16 v[120:123], v[176:179], v[192:195], v[120:123]
	v_mfma_f32_16x16x32_bf16 v[120:123], v[180:183], v[196:199], v[120:123]
	v_mfma_f32_16x16x32_bf16 v[112:115], v[188:191], v[196:199], v[112:115]
	v_mfma_f32_16x16x32_bf16 v[112:115], v[184:187], v[192:195], v[112:115]
	v_mfma_f32_16x16x32_bf16 v[96:99], v[184:187], v[200:203], v[96:99]
	v_mfma_f32_16x16x32_bf16 v[96:99], v[188:191], v[204:207], v[96:99]
	v_mfma_f32_16x16x32_bf16 v[104:107], v[180:183], v[204:207], v[104:107]
	v_mfma_f32_16x16x32_bf16 v[104:107], v[176:179], v[200:203], v[104:107]
	v_mfma_f32_16x16x32_bf16 v[88:91], v[176:179], v[208:211], v[88:91]
	v_mfma_f32_16x16x32_bf16 v[88:91], v[180:183], v[212:215], v[88:91]
	v_mfma_f32_16x16x32_bf16 v[80:83], v[188:191], v[212:215], v[80:83]
	v_mfma_f32_16x16x32_bf16 v[80:83], v[184:187], v[208:211], v[80:83]
	v_mfma_f32_16x16x32_bf16 v[64:67], v[184:187], v[216:219], v[64:67]
	v_mfma_f32_16x16x32_bf16 v[64:67], v[188:191], v[220:223], v[64:67]
	v_mfma_f32_16x16x32_bf16 v[72:75], v[180:183], v[220:223], v[72:75]
	v_mfma_f32_16x16x32_bf16 v[72:75], v[176:179], v[216:219], v[72:75]
	s_setprio 0
	s_barrier
	s_add_i32 s46, s71, s49
	v_lshl_add_u64 v[154:155], v[154:155], 0, s[14:15]
	s_mov_b32 m0, s46
	ds_read_b128 v[192:195], v150 offset:49152
	ds_read_b128 v[196:199], v150 offset:50176
	ds_read_b128 v[200:203], v150 offset:51200
	ds_read_b128 v[204:207], v150 offset:52224
	ds_read_b128 v[208:211], v150 offset:53248
	ds_read_b128 v[212:215], v150 offset:54272
	ds_read_b128 v[216:219], v150 offset:55296
	ds_read_b128 v[220:223], v150 offset:56320
	global_load_lds_dwordx4 v[154:155], off
	s_add_i32 m0, s46, 0x2000
	s_add_u32 s44, s44, 0x40080
	v_lshl_add_u64 v[154:155], v[224:225], 0, s[14:15]
	s_addc_u32 s45, s45, 0
	s_add_i32 s46, s72, s49
	global_load_lds_dwordx4 v[154:155], off
	v_lshl_add_u64 v[154:155], s[44:45], 0, v[132:133]
	s_mov_b32 m0, s46
	s_nop 0
	global_load_lds_dwordx4 v[154:155], off
	v_lshl_add_u64 v[154:155], s[44:45], 0, v[128:129]
	s_add_i32 m0, s46, 0x2000
	s_nop 0
	global_load_lds_dwordx4 v[154:155], off
	v_lshl_add_u64 v[154:155], v[226:227], 0, s[14:15]
	s_mov_b32 m0, s57
	s_nop 0
	global_load_lds_dwordx4 v[154:155], off
	v_lshl_add_u64 v[154:155], v[228:229], 0, s[14:15]
	s_mov_b32 m0, s58
	s_nop 0
	global_load_lds_dwordx4 v[154:155], off
	s_waitcnt vmcnt(8)
	s_waitcnt lgkmcnt(0)
	s_barrier
	s_setprio 1
	s_waitcnt lgkmcnt(0)
	v_mfma_f32_16x16x32_bf16 v[60:63], v[160:163], v[192:195], v[60:63]
	v_mfma_f32_16x16x32_bf16 v[60:63], v[164:167], v[196:199], v[60:63]
	v_mfma_f32_16x16x32_bf16 v[52:55], v[172:175], v[196:199], v[52:55]
	v_mfma_f32_16x16x32_bf16 v[52:55], v[168:171], v[192:195], v[52:55]
	v_mfma_f32_16x16x32_bf16 v[36:39], v[168:171], v[200:203], v[36:39]
	v_mfma_f32_16x16x32_bf16 v[36:39], v[172:175], v[204:207], v[36:39]
	v_mfma_f32_16x16x32_bf16 v[44:47], v[164:167], v[204:207], v[44:47]
	v_mfma_f32_16x16x32_bf16 v[44:47], v[160:163], v[200:203], v[44:47]
	v_mfma_f32_16x16x32_bf16 v[28:31], v[160:163], v[208:211], v[28:31]
	v_mfma_f32_16x16x32_bf16 v[28:31], v[164:167], v[212:215], v[28:31]
	v_mfma_f32_16x16x32_bf16 v[20:23], v[172:175], v[212:215], v[20:23]
	v_mfma_f32_16x16x32_bf16 v[20:23], v[168:171], v[208:211], v[20:23]
	v_mfma_f32_16x16x32_bf16 v[4:7], v[168:171], v[216:219], v[4:7]
	v_mfma_f32_16x16x32_bf16 v[4:7], v[172:175], v[220:223], v[4:7]
	v_mfma_f32_16x16x32_bf16 v[12:15], v[164:167], v[220:223], v[12:15]
	v_mfma_f32_16x16x32_bf16 v[12:15], v[160:163], v[216:219], v[12:15]
	s_setprio 0
	s_setprio 1
	v_mfma_f32_16x16x32_bf16 v[56:59], v[176:179], v[192:195], v[56:59]
	v_mfma_f32_16x16x32_bf16 v[56:59], v[180:183], v[196:199], v[56:59]
	v_mfma_f32_16x16x32_bf16 v[48:51], v[188:191], v[196:199], v[48:51]
	v_mfma_f32_16x16x32_bf16 v[48:51], v[184:187], v[192:195], v[48:51]
	v_mfma_f32_16x16x32_bf16 v[32:35], v[184:187], v[200:203], v[32:35]
	v_mfma_f32_16x16x32_bf16 v[32:35], v[188:191], v[204:207], v[32:35]
	v_mfma_f32_16x16x32_bf16 v[40:43], v[180:183], v[204:207], v[40:43]
	v_mfma_f32_16x16x32_bf16 v[40:43], v[176:179], v[200:203], v[40:43]
	v_mfma_f32_16x16x32_bf16 v[24:27], v[176:179], v[208:211], v[24:27]
	v_mfma_f32_16x16x32_bf16 v[24:27], v[180:183], v[212:215], v[24:27]
	v_mfma_f32_16x16x32_bf16 v[16:19], v[188:191], v[212:215], v[16:19]
	v_mfma_f32_16x16x32_bf16 v[16:19], v[184:187], v[208:211], v[16:19]
	v_mfma_f32_16x16x32_bf16 v[0:3], v[184:187], v[216:219], v[0:3]
	v_mfma_f32_16x16x32_bf16 v[0:3], v[188:191], v[220:223], v[0:3]
	v_mfma_f32_16x16x32_bf16 v[8:11], v[180:183], v[220:223], v[8:11]
	v_mfma_f32_16x16x32_bf16 v[8:11], v[176:179], v[216:219], v[8:11]
	s_setprio 0
	s_barrier
	s_add_i32 s70, s70, 2
	s_add_u32 s68, s68, 0x100
	s_addc_u32 s69, s69, 0
	s_add_u32 s30, s30, 0x100
	s_addc_u32 s31, s31, 0
	s_branch .LBB0_1098
.Lfa_10:
	v_add_u32_e32 v153, s61, v147
	ds_read_b128 v[160:163], v153
	ds_read_b128 v[164:167], v153 offset:1024
	ds_read_b128 v[168:171], v153 offset:2048
	ds_read_b128 v[172:175], v153 offset:3072
	v_add_u32_e32 v153, s62, v147
	ds_read_b128 v[176:179], v153
	ds_read_b128 v[180:183], v153 offset:1024
	ds_read_b128 v[184:187], v153 offset:2048
	ds_read_b128 v[188:191], v153 offset:3072
	s_add_u32 s46, s30, 0xfffc0080
	s_addc_u32 s47, s31, -1
	s_and_b64 s[44:45], s[44:45], exec
	s_cselect_b32 s47, s25, s47
	s_cselect_b32 s46, s65, s46
	s_cselect_b32 s45, s66, s69
	s_cselect_b32 s44, s67, s68
	v_lshl_add_u64 v[154:155], s[30:31], 0, v[138:139]
	s_add_i32 m0, s52, 0xc000
	ds_read_b128 v[192:195], v150
	ds_read_b128 v[196:199], v150 offset:1024
	ds_read_b128 v[200:203], v150 offset:2048
	ds_read_b128 v[204:207], v150 offset:3072
	ds_read_b128 v[208:211], v150 offset:4096
	ds_read_b128 v[212:215], v150 offset:5120
	ds_read_b128 v[216:219], v150 offset:6144
	ds_read_b128 v[220:223], v150 offset:7168
	global_load_lds_dwordx4 v[154:155], off
	v_lshl_add_u64 v[154:155], s[30:31], 0, v[136:137]
	s_add_i32 m0, s52, 0xe000
	s_nop 0
	global_load_lds_dwordx4 v[154:155], off
	s_waitcnt vmcnt(8)
	s_waitcnt lgkmcnt(0)
	s_barrier
	s_setprio 1
	s_waitcnt lgkmcnt(0)
	v_mfma_f32_16x16x32_bf16 v[124:127], v[160:163], v[192:195], 0
	v_mfma_f32_16x16x32_bf16 v[116:119], v[168:171], v[192:195], 0
	v_mfma_f32_16x16x32_bf16 v[108:111], v[160:163], v[200:203], 0
	v_mfma_f32_16x16x32_bf16 v[100:103], v[168:171], v[200:203], 0
	v_mfma_f32_16x16x32_bf16 v[92:95], v[160:163], v[208:211], 0
	v_mfma_f32_16x16x32_bf16 v[84:87], v[168:171], v[208:211], 0
	v_mfma_f32_16x16x32_bf16 v[76:79], v[160:163], v[216:219], 0
	v_mfma_f32_16x16x32_bf16 v[68:71], v[168:171], v[216:219], 0
	v_mfma_f32_16x16x32_bf16 v[124:127], v[164:167], v[196:199], v[124:127]
	v_mfma_f32_16x16x32_bf16 v[116:119], v[172:175], v[196:199], v[116:119]
	v_mfma_f32_16x16x32_bf16 v[108:111], v[164:167], v[204:207], v[108:111]
	v_mfma_f32_16x16x32_bf16 v[100:103], v[172:175], v[204:207], v[100:103]
	v_mfma_f32_16x16x32_bf16 v[92:95], v[164:167], v[212:215], v[92:95]
	v_mfma_f32_16x16x32_bf16 v[84:87], v[172:175], v[212:215], v[84:87]
	v_mfma_f32_16x16x32_bf16 v[76:79], v[164:167], v[220:223], v[76:79]
	v_mfma_f32_16x16x32_bf16 v[68:71], v[172:175], v[220:223], v[68:71]
	s_setprio 0
	s_setprio 1
	v_mfma_f32_16x16x32_bf16 v[120:123], v[176:179], v[192:195], 0
	v_mfma_f32_16x16x32_bf16 v[112:115], v[184:187], v[192:195], 0
	v_mfma_f32_16x16x32_bf16 v[104:107], v[176:179], v[200:203], 0
	v_mfma_f32_16x16x32_bf16 v[96:99], v[184:187], v[200:203], 0
	v_mfma_f32_16x16x32_bf16 v[88:91], v[176:179], v[208:211], 0
	v_mfma_f32_16x16x32_bf16 v[80:83], v[184:187], v[208:211], 0
	v_mfma_f32_16x16x32_bf16 v[72:75], v[176:179], v[216:219], 0
	v_mfma_f32_16x16x32_bf16 v[64:67], v[184:187], v[216:219], 0
	v_mfma_f32_16x16x32_bf16 v[120:123], v[180:183], v[196:199], v[120:123]
	v_mfma_f32_16x16x32_bf16 v[112:115], v[188:191], v[196:199], v[112:115]
	v_mfma_f32_16x16x32_bf16 v[104:107], v[180:183], v[204:207], v[104:107]
	v_mfma_f32_16x16x32_bf16 v[96:99], v[188:191], v[204:207], v[96:99]
	v_mfma_f32_16x16x32_bf16 v[88:91], v[180:183], v[212:215], v[88:91]
	v_mfma_f32_16x16x32_bf16 v[80:83], v[188:191], v[212:215], v[80:83]
	v_mfma_f32_16x16x32_bf16 v[72:75], v[180:183], v[220:223], v[72:75]
	v_mfma_f32_16x16x32_bf16 v[64:67], v[188:191], v[220:223], v[64:67]
	s_setprio 0
	s_barrier
	s_add_i32 s71, s61, s49
	v_lshl_add_u64 v[154:155], s[44:45], 0, v[132:133]
	s_mov_b32 m0, s71
	ds_read_b128 v[192:195], v150 offset:16384
	ds_read_b128 v[196:199], v150 offset:17408
	ds_read_b128 v[200:203], v150 offset:18432
	ds_read_b128 v[204:207], v150 offset:19456
	ds_read_b128 v[208:211], v150 offset:20480
	ds_read_b128 v[212:215], v150 offset:21504
	ds_read_b128 v[216:219], v150 offset:22528
	ds_read_b128 v[220:223], v150 offset:23552
	global_load_lds_dwordx4 v[154:155], off
	s_add_i32 m0, s71, 0x2000
	s_add_u32 s72, s44, 0x40000
	v_lshl_add_u64 v[224:225], s[44:45], 0, v[128:129]
	s_addc_u32 s73, s45, 0
	s_add_i32 s71, s62, s49
	global_load_lds_dwordx4 v[224:225], off
	v_lshl_add_u64 v[226:227], s[72:73], 0, v[132:133]
	s_mov_b32 m0, s71
	v_lshl_add_u64 v[228:229], s[46:47], 0, v[130:131]
	global_load_lds_dwordx4 v[226:227], off
	v_lshl_add_u64 v[226:227], s[72:73], 0, v[128:129]
	s_add_i32 m0, s71, 0x2000
	s_nop 0
	global_load_lds_dwordx4 v[226:227], off
	v_lshl_add_u64 v[226:227], s[46:47], 0, v[134:135]
	s_mov_b32 m0, s52
	s_nop 0
	global_load_lds_dwordx4 v[226:227], off
	s_mov_b32 m0, s53
	s_nop 0
	global_load_lds_dwordx4 v[228:229], off
	s_waitcnt vmcnt(8)
	s_waitcnt lgkmcnt(0)
	s_barrier
	s_setprio 1
	s_waitcnt lgkmcnt(0)
	v_mfma_f32_16x16x32_bf16 v[60:63], v[160:163], v[192:195], 0
	v_mfma_f32_16x16x32_bf16 v[52:55], v[168:171], v[192:195], 0
	v_mfma_f32_16x16x32_bf16 v[44:47], v[160:163], v[200:203], 0
	v_mfma_f32_16x16x32_bf16 v[36:39], v[168:171], v[200:203], 0
	v_mfma_f32_16x16x32_bf16 v[28:31], v[160:163], v[208:211], 0
	v_mfma_f32_16x16x32_bf16 v[20:23], v[168:171], v[208:211], 0
	v_mfma_f32_16x16x32_bf16 v[12:15], v[160:163], v[216:219], 0
	v_mfma_f32_16x16x32_bf16 v[4:7], v[168:171], v[216:219], 0
	v_mfma_f32_16x16x32_bf16 v[60:63], v[164:167], v[196:199], v[60:63]
	v_mfma_f32_16x16x32_bf16 v[52:55], v[172:175], v[196:199], v[52:55]
	v_mfma_f32_16x16x32_bf16 v[44:47], v[164:167], v[204:207], v[44:47]
	v_mfma_f32_16x16x32_bf16 v[36:39], v[172:175], v[204:207], v[36:39]
	v_mfma_f32_16x16x32_bf16 v[28:31], v[164:167], v[212:215], v[28:31]
	v_mfma_f32_16x16x32_bf16 v[20:23], v[172:175], v[212:215], v[20:23]
	v_mfma_f32_16x16x32_bf16 v[12:15], v[164:167], v[220:223], v[12:15]
	v_mfma_f32_16x16x32_bf16 v[4:7], v[172:175], v[220:223], v[4:7]
	s_setprio 0
	s_setprio 1
	v_mfma_f32_16x16x32_bf16 v[56:59], v[176:179], v[192:195], 0
	v_mfma_f32_16x16x32_bf16 v[48:51], v[184:187], v[192:195], 0
	v_mfma_f32_16x16x32_bf16 v[40:43], v[176:179], v[200:203], 0
	v_mfma_f32_16x16x32_bf16 v[32:35], v[184:187], v[200:203], 0
	v_mfma_f32_16x16x32_bf16 v[24:27], v[176:179], v[208:211], 0
	v_mfma_f32_16x16x32_bf16 v[16:19], v[184:187], v[208:211], 0
	v_mfma_f32_16x16x32_bf16 v[8:11], v[176:179], v[216:219], 0
	v_mfma_f32_16x16x32_bf16 v[0:3], v[184:187], v[216:219], 0
	v_mfma_f32_16x16x32_bf16 v[56:59], v[180:183], v[196:199], v[56:59]
	v_mfma_f32_16x16x32_bf16 v[48:51], v[188:191], v[196:199], v[48:51]
	v_mfma_f32_16x16x32_bf16 v[40:43], v[180:183], v[204:207], v[40:43]
	v_mfma_f32_16x16x32_bf16 v[32:35], v[188:191], v[204:207], v[32:35]
	v_mfma_f32_16x16x32_bf16 v[24:27], v[180:183], v[212:215], v[24:27]
	v_mfma_f32_16x16x32_bf16 v[16:19], v[188:191], v[212:215], v[16:19]
	v_mfma_f32_16x16x32_bf16 v[8:11], v[180:183], v[220:223], v[8:11]
	v_mfma_f32_16x16x32_bf16 v[0:3], v[188:191], v[220:223], v[0:3]
	s_setprio 0
	s_barrier
	s_add_i32 s71, 0, 0x18000
	v_add_u32_e32 v153, s71, v147
	s_add_i32 s72, 0, 0x1c000
	ds_read_b128 v[160:163], v153
	ds_read_b128 v[164:167], v153 offset:1024
	ds_read_b128 v[168:171], v153 offset:2048
	ds_read_b128 v[172:175], v153 offset:3072
	v_add_u32_e32 v153, s72, v147
	ds_read_b128 v[176:179], v153
	ds_read_b128 v[180:183], v153 offset:1024
	ds_read_b128 v[184:187], v153 offset:2048
	ds_read_b128 v[188:191], v153 offset:3072
	s_add_u32 s46, s46, 0x40000
	s_addc_u32 s47, s47, 0
	s_mov_b32 m0, s54
	v_lshl_add_u64 v[230:231], s[46:47], 0, v[134:135]
	ds_read_b128 v[192:195], v150 offset:32768
	ds_read_b128 v[196:199], v150 offset:33792
	ds_read_b128 v[200:203], v150 offset:34816
	ds_read_b128 v[204:207], v150 offset:35840
	ds_read_b128 v[208:211], v150 offset:36864
	ds_read_b128 v[212:215], v150 offset:37888
	ds_read_b128 v[216:219], v150 offset:38912
	ds_read_b128 v[220:223], v150 offset:39936
	global_load_lds_dwordx4 v[230:231], off
	v_lshl_add_u64 v[230:231], s[46:47], 0, v[130:131]
	s_mov_b32 m0, s55
	s_nop 0
	global_load_lds_dwordx4 v[230:231], off
	s_waitcnt vmcnt(8)
	s_waitcnt lgkmcnt(0)
	s_barrier
	s_setprio 1
	s_waitcnt lgkmcnt(0)
	v_mfma_f32_16x16x32_bf16 v[124:127], v[160:163], v[192:195], v[124:127]
	v_mfma_f32_16x16x32_bf16 v[124:127], v[164:167], v[196:199], v[124:127]
	v_mfma_f32_16x16x32_bf16 v[116:119], v[172:175], v[196:199], v[116:119]
	v_mfma_f32_16x16x32_bf16 v[116:119], v[168:171], v[192:195], v[116:119]
	v_mfma_f32_16x16x32_bf16 v[100:103], v[168:171], v[200:203], v[100:103]
	v_mfma_f32_16x16x32_bf16 v[100:103], v[172:175], v[204:207], v[100:103]
	v_mfma_f32_16x16x32_bf16 v[108:111], v[164:167], v[204:207], v[108:111]
	v_mfma_f32_16x16x32_bf16 v[108:111], v[160:163], v[200:203], v[108:111]
	v_mfma_f32_16x16x32_bf16 v[92:95], v[160:163], v[208:211], v[92:95]
	v_mfma_f32_16x16x32_bf16 v[92:95], v[164:167], v[212:215], v[92:95]
	v_mfma_f32_16x16x32_bf16 v[84:87], v[172:175], v[212:215], v[84:87]
	v_mfma_f32_16x16x32_bf16 v[84:87], v[168:171], v[208:211], v[84:87]
	v_mfma_f32_16x16x32_bf16 v[68:71], v[168:171], v[216:219], v[68:71]
	v_mfma_f32_16x16x32_bf16 v[68:71], v[172:175], v[220:223], v[68:71]
	v_mfma_f32_16x16x32_bf16 v[76:79], v[164:167], v[220:223], v[76:79]
	v_mfma_f32_16x16x32_bf16 v[76:79], v[160:163], v[216:219], v[76:79]
	s_setprio 0
	s_setprio 1
	v_mfma_f32_16x16x32_bf16 v[120:123], v[176:179], v[192:195], v[120:123]
	v_mfma_f32_16x16x32_bf16 v[120:123], v[180:183], v[196:199], v[120:123]
	v_mfma_f32_16x16x32_bf16 v[112:115], v[188:191], v[196:199], v[112:115]
	v_mfma_f32_16x16x32_bf16 v[112:115], v[184:187], v[192:195], v[112:115]
	v_mfma_f32_16x16x32_bf16 v[96:99], v[184:187], v[200:203], v[96:99]
	v_mfma_f32_16x16x32_bf16 v[96:99], v[188:191], v[204:207], v[96:99]
	v_mfma_f32_16x16x32_bf16 v[104:107], v[180:183], v[204:207], v[104:107]
	v_mfma_f32_16x16x32_bf16 v[104:107], v[176:179], v[200:203], v[104:107]
	v_mfma_f32_16x16x32_bf16 v[88:91], v[176:179], v[208:211], v[88:91]
	v_mfma_f32_16x16x32_bf16 v[88:91], v[180:183], v[212:215], v[88:91]
	v_mfma_f32_16x16x32_bf16 v[80:83], v[188:191], v[212:215], v[80:83]
	v_mfma_f32_16x16x32_bf16 v[80:83], v[184:187], v[208:211], v[80:83]
	v_mfma_f32_16x16x32_bf16 v[64:67], v[184:187], v[216:219], v[64:67]
	v_mfma_f32_16x16x32_bf16 v[64:67], v[188:191], v[220:223], v[64:67]
	v_mfma_f32_16x16x32_bf16 v[72:75], v[180:183], v[220:223], v[72:75]
	v_mfma_f32_16x16x32_bf16 v[72:75], v[176:179], v[216:219], v[72:75]
	s_setprio 0
	s_barrier
	s_add_i32 s46, s71, s49
	v_lshl_add_u64 v[154:155], v[154:155], 0, s[14:15]
	s_mov_b32 m0, s46
	ds_read_b128 v[192:195], v150 offset:49152
	ds_read_b128 v[196:199], v150 offset:50176
	ds_read_b128 v[200:203], v150 offset:51200
	ds_read_b128 v[204:207], v150 offset:52224
	ds_read_b128 v[208:211], v150 offset:53248
	ds_read_b128 v[212:215], v150 offset:54272
	ds_read_b128 v[216:219], v150 offset:55296
	ds_read_b128 v[220:223], v150 offset:56320
	global_load_lds_dwordx4 v[154:155], off
	s_add_i32 m0, s46, 0x2000
	s_add_u32 s44, s44, 0x40080
	v_lshl_add_u64 v[154:155], v[224:225], 0, s[14:15]
	s_addc_u32 s45, s45, 0
	s_add_i32 s46, s72, s49
	global_load_lds_dwordx4 v[154:155], off
	v_lshl_add_u64 v[154:155], s[44:45], 0, v[132:133]
	s_mov_b32 m0, s46
	s_nop 0
	global_load_lds_dwordx4 v[154:155], off
	v_lshl_add_u64 v[154:155], s[44:45], 0, v[128:129]
	s_add_i32 m0, s46, 0x2000
	s_nop 0
	global_load_lds_dwordx4 v[154:155], off
	v_lshl_add_u64 v[154:155], v[226:227], 0, s[14:15]
	s_mov_b32 m0, s57
	s_nop 0
	global_load_lds_dwordx4 v[154:155], off
	v_lshl_add_u64 v[154:155], v[228:229], 0, s[14:15]
	s_mov_b32 m0, s58
	s_nop 0
	global_load_lds_dwordx4 v[154:155], off
	s_waitcnt vmcnt(8)
	s_waitcnt lgkmcnt(0)
	s_barrier
	s_setprio 1
	s_waitcnt lgkmcnt(0)
	v_mfma_f32_16x16x32_bf16 v[60:63], v[160:163], v[192:195], v[60:63]
	v_mfma_f32_16x16x32_bf16 v[60:63], v[164:167], v[196:199], v[60:63]
	v_mfma_f32_16x16x32_bf16 v[52:55], v[172:175], v[196:199], v[52:55]
	v_mfma_f32_16x16x32_bf16 v[52:55], v[168:171], v[192:195], v[52:55]
	v_mfma_f32_16x16x32_bf16 v[36:39], v[168:171], v[200:203], v[36:39]
	v_mfma_f32_16x16x32_bf16 v[36:39], v[172:175], v[204:207], v[36:39]
	v_mfma_f32_16x16x32_bf16 v[44:47], v[164:167], v[204:207], v[44:47]
	v_mfma_f32_16x16x32_bf16 v[44:47], v[160:163], v[200:203], v[44:47]
	v_mfma_f32_16x16x32_bf16 v[28:31], v[160:163], v[208:211], v[28:31]
	v_mfma_f32_16x16x32_bf16 v[28:31], v[164:167], v[212:215], v[28:31]
	v_mfma_f32_16x16x32_bf16 v[20:23], v[172:175], v[212:215], v[20:23]
	v_mfma_f32_16x16x32_bf16 v[20:23], v[168:171], v[208:211], v[20:23]
	v_mfma_f32_16x16x32_bf16 v[4:7], v[168:171], v[216:219], v[4:7]
	v_mfma_f32_16x16x32_bf16 v[4:7], v[172:175], v[220:223], v[4:7]
	v_mfma_f32_16x16x32_bf16 v[12:15], v[164:167], v[220:223], v[12:15]
	v_mfma_f32_16x16x32_bf16 v[12:15], v[160:163], v[216:219], v[12:15]
	s_setprio 0
	s_setprio 1
	v_mfma_f32_16x16x32_bf16 v[56:59], v[176:179], v[192:195], v[56:59]
	v_mfma_f32_16x16x32_bf16 v[56:59], v[180:183], v[196:199], v[56:59]
	v_mfma_f32_16x16x32_bf16 v[48:51], v[188:191], v[196:199], v[48:51]
	v_mfma_f32_16x16x32_bf16 v[48:51], v[184:187], v[192:195], v[48:51]
	v_mfma_f32_16x16x32_bf16 v[32:35], v[184:187], v[200:203], v[32:35]
	v_mfma_f32_16x16x32_bf16 v[32:35], v[188:191], v[204:207], v[32:35]
	v_mfma_f32_16x16x32_bf16 v[40:43], v[180:183], v[204:207], v[40:43]
	v_mfma_f32_16x16x32_bf16 v[40:43], v[176:179], v[200:203], v[40:43]
	v_mfma_f32_16x16x32_bf16 v[24:27], v[176:179], v[208:211], v[24:27]
	v_mfma_f32_16x16x32_bf16 v[24:27], v[180:183], v[212:215], v[24:27]
	v_mfma_f32_16x16x32_bf16 v[16:19], v[188:191], v[212:215], v[16:19]
	v_mfma_f32_16x16x32_bf16 v[16:19], v[184:187], v[208:211], v[16:19]
	v_mfma_f32_16x16x32_bf16 v[0:3], v[184:187], v[216:219], v[0:3]
	v_mfma_f32_16x16x32_bf16 v[0:3], v[188:191], v[220:223], v[0:3]
	v_mfma_f32_16x16x32_bf16 v[8:11], v[180:183], v[220:223], v[8:11]
	v_mfma_f32_16x16x32_bf16 v[8:11], v[176:179], v[216:219], v[8:11]
	s_setprio 0
	s_barrier
	s_add_i32 s70, s70, 2
	s_add_u32 s68, s68, 0x100
	s_addc_u32 s69, s69, 0
	s_add_u32 s30, s30, 0x100
	s_addc_u32 s31, s31, 0
	s_branch .LBB0_1098
.LBB0_1097:
	v_add_u32_e32 v153, s61, v147
	ds_read_b128 v[160:163], v153
	ds_read_b128 v[164:167], v153 offset:1024
	ds_read_b128 v[168:171], v153 offset:2048
	ds_read_b128 v[172:175], v153 offset:3072
	v_add_u32_e32 v153, s62, v147
	ds_read_b128 v[176:179], v153
	ds_read_b128 v[180:183], v153 offset:1024
	ds_read_b128 v[184:187], v153 offset:2048
	ds_read_b128 v[188:191], v153 offset:3072
	s_add_u32 s46, s30, 0xfffc0080
	s_addc_u32 s47, s31, -1
	s_and_b64 s[44:45], s[44:45], exec
	s_cselect_b32 s47, s25, s47
	s_cselect_b32 s46, s65, s46
	s_cselect_b32 s45, s66, s69
	s_cselect_b32 s44, s67, s68
	v_lshl_add_u64 v[154:155], s[30:31], 0, v[138:139]
	s_add_i32 m0, s52, 0xc000
	ds_read_b128 v[192:195], v150
	ds_read_b128 v[196:199], v150 offset:1024
	ds_read_b128 v[200:203], v150 offset:2048
	ds_read_b128 v[204:207], v150 offset:3072
	ds_read_b128 v[208:211], v150 offset:4096
	ds_read_b128 v[212:215], v150 offset:5120
	ds_read_b128 v[216:219], v150 offset:6144
	ds_read_b128 v[220:223], v150 offset:7168
	global_load_lds_dwordx4 v[154:155], off
	v_lshl_add_u64 v[154:155], s[30:31], 0, v[136:137]
	s_add_i32 m0, s52, 0xe000
	s_nop 0
	global_load_lds_dwordx4 v[154:155], off
	s_waitcnt vmcnt(8)
	s_waitcnt lgkmcnt(0)
	s_barrier
	s_setprio 1
	s_waitcnt lgkmcnt(0)
	v_mfma_f32_16x16x32_bf16 v[124:127], v[160:163], v[192:195], v[124:127]
	v_mfma_f32_16x16x32_bf16 v[124:127], v[164:167], v[196:199], v[124:127]
	v_mfma_f32_16x16x32_bf16 v[116:119], v[172:175], v[196:199], v[116:119]
	v_mfma_f32_16x16x32_bf16 v[116:119], v[168:171], v[192:195], v[116:119]
	v_mfma_f32_16x16x32_bf16 v[100:103], v[168:171], v[200:203], v[100:103]
	v_mfma_f32_16x16x32_bf16 v[100:103], v[172:175], v[204:207], v[100:103]
	v_mfma_f32_16x16x32_bf16 v[108:111], v[164:167], v[204:207], v[108:111]
	v_mfma_f32_16x16x32_bf16 v[108:111], v[160:163], v[200:203], v[108:111]
	v_mfma_f32_16x16x32_bf16 v[92:95], v[160:163], v[208:211], v[92:95]
	v_mfma_f32_16x16x32_bf16 v[92:95], v[164:167], v[212:215], v[92:95]
	v_mfma_f32_16x16x32_bf16 v[84:87], v[172:175], v[212:215], v[84:87]
	v_mfma_f32_16x16x32_bf16 v[84:87], v[168:171], v[208:211], v[84:87]
	v_mfma_f32_16x16x32_bf16 v[68:71], v[168:171], v[216:219], v[68:71]
	v_mfma_f32_16x16x32_bf16 v[68:71], v[172:175], v[220:223], v[68:71]
	v_mfma_f32_16x16x32_bf16 v[76:79], v[164:167], v[220:223], v[76:79]
	v_mfma_f32_16x16x32_bf16 v[76:79], v[160:163], v[216:219], v[76:79]
	s_setprio 0
	s_setprio 1
	v_mfma_f32_16x16x32_bf16 v[120:123], v[176:179], v[192:195], v[120:123]
	v_mfma_f32_16x16x32_bf16 v[120:123], v[180:183], v[196:199], v[120:123]
	v_mfma_f32_16x16x32_bf16 v[112:115], v[188:191], v[196:199], v[112:115]
	v_mfma_f32_16x16x32_bf16 v[112:115], v[184:187], v[192:195], v[112:115]
	v_mfma_f32_16x16x32_bf16 v[96:99], v[184:187], v[200:203], v[96:99]
	v_mfma_f32_16x16x32_bf16 v[96:99], v[188:191], v[204:207], v[96:99]
	v_mfma_f32_16x16x32_bf16 v[104:107], v[180:183], v[204:207], v[104:107]
	v_mfma_f32_16x16x32_bf16 v[104:107], v[176:179], v[200:203], v[104:107]
	v_mfma_f32_16x16x32_bf16 v[88:91], v[176:179], v[208:211], v[88:91]
	v_mfma_f32_16x16x32_bf16 v[88:91], v[180:183], v[212:215], v[88:91]
	v_mfma_f32_16x16x32_bf16 v[80:83], v[188:191], v[212:215], v[80:83]
	v_mfma_f32_16x16x32_bf16 v[80:83], v[184:187], v[208:211], v[80:83]
	v_mfma_f32_16x16x32_bf16 v[64:67], v[184:187], v[216:219], v[64:67]
	v_mfma_f32_16x16x32_bf16 v[64:67], v[188:191], v[220:223], v[64:67]
	v_mfma_f32_16x16x32_bf16 v[72:75], v[180:183], v[220:223], v[72:75]
	v_mfma_f32_16x16x32_bf16 v[72:75], v[176:179], v[216:219], v[72:75]
	s_setprio 0
	s_barrier
	s_add_i32 s71, s61, s49
	v_lshl_add_u64 v[154:155], s[44:45], 0, v[132:133]
	s_mov_b32 m0, s71
	ds_read_b128 v[192:195], v150 offset:16384
	ds_read_b128 v[196:199], v150 offset:17408
	ds_read_b128 v[200:203], v150 offset:18432
	ds_read_b128 v[204:207], v150 offset:19456
	ds_read_b128 v[208:211], v150 offset:20480
	ds_read_b128 v[212:215], v150 offset:21504
	ds_read_b128 v[216:219], v150 offset:22528
	ds_read_b128 v[220:223], v150 offset:23552
	global_load_lds_dwordx4 v[154:155], off
	s_add_i32 m0, s71, 0x2000
	s_add_u32 s72, s44, 0x40000
	v_lshl_add_u64 v[224:225], s[44:45], 0, v[128:129]
	s_addc_u32 s73, s45, 0
	s_add_i32 s71, s62, s49
	global_load_lds_dwordx4 v[224:225], off
	v_lshl_add_u64 v[226:227], s[72:73], 0, v[132:133]
	s_mov_b32 m0, s71
	v_lshl_add_u64 v[228:229], s[46:47], 0, v[130:131]
	global_load_lds_dwordx4 v[226:227], off
	v_lshl_add_u64 v[226:227], s[72:73], 0, v[128:129]
	s_add_i32 m0, s71, 0x2000
	s_nop 0
	global_load_lds_dwordx4 v[226:227], off
	v_lshl_add_u64 v[226:227], s[46:47], 0, v[134:135]
	s_mov_b32 m0, s52
	s_nop 0
	global_load_lds_dwordx4 v[226:227], off
	s_mov_b32 m0, s53
	s_nop 0
	global_load_lds_dwordx4 v[228:229], off
	s_waitcnt vmcnt(8)
	s_waitcnt lgkmcnt(0)
	s_barrier
	s_setprio 1
	s_waitcnt lgkmcnt(0)
	v_mfma_f32_16x16x32_bf16 v[60:63], v[160:163], v[192:195], v[60:63]
	v_mfma_f32_16x16x32_bf16 v[60:63], v[164:167], v[196:199], v[60:63]
	v_mfma_f32_16x16x32_bf16 v[52:55], v[172:175], v[196:199], v[52:55]
	v_mfma_f32_16x16x32_bf16 v[52:55], v[168:171], v[192:195], v[52:55]
	v_mfma_f32_16x16x32_bf16 v[36:39], v[168:171], v[200:203], v[36:39]
	v_mfma_f32_16x16x32_bf16 v[36:39], v[172:175], v[204:207], v[36:39]
	v_mfma_f32_16x16x32_bf16 v[44:47], v[164:167], v[204:207], v[44:47]
	v_mfma_f32_16x16x32_bf16 v[44:47], v[160:163], v[200:203], v[44:47]
	v_mfma_f32_16x16x32_bf16 v[28:31], v[160:163], v[208:211], v[28:31]
	v_mfma_f32_16x16x32_bf16 v[28:31], v[164:167], v[212:215], v[28:31]
	v_mfma_f32_16x16x32_bf16 v[20:23], v[172:175], v[212:215], v[20:23]
	v_mfma_f32_16x16x32_bf16 v[20:23], v[168:171], v[208:211], v[20:23]
	v_mfma_f32_16x16x32_bf16 v[4:7], v[168:171], v[216:219], v[4:7]
	v_mfma_f32_16x16x32_bf16 v[4:7], v[172:175], v[220:223], v[4:7]
	v_mfma_f32_16x16x32_bf16 v[12:15], v[164:167], v[220:223], v[12:15]
	v_mfma_f32_16x16x32_bf16 v[12:15], v[160:163], v[216:219], v[12:15]
	s_setprio 0
	s_setprio 1
	v_mfma_f32_16x16x32_bf16 v[56:59], v[176:179], v[192:195], v[56:59]
	v_mfma_f32_16x16x32_bf16 v[56:59], v[180:183], v[196:199], v[56:59]
	v_mfma_f32_16x16x32_bf16 v[48:51], v[188:191], v[196:199], v[48:51]
	v_mfma_f32_16x16x32_bf16 v[48:51], v[184:187], v[192:195], v[48:51]
	v_mfma_f32_16x16x32_bf16 v[32:35], v[184:187], v[200:203], v[32:35]
	v_mfma_f32_16x16x32_bf16 v[32:35], v[188:191], v[204:207], v[32:35]
	v_mfma_f32_16x16x32_bf16 v[40:43], v[180:183], v[204:207], v[40:43]
	v_mfma_f32_16x16x32_bf16 v[40:43], v[176:179], v[200:203], v[40:43]
	v_mfma_f32_16x16x32_bf16 v[24:27], v[176:179], v[208:211], v[24:27]
	v_mfma_f32_16x16x32_bf16 v[24:27], v[180:183], v[212:215], v[24:27]
	v_mfma_f32_16x16x32_bf16 v[16:19], v[188:191], v[212:215], v[16:19]
	v_mfma_f32_16x16x32_bf16 v[16:19], v[184:187], v[208:211], v[16:19]
	v_mfma_f32_16x16x32_bf16 v[0:3], v[184:187], v[216:219], v[0:3]
	v_mfma_f32_16x16x32_bf16 v[0:3], v[188:191], v[220:223], v[0:3]
	v_mfma_f32_16x16x32_bf16 v[8:11], v[180:183], v[220:223], v[8:11]
	v_mfma_f32_16x16x32_bf16 v[8:11], v[176:179], v[216:219], v[8:11]
	s_setprio 0
	s_barrier
	s_add_i32 s71, 0, 0x18000
	v_add_u32_e32 v153, s71, v147
	s_add_i32 s72, 0, 0x1c000
	ds_read_b128 v[160:163], v153
	ds_read_b128 v[164:167], v153 offset:1024
	ds_read_b128 v[168:171], v153 offset:2048
	ds_read_b128 v[172:175], v153 offset:3072
	v_add_u32_e32 v153, s72, v147
	ds_read_b128 v[176:179], v153
	ds_read_b128 v[180:183], v153 offset:1024
	ds_read_b128 v[184:187], v153 offset:2048
	ds_read_b128 v[188:191], v153 offset:3072
	s_add_u32 s46, s46, 0x40000
	s_addc_u32 s47, s47, 0
	s_mov_b32 m0, s54
	v_lshl_add_u64 v[230:231], s[46:47], 0, v[134:135]
	ds_read_b128 v[192:195], v150 offset:32768
	ds_read_b128 v[196:199], v150 offset:33792
	ds_read_b128 v[200:203], v150 offset:34816
	ds_read_b128 v[204:207], v150 offset:35840
	ds_read_b128 v[208:211], v150 offset:36864
	ds_read_b128 v[212:215], v150 offset:37888
	ds_read_b128 v[216:219], v150 offset:38912
	ds_read_b128 v[220:223], v150 offset:39936
	global_load_lds_dwordx4 v[230:231], off
	v_lshl_add_u64 v[230:231], s[46:47], 0, v[130:131]
	s_mov_b32 m0, s55
	s_nop 0
	global_load_lds_dwordx4 v[230:231], off
	s_waitcnt vmcnt(8)
	s_waitcnt lgkmcnt(0)
	s_barrier
	s_setprio 1
	s_waitcnt lgkmcnt(0)
	v_mfma_f32_16x16x32_bf16 v[124:127], v[160:163], v[192:195], v[124:127]
	v_mfma_f32_16x16x32_bf16 v[124:127], v[164:167], v[196:199], v[124:127]
	v_mfma_f32_16x16x32_bf16 v[116:119], v[172:175], v[196:199], v[116:119]
	v_mfma_f32_16x16x32_bf16 v[116:119], v[168:171], v[192:195], v[116:119]
	v_mfma_f32_16x16x32_bf16 v[100:103], v[168:171], v[200:203], v[100:103]
	v_mfma_f32_16x16x32_bf16 v[100:103], v[172:175], v[204:207], v[100:103]
	v_mfma_f32_16x16x32_bf16 v[108:111], v[164:167], v[204:207], v[108:111]
	v_mfma_f32_16x16x32_bf16 v[108:111], v[160:163], v[200:203], v[108:111]
	v_mfma_f32_16x16x32_bf16 v[92:95], v[160:163], v[208:211], v[92:95]
	v_mfma_f32_16x16x32_bf16 v[92:95], v[164:167], v[212:215], v[92:95]
	v_mfma_f32_16x16x32_bf16 v[84:87], v[172:175], v[212:215], v[84:87]
	v_mfma_f32_16x16x32_bf16 v[84:87], v[168:171], v[208:211], v[84:87]
	v_mfma_f32_16x16x32_bf16 v[68:71], v[168:171], v[216:219], v[68:71]
	v_mfma_f32_16x16x32_bf16 v[68:71], v[172:175], v[220:223], v[68:71]
	v_mfma_f32_16x16x32_bf16 v[76:79], v[164:167], v[220:223], v[76:79]
	v_mfma_f32_16x16x32_bf16 v[76:79], v[160:163], v[216:219], v[76:79]
	s_setprio 0
	s_setprio 1
	v_mfma_f32_16x16x32_bf16 v[120:123], v[176:179], v[192:195], v[120:123]
	v_mfma_f32_16x16x32_bf16 v[120:123], v[180:183], v[196:199], v[120:123]
	v_mfma_f32_16x16x32_bf16 v[112:115], v[188:191], v[196:199], v[112:115]
	v_mfma_f32_16x16x32_bf16 v[112:115], v[184:187], v[192:195], v[112:115]
	v_mfma_f32_16x16x32_bf16 v[96:99], v[184:187], v[200:203], v[96:99]
	v_mfma_f32_16x16x32_bf16 v[96:99], v[188:191], v[204:207], v[96:99]
	v_mfma_f32_16x16x32_bf16 v[104:107], v[180:183], v[204:207], v[104:107]
	v_mfma_f32_16x16x32_bf16 v[104:107], v[176:179], v[200:203], v[104:107]
	v_mfma_f32_16x16x32_bf16 v[88:91], v[176:179], v[208:211], v[88:91]
	v_mfma_f32_16x16x32_bf16 v[88:91], v[180:183], v[212:215], v[88:91]
	v_mfma_f32_16x16x32_bf16 v[80:83], v[188:191], v[212:215], v[80:83]
	v_mfma_f32_16x16x32_bf16 v[80:83], v[184:187], v[208:211], v[80:83]
	v_mfma_f32_16x16x32_bf16 v[64:67], v[184:187], v[216:219], v[64:67]
	v_mfma_f32_16x16x32_bf16 v[64:67], v[188:191], v[220:223], v[64:67]
	v_mfma_f32_16x16x32_bf16 v[72:75], v[180:183], v[220:223], v[72:75]
	v_mfma_f32_16x16x32_bf16 v[72:75], v[176:179], v[216:219], v[72:75]
	s_setprio 0
	s_barrier
	s_add_i32 s46, s71, s49
	v_lshl_add_u64 v[154:155], v[154:155], 0, s[14:15]
	s_mov_b32 m0, s46
	ds_read_b128 v[192:195], v150 offset:49152
	ds_read_b128 v[196:199], v150 offset:50176
	ds_read_b128 v[200:203], v150 offset:51200
	ds_read_b128 v[204:207], v150 offset:52224
	ds_read_b128 v[208:211], v150 offset:53248
	ds_read_b128 v[212:215], v150 offset:54272
	ds_read_b128 v[216:219], v150 offset:55296
	ds_read_b128 v[220:223], v150 offset:56320
	global_load_lds_dwordx4 v[154:155], off
	s_add_i32 m0, s46, 0x2000
	s_add_u32 s44, s44, 0x40080
	v_lshl_add_u64 v[154:155], v[224:225], 0, s[14:15]
	s_addc_u32 s45, s45, 0
	s_add_i32 s46, s72, s49
	global_load_lds_dwordx4 v[154:155], off
	v_lshl_add_u64 v[154:155], s[44:45], 0, v[132:133]
	s_mov_b32 m0, s46
	s_nop 0
	global_load_lds_dwordx4 v[154:155], off
	v_lshl_add_u64 v[154:155], s[44:45], 0, v[128:129]
	s_add_i32 m0, s46, 0x2000
	s_nop 0
	global_load_lds_dwordx4 v[154:155], off
	v_lshl_add_u64 v[154:155], v[226:227], 0, s[14:15]
	s_mov_b32 m0, s57
	s_nop 0
	global_load_lds_dwordx4 v[154:155], off
	v_lshl_add_u64 v[154:155], v[228:229], 0, s[14:15]
	s_mov_b32 m0, s58
	s_nop 0
	global_load_lds_dwordx4 v[154:155], off
	s_waitcnt vmcnt(8)
	s_waitcnt lgkmcnt(0)
	s_barrier
	s_setprio 1
	s_waitcnt lgkmcnt(0)
	v_mfma_f32_16x16x32_bf16 v[60:63], v[160:163], v[192:195], v[60:63]
	v_mfma_f32_16x16x32_bf16 v[60:63], v[164:167], v[196:199], v[60:63]
	v_mfma_f32_16x16x32_bf16 v[52:55], v[172:175], v[196:199], v[52:55]
	v_mfma_f32_16x16x32_bf16 v[52:55], v[168:171], v[192:195], v[52:55]
	v_mfma_f32_16x16x32_bf16 v[36:39], v[168:171], v[200:203], v[36:39]
	v_mfma_f32_16x16x32_bf16 v[36:39], v[172:175], v[204:207], v[36:39]
	v_mfma_f32_16x16x32_bf16 v[44:47], v[164:167], v[204:207], v[44:47]
	v_mfma_f32_16x16x32_bf16 v[44:47], v[160:163], v[200:203], v[44:47]
	v_mfma_f32_16x16x32_bf16 v[28:31], v[160:163], v[208:211], v[28:31]
	v_mfma_f32_16x16x32_bf16 v[28:31], v[164:167], v[212:215], v[28:31]
	v_mfma_f32_16x16x32_bf16 v[20:23], v[172:175], v[212:215], v[20:23]
	v_mfma_f32_16x16x32_bf16 v[20:23], v[168:171], v[208:211], v[20:23]
	v_mfma_f32_16x16x32_bf16 v[4:7], v[168:171], v[216:219], v[4:7]
	v_mfma_f32_16x16x32_bf16 v[4:7], v[172:175], v[220:223], v[4:7]
	v_mfma_f32_16x16x32_bf16 v[12:15], v[164:167], v[220:223], v[12:15]
	v_mfma_f32_16x16x32_bf16 v[12:15], v[160:163], v[216:219], v[12:15]
	s_setprio 0
	s_setprio 1
	v_mfma_f32_16x16x32_bf16 v[56:59], v[176:179], v[192:195], v[56:59]
	v_mfma_f32_16x16x32_bf16 v[56:59], v[180:183], v[196:199], v[56:59]
	v_mfma_f32_16x16x32_bf16 v[48:51], v[188:191], v[196:199], v[48:51]
	v_mfma_f32_16x16x32_bf16 v[48:51], v[184:187], v[192:195], v[48:51]
	v_mfma_f32_16x16x32_bf16 v[32:35], v[184:187], v[200:203], v[32:35]
	v_mfma_f32_16x16x32_bf16 v[32:35], v[188:191], v[204:207], v[32:35]
	v_mfma_f32_16x16x32_bf16 v[40:43], v[180:183], v[204:207], v[40:43]
	v_mfma_f32_16x16x32_bf16 v[40:43], v[176:179], v[200:203], v[40:43]
	v_mfma_f32_16x16x32_bf16 v[24:27], v[176:179], v[208:211], v[24:27]
	v_mfma_f32_16x16x32_bf16 v[24:27], v[180:183], v[212:215], v[24:27]
	v_mfma_f32_16x16x32_bf16 v[16:19], v[188:191], v[212:215], v[16:19]
	v_mfma_f32_16x16x32_bf16 v[16:19], v[184:187], v[208:211], v[16:19]
	v_mfma_f32_16x16x32_bf16 v[0:3], v[184:187], v[216:219], v[0:3]
	v_mfma_f32_16x16x32_bf16 v[0:3], v[188:191], v[220:223], v[0:3]
	v_mfma_f32_16x16x32_bf16 v[8:11], v[180:183], v[220:223], v[8:11]
	v_mfma_f32_16x16x32_bf16 v[8:11], v[176:179], v[216:219], v[8:11]
	s_setprio 0
	s_barrier
	s_add_i32 s70, s70, 2
	s_add_u32 s68, s68, 0x100
	s_addc_u32 s69, s69, 0
	s_add_u32 s30, s30, 0x100
	s_addc_u32 s31, s31, 0
	s_cmp_gt_u32 s70, 13
	s_cbranch_scc1 .LBB0_1100

.Llast_10:
	v_add_u32_e32 v153, s61, v147
	ds_read_b128 v[160:163], v153
	ds_read_b128 v[164:167], v153 offset:1024
	ds_read_b128 v[168:171], v153 offset:2048
	ds_read_b128 v[172:175], v153 offset:3072
	v_add_u32_e32 v153, s62, v147
	ds_read_b128 v[176:179], v153
	ds_read_b128 v[180:183], v153 offset:1024
	ds_read_b128 v[184:187], v153 offset:2048
	ds_read_b128 v[188:191], v153 offset:3072
	s_add_u32 s46, s30, 0xfffc0080
	s_addc_u32 s47, s31, -1
	s_and_b64 s[44:45], s[44:45], exec
	s_cselect_b32 s47, s25, s47
	s_cselect_b32 s46, s65, s46
	s_cselect_b32 s45, s66, s69
	s_cselect_b32 s44, s67, s68
	v_lshl_add_u64 v[154:155], s[30:31], 0, v[138:139]
	s_add_i32 m0, s52, 0xc000
	ds_read_b128 v[192:195], v150
	ds_read_b128 v[196:199], v150 offset:1024
	ds_read_b128 v[200:203], v150 offset:2048
	ds_read_b128 v[204:207], v150 offset:3072
	ds_read_b128 v[208:211], v150 offset:4096
	ds_read_b128 v[212:215], v150 offset:5120
	ds_read_b128 v[216:219], v150 offset:6144
	ds_read_b128 v[220:223], v150 offset:7168
	global_load_lds_dwordx4 v[154:155], off
	v_lshl_add_u64 v[154:155], s[30:31], 0, v[136:137]
	s_add_i32 m0, s52, 0xe000
	s_nop 0
	global_load_lds_dwordx4 v[154:155], off
	s_waitcnt vmcnt(8)
	s_waitcnt lgkmcnt(0)
	s_barrier
	s_setprio 1
	s_waitcnt lgkmcnt(0)
	v_mfma_f32_16x16x32_bf16 v[124:127], v[160:163], v[192:195], v[124:127]
	v_mfma_f32_16x16x32_bf16 v[124:127], v[164:167], v[196:199], v[124:127]
	v_mfma_f32_16x16x32_bf16 v[116:119], v[172:175], v[196:199], v[116:119]
	v_mfma_f32_16x16x32_bf16 v[116:119], v[168:171], v[192:195], v[116:119]
	v_mfma_f32_16x16x32_bf16 v[100:103], v[168:171], v[200:203], v[100:103]
	v_mfma_f32_16x16x32_bf16 v[100:103], v[172:175], v[204:207], v[100:103]
	v_mfma_f32_16x16x32_bf16 v[108:111], v[164:167], v[204:207], v[108:111]
	v_mfma_f32_16x16x32_bf16 v[108:111], v[160:163], v[200:203], v[108:111]
	v_mfma_f32_16x16x32_bf16 v[92:95], v[160:163], v[208:211], v[92:95]
	v_mfma_f32_16x16x32_bf16 v[92:95], v[164:167], v[212:215], v[92:95]
	v_mfma_f32_16x16x32_bf16 v[84:87], v[172:175], v[212:215], v[84:87]
	v_mfma_f32_16x16x32_bf16 v[84:87], v[168:171], v[208:211], v[84:87]
	v_mfma_f32_16x16x32_bf16 v[68:71], v[168:171], v[216:219], v[68:71]
	v_mfma_f32_16x16x32_bf16 v[68:71], v[172:175], v[220:223], v[68:71]
	v_mfma_f32_16x16x32_bf16 v[76:79], v[164:167], v[220:223], v[76:79]
	v_mfma_f32_16x16x32_bf16 v[76:79], v[160:163], v[216:219], v[76:79]
	s_setprio 0
	s_setprio 1
	v_mfma_f32_16x16x32_bf16 v[120:123], v[176:179], v[192:195], v[120:123]
	v_mfma_f32_16x16x32_bf16 v[120:123], v[180:183], v[196:199], v[120:123]
	v_mfma_f32_16x16x32_bf16 v[112:115], v[188:191], v[196:199], v[112:115]
	v_mfma_f32_16x16x32_bf16 v[112:115], v[184:187], v[192:195], v[112:115]
	v_mfma_f32_16x16x32_bf16 v[96:99], v[184:187], v[200:203], v[96:99]
	v_mfma_f32_16x16x32_bf16 v[96:99], v[188:191], v[204:207], v[96:99]
	v_mfma_f32_16x16x32_bf16 v[104:107], v[180:183], v[204:207], v[104:107]
	v_mfma_f32_16x16x32_bf16 v[104:107], v[176:179], v[200:203], v[104:107]
	v_mfma_f32_16x16x32_bf16 v[88:91], v[176:179], v[208:211], v[88:91]
	v_mfma_f32_16x16x32_bf16 v[88:91], v[180:183], v[212:215], v[88:91]
	v_mfma_f32_16x16x32_bf16 v[80:83], v[188:191], v[212:215], v[80:83]
	v_mfma_f32_16x16x32_bf16 v[80:83], v[184:187], v[208:211], v[80:83]
	v_mfma_f32_16x16x32_bf16 v[64:67], v[184:187], v[216:219], v[64:67]
	v_mfma_f32_16x16x32_bf16 v[64:67], v[188:191], v[220:223], v[64:67]
	v_mfma_f32_16x16x32_bf16 v[72:75], v[180:183], v[220:223], v[72:75]
	v_mfma_f32_16x16x32_bf16 v[72:75], v[176:179], v[216:219], v[72:75]
	s_setprio 0
	s_barrier
	s_add_i32 s71, s61, s49
	v_lshl_add_u64 v[154:155], s[44:45], 0, v[132:133]
	s_mov_b32 m0, s71
	ds_read_b128 v[192:195], v150 offset:16384
	ds_read_b128 v[196:199], v150 offset:17408
	ds_read_b128 v[200:203], v150 offset:18432
	ds_read_b128 v[204:207], v150 offset:19456
	ds_read_b128 v[208:211], v150 offset:20480
	ds_read_b128 v[212:215], v150 offset:21504
	ds_read_b128 v[216:219], v150 offset:22528
	ds_read_b128 v[220:223], v150 offset:23552
	global_load_lds_dwordx4 v[154:155], off
	s_add_i32 m0, s71, 0x2000
	s_add_u32 s72, s44, 0x40000
	v_lshl_add_u64 v[224:225], s[44:45], 0, v[128:129]
	s_addc_u32 s73, s45, 0
	s_add_i32 s71, s62, s49
	global_load_lds_dwordx4 v[224:225], off
	v_lshl_add_u64 v[226:227], s[72:73], 0, v[132:133]
	s_mov_b32 m0, s71
	v_lshl_add_u64 v[228:229], s[46:47], 0, v[130:131]
	global_load_lds_dwordx4 v[226:227], off
	v_lshl_add_u64 v[226:227], s[72:73], 0, v[128:129]
	s_add_i32 m0, s71, 0x2000
	s_nop 0
	global_load_lds_dwordx4 v[226:227], off
	v_lshl_add_u64 v[226:227], s[46:47], 0, v[134:135]
	s_mov_b32 m0, s52
	s_nop 0
	global_load_lds_dwordx4 v[226:227], off
	s_mov_b32 m0, s53
	s_nop 0
	global_load_lds_dwordx4 v[228:229], off
	s_waitcnt vmcnt(8)
	s_waitcnt lgkmcnt(0)
	s_barrier
	s_setprio 1
	s_waitcnt lgkmcnt(0)
	v_mfma_f32_16x16x32_bf16 v[60:63], v[160:163], v[192:195], v[60:63]
	v_mfma_f32_16x16x32_bf16 v[60:63], v[164:167], v[196:199], v[60:63]
	v_mfma_f32_16x16x32_bf16 v[52:55], v[172:175], v[196:199], v[52:55]
	v_mfma_f32_16x16x32_bf16 v[52:55], v[168:171], v[192:195], v[52:55]
	v_mfma_f32_16x16x32_bf16 v[36:39], v[168:171], v[200:203], v[36:39]
	v_mfma_f32_16x16x32_bf16 v[36:39], v[172:175], v[204:207], v[36:39]
	v_mfma_f32_16x16x32_bf16 v[44:47], v[164:167], v[204:207], v[44:47]
	v_mfma_f32_16x16x32_bf16 v[44:47], v[160:163], v[200:203], v[44:47]
	v_mfma_f32_16x16x32_bf16 v[28:31], v[160:163], v[208:211], v[28:31]
	v_mfma_f32_16x16x32_bf16 v[28:31], v[164:167], v[212:215], v[28:31]
	v_mfma_f32_16x16x32_bf16 v[20:23], v[172:175], v[212:215], v[20:23]
	v_mfma_f32_16x16x32_bf16 v[20:23], v[168:171], v[208:211], v[20:23]
	v_mfma_f32_16x16x32_bf16 v[4:7], v[168:171], v[216:219], v[4:7]
	v_mfma_f32_16x16x32_bf16 v[4:7], v[172:175], v[220:223], v[4:7]
	v_mfma_f32_16x16x32_bf16 v[12:15], v[164:167], v[220:223], v[12:15]
	v_mfma_f32_16x16x32_bf16 v[12:15], v[160:163], v[216:219], v[12:15]
	s_setprio 0
	s_setprio 1
	v_mfma_f32_16x16x32_bf16 v[56:59], v[176:179], v[192:195], v[56:59]
	v_mfma_f32_16x16x32_bf16 v[56:59], v[180:183], v[196:199], v[56:59]
	v_mfma_f32_16x16x32_bf16 v[48:51], v[188:191], v[196:199], v[48:51]
	v_mfma_f32_16x16x32_bf16 v[48:51], v[184:187], v[192:195], v[48:51]
	v_mfma_f32_16x16x32_bf16 v[32:35], v[184:187], v[200:203], v[32:35]
	v_mfma_f32_16x16x32_bf16 v[32:35], v[188:191], v[204:207], v[32:35]
	v_mfma_f32_16x16x32_bf16 v[40:43], v[180:183], v[204:207], v[40:43]
	v_mfma_f32_16x16x32_bf16 v[40:43], v[176:179], v[200:203], v[40:43]
	v_mfma_f32_16x16x32_bf16 v[24:27], v[176:179], v[208:211], v[24:27]
	v_mfma_f32_16x16x32_bf16 v[24:27], v[180:183], v[212:215], v[24:27]
	v_mfma_f32_16x16x32_bf16 v[16:19], v[188:191], v[212:215], v[16:19]
	v_mfma_f32_16x16x32_bf16 v[16:19], v[184:187], v[208:211], v[16:19]
	v_mfma_f32_16x16x32_bf16 v[0:3], v[184:187], v[216:219], v[0:3]
	v_mfma_f32_16x16x32_bf16 v[0:3], v[188:191], v[220:223], v[0:3]
	v_mfma_f32_16x16x32_bf16 v[8:11], v[180:183], v[220:223], v[8:11]
	v_mfma_f32_16x16x32_bf16 v[8:11], v[176:179], v[216:219], v[8:11]
	s_setprio 0
	s_barrier
	s_add_i32 s71, 0, 0x18000
	v_add_u32_e32 v153, s71, v147
	s_add_i32 s72, 0, 0x1c000
	ds_read_b128 v[160:163], v153
	ds_read_b128 v[164:167], v153 offset:1024
	ds_read_b128 v[168:171], v153 offset:2048
	ds_read_b128 v[172:175], v153 offset:3072
	v_add_u32_e32 v153, s72, v147
	ds_read_b128 v[176:179], v153
	ds_read_b128 v[180:183], v153 offset:1024
	ds_read_b128 v[184:187], v153 offset:2048
	ds_read_b128 v[188:191], v153 offset:3072
	s_add_u32 s46, s46, 0x40000
	s_addc_u32 s47, s47, 0
	s_mov_b32 m0, s54
	v_lshl_add_u64 v[230:231], s[46:47], 0, v[134:135]
	ds_read_b128 v[192:195], v150 offset:32768
	ds_read_b128 v[196:199], v150 offset:33792
	ds_read_b128 v[200:203], v150 offset:34816
	ds_read_b128 v[204:207], v150 offset:35840
	ds_read_b128 v[208:211], v150 offset:36864
	ds_read_b128 v[212:215], v150 offset:37888
	ds_read_b128 v[216:219], v150 offset:38912
	ds_read_b128 v[220:223], v150 offset:39936
	global_load_lds_dwordx4 v[230:231], off
	v_lshl_add_u64 v[230:231], s[46:47], 0, v[130:131]
	s_mov_b32 m0, s55
	s_nop 0
	global_load_lds_dwordx4 v[230:231], off
	s_waitcnt vmcnt(8)
	s_waitcnt lgkmcnt(0)
	s_barrier
	s_setprio 1
	s_waitcnt lgkmcnt(0)
	v_mfma_f32_16x16x32_bf16 v[124:127], v[160:163], v[192:195], v[124:127]
	v_mfma_f32_16x16x32_bf16 v[124:127], v[164:167], v[196:199], v[124:127]
	v_mfma_f32_16x16x32_bf16 v[116:119], v[172:175], v[196:199], v[116:119]
	v_mfma_f32_16x16x32_bf16 v[116:119], v[168:171], v[192:195], v[116:119]
	v_mfma_f32_16x16x32_bf16 v[100:103], v[168:171], v[200:203], v[100:103]
	v_mfma_f32_16x16x32_bf16 v[100:103], v[172:175], v[204:207], v[100:103]
	v_mfma_f32_16x16x32_bf16 v[108:111], v[164:167], v[204:207], v[108:111]
	v_mfma_f32_16x16x32_bf16 v[108:111], v[160:163], v[200:203], v[108:111]
	v_mfma_f32_16x16x32_bf16 v[92:95], v[160:163], v[208:211], v[92:95]
	v_mfma_f32_16x16x32_bf16 v[92:95], v[164:167], v[212:215], v[92:95]
	v_mfma_f32_16x16x32_bf16 v[84:87], v[172:175], v[212:215], v[84:87]
	v_mfma_f32_16x16x32_bf16 v[84:87], v[168:171], v[208:211], v[84:87]
	v_mfma_f32_16x16x32_bf16 v[68:71], v[168:171], v[216:219], v[68:71]
	v_mfma_f32_16x16x32_bf16 v[68:71], v[172:175], v[220:223], v[68:71]
	v_mfma_f32_16x16x32_bf16 v[76:79], v[164:167], v[220:223], v[76:79]
	v_mfma_f32_16x16x32_bf16 v[76:79], v[160:163], v[216:219], v[76:79]
	s_setprio 0
	s_setprio 1
	v_mfma_f32_16x16x32_bf16 v[120:123], v[176:179], v[192:195], v[120:123]
	v_mfma_f32_16x16x32_bf16 v[120:123], v[180:183], v[196:199], v[120:123]
	v_mfma_f32_16x16x32_bf16 v[112:115], v[188:191], v[196:199], v[112:115]
	v_mfma_f32_16x16x32_bf16 v[112:115], v[184:187], v[192:195], v[112:115]
	v_mfma_f32_16x16x32_bf16 v[96:99], v[184:187], v[200:203], v[96:99]
	v_mfma_f32_16x16x32_bf16 v[96:99], v[188:191], v[204:207], v[96:99]
	v_mfma_f32_16x16x32_bf16 v[104:107], v[180:183], v[204:207], v[104:107]
	v_mfma_f32_16x16x32_bf16 v[104:107], v[176:179], v[200:203], v[104:107]
	v_mfma_f32_16x16x32_bf16 v[88:91], v[176:179], v[208:211], v[88:91]
	v_mfma_f32_16x16x32_bf16 v[88:91], v[180:183], v[212:215], v[88:91]
	v_mfma_f32_16x16x32_bf16 v[80:83], v[188:191], v[212:215], v[80:83]
	v_mfma_f32_16x16x32_bf16 v[80:83], v[184:187], v[208:211], v[80:83]
	v_mfma_f32_16x16x32_bf16 v[64:67], v[184:187], v[216:219], v[64:67]
	v_mfma_f32_16x16x32_bf16 v[64:67], v[188:191], v[220:223], v[64:67]
	v_mfma_f32_16x16x32_bf16 v[72:75], v[180:183], v[220:223], v[72:75]
	v_mfma_f32_16x16x32_bf16 v[72:75], v[176:179], v[216:219], v[72:75]
	s_setprio 0
	s_barrier
	v_add_u32_e32 v234, 0x21000, v151
	ds_read_b128 v[236:239], v234
	ds_read_b128 v[240:243], v234 offset:256
	ds_read_b128 v[244:247], v234 offset:512
	ds_read_b128 v[248:251], v234 offset:768
	v_add_u32_e32 v235, s23, v146
	v_mul_u32_u24_e32 v235, 0x1600, v235
	v_lshl_or_b32 v234, s64, 7, v149
	v_lshl_add_u32 v235, v234, 1, v235
	s_add_i32 s46, s71, s49
	v_lshl_add_u64 v[154:155], v[154:155], 0, s[14:15]
	s_mov_b32 m0, s46
	ds_read_b128 v[192:195], v150 offset:49152
	ds_read_b128 v[196:199], v150 offset:50176
	ds_read_b128 v[200:203], v150 offset:51200
	ds_read_b128 v[204:207], v150 offset:52224
	ds_read_b128 v[208:211], v150 offset:53248
	ds_read_b128 v[212:215], v150 offset:54272
	ds_read_b128 v[216:219], v150 offset:55296
	ds_read_b128 v[220:223], v150 offset:56320
	global_load_lds_dwordx4 v[154:155], off
	s_add_i32 m0, s46, 0x2000
	s_add_u32 s44, s44, 0x40080
	v_lshl_add_u64 v[154:155], v[224:225], 0, s[14:15]
	s_addc_u32 s45, s45, 0
	s_add_i32 s46, s72, s49
	global_load_lds_dwordx4 v[154:155], off
	v_lshl_add_u64 v[154:155], s[44:45], 0, v[132:133]
	s_mov_b32 m0, s46
	s_nop 0
	global_load_lds_dwordx4 v[154:155], off
	v_lshl_add_u64 v[154:155], s[44:45], 0, v[128:129]
	s_add_i32 m0, s46, 0x2000
	s_nop 0
	global_load_lds_dwordx4 v[154:155], off
	v_lshl_add_u64 v[154:155], v[226:227], 0, s[14:15]
	s_mov_b32 m0, s57
	s_nop 0
	global_load_lds_dwordx4 v[154:155], off
	v_lshl_add_u64 v[154:155], v[228:229], 0, s[14:15]
	s_mov_b32 m0, s58
	s_nop 0
	global_load_lds_dwordx4 v[154:155], off
	s_waitcnt lgkmcnt(8)
	v_add_f32_e32 v236, v236, v237
	v_add_f32_e32 v238, v238, v239
	v_add_f32_e32 v240, v240, v241
	v_add_f32_e32 v242, v242, v243
	v_add_f32_e32 v244, v244, v245
	v_add_f32_e32 v246, v246, v247
	v_add_f32_e32 v248, v248, v249
	v_add_f32_e32 v250, v250, v251
	v_add_f32_e32 v236, v236, v238
	v_add_f32_e32 v240, v240, v242
	v_add_f32_e32 v244, v244, v246
	v_add_f32_e32 v248, v248, v250
	v_fmamk_f32 v236, v236, 0x3a800000, v152
	v_fmamk_f32 v240, v240, 0x3a800000, v152
	v_fmamk_f32 v244, v244, 0x3a800000, v152
	v_fmamk_f32 v248, v248, 0x3a800000, v152
	v_rsq_f32_e32 v236, v236
	v_rsq_f32_e32 v240, v240
	v_rsq_f32_e32 v244, v244
	v_rsq_f32_e32 v248, v248
	v_mul_f32_e32 v252, 0xbfb8aa3b, v236
	v_mul_f32_e32 v254, v236, v236
	v_pk_mul_f32 v[120:121], v[124:125], v[120:121]
	v_pk_mul_f32 v[122:123], v[126:127], v[122:123]
	v_pk_mul_f32 v[112:113], v[116:117], v[112:113]
	v_pk_mul_f32 v[114:115], v[118:119], v[114:115]
	v_pk_mul_f32 v[124:125], v[124:125], v[252:253] op_sel_hi:[1,0]
	v_pk_mul_f32 v[126:127], v[126:127], v[252:253] op_sel_hi:[1,0]
	v_pk_mul_f32 v[116:117], v[116:117], v[252:253] op_sel_hi:[1,0]
	v_pk_mul_f32 v[118:119], v[118:119], v[252:253] op_sel_hi:[1,0]
	v_exp_f32_e32 v124, v124
	v_exp_f32_e32 v125, v125
	v_exp_f32_e32 v126, v126
	v_exp_f32_e32 v127, v127
	v_exp_f32_e32 v116, v116
	v_exp_f32_e32 v117, v117
	v_exp_f32_e32 v118, v118
	v_exp_f32_e32 v119, v119
	v_pk_add_f32 v[124:125], v[124:125], 1.0 op_sel_hi:[1,0]
	v_pk_add_f32 v[126:127], v[126:127], 1.0 op_sel_hi:[1,0]
	v_pk_add_f32 v[116:117], v[116:117], 1.0 op_sel_hi:[1,0]
	v_pk_add_f32 v[118:119], v[118:119], 1.0 op_sel_hi:[1,0]
	v_rcp_f32_e32 v124, v124
	v_rcp_f32_e32 v125, v125
	v_rcp_f32_e32 v126, v126
	v_rcp_f32_e32 v127, v127
	v_rcp_f32_e32 v116, v116
	v_rcp_f32_e32 v117, v117
	v_rcp_f32_e32 v118, v118
	v_rcp_f32_e32 v119, v119
	v_pk_mul_f32 v[120:121], v[120:121], v[254:255] op_sel_hi:[1,0]
	v_pk_mul_f32 v[122:123], v[122:123], v[254:255] op_sel_hi:[1,0]
	v_pk_mul_f32 v[112:113], v[112:113], v[254:255] op_sel_hi:[1,0]
	v_pk_mul_f32 v[114:115], v[114:115], v[254:255] op_sel_hi:[1,0]
	v_pk_mul_f32 v[120:121], v[120:121], v[124:125]
	v_pk_mul_f32 v[122:123], v[122:123], v[126:127]
	v_pk_mul_f32 v[112:113], v[112:113], v[116:117]
	v_pk_mul_f32 v[114:115], v[114:115], v[118:119]
	v_cvt_pk_bf16_f32 v120, v120, v121
	v_cvt_pk_bf16_f32 v121, v122, v123
	v_cvt_pk_bf16_f32 v122, v112, v113
	v_cvt_pk_bf16_f32 v123, v114, v115
	global_store_dwordx4 v235, v[120:123], s[10:11]
	v_add_u32_e32 v234, 0x16000, v235
	v_mul_f32_e32 v252, 0xbfb8aa3b, v240
	v_mul_f32_e32 v254, v240, v240
	v_pk_mul_f32 v[104:105], v[108:109], v[104:105]
	v_pk_mul_f32 v[106:107], v[110:111], v[106:107]
	v_pk_mul_f32 v[96:97], v[100:101], v[96:97]
	v_pk_mul_f32 v[98:99], v[102:103], v[98:99]
	v_pk_mul_f32 v[108:109], v[108:109], v[252:253] op_sel_hi:[1,0]
	v_pk_mul_f32 v[110:111], v[110:111], v[252:253] op_sel_hi:[1,0]
	v_pk_mul_f32 v[100:101], v[100:101], v[252:253] op_sel_hi:[1,0]
	v_pk_mul_f32 v[102:103], v[102:103], v[252:253] op_sel_hi:[1,0]
	v_exp_f32_e32 v108, v108
	v_exp_f32_e32 v109, v109
	v_exp_f32_e32 v110, v110
	v_exp_f32_e32 v111, v111
	v_exp_f32_e32 v100, v100
	v_exp_f32_e32 v101, v101
	v_exp_f32_e32 v102, v102
	v_exp_f32_e32 v103, v103
	v_pk_add_f32 v[108:109], v[108:109], 1.0 op_sel_hi:[1,0]
	v_pk_add_f32 v[110:111], v[110:111], 1.0 op_sel_hi:[1,0]
	v_pk_add_f32 v[100:101], v[100:101], 1.0 op_sel_hi:[1,0]
	v_pk_add_f32 v[102:103], v[102:103], 1.0 op_sel_hi:[1,0]
	v_rcp_f32_e32 v108, v108
	v_rcp_f32_e32 v109, v109
	v_rcp_f32_e32 v110, v110
	v_rcp_f32_e32 v111, v111
	v_rcp_f32_e32 v100, v100
	v_rcp_f32_e32 v101, v101
	v_rcp_f32_e32 v102, v102
	v_rcp_f32_e32 v103, v103
	v_pk_mul_f32 v[104:105], v[104:105], v[254:255] op_sel_hi:[1,0]
	v_pk_mul_f32 v[106:107], v[106:107], v[254:255] op_sel_hi:[1,0]
	v_pk_mul_f32 v[96:97], v[96:97], v[254:255] op_sel_hi:[1,0]
	v_pk_mul_f32 v[98:99], v[98:99], v[254:255] op_sel_hi:[1,0]
	v_pk_mul_f32 v[104:105], v[104:105], v[108:109]
	v_pk_mul_f32 v[106:107], v[106:107], v[110:111]
	v_pk_mul_f32 v[96:97], v[96:97], v[100:101]
	v_pk_mul_f32 v[98:99], v[98:99], v[102:103]
	v_cvt_pk_bf16_f32 v104, v104, v105
	v_cvt_pk_bf16_f32 v105, v106, v107
	v_cvt_pk_bf16_f32 v106, v96, v97
	v_cvt_pk_bf16_f32 v107, v98, v99
	global_store_dwordx4 v234, v[104:107], s[10:11]
	v_add_u32_e32 v235, 0x16000, v234
	v_mul_f32_e32 v252, 0xbfb8aa3b, v244
	v_mul_f32_e32 v254, v244, v244
	v_pk_mul_f32 v[88:89], v[92:93], v[88:89]
	v_pk_mul_f32 v[90:91], v[94:95], v[90:91]
	v_pk_mul_f32 v[80:81], v[84:85], v[80:81]
	v_pk_mul_f32 v[82:83], v[86:87], v[82:83]
	v_pk_mul_f32 v[92:93], v[92:93], v[252:253] op_sel_hi:[1,0]
	v_pk_mul_f32 v[94:95], v[94:95], v[252:253] op_sel_hi:[1,0]
	v_pk_mul_f32 v[84:85], v[84:85], v[252:253] op_sel_hi:[1,0]
	v_pk_mul_f32 v[86:87], v[86:87], v[252:253] op_sel_hi:[1,0]
	v_exp_f32_e32 v92, v92
	v_exp_f32_e32 v93, v93
	v_exp_f32_e32 v94, v94
	v_exp_f32_e32 v95, v95
	v_exp_f32_e32 v84, v84
	v_exp_f32_e32 v85, v85
	v_exp_f32_e32 v86, v86
	v_exp_f32_e32 v87, v87
	v_pk_add_f32 v[92:93], v[92:93], 1.0 op_sel_hi:[1,0]
	v_pk_add_f32 v[94:95], v[94:95], 1.0 op_sel_hi:[1,0]
	v_pk_add_f32 v[84:85], v[84:85], 1.0 op_sel_hi:[1,0]
	v_pk_add_f32 v[86:87], v[86:87], 1.0 op_sel_hi:[1,0]
	v_rcp_f32_e32 v92, v92
	v_rcp_f32_e32 v93, v93
	v_rcp_f32_e32 v94, v94
	v_rcp_f32_e32 v95, v95
	v_rcp_f32_e32 v84, v84
	v_rcp_f32_e32 v85, v85
	v_rcp_f32_e32 v86, v86
	v_rcp_f32_e32 v87, v87
	v_pk_mul_f32 v[88:89], v[88:89], v[254:255] op_sel_hi:[1,0]
	v_pk_mul_f32 v[90:91], v[90:91], v[254:255] op_sel_hi:[1,0]
	v_pk_mul_f32 v[80:81], v[80:81], v[254:255] op_sel_hi:[1,0]
	v_pk_mul_f32 v[82:83], v[82:83], v[254:255] op_sel_hi:[1,0]
	v_pk_mul_f32 v[88:89], v[88:89], v[92:93]
	v_pk_mul_f32 v[90:91], v[90:91], v[94:95]
	v_pk_mul_f32 v[80:81], v[80:81], v[84:85]
	v_pk_mul_f32 v[82:83], v[82:83], v[86:87]
	v_cvt_pk_bf16_f32 v88, v88, v89
	v_cvt_pk_bf16_f32 v89, v90, v91
	v_cvt_pk_bf16_f32 v90, v80, v81
	v_cvt_pk_bf16_f32 v91, v82, v83
	global_store_dwordx4 v235, v[88:91], s[10:11]
	v_add_u32_e32 v234, 0x16000, v235
	v_mul_f32_e32 v252, 0xbfb8aa3b, v248
	v_mul_f32_e32 v254, v248, v248
	v_pk_mul_f32 v[72:73], v[76:77], v[72:73]
	v_pk_mul_f32 v[74:75], v[78:79], v[74:75]
	v_pk_mul_f32 v[64:65], v[68:69], v[64:65]
	v_pk_mul_f32 v[66:67], v[70:71], v[66:67]
	v_pk_mul_f32 v[76:77], v[76:77], v[252:253] op_sel_hi:[1,0]
	v_pk_mul_f32 v[78:79], v[78:79], v[252:253] op_sel_hi:[1,0]
	v_pk_mul_f32 v[68:69], v[68:69], v[252:253] op_sel_hi:[1,0]
	v_pk_mul_f32 v[70:71], v[70:71], v[252:253] op_sel_hi:[1,0]
	v_exp_f32_e32 v76, v76
	v_exp_f32_e32 v77, v77
	v_exp_f32_e32 v78, v78
	v_exp_f32_e32 v79, v79
	v_exp_f32_e32 v68, v68
	v_exp_f32_e32 v69, v69
	v_exp_f32_e32 v70, v70
	v_exp_f32_e32 v71, v71
	v_pk_add_f32 v[76:77], v[76:77], 1.0 op_sel_hi:[1,0]
	v_pk_add_f32 v[78:79], v[78:79], 1.0 op_sel_hi:[1,0]
	v_pk_add_f32 v[68:69], v[68:69], 1.0 op_sel_hi:[1,0]
	v_pk_add_f32 v[70:71], v[70:71], 1.0 op_sel_hi:[1,0]
	v_rcp_f32_e32 v76, v76
	v_rcp_f32_e32 v77, v77
	v_rcp_f32_e32 v78, v78
	v_rcp_f32_e32 v79, v79
	v_rcp_f32_e32 v68, v68
	v_rcp_f32_e32 v69, v69
	v_rcp_f32_e32 v70, v70
	v_rcp_f32_e32 v71, v71
	v_pk_mul_f32 v[72:73], v[72:73], v[254:255] op_sel_hi:[1,0]
	v_pk_mul_f32 v[74:75], v[74:75], v[254:255] op_sel_hi:[1,0]
	v_pk_mul_f32 v[64:65], v[64:65], v[254:255] op_sel_hi:[1,0]
	v_pk_mul_f32 v[66:67], v[66:67], v[254:255] op_sel_hi:[1,0]
	v_pk_mul_f32 v[72:73], v[72:73], v[76:77]
	v_pk_mul_f32 v[74:75], v[74:75], v[78:79]
	v_pk_mul_f32 v[64:65], v[64:65], v[68:69]
	v_pk_mul_f32 v[66:67], v[66:67], v[70:71]
	v_cvt_pk_bf16_f32 v72, v72, v73
	v_cvt_pk_bf16_f32 v73, v74, v75
	v_cvt_pk_bf16_f32 v74, v64, v65
	v_cvt_pk_bf16_f32 v75, v66, v67
	global_store_dwordx4 v234, v[72:75], s[10:11]
	s_waitcnt vmcnt(12)
	s_waitcnt lgkmcnt(0)
	s_barrier
	s_setprio 1
	s_waitcnt lgkmcnt(0)
	v_mfma_f32_16x16x32_bf16 v[60:63], v[160:163], v[192:195], v[60:63]
	v_mfma_f32_16x16x32_bf16 v[60:63], v[164:167], v[196:199], v[60:63]
	v_mfma_f32_16x16x32_bf16 v[52:55], v[172:175], v[196:199], v[52:55]
	v_mfma_f32_16x16x32_bf16 v[52:55], v[168:171], v[192:195], v[52:55]
	v_mfma_f32_16x16x32_bf16 v[36:39], v[168:171], v[200:203], v[36:39]
	v_mfma_f32_16x16x32_bf16 v[36:39], v[172:175], v[204:207], v[36:39]
	v_mfma_f32_16x16x32_bf16 v[44:47], v[164:167], v[204:207], v[44:47]
	v_mfma_f32_16x16x32_bf16 v[44:47], v[160:163], v[200:203], v[44:47]
	v_mfma_f32_16x16x32_bf16 v[28:31], v[160:163], v[208:211], v[28:31]
	v_mfma_f32_16x16x32_bf16 v[28:31], v[164:167], v[212:215], v[28:31]
	v_mfma_f32_16x16x32_bf16 v[20:23], v[172:175], v[212:215], v[20:23]
	v_mfma_f32_16x16x32_bf16 v[20:23], v[168:171], v[208:211], v[20:23]
	v_mfma_f32_16x16x32_bf16 v[4:7], v[168:171], v[216:219], v[4:7]
	v_mfma_f32_16x16x32_bf16 v[4:7], v[172:175], v[220:223], v[4:7]
	v_mfma_f32_16x16x32_bf16 v[12:15], v[164:167], v[220:223], v[12:15]
	v_mfma_f32_16x16x32_bf16 v[12:15], v[160:163], v[216:219], v[12:15]
	s_setprio 0
	s_setprio 1
	v_mfma_f32_16x16x32_bf16 v[56:59], v[176:179], v[192:195], v[56:59]
	v_mfma_f32_16x16x32_bf16 v[56:59], v[180:183], v[196:199], v[56:59]
	v_mfma_f32_16x16x32_bf16 v[48:51], v[188:191], v[196:199], v[48:51]
	v_mfma_f32_16x16x32_bf16 v[48:51], v[184:187], v[192:195], v[48:51]
	v_mfma_f32_16x16x32_bf16 v[32:35], v[184:187], v[200:203], v[32:35]
	v_mfma_f32_16x16x32_bf16 v[32:35], v[188:191], v[204:207], v[32:35]
	v_mfma_f32_16x16x32_bf16 v[40:43], v[180:183], v[204:207], v[40:43]
	v_mfma_f32_16x16x32_bf16 v[40:43], v[176:179], v[200:203], v[40:43]
	v_mfma_f32_16x16x32_bf16 v[24:27], v[176:179], v[208:211], v[24:27]
	v_mfma_f32_16x16x32_bf16 v[24:27], v[180:183], v[212:215], v[24:27]
	v_mfma_f32_16x16x32_bf16 v[16:19], v[188:191], v[212:215], v[16:19]
	v_mfma_f32_16x16x32_bf16 v[16:19], v[184:187], v[208:211], v[16:19]
	v_mfma_f32_16x16x32_bf16 v[0:3], v[184:187], v[216:219], v[0:3]
	v_mfma_f32_16x16x32_bf16 v[0:3], v[188:191], v[220:223], v[0:3]
	v_mfma_f32_16x16x32_bf16 v[8:11], v[180:183], v[220:223], v[8:11]
	v_mfma_f32_16x16x32_bf16 v[8:11], v[176:179], v[216:219], v[8:11]
	s_setprio 0
	s_barrier
	s_add_i32 s70, s70, 2
	s_add_u32 s68, s68, 0x100
	s_addc_u32 s69, s69, 0
	s_add_u32 s30, s30, 0x100
	s_addc_u32 s31, s31, 0

.LBB0_1180:
	s_add_u32 s72, s50, 0x100
	s_addc_u32 s73, s51, 0
	s_mov_b32 s74, -2
	s_waitcnt lgkmcnt(0)
	s_cmp_eq_u32 s63, 1
	s_cbranch_scc1 .Lfa_11
	ds_read_b128 v[128:131], v188
	ds_read_b128 v[132:135], v188 offset:1024
	ds_read_b128 v[136:139], v188 offset:2048
	ds_read_b128 v[140:143], v188 offset:3072
	ds_read_b128 v[144:147], v189
	ds_read_b128 v[148:151], v189 offset:1024
	ds_read_b128 v[172:175], v189 offset:2048
	ds_read_b128 v[176:179], v189 offset:3072
	s_add_u32 s50, s48, 0x100
	s_addc_u32 s51, s49, 0
	s_cmp_eq_u32 s74, 40
	s_cselect_b32 s55, s11, s51
	s_cselect_b32 s54, s10, s50
	s_cselect_b32 s53, s47, s73
	s_cselect_b32 s52, s46, s72
	v_lshl_add_u64 v[220:221], s[48:49], 0, v[166:167]
	s_add_i32 m0, s59, 0xc000
	ds_read_b128 v[180:183], v190
	ds_read_b128 v[192:195], v190 offset:1024
	ds_read_b128 v[196:199], v190 offset:2048
	ds_read_b128 v[200:203], v190 offset:3072
	ds_read_b128 v[204:207], v190 offset:4096
	ds_read_b128 v[208:211], v190 offset:5120
	ds_read_b128 v[212:215], v190 offset:6144
	ds_read_b128 v[216:219], v190 offset:7168
	global_load_lds_dwordx4 v[220:221], off
	v_lshl_add_u64 v[220:221], s[48:49], 0, v[164:165]
	s_add_i32 m0, s59, 0xe000
	s_nop 0
	global_load_lds_dwordx4 v[220:221], off
	s_waitcnt vmcnt(24)
	s_waitcnt lgkmcnt(0)
	s_barrier
	s_setprio 1
	s_waitcnt lgkmcnt(0)
	v_mfma_f32_16x16x32_bf16 v[124:127], v[128:131], v[180:183], 0
	v_mfma_f32_16x16x32_bf16 v[120:123], v[136:139], v[180:183], 0
	v_mfma_f32_16x16x32_bf16 v[108:111], v[128:131], v[196:199], 0
	v_mfma_f32_16x16x32_bf16 v[104:107], v[136:139], v[196:199], 0
	v_mfma_f32_16x16x32_bf16 v[92:95], v[128:131], v[204:207], 0
	v_mfma_f32_16x16x32_bf16 v[88:91], v[136:139], v[204:207], 0
	v_mfma_f32_16x16x32_bf16 v[76:79], v[128:131], v[212:215], 0
	v_mfma_f32_16x16x32_bf16 v[72:75], v[136:139], v[212:215], 0
	v_mfma_f32_16x16x32_bf16 v[124:127], v[132:135], v[192:195], v[124:127]
	v_mfma_f32_16x16x32_bf16 v[120:123], v[140:143], v[192:195], v[120:123]
	v_mfma_f32_16x16x32_bf16 v[108:111], v[132:135], v[200:203], v[108:111]
	v_mfma_f32_16x16x32_bf16 v[104:107], v[140:143], v[200:203], v[104:107]
	v_mfma_f32_16x16x32_bf16 v[92:95], v[132:135], v[208:211], v[92:95]
	v_mfma_f32_16x16x32_bf16 v[88:91], v[140:143], v[208:211], v[88:91]
	v_mfma_f32_16x16x32_bf16 v[76:79], v[132:135], v[216:219], v[76:79]
	v_mfma_f32_16x16x32_bf16 v[72:75], v[140:143], v[216:219], v[72:75]
	s_setprio 0
	s_setprio 1
	v_mfma_f32_16x16x32_bf16 v[116:119], v[144:147], v[180:183], 0
	v_mfma_f32_16x16x32_bf16 v[112:115], v[172:175], v[180:183], 0
	v_mfma_f32_16x16x32_bf16 v[100:103], v[144:147], v[196:199], 0
	v_mfma_f32_16x16x32_bf16 v[96:99], v[172:175], v[196:199], 0
	v_mfma_f32_16x16x32_bf16 v[84:87], v[144:147], v[204:207], 0
	v_mfma_f32_16x16x32_bf16 v[80:83], v[172:175], v[204:207], 0
	v_mfma_f32_16x16x32_bf16 v[68:71], v[144:147], v[212:215], 0
	v_mfma_f32_16x16x32_bf16 v[64:67], v[172:175], v[212:215], 0
	v_mfma_f32_16x16x32_bf16 v[116:119], v[148:151], v[192:195], v[116:119]
	v_mfma_f32_16x16x32_bf16 v[112:115], v[176:179], v[192:195], v[112:115]
	v_mfma_f32_16x16x32_bf16 v[100:103], v[148:151], v[200:203], v[100:103]
	v_mfma_f32_16x16x32_bf16 v[96:99], v[176:179], v[200:203], v[96:99]
	v_mfma_f32_16x16x32_bf16 v[84:87], v[148:151], v[208:211], v[84:87]
	v_mfma_f32_16x16x32_bf16 v[80:83], v[176:179], v[208:211], v[80:83]
	v_mfma_f32_16x16x32_bf16 v[68:71], v[148:151], v[216:219], v[68:71]
	v_mfma_f32_16x16x32_bf16 v[64:67], v[176:179], v[216:219], v[64:67]
	s_setprio 0
	s_barrier
	s_add_i32 s48, s68, s58
	v_lshl_add_u64 v[220:221], s[52:53], 0, v[154:155]
	s_mov_b32 m0, s48
	ds_read_b128 v[180:183], v190 offset:16384
	ds_read_b128 v[192:195], v190 offset:17408
	ds_read_b128 v[196:199], v190 offset:18432
	ds_read_b128 v[200:203], v190 offset:19456
	ds_read_b128 v[204:207], v190 offset:20480
	ds_read_b128 v[208:211], v190 offset:21504
	ds_read_b128 v[212:215], v190 offset:22528
	ds_read_b128 v[216:219], v190 offset:23552
	global_load_lds_dwordx4 v[220:221], off
	s_add_i32 m0, s48, 0x2000
	s_add_u32 s48, s52, 0xb0000
	v_lshl_add_u64 v[222:223], s[52:53], 0, v[162:163]
	s_addc_u32 s49, s53, 0
	s_add_i32 s75, s69, s58
	global_load_lds_dwordx4 v[222:223], off
	v_lshl_add_u64 v[224:225], s[48:49], 0, v[154:155]
	s_mov_b32 m0, s75
	v_lshl_add_u64 v[226:227], s[54:55], 0, v[160:161]
	global_load_lds_dwordx4 v[224:225], off
	v_lshl_add_u64 v[224:225], s[48:49], 0, v[162:163]
	s_add_i32 m0, s75, 0x2000
	s_nop 0
	global_load_lds_dwordx4 v[224:225], off
	v_lshl_add_u64 v[224:225], s[54:55], 0, v[152:153]
	s_mov_b32 m0, s59
	s_nop 0
	global_load_lds_dwordx4 v[224:225], off
	s_mov_b32 m0, s60
	s_nop 0
	global_load_lds_dwordx4 v[226:227], off
	s_waitcnt vmcnt(24)
	s_waitcnt lgkmcnt(0)
	s_barrier
	s_setprio 1
	s_waitcnt lgkmcnt(0)
	v_mfma_f32_16x16x32_bf16 v[60:63], v[128:131], v[180:183], 0
	v_mfma_f32_16x16x32_bf16 v[56:59], v[136:139], v[180:183], 0
	v_mfma_f32_16x16x32_bf16 v[44:47], v[128:131], v[196:199], 0
	v_mfma_f32_16x16x32_bf16 v[40:43], v[136:139], v[196:199], 0
	v_mfma_f32_16x16x32_bf16 v[28:31], v[128:131], v[204:207], 0
	v_mfma_f32_16x16x32_bf16 v[24:27], v[136:139], v[204:207], 0
	v_mfma_f32_16x16x32_bf16 v[12:15], v[128:131], v[212:215], 0
	v_mfma_f32_16x16x32_bf16 v[8:11], v[136:139], v[212:215], 0
	v_mfma_f32_16x16x32_bf16 v[60:63], v[132:135], v[192:195], v[60:63]
	v_mfma_f32_16x16x32_bf16 v[56:59], v[140:143], v[192:195], v[56:59]
	v_mfma_f32_16x16x32_bf16 v[44:47], v[132:135], v[200:203], v[44:47]
	v_mfma_f32_16x16x32_bf16 v[40:43], v[140:143], v[200:203], v[40:43]
	v_mfma_f32_16x16x32_bf16 v[28:31], v[132:135], v[208:211], v[28:31]
	v_mfma_f32_16x16x32_bf16 v[24:27], v[140:143], v[208:211], v[24:27]
	v_mfma_f32_16x16x32_bf16 v[12:15], v[132:135], v[216:219], v[12:15]
	v_mfma_f32_16x16x32_bf16 v[8:11], v[140:143], v[216:219], v[8:11]
	s_setprio 0
	s_setprio 1
	v_mfma_f32_16x16x32_bf16 v[52:55], v[144:147], v[180:183], 0
	v_mfma_f32_16x16x32_bf16 v[48:51], v[172:175], v[180:183], 0
	v_mfma_f32_16x16x32_bf16 v[36:39], v[144:147], v[196:199], 0
	v_mfma_f32_16x16x32_bf16 v[32:35], v[172:175], v[196:199], 0
	v_mfma_f32_16x16x32_bf16 v[20:23], v[144:147], v[204:207], 0
	v_mfma_f32_16x16x32_bf16 v[16:19], v[172:175], v[204:207], 0
	v_mfma_f32_16x16x32_bf16 v[4:7], v[144:147], v[212:215], 0
	v_mfma_f32_16x16x32_bf16 v[0:3], v[172:175], v[212:215], 0
	v_mfma_f32_16x16x32_bf16 v[52:55], v[148:151], v[192:195], v[52:55]
	v_mfma_f32_16x16x32_bf16 v[48:51], v[176:179], v[192:195], v[48:51]
	v_mfma_f32_16x16x32_bf16 v[36:39], v[148:151], v[200:203], v[36:39]
	v_mfma_f32_16x16x32_bf16 v[32:35], v[176:179], v[200:203], v[32:35]
	v_mfma_f32_16x16x32_bf16 v[20:23], v[148:151], v[208:211], v[20:23]
	v_mfma_f32_16x16x32_bf16 v[16:19], v[176:179], v[208:211], v[16:19]
	v_mfma_f32_16x16x32_bf16 v[4:7], v[148:151], v[216:219], v[4:7]
	v_mfma_f32_16x16x32_bf16 v[0:3], v[176:179], v[216:219], v[0:3]
	s_setprio 0
	s_barrier
	s_add_i32 s75, 0, 0x18000
	s_add_i32 s76, 0, 0x1c000
	v_add_u32_e32 v140, s75, v185
	v_add_u32_e32 v176, s76, v185
	ds_read_b128 v[128:131], v140
	ds_read_b128 v[132:135], v140 offset:1024
	ds_read_b128 v[136:139], v140 offset:2048
	ds_read_b128 v[140:143], v140 offset:3072
	ds_read_b128 v[144:147], v176
	ds_read_b128 v[148:151], v176 offset:1024
	ds_read_b128 v[172:175], v176 offset:2048
	ds_read_b128 v[176:179], v176 offset:3072
	s_add_u32 s48, s54, 0xb0000
	s_addc_u32 s49, s55, 0
	s_mov_b32 m0, s61
	v_lshl_add_u64 v[228:229], s[48:49], 0, v[152:153]
	ds_read_b128 v[180:183], v190 offset:32768
	ds_read_b128 v[192:195], v190 offset:33792
	ds_read_b128 v[196:199], v190 offset:34816
	ds_read_b128 v[200:203], v190 offset:35840
	ds_read_b128 v[204:207], v190 offset:36864
	ds_read_b128 v[208:211], v190 offset:37888
	ds_read_b128 v[212:215], v190 offset:38912
	ds_read_b128 v[216:219], v190 offset:39936
	global_load_lds_dwordx4 v[228:229], off
	v_lshl_add_u64 v[228:229], s[48:49], 0, v[160:161]
	s_mov_b32 m0, s62
	s_nop 0
	global_load_lds_dwordx4 v[228:229], off
	s_waitcnt vmcnt(8)
	s_waitcnt lgkmcnt(0)
	s_barrier
	s_setprio 1
	s_waitcnt lgkmcnt(0)
	v_mfma_f32_16x16x32_bf16 v[124:127], v[128:131], v[180:183], v[124:127]
	v_mfma_f32_16x16x32_bf16 v[124:127], v[132:135], v[192:195], v[124:127]
	v_mfma_f32_16x16x32_bf16 v[120:123], v[140:143], v[192:195], v[120:123]
	v_mfma_f32_16x16x32_bf16 v[120:123], v[136:139], v[180:183], v[120:123]
	v_mfma_f32_16x16x32_bf16 v[104:107], v[136:139], v[196:199], v[104:107]
	v_mfma_f32_16x16x32_bf16 v[104:107], v[140:143], v[200:203], v[104:107]
	v_mfma_f32_16x16x32_bf16 v[108:111], v[132:135], v[200:203], v[108:111]
	v_mfma_f32_16x16x32_bf16 v[108:111], v[128:131], v[196:199], v[108:111]
	v_mfma_f32_16x16x32_bf16 v[92:95], v[128:131], v[204:207], v[92:95]
	v_mfma_f32_16x16x32_bf16 v[92:95], v[132:135], v[208:211], v[92:95]
	v_mfma_f32_16x16x32_bf16 v[88:91], v[140:143], v[208:211], v[88:91]
	v_mfma_f32_16x16x32_bf16 v[88:91], v[136:139], v[204:207], v[88:91]
	v_mfma_f32_16x16x32_bf16 v[72:75], v[136:139], v[212:215], v[72:75]
	v_mfma_f32_16x16x32_bf16 v[72:75], v[140:143], v[216:219], v[72:75]
	v_mfma_f32_16x16x32_bf16 v[76:79], v[132:135], v[216:219], v[76:79]
	v_mfma_f32_16x16x32_bf16 v[76:79], v[128:131], v[212:215], v[76:79]
	s_setprio 0
	s_setprio 1
	v_mfma_f32_16x16x32_bf16 v[116:119], v[144:147], v[180:183], v[116:119]
	v_mfma_f32_16x16x32_bf16 v[116:119], v[148:151], v[192:195], v[116:119]
	v_mfma_f32_16x16x32_bf16 v[112:115], v[176:179], v[192:195], v[112:115]
	v_mfma_f32_16x16x32_bf16 v[112:115], v[172:175], v[180:183], v[112:115]
	v_mfma_f32_16x16x32_bf16 v[96:99], v[172:175], v[196:199], v[96:99]
	v_mfma_f32_16x16x32_bf16 v[96:99], v[176:179], v[200:203], v[96:99]
	v_mfma_f32_16x16x32_bf16 v[100:103], v[148:151], v[200:203], v[100:103]
	v_mfma_f32_16x16x32_bf16 v[100:103], v[144:147], v[196:199], v[100:103]
	v_mfma_f32_16x16x32_bf16 v[84:87], v[144:147], v[204:207], v[84:87]
	v_mfma_f32_16x16x32_bf16 v[84:87], v[148:151], v[208:211], v[84:87]
	v_mfma_f32_16x16x32_bf16 v[80:83], v[176:179], v[208:211], v[80:83]
	v_mfma_f32_16x16x32_bf16 v[80:83], v[172:175], v[204:207], v[80:83]
	v_mfma_f32_16x16x32_bf16 v[64:67], v[172:175], v[212:215], v[64:67]
	v_mfma_f32_16x16x32_bf16 v[64:67], v[176:179], v[216:219], v[64:67]
	v_mfma_f32_16x16x32_bf16 v[68:71], v[148:151], v[216:219], v[68:71]
	v_mfma_f32_16x16x32_bf16 v[68:71], v[144:147], v[212:215], v[68:71]
	s_setprio 0
	s_barrier
	s_add_i32 s48, s75, s58
	v_lshl_add_u64 v[220:221], v[220:221], 0, s[22:23]
	s_mov_b32 m0, s48
	ds_read_b128 v[180:183], v190 offset:49152
	ds_read_b128 v[192:195], v190 offset:50176
	ds_read_b128 v[196:199], v190 offset:51200
	ds_read_b128 v[200:203], v190 offset:52224
	ds_read_b128 v[204:207], v190 offset:53248
	ds_read_b128 v[208:211], v190 offset:54272
	ds_read_b128 v[212:215], v190 offset:55296
	ds_read_b128 v[216:219], v190 offset:56320
	global_load_lds_dwordx4 v[220:221], off
	s_add_i32 m0, s48, 0x2000
	s_add_u32 s48, s52, 0xb0080
	v_lshl_add_u64 v[220:221], v[222:223], 0, s[22:23]
	s_addc_u32 s49, s53, 0
	s_add_i32 s52, s76, s58
	global_load_lds_dwordx4 v[220:221], off
	v_lshl_add_u64 v[220:221], s[48:49], 0, v[154:155]
	s_mov_b32 m0, s52
	s_nop 0
	global_load_lds_dwordx4 v[220:221], off
	v_lshl_add_u64 v[220:221], s[48:49], 0, v[162:163]
	s_add_i32 m0, s52, 0x2000
	s_nop 0
	global_load_lds_dwordx4 v[220:221], off
	v_lshl_add_u64 v[220:221], v[224:225], 0, s[22:23]
	s_mov_b32 m0, s3
	s_nop 0
	global_load_lds_dwordx4 v[220:221], off
	v_lshl_add_u64 v[220:221], v[226:227], 0, s[22:23]
	s_mov_b32 m0, s64
	s_nop 0
	global_load_lds_dwordx4 v[220:221], off
	s_waitcnt vmcnt(8)
	s_waitcnt lgkmcnt(0)
	s_barrier
	s_setprio 1
	s_waitcnt lgkmcnt(0)
	v_mfma_f32_16x16x32_bf16 v[60:63], v[128:131], v[180:183], v[60:63]
	v_mfma_f32_16x16x32_bf16 v[60:63], v[132:135], v[192:195], v[60:63]
	v_mfma_f32_16x16x32_bf16 v[56:59], v[140:143], v[192:195], v[56:59]
	v_mfma_f32_16x16x32_bf16 v[56:59], v[136:139], v[180:183], v[56:59]
	v_mfma_f32_16x16x32_bf16 v[40:43], v[136:139], v[196:199], v[40:43]
	v_mfma_f32_16x16x32_bf16 v[40:43], v[140:143], v[200:203], v[40:43]
	v_mfma_f32_16x16x32_bf16 v[44:47], v[132:135], v[200:203], v[44:47]
	v_mfma_f32_16x16x32_bf16 v[44:47], v[128:131], v[196:199], v[44:47]
	v_mfma_f32_16x16x32_bf16 v[28:31], v[128:131], v[204:207], v[28:31]
	v_mfma_f32_16x16x32_bf16 v[28:31], v[132:135], v[208:211], v[28:31]
	v_mfma_f32_16x16x32_bf16 v[24:27], v[140:143], v[208:211], v[24:27]
	v_mfma_f32_16x16x32_bf16 v[24:27], v[136:139], v[204:207], v[24:27]
	v_mfma_f32_16x16x32_bf16 v[8:11], v[136:139], v[212:215], v[8:11]
	v_mfma_f32_16x16x32_bf16 v[8:11], v[140:143], v[216:219], v[8:11]
	v_mfma_f32_16x16x32_bf16 v[12:15], v[132:135], v[216:219], v[12:15]
	v_mfma_f32_16x16x32_bf16 v[12:15], v[128:131], v[212:215], v[12:15]
	s_setprio 0
	s_setprio 1
	v_mfma_f32_16x16x32_bf16 v[52:55], v[144:147], v[180:183], v[52:55]
	v_mfma_f32_16x16x32_bf16 v[52:55], v[148:151], v[192:195], v[52:55]
	v_mfma_f32_16x16x32_bf16 v[48:51], v[176:179], v[192:195], v[48:51]
	v_mfma_f32_16x16x32_bf16 v[48:51], v[172:175], v[180:183], v[48:51]
	v_mfma_f32_16x16x32_bf16 v[32:35], v[172:175], v[196:199], v[32:35]
	v_mfma_f32_16x16x32_bf16 v[32:35], v[176:179], v[200:203], v[32:35]
	v_mfma_f32_16x16x32_bf16 v[36:39], v[148:151], v[200:203], v[36:39]
	v_mfma_f32_16x16x32_bf16 v[36:39], v[144:147], v[196:199], v[36:39]
	v_mfma_f32_16x16x32_bf16 v[20:23], v[144:147], v[204:207], v[20:23]
	v_mfma_f32_16x16x32_bf16 v[20:23], v[148:151], v[208:211], v[20:23]
	v_mfma_f32_16x16x32_bf16 v[16:19], v[176:179], v[208:211], v[16:19]
	v_mfma_f32_16x16x32_bf16 v[16:19], v[172:175], v[204:207], v[16:19]
	v_mfma_f32_16x16x32_bf16 v[0:3], v[172:175], v[212:215], v[0:3]
	v_mfma_f32_16x16x32_bf16 v[0:3], v[176:179], v[216:219], v[0:3]
	v_mfma_f32_16x16x32_bf16 v[4:7], v[148:151], v[216:219], v[4:7]
	v_mfma_f32_16x16x32_bf16 v[4:7], v[144:147], v[212:215], v[4:7]
	s_setprio 0
	s_barrier
	s_add_i32 s74, s74, 2
	s_add_u32 s72, s72, 0x100
	s_addc_u32 s73, s73, 0
	s_cmp_gt_u32 s74, 41
	s_mov_b64 s[48:49], s[50:51]
	s_branch .LBB0_1181
.Lfa_11:
	ds_read_b128 v[128:131], v188
	ds_read_b128 v[132:135], v188 offset:1024
	ds_read_b128 v[136:139], v188 offset:2048
	ds_read_b128 v[140:143], v188 offset:3072
	ds_read_b128 v[144:147], v189
	ds_read_b128 v[148:151], v189 offset:1024
	ds_read_b128 v[172:175], v189 offset:2048
	ds_read_b128 v[176:179], v189 offset:3072
	s_add_u32 s50, s48, 0x100
	s_addc_u32 s51, s49, 0
	s_cmp_eq_u32 s74, 40
	s_cselect_b32 s55, s11, s51
	s_cselect_b32 s54, s10, s50
	s_cselect_b32 s53, s47, s73
	s_cselect_b32 s52, s46, s72
	v_lshl_add_u64 v[220:221], s[48:49], 0, v[166:167]
	s_add_i32 m0, s59, 0xc000
	ds_read_b128 v[180:183], v190
	ds_read_b128 v[192:195], v190 offset:1024
	ds_read_b128 v[196:199], v190 offset:2048
	ds_read_b128 v[200:203], v190 offset:3072
	ds_read_b128 v[204:207], v190 offset:4096
	ds_read_b128 v[208:211], v190 offset:5120
	ds_read_b128 v[212:215], v190 offset:6144
	ds_read_b128 v[216:219], v190 offset:7168
	global_load_lds_dwordx4 v[220:221], off
	v_lshl_add_u64 v[220:221], s[48:49], 0, v[164:165]
	s_add_i32 m0, s59, 0xe000
	s_nop 0
	global_load_lds_dwordx4 v[220:221], off
	s_waitcnt vmcnt(8)
	s_waitcnt lgkmcnt(0)
	s_barrier
	s_setprio 1
	s_waitcnt lgkmcnt(0)
	v_mfma_f32_16x16x32_bf16 v[124:127], v[128:131], v[180:183], 0
	v_mfma_f32_16x16x32_bf16 v[120:123], v[136:139], v[180:183], 0
	v_mfma_f32_16x16x32_bf16 v[108:111], v[128:131], v[196:199], 0
	v_mfma_f32_16x16x32_bf16 v[104:107], v[136:139], v[196:199], 0
	v_mfma_f32_16x16x32_bf16 v[92:95], v[128:131], v[204:207], 0
	v_mfma_f32_16x16x32_bf16 v[88:91], v[136:139], v[204:207], 0
	v_mfma_f32_16x16x32_bf16 v[76:79], v[128:131], v[212:215], 0
	v_mfma_f32_16x16x32_bf16 v[72:75], v[136:139], v[212:215], 0
	v_mfma_f32_16x16x32_bf16 v[124:127], v[132:135], v[192:195], v[124:127]
	v_mfma_f32_16x16x32_bf16 v[120:123], v[140:143], v[192:195], v[120:123]
	v_mfma_f32_16x16x32_bf16 v[108:111], v[132:135], v[200:203], v[108:111]
	v_mfma_f32_16x16x32_bf16 v[104:107], v[140:143], v[200:203], v[104:107]
	v_mfma_f32_16x16x32_bf16 v[92:95], v[132:135], v[208:211], v[92:95]
	v_mfma_f32_16x16x32_bf16 v[88:91], v[140:143], v[208:211], v[88:91]
	v_mfma_f32_16x16x32_bf16 v[76:79], v[132:135], v[216:219], v[76:79]
	v_mfma_f32_16x16x32_bf16 v[72:75], v[140:143], v[216:219], v[72:75]
	s_setprio 0
	s_setprio 1
	v_mfma_f32_16x16x32_bf16 v[116:119], v[144:147], v[180:183], 0
	v_mfma_f32_16x16x32_bf16 v[112:115], v[172:175], v[180:183], 0
	v_mfma_f32_16x16x32_bf16 v[100:103], v[144:147], v[196:199], 0
	v_mfma_f32_16x16x32_bf16 v[96:99], v[172:175], v[196:199], 0
	v_mfma_f32_16x16x32_bf16 v[84:87], v[144:147], v[204:207], 0
	v_mfma_f32_16x16x32_bf16 v[80:83], v[172:175], v[204:207], 0
	v_mfma_f32_16x16x32_bf16 v[68:71], v[144:147], v[212:215], 0
	v_mfma_f32_16x16x32_bf16 v[64:67], v[172:175], v[212:215], 0
	v_mfma_f32_16x16x32_bf16 v[116:119], v[148:151], v[192:195], v[116:119]
	v_mfma_f32_16x16x32_bf16 v[112:115], v[176:179], v[192:195], v[112:115]
	v_mfma_f32_16x16x32_bf16 v[100:103], v[148:151], v[200:203], v[100:103]
	v_mfma_f32_16x16x32_bf16 v[96:99], v[176:179], v[200:203], v[96:99]
	v_mfma_f32_16x16x32_bf16 v[84:87], v[148:151], v[208:211], v[84:87]
	v_mfma_f32_16x16x32_bf16 v[80:83], v[176:179], v[208:211], v[80:83]
	v_mfma_f32_16x16x32_bf16 v[68:71], v[148:151], v[216:219], v[68:71]
	v_mfma_f32_16x16x32_bf16 v[64:67], v[176:179], v[216:219], v[64:67]
	s_setprio 0
	s_barrier
	s_add_i32 s48, s68, s58
	v_lshl_add_u64 v[220:221], s[52:53], 0, v[154:155]
	s_mov_b32 m0, s48
	ds_read_b128 v[180:183], v190 offset:16384
	ds_read_b128 v[192:195], v190 offset:17408
	ds_read_b128 v[196:199], v190 offset:18432
	ds_read_b128 v[200:203], v190 offset:19456
	ds_read_b128 v[204:207], v190 offset:20480
	ds_read_b128 v[208:211], v190 offset:21504
	ds_read_b128 v[212:215], v190 offset:22528
	ds_read_b128 v[216:219], v190 offset:23552
	global_load_lds_dwordx4 v[220:221], off
	s_add_i32 m0, s48, 0x2000
	s_add_u32 s48, s52, 0xb0000
	v_lshl_add_u64 v[222:223], s[52:53], 0, v[162:163]
	s_addc_u32 s49, s53, 0
	s_add_i32 s75, s69, s58
	global_load_lds_dwordx4 v[222:223], off
	v_lshl_add_u64 v[224:225], s[48:49], 0, v[154:155]
	s_mov_b32 m0, s75
	v_lshl_add_u64 v[226:227], s[54:55], 0, v[160:161]
	global_load_lds_dwordx4 v[224:225], off
	v_lshl_add_u64 v[224:225], s[48:49], 0, v[162:163]
	s_add_i32 m0, s75, 0x2000
	s_nop 0
	global_load_lds_dwordx4 v[224:225], off
	v_lshl_add_u64 v[224:225], s[54:55], 0, v[152:153]
	s_mov_b32 m0, s59
	s_nop 0
	global_load_lds_dwordx4 v[224:225], off
	s_mov_b32 m0, s60
	s_nop 0
	global_load_lds_dwordx4 v[226:227], off
	s_waitcnt vmcnt(8)
	s_waitcnt lgkmcnt(0)
	s_barrier
	s_setprio 1
	s_waitcnt lgkmcnt(0)
	v_mfma_f32_16x16x32_bf16 v[60:63], v[128:131], v[180:183], 0
	v_mfma_f32_16x16x32_bf16 v[56:59], v[136:139], v[180:183], 0
	v_mfma_f32_16x16x32_bf16 v[44:47], v[128:131], v[196:199], 0
	v_mfma_f32_16x16x32_bf16 v[40:43], v[136:139], v[196:199], 0
	v_mfma_f32_16x16x32_bf16 v[28:31], v[128:131], v[204:207], 0
	v_mfma_f32_16x16x32_bf16 v[24:27], v[136:139], v[204:207], 0
	v_mfma_f32_16x16x32_bf16 v[12:15], v[128:131], v[212:215], 0
	v_mfma_f32_16x16x32_bf16 v[8:11], v[136:139], v[212:215], 0
	v_mfma_f32_16x16x32_bf16 v[60:63], v[132:135], v[192:195], v[60:63]
	v_mfma_f32_16x16x32_bf16 v[56:59], v[140:143], v[192:195], v[56:59]
	v_mfma_f32_16x16x32_bf16 v[44:47], v[132:135], v[200:203], v[44:47]
	v_mfma_f32_16x16x32_bf16 v[40:43], v[140:143], v[200:203], v[40:43]
	v_mfma_f32_16x16x32_bf16 v[28:31], v[132:135], v[208:211], v[28:31]
	v_mfma_f32_16x16x32_bf16 v[24:27], v[140:143], v[208:211], v[24:27]
	v_mfma_f32_16x16x32_bf16 v[12:15], v[132:135], v[216:219], v[12:15]
	v_mfma_f32_16x16x32_bf16 v[8:11], v[140:143], v[216:219], v[8:11]
	s_setprio 0
	s_setprio 1
	v_mfma_f32_16x16x32_bf16 v[52:55], v[144:147], v[180:183], 0
	v_mfma_f32_16x16x32_bf16 v[48:51], v[172:175], v[180:183], 0
	v_mfma_f32_16x16x32_bf16 v[36:39], v[144:147], v[196:199], 0
	v_mfma_f32_16x16x32_bf16 v[32:35], v[172:175], v[196:199], 0
	v_mfma_f32_16x16x32_bf16 v[20:23], v[144:147], v[204:207], 0
	v_mfma_f32_16x16x32_bf16 v[16:19], v[172:175], v[204:207], 0
	v_mfma_f32_16x16x32_bf16 v[4:7], v[144:147], v[212:215], 0
	v_mfma_f32_16x16x32_bf16 v[0:3], v[172:175], v[212:215], 0
	v_mfma_f32_16x16x32_bf16 v[52:55], v[148:151], v[192:195], v[52:55]
	v_mfma_f32_16x16x32_bf16 v[48:51], v[176:179], v[192:195], v[48:51]
	v_mfma_f32_16x16x32_bf16 v[36:39], v[148:151], v[200:203], v[36:39]
	v_mfma_f32_16x16x32_bf16 v[32:35], v[176:179], v[200:203], v[32:35]
	v_mfma_f32_16x16x32_bf16 v[20:23], v[148:151], v[208:211], v[20:23]
	v_mfma_f32_16x16x32_bf16 v[16:19], v[176:179], v[208:211], v[16:19]
	v_mfma_f32_16x16x32_bf16 v[4:7], v[148:151], v[216:219], v[4:7]
	v_mfma_f32_16x16x32_bf16 v[0:3], v[176:179], v[216:219], v[0:3]
	s_setprio 0
	s_barrier
	s_add_i32 s75, 0, 0x18000
	s_add_i32 s76, 0, 0x1c000
	v_add_u32_e32 v140, s75, v185
	v_add_u32_e32 v176, s76, v185
	ds_read_b128 v[128:131], v140
	ds_read_b128 v[132:135], v140 offset:1024
	ds_read_b128 v[136:139], v140 offset:2048
	ds_read_b128 v[140:143], v140 offset:3072
	ds_read_b128 v[144:147], v176
	ds_read_b128 v[148:151], v176 offset:1024
	ds_read_b128 v[172:175], v176 offset:2048
	ds_read_b128 v[176:179], v176 offset:3072
	s_add_u32 s48, s54, 0xb0000
	s_addc_u32 s49, s55, 0
	s_mov_b32 m0, s61
	v_lshl_add_u64 v[228:229], s[48:49], 0, v[152:153]
	ds_read_b128 v[180:183], v190 offset:32768
	ds_read_b128 v[192:195], v190 offset:33792
	ds_read_b128 v[196:199], v190 offset:34816
	ds_read_b128 v[200:203], v190 offset:35840
	ds_read_b128 v[204:207], v190 offset:36864
	ds_read_b128 v[208:211], v190 offset:37888
	ds_read_b128 v[212:215], v190 offset:38912
	ds_read_b128 v[216:219], v190 offset:39936
	global_load_lds_dwordx4 v[228:229], off
	v_lshl_add_u64 v[228:229], s[48:49], 0, v[160:161]
	s_mov_b32 m0, s62
	s_nop 0
	global_load_lds_dwordx4 v[228:229], off
	s_waitcnt vmcnt(8)
	s_waitcnt lgkmcnt(0)
	s_barrier
	s_setprio 1
	s_waitcnt lgkmcnt(0)
	v_mfma_f32_16x16x32_bf16 v[124:127], v[128:131], v[180:183], v[124:127]
	v_mfma_f32_16x16x32_bf16 v[124:127], v[132:135], v[192:195], v[124:127]
	v_mfma_f32_16x16x32_bf16 v[120:123], v[140:143], v[192:195], v[120:123]
	v_mfma_f32_16x16x32_bf16 v[120:123], v[136:139], v[180:183], v[120:123]
	v_mfma_f32_16x16x32_bf16 v[104:107], v[136:139], v[196:199], v[104:107]
	v_mfma_f32_16x16x32_bf16 v[104:107], v[140:143], v[200:203], v[104:107]
	v_mfma_f32_16x16x32_bf16 v[108:111], v[132:135], v[200:203], v[108:111]
	v_mfma_f32_16x16x32_bf16 v[108:111], v[128:131], v[196:199], v[108:111]
	v_mfma_f32_16x16x32_bf16 v[92:95], v[128:131], v[204:207], v[92:95]
	v_mfma_f32_16x16x32_bf16 v[92:95], v[132:135], v[208:211], v[92:95]
	v_mfma_f32_16x16x32_bf16 v[88:91], v[140:143], v[208:211], v[88:91]
	v_mfma_f32_16x16x32_bf16 v[88:91], v[136:139], v[204:207], v[88:91]
	v_mfma_f32_16x16x32_bf16 v[72:75], v[136:139], v[212:215], v[72:75]
	v_mfma_f32_16x16x32_bf16 v[72:75], v[140:143], v[216:219], v[72:75]
	v_mfma_f32_16x16x32_bf16 v[76:79], v[132:135], v[216:219], v[76:79]
	v_mfma_f32_16x16x32_bf16 v[76:79], v[128:131], v[212:215], v[76:79]
	s_setprio 0
	s_setprio 1
	v_mfma_f32_16x16x32_bf16 v[116:119], v[144:147], v[180:183], v[116:119]
	v_mfma_f32_16x16x32_bf16 v[116:119], v[148:151], v[192:195], v[116:119]
	v_mfma_f32_16x16x32_bf16 v[112:115], v[176:179], v[192:195], v[112:115]
	v_mfma_f32_16x16x32_bf16 v[112:115], v[172:175], v[180:183], v[112:115]
	v_mfma_f32_16x16x32_bf16 v[96:99], v[172:175], v[196:199], v[96:99]
	v_mfma_f32_16x16x32_bf16 v[96:99], v[176:179], v[200:203], v[96:99]
	v_mfma_f32_16x16x32_bf16 v[100:103], v[148:151], v[200:203], v[100:103]
	v_mfma_f32_16x16x32_bf16 v[100:103], v[144:147], v[196:199], v[100:103]
	v_mfma_f32_16x16x32_bf16 v[84:87], v[144:147], v[204:207], v[84:87]
	v_mfma_f32_16x16x32_bf16 v[84:87], v[148:151], v[208:211], v[84:87]
	v_mfma_f32_16x16x32_bf16 v[80:83], v[176:179], v[208:211], v[80:83]
	v_mfma_f32_16x16x32_bf16 v[80:83], v[172:175], v[204:207], v[80:83]
	v_mfma_f32_16x16x32_bf16 v[64:67], v[172:175], v[212:215], v[64:67]
	v_mfma_f32_16x16x32_bf16 v[64:67], v[176:179], v[216:219], v[64:67]
	v_mfma_f32_16x16x32_bf16 v[68:71], v[148:151], v[216:219], v[68:71]
	v_mfma_f32_16x16x32_bf16 v[68:71], v[144:147], v[212:215], v[68:71]
	s_setprio 0
	s_barrier
	s_add_i32 s48, s75, s58
	v_lshl_add_u64 v[220:221], v[220:221], 0, s[22:23]
	s_mov_b32 m0, s48
	ds_read_b128 v[180:183], v190 offset:49152
	ds_read_b128 v[192:195], v190 offset:50176
	ds_read_b128 v[196:199], v190 offset:51200
	ds_read_b128 v[200:203], v190 offset:52224
	ds_read_b128 v[204:207], v190 offset:53248
	ds_read_b128 v[208:211], v190 offset:54272
	ds_read_b128 v[212:215], v190 offset:55296
	ds_read_b128 v[216:219], v190 offset:56320
	global_load_lds_dwordx4 v[220:221], off
	s_add_i32 m0, s48, 0x2000
	s_add_u32 s48, s52, 0xb0080
	v_lshl_add_u64 v[220:221], v[222:223], 0, s[22:23]
	s_addc_u32 s49, s53, 0
	s_add_i32 s52, s76, s58
	global_load_lds_dwordx4 v[220:221], off
	v_lshl_add_u64 v[220:221], s[48:49], 0, v[154:155]
	s_mov_b32 m0, s52
	s_nop 0
	global_load_lds_dwordx4 v[220:221], off
	v_lshl_add_u64 v[220:221], s[48:49], 0, v[162:163]
	s_add_i32 m0, s52, 0x2000
	s_nop 0
	global_load_lds_dwordx4 v[220:221], off
	v_lshl_add_u64 v[220:221], v[224:225], 0, s[22:23]
	s_mov_b32 m0, s3
	s_nop 0
	global_load_lds_dwordx4 v[220:221], off
	v_lshl_add_u64 v[220:221], v[226:227], 0, s[22:23]
	s_mov_b32 m0, s64
	s_nop 0
	global_load_lds_dwordx4 v[220:221], off
	s_waitcnt vmcnt(8)
	s_waitcnt lgkmcnt(0)
	s_barrier
	s_setprio 1
	s_waitcnt lgkmcnt(0)
	v_mfma_f32_16x16x32_bf16 v[60:63], v[128:131], v[180:183], v[60:63]
	v_mfma_f32_16x16x32_bf16 v[60:63], v[132:135], v[192:195], v[60:63]
	v_mfma_f32_16x16x32_bf16 v[56:59], v[140:143], v[192:195], v[56:59]
	v_mfma_f32_16x16x32_bf16 v[56:59], v[136:139], v[180:183], v[56:59]
	v_mfma_f32_16x16x32_bf16 v[40:43], v[136:139], v[196:199], v[40:43]
	v_mfma_f32_16x16x32_bf16 v[40:43], v[140:143], v[200:203], v[40:43]
	v_mfma_f32_16x16x32_bf16 v[44:47], v[132:135], v[200:203], v[44:47]
	v_mfma_f32_16x16x32_bf16 v[44:47], v[128:131], v[196:199], v[44:47]
	v_mfma_f32_16x16x32_bf16 v[28:31], v[128:131], v[204:207], v[28:31]
	v_mfma_f32_16x16x32_bf16 v[28:31], v[132:135], v[208:211], v[28:31]
	v_mfma_f32_16x16x32_bf16 v[24:27], v[140:143], v[208:211], v[24:27]
	v_mfma_f32_16x16x32_bf16 v[24:27], v[136:139], v[204:207], v[24:27]
	v_mfma_f32_16x16x32_bf16 v[8:11], v[136:139], v[212:215], v[8:11]
	v_mfma_f32_16x16x32_bf16 v[8:11], v[140:143], v[216:219], v[8:11]
	v_mfma_f32_16x16x32_bf16 v[12:15], v[132:135], v[216:219], v[12:15]
	v_mfma_f32_16x16x32_bf16 v[12:15], v[128:131], v[212:215], v[12:15]
	s_setprio 0
	s_setprio 1
	v_mfma_f32_16x16x32_bf16 v[52:55], v[144:147], v[180:183], v[52:55]
	v_mfma_f32_16x16x32_bf16 v[52:55], v[148:151], v[192:195], v[52:55]
	v_mfma_f32_16x16x32_bf16 v[48:51], v[176:179], v[192:195], v[48:51]
	v_mfma_f32_16x16x32_bf16 v[48:51], v[172:175], v[180:183], v[48:51]
	v_mfma_f32_16x16x32_bf16 v[32:35], v[172:175], v[196:199], v[32:35]
	v_mfma_f32_16x16x32_bf16 v[32:35], v[176:179], v[200:203], v[32:35]
	v_mfma_f32_16x16x32_bf16 v[36:39], v[148:151], v[200:203], v[36:39]
	v_mfma_f32_16x16x32_bf16 v[36:39], v[144:147], v[196:199], v[36:39]
	v_mfma_f32_16x16x32_bf16 v[20:23], v[144:147], v[204:207], v[20:23]
	v_mfma_f32_16x16x32_bf16 v[20:23], v[148:151], v[208:211], v[20:23]
	v_mfma_f32_16x16x32_bf16 v[16:19], v[176:179], v[208:211], v[16:19]
	v_mfma_f32_16x16x32_bf16 v[16:19], v[172:175], v[204:207], v[16:19]
	v_mfma_f32_16x16x32_bf16 v[0:3], v[172:175], v[212:215], v[0:3]
	v_mfma_f32_16x16x32_bf16 v[0:3], v[176:179], v[216:219], v[0:3]
	v_mfma_f32_16x16x32_bf16 v[4:7], v[148:151], v[216:219], v[4:7]
	v_mfma_f32_16x16x32_bf16 v[4:7], v[144:147], v[212:215], v[4:7]
	s_setprio 0
	s_barrier
	s_add_i32 s74, s74, 2
	s_add_u32 s72, s72, 0x100
	s_addc_u32 s73, s73, 0
	s_cmp_gt_u32 s74, 41
	s_mov_b64 s[48:49], s[50:51]
.LBB0_1181:
	ds_read_b128 v[128:131], v188
	ds_read_b128 v[132:135], v188 offset:1024
	ds_read_b128 v[136:139], v188 offset:2048
	ds_read_b128 v[140:143], v188 offset:3072
	ds_read_b128 v[144:147], v189
	ds_read_b128 v[148:151], v189 offset:1024
	ds_read_b128 v[172:175], v189 offset:2048
	ds_read_b128 v[176:179], v189 offset:3072
	s_add_u32 s50, s48, 0x100
	s_addc_u32 s51, s49, 0
	s_cmp_eq_u32 s74, 40
	s_cselect_b32 s55, s11, s51
	s_cselect_b32 s54, s10, s50
	s_cselect_b32 s53, s47, s73
	s_cselect_b32 s52, s46, s72
	v_lshl_add_u64 v[220:221], s[48:49], 0, v[166:167]
	s_add_i32 m0, s59, 0xc000
	ds_read_b128 v[180:183], v190
	ds_read_b128 v[192:195], v190 offset:1024
	ds_read_b128 v[196:199], v190 offset:2048
	ds_read_b128 v[200:203], v190 offset:3072
	ds_read_b128 v[204:207], v190 offset:4096
	ds_read_b128 v[208:211], v190 offset:5120
	ds_read_b128 v[212:215], v190 offset:6144
	ds_read_b128 v[216:219], v190 offset:7168
	global_load_lds_dwordx4 v[220:221], off
	v_lshl_add_u64 v[220:221], s[48:49], 0, v[164:165]
	s_add_i32 m0, s59, 0xe000
	s_nop 0
	global_load_lds_dwordx4 v[220:221], off
	s_waitcnt vmcnt(8)
	s_waitcnt lgkmcnt(0)
	s_barrier
	s_setprio 1
	s_waitcnt lgkmcnt(0)
	v_mfma_f32_16x16x32_bf16 v[124:127], v[128:131], v[180:183], v[124:127]
	v_mfma_f32_16x16x32_bf16 v[124:127], v[132:135], v[192:195], v[124:127]
	v_mfma_f32_16x16x32_bf16 v[120:123], v[140:143], v[192:195], v[120:123]
	v_mfma_f32_16x16x32_bf16 v[120:123], v[136:139], v[180:183], v[120:123]
	v_mfma_f32_16x16x32_bf16 v[104:107], v[136:139], v[196:199], v[104:107]
	v_mfma_f32_16x16x32_bf16 v[104:107], v[140:143], v[200:203], v[104:107]
	v_mfma_f32_16x16x32_bf16 v[108:111], v[132:135], v[200:203], v[108:111]
	v_mfma_f32_16x16x32_bf16 v[108:111], v[128:131], v[196:199], v[108:111]
	v_mfma_f32_16x16x32_bf16 v[92:95], v[128:131], v[204:207], v[92:95]
	v_mfma_f32_16x16x32_bf16 v[92:95], v[132:135], v[208:211], v[92:95]
	v_mfma_f32_16x16x32_bf16 v[88:91], v[140:143], v[208:211], v[88:91]
	v_mfma_f32_16x16x32_bf16 v[88:91], v[136:139], v[204:207], v[88:91]
	v_mfma_f32_16x16x32_bf16 v[72:75], v[136:139], v[212:215], v[72:75]
	v_mfma_f32_16x16x32_bf16 v[72:75], v[140:143], v[216:219], v[72:75]
	v_mfma_f32_16x16x32_bf16 v[76:79], v[132:135], v[216:219], v[76:79]
	v_mfma_f32_16x16x32_bf16 v[76:79], v[128:131], v[212:215], v[76:79]
	s_setprio 0
	s_setprio 1
	v_mfma_f32_16x16x32_bf16 v[116:119], v[144:147], v[180:183], v[116:119]
	v_mfma_f32_16x16x32_bf16 v[116:119], v[148:151], v[192:195], v[116:119]
	v_mfma_f32_16x16x32_bf16 v[112:115], v[176:179], v[192:195], v[112:115]
	v_mfma_f32_16x16x32_bf16 v[112:115], v[172:175], v[180:183], v[112:115]
	v_mfma_f32_16x16x32_bf16 v[96:99], v[172:175], v[196:199], v[96:99]
	v_mfma_f32_16x16x32_bf16 v[96:99], v[176:179], v[200:203], v[96:99]
	v_mfma_f32_16x16x32_bf16 v[100:103], v[148:151], v[200:203], v[100:103]
	v_mfma_f32_16x16x32_bf16 v[100:103], v[144:147], v[196:199], v[100:103]
	v_mfma_f32_16x16x32_bf16 v[84:87], v[144:147], v[204:207], v[84:87]
	v_mfma_f32_16x16x32_bf16 v[84:87], v[148:151], v[208:211], v[84:87]
	v_mfma_f32_16x16x32_bf16 v[80:83], v[176:179], v[208:211], v[80:83]
	v_mfma_f32_16x16x32_bf16 v[80:83], v[172:175], v[204:207], v[80:83]
	v_mfma_f32_16x16x32_bf16 v[64:67], v[172:175], v[212:215], v[64:67]
	v_mfma_f32_16x16x32_bf16 v[64:67], v[176:179], v[216:219], v[64:67]
	v_mfma_f32_16x16x32_bf16 v[68:71], v[148:151], v[216:219], v[68:71]
	v_mfma_f32_16x16x32_bf16 v[68:71], v[144:147], v[212:215], v[68:71]
	s_setprio 0
	s_barrier
	s_add_i32 s48, s68, s58
	v_lshl_add_u64 v[220:221], s[52:53], 0, v[154:155]
	s_mov_b32 m0, s48
	ds_read_b128 v[180:183], v190 offset:16384
	ds_read_b128 v[192:195], v190 offset:17408
	ds_read_b128 v[196:199], v190 offset:18432
	ds_read_b128 v[200:203], v190 offset:19456
	ds_read_b128 v[204:207], v190 offset:20480
	ds_read_b128 v[208:211], v190 offset:21504
	ds_read_b128 v[212:215], v190 offset:22528
	ds_read_b128 v[216:219], v190 offset:23552
	global_load_lds_dwordx4 v[220:221], off
	s_add_i32 m0, s48, 0x2000
	s_add_u32 s48, s52, 0xb0000
	v_lshl_add_u64 v[222:223], s[52:53], 0, v[162:163]
	s_addc_u32 s49, s53, 0
	s_add_i32 s75, s69, s58
	global_load_lds_dwordx4 v[222:223], off
	v_lshl_add_u64 v[224:225], s[48:49], 0, v[154:155]
	s_mov_b32 m0, s75
	v_lshl_add_u64 v[226:227], s[54:55], 0, v[160:161]
	global_load_lds_dwordx4 v[224:225], off
	v_lshl_add_u64 v[224:225], s[48:49], 0, v[162:163]
	s_add_i32 m0, s75, 0x2000
	s_nop 0
	global_load_lds_dwordx4 v[224:225], off
	v_lshl_add_u64 v[224:225], s[54:55], 0, v[152:153]
	s_mov_b32 m0, s59
	s_nop 0
	global_load_lds_dwordx4 v[224:225], off
	s_mov_b32 m0, s60
	s_nop 0
	global_load_lds_dwordx4 v[226:227], off
	s_waitcnt vmcnt(8)
	s_waitcnt lgkmcnt(0)
	s_barrier
	s_setprio 1
	s_waitcnt lgkmcnt(0)
	v_mfma_f32_16x16x32_bf16 v[60:63], v[128:131], v[180:183], v[60:63]
	v_mfma_f32_16x16x32_bf16 v[60:63], v[132:135], v[192:195], v[60:63]
	v_mfma_f32_16x16x32_bf16 v[56:59], v[140:143], v[192:195], v[56:59]
	v_mfma_f32_16x16x32_bf16 v[56:59], v[136:139], v[180:183], v[56:59]
	v_mfma_f32_16x16x32_bf16 v[40:43], v[136:139], v[196:199], v[40:43]
	v_mfma_f32_16x16x32_bf16 v[40:43], v[140:143], v[200:203], v[40:43]
	v_mfma_f32_16x16x32_bf16 v[44:47], v[132:135], v[200:203], v[44:47]
	v_mfma_f32_16x16x32_bf16 v[44:47], v[128:131], v[196:199], v[44:47]
	v_mfma_f32_16x16x32_bf16 v[28:31], v[128:131], v[204:207], v[28:31]
	v_mfma_f32_16x16x32_bf16 v[28:31], v[132:135], v[208:211], v[28:31]
	v_mfma_f32_16x16x32_bf16 v[24:27], v[140:143], v[208:211], v[24:27]
	v_mfma_f32_16x16x32_bf16 v[24:27], v[136:139], v[204:207], v[24:27]
	v_mfma_f32_16x16x32_bf16 v[8:11], v[136:139], v[212:215], v[8:11]
	v_mfma_f32_16x16x32_bf16 v[8:11], v[140:143], v[216:219], v[8:11]
	v_mfma_f32_16x16x32_bf16 v[12:15], v[132:135], v[216:219], v[12:15]
	v_mfma_f32_16x16x32_bf16 v[12:15], v[128:131], v[212:215], v[12:15]
	s_setprio 0
	s_setprio 1
	v_mfma_f32_16x16x32_bf16 v[52:55], v[144:147], v[180:183], v[52:55]
	v_mfma_f32_16x16x32_bf16 v[52:55], v[148:151], v[192:195], v[52:55]
	v_mfma_f32_16x16x32_bf16 v[48:51], v[176:179], v[192:195], v[48:51]
	v_mfma_f32_16x16x32_bf16 v[48:51], v[172:175], v[180:183], v[48:51]
	v_mfma_f32_16x16x32_bf16 v[32:35], v[172:175], v[196:199], v[32:35]
	v_mfma_f32_16x16x32_bf16 v[32:35], v[176:179], v[200:203], v[32:35]
	v_mfma_f32_16x16x32_bf16 v[36:39], v[148:151], v[200:203], v[36:39]
	v_mfma_f32_16x16x32_bf16 v[36:39], v[144:147], v[196:199], v[36:39]
	v_mfma_f32_16x16x32_bf16 v[20:23], v[144:147], v[204:207], v[20:23]
	v_mfma_f32_16x16x32_bf16 v[20:23], v[148:151], v[208:211], v[20:23]
	v_mfma_f32_16x16x32_bf16 v[16:19], v[176:179], v[208:211], v[16:19]
	v_mfma_f32_16x16x32_bf16 v[16:19], v[172:175], v[204:207], v[16:19]
	v_mfma_f32_16x16x32_bf16 v[0:3], v[172:175], v[212:215], v[0:3]
	v_mfma_f32_16x16x32_bf16 v[0:3], v[176:179], v[216:219], v[0:3]
	v_mfma_f32_16x16x32_bf16 v[4:7], v[148:151], v[216:219], v[4:7]
	v_mfma_f32_16x16x32_bf16 v[4:7], v[144:147], v[212:215], v[4:7]
	s_setprio 0
	s_barrier
	s_add_i32 s75, 0, 0x18000
	s_add_i32 s76, 0, 0x1c000
	v_add_u32_e32 v140, s75, v185
	v_add_u32_e32 v176, s76, v185
	ds_read_b128 v[128:131], v140
	ds_read_b128 v[132:135], v140 offset:1024
	ds_read_b128 v[136:139], v140 offset:2048
	ds_read_b128 v[140:143], v140 offset:3072
	ds_read_b128 v[144:147], v176
	ds_read_b128 v[148:151], v176 offset:1024
	ds_read_b128 v[172:175], v176 offset:2048
	ds_read_b128 v[176:179], v176 offset:3072
	s_add_u32 s48, s54, 0xb0000
	s_addc_u32 s49, s55, 0
	s_mov_b32 m0, s61
	v_lshl_add_u64 v[228:229], s[48:49], 0, v[152:153]
	ds_read_b128 v[180:183], v190 offset:32768
	ds_read_b128 v[192:195], v190 offset:33792
	ds_read_b128 v[196:199], v190 offset:34816
	ds_read_b128 v[200:203], v190 offset:35840
	ds_read_b128 v[204:207], v190 offset:36864
	ds_read_b128 v[208:211], v190 offset:37888
	ds_read_b128 v[212:215], v190 offset:38912
	ds_read_b128 v[216:219], v190 offset:39936
	global_load_lds_dwordx4 v[228:229], off
	v_lshl_add_u64 v[228:229], s[48:49], 0, v[160:161]
	s_mov_b32 m0, s62
	s_nop 0
	global_load_lds_dwordx4 v[228:229], off
	s_waitcnt vmcnt(8)
	s_waitcnt lgkmcnt(0)
	s_barrier
	s_setprio 1
	s_waitcnt lgkmcnt(0)
	v_mfma_f32_16x16x32_bf16 v[124:127], v[128:131], v[180:183], v[124:127]
	v_mfma_f32_16x16x32_bf16 v[124:127], v[132:135], v[192:195], v[124:127]
	v_mfma_f32_16x16x32_bf16 v[120:123], v[140:143], v[192:195], v[120:123]
	v_mfma_f32_16x16x32_bf16 v[120:123], v[136:139], v[180:183], v[120:123]
	v_mfma_f32_16x16x32_bf16 v[104:107], v[136:139], v[196:199], v[104:107]
	v_mfma_f32_16x16x32_bf16 v[104:107], v[140:143], v[200:203], v[104:107]
	v_mfma_f32_16x16x32_bf16 v[108:111], v[132:135], v[200:203], v[108:111]
	v_mfma_f32_16x16x32_bf16 v[108:111], v[128:131], v[196:199], v[108:111]
	v_mfma_f32_16x16x32_bf16 v[92:95], v[128:131], v[204:207], v[92:95]
	v_mfma_f32_16x16x32_bf16 v[92:95], v[132:135], v[208:211], v[92:95]
	v_mfma_f32_16x16x32_bf16 v[88:91], v[140:143], v[208:211], v[88:91]
	v_mfma_f32_16x16x32_bf16 v[88:91], v[136:139], v[204:207], v[88:91]
	v_mfma_f32_16x16x32_bf16 v[72:75], v[136:139], v[212:215], v[72:75]
	v_mfma_f32_16x16x32_bf16 v[72:75], v[140:143], v[216:219], v[72:75]
	v_mfma_f32_16x16x32_bf16 v[76:79], v[132:135], v[216:219], v[76:79]
	v_mfma_f32_16x16x32_bf16 v[76:79], v[128:131], v[212:215], v[76:79]
	s_setprio 0
	s_setprio 1
	v_mfma_f32_16x16x32_bf16 v[116:119], v[144:147], v[180:183], v[116:119]
	v_mfma_f32_16x16x32_bf16 v[116:119], v[148:151], v[192:195], v[116:119]
	v_mfma_f32_16x16x32_bf16 v[112:115], v[176:179], v[192:195], v[112:115]
	v_mfma_f32_16x16x32_bf16 v[112:115], v[172:175], v[180:183], v[112:115]
	v_mfma_f32_16x16x32_bf16 v[96:99], v[172:175], v[196:199], v[96:99]
	v_mfma_f32_16x16x32_bf16 v[96:99], v[176:179], v[200:203], v[96:99]
	v_mfma_f32_16x16x32_bf16 v[100:103], v[148:151], v[200:203], v[100:103]
	v_mfma_f32_16x16x32_bf16 v[100:103], v[144:147], v[196:199], v[100:103]
	v_mfma_f32_16x16x32_bf16 v[84:87], v[144:147], v[204:207], v[84:87]
	v_mfma_f32_16x16x32_bf16 v[84:87], v[148:151], v[208:211], v[84:87]
	v_mfma_f32_16x16x32_bf16 v[80:83], v[176:179], v[208:211], v[80:83]
	v_mfma_f32_16x16x32_bf16 v[80:83], v[172:175], v[204:207], v[80:83]
	v_mfma_f32_16x16x32_bf16 v[64:67], v[172:175], v[212:215], v[64:67]
	v_mfma_f32_16x16x32_bf16 v[64:67], v[176:179], v[216:219], v[64:67]
	v_mfma_f32_16x16x32_bf16 v[68:71], v[148:151], v[216:219], v[68:71]
	v_mfma_f32_16x16x32_bf16 v[68:71], v[144:147], v[212:215], v[68:71]
	s_setprio 0
	s_barrier
	s_add_i32 s48, s75, s58
	v_lshl_add_u64 v[220:221], v[220:221], 0, s[22:23]
	s_mov_b32 m0, s48
	ds_read_b128 v[180:183], v190 offset:49152
	ds_read_b128 v[192:195], v190 offset:50176
	ds_read_b128 v[196:199], v190 offset:51200
	ds_read_b128 v[200:203], v190 offset:52224
	ds_read_b128 v[204:207], v190 offset:53248
	ds_read_b128 v[208:211], v190 offset:54272
	ds_read_b128 v[212:215], v190 offset:55296
	ds_read_b128 v[216:219], v190 offset:56320
	global_load_lds_dwordx4 v[220:221], off
	s_add_i32 m0, s48, 0x2000
	s_add_u32 s48, s52, 0xb0080
	v_lshl_add_u64 v[220:221], v[222:223], 0, s[22:23]
	s_addc_u32 s49, s53, 0
	s_add_i32 s52, s76, s58
	global_load_lds_dwordx4 v[220:221], off
	v_lshl_add_u64 v[220:221], s[48:49], 0, v[154:155]
	s_mov_b32 m0, s52
	s_nop 0
	global_load_lds_dwordx4 v[220:221], off
	v_lshl_add_u64 v[220:221], s[48:49], 0, v[162:163]
	s_add_i32 m0, s52, 0x2000
	s_nop 0
	global_load_lds_dwordx4 v[220:221], off
	v_lshl_add_u64 v[220:221], v[224:225], 0, s[22:23]
	s_mov_b32 m0, s3
	s_nop 0
	global_load_lds_dwordx4 v[220:221], off
	v_lshl_add_u64 v[220:221], v[226:227], 0, s[22:23]
	s_mov_b32 m0, s64
	s_nop 0
	global_load_lds_dwordx4 v[220:221], off
	s_waitcnt vmcnt(8)
	s_waitcnt lgkmcnt(0)
	s_barrier
	s_setprio 1
	s_waitcnt lgkmcnt(0)
	v_mfma_f32_16x16x32_bf16 v[60:63], v[128:131], v[180:183], v[60:63]
	v_mfma_f32_16x16x32_bf16 v[60:63], v[132:135], v[192:195], v[60:63]
	v_mfma_f32_16x16x32_bf16 v[56:59], v[140:143], v[192:195], v[56:59]
	v_mfma_f32_16x16x32_bf16 v[56:59], v[136:139], v[180:183], v[56:59]
	v_mfma_f32_16x16x32_bf16 v[40:43], v[136:139], v[196:199], v[40:43]
	v_mfma_f32_16x16x32_bf16 v[40:43], v[140:143], v[200:203], v[40:43]
	v_mfma_f32_16x16x32_bf16 v[44:47], v[132:135], v[200:203], v[44:47]
	v_mfma_f32_16x16x32_bf16 v[44:47], v[128:131], v[196:199], v[44:47]
	v_mfma_f32_16x16x32_bf16 v[28:31], v[128:131], v[204:207], v[28:31]
	v_mfma_f32_16x16x32_bf16 v[28:31], v[132:135], v[208:211], v[28:31]
	v_mfma_f32_16x16x32_bf16 v[24:27], v[140:143], v[208:211], v[24:27]
	v_mfma_f32_16x16x32_bf16 v[24:27], v[136:139], v[204:207], v[24:27]
	v_mfma_f32_16x16x32_bf16 v[8:11], v[136:139], v[212:215], v[8:11]
	v_mfma_f32_16x16x32_bf16 v[8:11], v[140:143], v[216:219], v[8:11]
	v_mfma_f32_16x16x32_bf16 v[12:15], v[132:135], v[216:219], v[12:15]
	v_mfma_f32_16x16x32_bf16 v[12:15], v[128:131], v[212:215], v[12:15]
	s_setprio 0
	s_setprio 1
	v_mfma_f32_16x16x32_bf16 v[52:55], v[144:147], v[180:183], v[52:55]
	v_mfma_f32_16x16x32_bf16 v[52:55], v[148:151], v[192:195], v[52:55]
	v_mfma_f32_16x16x32_bf16 v[48:51], v[176:179], v[192:195], v[48:51]
	v_mfma_f32_16x16x32_bf16 v[48:51], v[172:175], v[180:183], v[48:51]
	v_mfma_f32_16x16x32_bf16 v[32:35], v[172:175], v[196:199], v[32:35]
	v_mfma_f32_16x16x32_bf16 v[32:35], v[176:179], v[200:203], v[32:35]
	v_mfma_f32_16x16x32_bf16 v[36:39], v[148:151], v[200:203], v[36:39]
	v_mfma_f32_16x16x32_bf16 v[36:39], v[144:147], v[196:199], v[36:39]
	v_mfma_f32_16x16x32_bf16 v[20:23], v[144:147], v[204:207], v[20:23]
	v_mfma_f32_16x16x32_bf16 v[20:23], v[148:151], v[208:211], v[20:23]
	v_mfma_f32_16x16x32_bf16 v[16:19], v[176:179], v[208:211], v[16:19]
	v_mfma_f32_16x16x32_bf16 v[16:19], v[172:175], v[204:207], v[16:19]
	v_mfma_f32_16x16x32_bf16 v[0:3], v[172:175], v[212:215], v[0:3]
	v_mfma_f32_16x16x32_bf16 v[0:3], v[176:179], v[216:219], v[0:3]
	v_mfma_f32_16x16x32_bf16 v[4:7], v[148:151], v[216:219], v[4:7]
	v_mfma_f32_16x16x32_bf16 v[4:7], v[144:147], v[212:215], v[4:7]
	s_setprio 0
	s_barrier
	s_add_i32 s74, s74, 2
	s_add_u32 s72, s72, 0x100
	s_addc_u32 s73, s73, 0
	s_cmp_gt_u32 s74, 41
	s_mov_b64 s[48:49], s[50:51]
	s_cbranch_scc0 .LBB0_1181
	s_and_b64 vcc, exec, s[24:25]
	s_cbranch_vccz .LBB0_1184
	s_barrier
